# speedup vs baseline: 1.0212x; 1.0002x over previous
; DEVI unsigned cvtpk(float lo, float hi) { unsigned r; asm("v_cvt_pk_bf16_f32 %0, %1, %2" : "=v"(r) : "v"(lo), "v"(hi)); return r; }
; DEVI float bflo(unsigned u) { return __uint_as_float(u << 16); }
; DEVI float bfhi(unsigned u) { return __uint_as_float(u & 0xffff0000u); }
; DEVI float geluf_(float x) { return 0.5f * x * (1.f + erff(x * 0.70710678118654752f)); }
; DEVI void lru_p3_phase(const Params& p) {
;     ...
; #pragma unroll
;       for (int t = 0; t < 64; ++t) {
;         const unsigned l = *(const unsigned*)(la + (size_t)t * 1024), bv = *(const unsigned*)(bb + (size_t)t * 1024);
;         h0 = __expf(bflo(l)) * h0 + bflo(bv); h1 = __expf(bfhi(l)) * h1 + bfhi(bv); s0[t] = h0; s1[t] = h1;
;       }
;     }
;     {
;       const bf16_t* la = LA + ((size_t)MT + rbase) * 1024 + ch; const bf16_t* bb = BB + ((size_t)MT + rbase) * 1024 + ch;
;       const float2 h2 = *(const float2*)(CAR + ((size_t)(1 * 2 + b) * NCH64B + posb) * 1024 + ch);
;       float h0 = h2.x, h1 = h2.y;
; #pragma unroll
;       for (int t = 63; t >= 0; --t) {
;         const unsigned l = *(const unsigned*)(la + (size_t)t * 1024), bv = *(const unsigned*)(bb + (size_t)t * 1024);
;         h0 = __expf(bflo(l)) * h0 + bflo(bv); h1 = __expf(bfhi(l)) * h1 + bfhi(bv);
;         const unsigned g = *(const unsigned*)(GX + (size_t)(rbase + t) * 2048 + ch);
;         *(unsigned*)(YG + (size_t)(rbase + t) * 1024 + ch) = cvtpk((s0[t] + h0) * geluf_(bflo(g)), (s1[t] + h1) * geluf_(bfhi(g)));
.LBB0_616:
	s_andn2_saveexec_b64 s[16:17], s[16:17]
	v_mul_f32_e32 v0, v151, v151
	v_fmamk_f32 v153, v0, 0xba1345e1, v217
	v_fmaak_f32 v153, v0, v153, 0xbcdac9b8
	v_fmaak_f32 v153, v0, v153, 0x3de703be
	v_fmaak_f32 v153, v0, v153, 0xbec09330
	v_fmaak_f32 v0, v0, v153, 0x3e0375d0
	v_fma_f32 v153, |v151|, v0, |v151|
	s_or_b64 exec, exec, s[16:17]
	v_lshlrev_b32_e32 v0, 16, v155
	v_mul_f32_e32 v0, 0x3fb8aa3b, v0
	v_exp_f32_e32 v156, v0
	v_lshlrev_b32_e32 v0, 16, v154
	s_mov_b64 s[0:1], 0x4100000
	v_lshl_add_u64 v[12:13], v[12:13], 0, s[0:1]
	v_fmac_f32_e32 v0, v18, v156
	v_and_b32_e32 v18, 0xffff0000, v155
	v_mul_f32_e32 v18, 0x3fb8aa3b, v18
	v_exp_f32_e32 v155, v18
	v_and_b32_e32 v18, 0xffff0000, v154
	v_lshl_add_u64 v[14:15], v[14:15], 0, s[0:1]
	s_mov_b32 s0, 0x1f000
	s_mov_b32 s1, 0
	v_lshl_add_u64 v[198:199], v[12:13], 0, s[0:1]
	v_lshl_add_u64 v[200:201], v[14:15], 0, s[0:1]
	s_add_i32 s0, s14, 62
	s_ashr_i32 s1, s0, 31
	s_lshl_b64 s[0:1], s[0:1], 12
	global_load_dword v166, v[198:199], off
	global_load_dword v167, v[200:201], off
	v_lshl_add_u64 v[202:203], v[8:9], 0, s[0:1]
	global_load_dword v168, v[202:203], off
	s_mov_b32 s0, 0x1e800
	s_mov_b32 s1, 0
	v_lshl_add_u64 v[198:199], v[12:13], 0, s[0:1]
	v_lshl_add_u64 v[200:201], v[14:15], 0, s[0:1]
	s_add_i32 s0, s14, 61
	s_ashr_i32 s1, s0, 31
	s_lshl_b64 s[0:1], s[0:1], 12
	global_load_dword v163, v[198:199], off
	global_load_dword v164, v[200:201], off
	v_lshl_add_u64 v[202:203], v[8:9], 0, s[0:1]
	global_load_dword v165, v[202:203], off
	s_mov_b32 s0, 0x1e000
	s_mov_b32 s1, 0
	v_lshl_add_u64 v[198:199], v[12:13], 0, s[0:1]
	v_lshl_add_u64 v[200:201], v[14:15], 0, s[0:1]
	s_add_i32 s0, s14, 60
	s_ashr_i32 s1, s0, 31
	s_lshl_b64 s[0:1], s[0:1], 12
	global_load_dword v160, v[198:199], off
	global_load_dword v161, v[200:201], off
	v_lshl_add_u64 v[202:203], v[8:9], 0, s[0:1]
	global_load_dword v162, v[202:203], off
	s_mov_b32 s0, 0x1d800
	s_mov_b32 s1, 0
	v_lshl_add_u64 v[198:199], v[12:13], 0, s[0:1]
	v_lshl_add_u64 v[200:201], v[14:15], 0, s[0:1]
	s_add_i32 s0, s14, 59
	s_ashr_i32 s1, s0, 31
	s_lshl_b64 s[0:1], s[0:1], 12
	global_load_dword v195, v[198:199], off
	global_load_dword v196, v[200:201], off
	v_lshl_add_u64 v[202:203], v[8:9], 0, s[0:1]
	global_load_dword v197, v[202:203], off
	s_mov_b32 s0, 0x1d000
	s_mov_b32 s1, 0
	v_lshl_add_u64 v[198:199], v[12:13], 0, s[0:1]
	v_lshl_add_u64 v[200:201], v[14:15], 0, s[0:1]
	s_add_i32 s0, s14, 58
	s_ashr_i32 s1, s0, 31
	s_lshl_b64 s[0:1], s[0:1], 12
	global_load_dword v192, v[198:199], off
	global_load_dword v193, v[200:201], off
	v_lshl_add_u64 v[202:203], v[8:9], 0, s[0:1]
	global_load_dword v194, v[202:203], off
	s_mov_b32 s0, 0x1c800
	s_mov_b32 s1, 0
	v_lshl_add_u64 v[198:199], v[12:13], 0, s[0:1]
	v_lshl_add_u64 v[200:201], v[14:15], 0, s[0:1]
	s_add_i32 s0, s14, 57
	s_ashr_i32 s1, s0, 31
	s_lshl_b64 s[0:1], s[0:1], 12
	global_load_dword v189, v[198:199], off
	global_load_dword v190, v[200:201], off
	v_lshl_add_u64 v[202:203], v[8:9], 0, s[0:1]
	global_load_dword v191, v[202:203], off
	s_mov_b32 s0, 0x1c000
	s_mov_b32 s1, 0
	v_lshl_add_u64 v[198:199], v[12:13], 0, s[0:1]
	v_lshl_add_u64 v[200:201], v[14:15], 0, s[0:1]
	s_add_i32 s0, s14, 56
	s_ashr_i32 s1, s0, 31
	s_lshl_b64 s[0:1], s[0:1], 12
	global_load_dword v186, v[198:199], off
	global_load_dword v187, v[200:201], off
	v_lshl_add_u64 v[202:203], v[8:9], 0, s[0:1]
	global_load_dword v188, v[202:203], off
	s_mov_b32 s0, 0x1b800
	s_mov_b32 s1, 0
	v_lshl_add_u64 v[198:199], v[12:13], 0, s[0:1]
	v_lshl_add_u64 v[200:201], v[14:15], 0, s[0:1]
	s_add_i32 s0, s14, 55
	s_ashr_i32 s1, s0, 31
	s_lshl_b64 s[0:1], s[0:1], 12
	global_load_dword v183, v[198:199], off
	global_load_dword v184, v[200:201], off
	v_lshl_add_u64 v[202:203], v[8:9], 0, s[0:1]
	global_load_dword v185, v[202:203], off
	s_mov_b32 s0, 0x1b000
	s_mov_b32 s1, 0
	v_lshl_add_u64 v[198:199], v[12:13], 0, s[0:1]
	v_lshl_add_u64 v[200:201], v[14:15], 0, s[0:1]
	s_add_i32 s0, s14, 54
	s_ashr_i32 s1, s0, 31
	s_lshl_b64 s[0:1], s[0:1], 12
	global_load_dword v180, v[198:199], off
	global_load_dword v181, v[200:201], off
	v_lshl_add_u64 v[202:203], v[8:9], 0, s[0:1]
	global_load_dword v182, v[202:203], off
	s_mov_b32 s0, 0x1a800
	s_mov_b32 s1, 0
	v_lshl_add_u64 v[198:199], v[12:13], 0, s[0:1]
	v_lshl_add_u64 v[200:201], v[14:15], 0, s[0:1]
	s_add_i32 s0, s14, 53
	s_ashr_i32 s1, s0, 31
	s_lshl_b64 s[0:1], s[0:1], 12
	global_load_dword v175, v[198:199], off
	global_load_dword v176, v[200:201], off
	v_lshl_add_u64 v[202:203], v[8:9], 0, s[0:1]
	global_load_dword v177, v[202:203], off
	s_mov_b32 s0, 0x1a000
	s_mov_b32 s1, 0
	v_lshl_add_u64 v[198:199], v[12:13], 0, s[0:1]
	v_lshl_add_u64 v[200:201], v[14:15], 0, s[0:1]
	s_add_i32 s0, s14, 52
	s_ashr_i32 s1, s0, 31
	s_lshl_b64 s[0:1], s[0:1], 12
	global_load_dword v172, v[198:199], off
	global_load_dword v173, v[200:201], off
	v_lshl_add_u64 v[202:203], v[8:9], 0, s[0:1]
	global_load_dword v174, v[202:203], off
	s_mov_b32 s0, 0x19800
	s_mov_b32 s1, 0
	v_lshl_add_u64 v[198:199], v[12:13], 0, s[0:1]
	v_lshl_add_u64 v[200:201], v[14:15], 0, s[0:1]
	s_add_i32 s0, s14, 51
	s_ashr_i32 s1, s0, 31
	s_lshl_b64 s[0:1], s[0:1], 12
	global_load_dword v169, v[198:199], off
	global_load_dword v170, v[200:201], off
	v_lshl_add_u64 v[202:203], v[8:9], 0, s[0:1]
	global_load_dword v171, v[202:203], off
	s_lshl_b64 s[0:1], s[2:3], 11
	v_fmac_f32_e32 v18, v19, v155
	v_lshlrev_b32_e32 v19, 16, v21
	v_and_b32_e32 v21, 0xffff0000, v21
	v_mul_f32_e32 v21, 0x3fb8aa3b, v21
	v_exp_f32_e32 v21, v21
	v_mul_f32_e32 v19, 0x3fb8aa3b, v19
	v_exp_f32_e32 v154, v19
	v_lshlrev_b32_e32 v19, 16, v20
; DEVI float bflo(unsigned u) { return __uint_as_float(u << 16); }
; DEVI float bfhi(unsigned u) { return __uint_as_float(u & 0xffff0000u); }
; DEVI void lru_p3_phase(const Params& p) {
;     ...
; #pragma unroll
;       for (int t = 0; t < 64; ++t) {
;         const unsigned l = *(const unsigned*)(la + (size_t)t * 1024), bv = *(const unsigned*)(bb + (size_t)t * 1024);
;         h0 = __expf(bflo(l)) * h0 + bflo(bv); h1 = __expf(bfhi(l)) * h1 + bfhi(bv); s0[t] = h0; s1[t] = h1;
;       }
	v_and_b32_e32 v20, 0xffff0000, v20
	v_fmac_f32_e32 v20, v18, v21
	v_lshlrev_b32_e32 v21, 16, v22
	v_mul_f32_e32 v21, 0x3fb8aa3b, v21
	v_fmac_f32_e32 v19, v0, v154
	v_exp_f32_e32 v154, v21
	v_and_b32_e32 v22, 0xffff0000, v22
	v_lshlrev_b32_e32 v21, 16, v23
	v_mul_f32_e32 v22, 0x3fb8aa3b, v22
	v_fmac_f32_e32 v21, v19, v154
	v_exp_f32_e32 v154, v22
	v_and_b32_e32 v22, 0xffff0000, v23
	v_lshlrev_b32_e32 v23, 16, v25
	v_and_b32_e32 v25, 0xffff0000, v25
	v_mul_f32_e32 v25, 0x3fb8aa3b, v25
	v_exp_f32_e32 v25, v25
	v_mul_f32_e32 v23, 0x3fb8aa3b, v23
	v_fmac_f32_e32 v22, v20, v154
	v_exp_f32_e32 v154, v23
	v_lshlrev_b32_e32 v23, 16, v24
	v_and_b32_e32 v24, 0xffff0000, v24
	v_fmac_f32_e32 v24, v22, v25
	v_lshlrev_b32_e32 v25, 16, v27
	v_and_b32_e32 v27, 0xffff0000, v27
	v_mul_f32_e32 v27, 0x3fb8aa3b, v27
	v_exp_f32_e32 v27, v27
	v_mul_f32_e32 v25, 0x3fb8aa3b, v25
	v_fmac_f32_e32 v23, v21, v154
	v_exp_f32_e32 v154, v25
	v_lshlrev_b32_e32 v25, 16, v26
	v_and_b32_e32 v26, 0xffff0000, v26
	v_fmac_f32_e32 v26, v24, v27
	v_lshlrev_b32_e32 v27, 16, v29
	v_and_b32_e32 v29, 0xffff0000, v29
	v_mul_f32_e32 v29, 0x3fb8aa3b, v29
	v_exp_f32_e32 v29, v29
	v_mul_f32_e32 v27, 0x3fb8aa3b, v27
	v_fmac_f32_e32 v25, v23, v154
	v_exp_f32_e32 v154, v27
	v_lshlrev_b32_e32 v27, 16, v28
	v_and_b32_e32 v28, 0xffff0000, v28
	v_fmac_f32_e32 v28, v26, v29
	v_lshlrev_b32_e32 v29, 16, v31
	v_and_b32_e32 v31, 0xffff0000, v31
	v_mul_f32_e32 v31, 0x3fb8aa3b, v31
	v_exp_f32_e32 v31, v31
	v_mul_f32_e32 v29, 0x3fb8aa3b, v29
	v_fmac_f32_e32 v27, v25, v154
	v_exp_f32_e32 v154, v29
	v_lshlrev_b32_e32 v29, 16, v30
	v_and_b32_e32 v30, 0xffff0000, v30
	v_fmac_f32_e32 v30, v28, v31
	v_lshlrev_b32_e32 v31, 16, v33
	v_and_b32_e32 v33, 0xffff0000, v33
	v_mul_f32_e32 v33, 0x3fb8aa3b, v33
	v_exp_f32_e32 v33, v33
	v_mul_f32_e32 v31, 0x3fb8aa3b, v31
	v_fmac_f32_e32 v29, v27, v154
	v_exp_f32_e32 v154, v31
	v_lshlrev_b32_e32 v31, 16, v32
	v_and_b32_e32 v32, 0xffff0000, v32
	v_fmac_f32_e32 v32, v30, v33
	v_lshlrev_b32_e32 v33, 16, v35
	v_and_b32_e32 v35, 0xffff0000, v35
	v_mul_f32_e32 v35, 0x3fb8aa3b, v35
	v_exp_f32_e32 v35, v35
	v_mul_f32_e32 v33, 0x3fb8aa3b, v33
	v_fmac_f32_e32 v31, v29, v154
	v_exp_f32_e32 v154, v33
	v_lshlrev_b32_e32 v33, 16, v34
	v_and_b32_e32 v34, 0xffff0000, v34
	v_fmac_f32_e32 v34, v32, v35
	v_lshlrev_b32_e32 v35, 16, v37
	v_and_b32_e32 v37, 0xffff0000, v37
	v_mul_f32_e32 v37, 0x3fb8aa3b, v37
	v_exp_f32_e32 v37, v37
	v_mul_f32_e32 v35, 0x3fb8aa3b, v35
	v_fmac_f32_e32 v33, v31, v154
	v_exp_f32_e32 v154, v35
	v_lshlrev_b32_e32 v35, 16, v36
	v_and_b32_e32 v36, 0xffff0000, v36
	v_fmac_f32_e32 v36, v34, v37
	v_lshlrev_b32_e32 v37, 16, v38
	v_mul_f32_e32 v37, 0x3fb8aa3b, v37
	v_fmac_f32_e32 v35, v33, v154
	v_exp_f32_e32 v154, v37
	v_and_b32_e32 v38, 0xffff0000, v38
	v_lshlrev_b32_e32 v37, 16, v39
	v_mul_f32_e32 v38, 0x3fb8aa3b, v38
	v_fmac_f32_e32 v37, v35, v154
	v_exp_f32_e32 v154, v38
	v_and_b32_e32 v38, 0xffff0000, v39
	v_lshlrev_b32_e32 v39, 16, v41
	v_and_b32_e32 v41, 0xffff0000, v41
	v_mul_f32_e32 v41, 0x3fb8aa3b, v41
	v_exp_f32_e32 v41, v41
	v_mul_f32_e32 v39, 0x3fb8aa3b, v39
	v_fmac_f32_e32 v38, v36, v154
	v_exp_f32_e32 v154, v39
	v_lshlrev_b32_e32 v39, 16, v40
	v_and_b32_e32 v40, 0xffff0000, v40
	v_fmac_f32_e32 v40, v38, v41
	v_lshlrev_b32_e32 v41, 16, v43
	v_and_b32_e32 v43, 0xffff0000, v43
	v_mul_f32_e32 v43, 0x3fb8aa3b, v43
	v_exp_f32_e32 v43, v43
	v_mul_f32_e32 v41, 0x3fb8aa3b, v41
	v_fmac_f32_e32 v39, v37, v154
	v_exp_f32_e32 v154, v41
	v_lshlrev_b32_e32 v41, 16, v42
	v_and_b32_e32 v42, 0xffff0000, v42
	v_fmac_f32_e32 v42, v40, v43
	v_lshlrev_b32_e32 v43, 16, v45
	v_and_b32_e32 v45, 0xffff0000, v45
	v_mul_f32_e32 v45, 0x3fb8aa3b, v45
	v_exp_f32_e32 v45, v45
	v_mul_f32_e32 v43, 0x3fb8aa3b, v43
	v_fmac_f32_e32 v41, v39, v154
	v_exp_f32_e32 v154, v43
	v_lshlrev_b32_e32 v43, 16, v44
	v_and_b32_e32 v44, 0xffff0000, v44
	v_fmac_f32_e32 v44, v42, v45
	v_lshlrev_b32_e32 v45, 16, v47
	v_and_b32_e32 v47, 0xffff0000, v47
	v_mul_f32_e32 v47, 0x3fb8aa3b, v47
	v_exp_f32_e32 v47, v47
	v_mul_f32_e32 v45, 0x3fb8aa3b, v45
	v_fmac_f32_e32 v43, v41, v154
	v_exp_f32_e32 v154, v45
	v_lshlrev_b32_e32 v45, 16, v46
	v_and_b32_e32 v46, 0xffff0000, v46
	v_fmac_f32_e32 v46, v44, v47
	v_lshlrev_b32_e32 v47, 16, v49
	v_and_b32_e32 v49, 0xffff0000, v49
	v_mul_f32_e32 v49, 0x3fb8aa3b, v49
	v_exp_f32_e32 v49, v49
	v_mul_f32_e32 v47, 0x3fb8aa3b, v47
	v_fmac_f32_e32 v45, v43, v154
	v_exp_f32_e32 v154, v47
	v_lshlrev_b32_e32 v47, 16, v48
	v_and_b32_e32 v48, 0xffff0000, v48
	v_fmac_f32_e32 v48, v46, v49
	v_lshlrev_b32_e32 v49, 16, v51
	v_and_b32_e32 v51, 0xffff0000, v51
	v_mul_f32_e32 v51, 0x3fb8aa3b, v51
	v_exp_f32_e32 v51, v51
	v_mul_f32_e32 v49, 0x3fb8aa3b, v49
	v_fmac_f32_e32 v47, v45, v154
	v_exp_f32_e32 v154, v49
	v_lshlrev_b32_e32 v49, 16, v50
	v_and_b32_e32 v50, 0xffff0000, v50
	v_fmac_f32_e32 v50, v48, v51
	v_lshlrev_b32_e32 v51, 16, v53
	v_and_b32_e32 v53, 0xffff0000, v53
	v_mul_f32_e32 v53, 0x3fb8aa3b, v53
	v_exp_f32_e32 v53, v53
	v_mul_f32_e32 v51, 0x3fb8aa3b, v51
	v_fmac_f32_e32 v49, v47, v154
	v_exp_f32_e32 v154, v51
	v_lshlrev_b32_e32 v51, 16, v52
	v_and_b32_e32 v52, 0xffff0000, v52
	v_fmac_f32_e32 v52, v50, v53
	v_lshlrev_b32_e32 v53, 16, v54
	v_mul_f32_e32 v53, 0x3fb8aa3b, v53
	v_fmac_f32_e32 v51, v49, v154
	v_exp_f32_e32 v154, v53
	v_and_b32_e32 v54, 0xffff0000, v54
	v_lshlrev_b32_e32 v53, 16, v55
	v_mul_f32_e32 v54, 0x3fb8aa3b, v54
	v_fmac_f32_e32 v53, v51, v154
	v_exp_f32_e32 v154, v54
	v_and_b32_e32 v54, 0xffff0000, v55
	v_lshlrev_b32_e32 v55, 16, v57
	v_and_b32_e32 v57, 0xffff0000, v57
	v_mul_f32_e32 v57, 0x3fb8aa3b, v57
	v_exp_f32_e32 v57, v57
	v_mul_f32_e32 v55, 0x3fb8aa3b, v55
; DEVI float bflo(unsigned u) { return __uint_as_float(u << 16); }
; DEVI float bfhi(unsigned u) { return __uint_as_float(u & 0xffff0000u); }
; DEVI void lru_p3_phase(const Params& p) {
;     ...
; #pragma unroll
;       for (int t = 0; t < 64; ++t) {
;         const unsigned l = *(const unsigned*)(la + (size_t)t * 1024), bv = *(const unsigned*)(bb + (size_t)t * 1024);
;         h0 = __expf(bflo(l)) * h0 + bflo(bv); h1 = __expf(bfhi(l)) * h1 + bfhi(bv); s0[t] = h0; s1[t] = h1;
;       }
	v_fmac_f32_e32 v54, v52, v154
	v_exp_f32_e32 v154, v55
	v_lshlrev_b32_e32 v55, 16, v56
	v_and_b32_e32 v56, 0xffff0000, v56
	v_fmac_f32_e32 v56, v54, v57
	v_lshlrev_b32_e32 v57, 16, v59
	v_and_b32_e32 v59, 0xffff0000, v59
	v_mul_f32_e32 v59, 0x3fb8aa3b, v59
	v_exp_f32_e32 v59, v59
	v_mul_f32_e32 v57, 0x3fb8aa3b, v57
	v_fmac_f32_e32 v55, v53, v154
	v_exp_f32_e32 v154, v57
	v_lshlrev_b32_e32 v57, 16, v58
	v_and_b32_e32 v58, 0xffff0000, v58
	v_fmac_f32_e32 v58, v56, v59
	v_lshlrev_b32_e32 v59, 16, v61
	v_and_b32_e32 v61, 0xffff0000, v61
	v_mul_f32_e32 v61, 0x3fb8aa3b, v61
	v_exp_f32_e32 v61, v61
	v_mul_f32_e32 v59, 0x3fb8aa3b, v59
	v_fmac_f32_e32 v57, v55, v154
	v_exp_f32_e32 v154, v59
	v_lshlrev_b32_e32 v59, 16, v60
	v_and_b32_e32 v60, 0xffff0000, v60
	v_fmac_f32_e32 v60, v58, v61
	v_lshlrev_b32_e32 v61, 16, v62
	v_mul_f32_e32 v61, 0x3fb8aa3b, v61
	v_fmac_f32_e32 v59, v57, v154
	v_exp_f32_e32 v154, v61
	v_and_b32_e32 v62, 0xffff0000, v62
	v_lshlrev_b32_e32 v61, 16, v63
	v_mul_f32_e32 v62, 0x3fb8aa3b, v62
	v_fmac_f32_e32 v61, v59, v154
	v_exp_f32_e32 v154, v62
	v_and_b32_e32 v62, 0xffff0000, v63
	v_lshlrev_b32_e32 v63, 16, v65
	v_and_b32_e32 v65, 0xffff0000, v65
	v_mul_f32_e32 v65, 0x3fb8aa3b, v65
	v_exp_f32_e32 v65, v65
	v_mul_f32_e32 v63, 0x3fb8aa3b, v63
	v_fmac_f32_e32 v62, v60, v154
	v_exp_f32_e32 v154, v63
	v_lshlrev_b32_e32 v63, 16, v64
	v_and_b32_e32 v64, 0xffff0000, v64
	v_fmac_f32_e32 v64, v62, v65
	v_lshlrev_b32_e32 v65, 16, v67
	v_and_b32_e32 v67, 0xffff0000, v67
	v_mul_f32_e32 v67, 0x3fb8aa3b, v67
	v_exp_f32_e32 v67, v67
	v_mul_f32_e32 v65, 0x3fb8aa3b, v65
	v_fmac_f32_e32 v63, v61, v154
	v_exp_f32_e32 v154, v65
	v_lshlrev_b32_e32 v65, 16, v66
	v_and_b32_e32 v66, 0xffff0000, v66
	v_fmac_f32_e32 v66, v64, v67
	v_lshlrev_b32_e32 v67, 16, v69
	v_and_b32_e32 v69, 0xffff0000, v69
	v_mul_f32_e32 v69, 0x3fb8aa3b, v69
	v_exp_f32_e32 v69, v69
	v_mul_f32_e32 v67, 0x3fb8aa3b, v67
	v_fmac_f32_e32 v65, v63, v154
	v_exp_f32_e32 v154, v67
	v_lshlrev_b32_e32 v67, 16, v68
	v_and_b32_e32 v68, 0xffff0000, v68
	v_fmac_f32_e32 v68, v66, v69
	v_lshlrev_b32_e32 v69, 16, v70
	v_mul_f32_e32 v69, 0x3fb8aa3b, v69
	v_fmac_f32_e32 v67, v65, v154
	v_exp_f32_e32 v154, v69
	v_and_b32_e32 v70, 0xffff0000, v70
	v_lshlrev_b32_e32 v69, 16, v71
	v_mul_f32_e32 v70, 0x3fb8aa3b, v70
	v_fmac_f32_e32 v69, v67, v154
	v_exp_f32_e32 v154, v70
	v_and_b32_e32 v70, 0xffff0000, v71
	v_lshlrev_b32_e32 v71, 16, v73
	v_and_b32_e32 v73, 0xffff0000, v73
	v_mul_f32_e32 v73, 0x3fb8aa3b, v73
	v_exp_f32_e32 v73, v73
	v_mul_f32_e32 v71, 0x3fb8aa3b, v71
	v_fmac_f32_e32 v70, v68, v154
	v_exp_f32_e32 v154, v71
	v_lshlrev_b32_e32 v71, 16, v72
	v_and_b32_e32 v72, 0xffff0000, v72
	v_fmac_f32_e32 v72, v70, v73
	v_lshlrev_b32_e32 v73, 16, v75
	v_and_b32_e32 v75, 0xffff0000, v75
	v_mul_f32_e32 v75, 0x3fb8aa3b, v75
	v_exp_f32_e32 v75, v75
	v_mul_f32_e32 v73, 0x3fb8aa3b, v73
	v_fmac_f32_e32 v71, v69, v154
	v_exp_f32_e32 v154, v73
	v_lshlrev_b32_e32 v73, 16, v74
	v_and_b32_e32 v74, 0xffff0000, v74
	v_fmac_f32_e32 v74, v72, v75
	v_lshlrev_b32_e32 v75, 16, v77
	v_and_b32_e32 v77, 0xffff0000, v77
	v_mul_f32_e32 v77, 0x3fb8aa3b, v77
	v_exp_f32_e32 v77, v77
	v_mul_f32_e32 v75, 0x3fb8aa3b, v75
	v_fmac_f32_e32 v73, v71, v154
	v_exp_f32_e32 v154, v75
	v_lshlrev_b32_e32 v75, 16, v76
	v_and_b32_e32 v76, 0xffff0000, v76
	v_fmac_f32_e32 v76, v74, v77
	v_lshlrev_b32_e32 v77, 16, v79
	v_and_b32_e32 v79, 0xffff0000, v79
	v_mul_f32_e32 v79, 0x3fb8aa3b, v79
	v_exp_f32_e32 v79, v79
	v_mul_f32_e32 v77, 0x3fb8aa3b, v77
	v_fmac_f32_e32 v75, v73, v154
	v_exp_f32_e32 v154, v77
	v_lshlrev_b32_e32 v77, 16, v78
	v_and_b32_e32 v78, 0xffff0000, v78
	v_fmac_f32_e32 v78, v76, v79
	v_lshlrev_b32_e32 v79, 16, v81
	v_and_b32_e32 v81, 0xffff0000, v81
	v_mul_f32_e32 v81, 0x3fb8aa3b, v81
	v_exp_f32_e32 v81, v81
	v_mul_f32_e32 v79, 0x3fb8aa3b, v79
	v_fmac_f32_e32 v77, v75, v154
	v_exp_f32_e32 v154, v79
	v_lshlrev_b32_e32 v79, 16, v80
	v_and_b32_e32 v80, 0xffff0000, v80
	v_fmac_f32_e32 v80, v78, v81
	v_lshlrev_b32_e32 v81, 16, v83
	v_and_b32_e32 v83, 0xffff0000, v83
	v_mul_f32_e32 v83, 0x3fb8aa3b, v83
	v_exp_f32_e32 v83, v83
	v_mul_f32_e32 v81, 0x3fb8aa3b, v81
	v_fmac_f32_e32 v79, v77, v154
	v_exp_f32_e32 v154, v81
	v_lshlrev_b32_e32 v81, 16, v82
	v_and_b32_e32 v82, 0xffff0000, v82
	v_fmac_f32_e32 v82, v80, v83
	v_lshlrev_b32_e32 v83, 16, v85
	v_and_b32_e32 v85, 0xffff0000, v85
	v_mul_f32_e32 v85, 0x3fb8aa3b, v85
	v_exp_f32_e32 v85, v85
	v_mul_f32_e32 v83, 0x3fb8aa3b, v83
	v_fmac_f32_e32 v81, v79, v154
	v_exp_f32_e32 v154, v83
	v_lshlrev_b32_e32 v83, 16, v84
	v_and_b32_e32 v84, 0xffff0000, v84
	v_fmac_f32_e32 v84, v82, v85
	v_lshlrev_b32_e32 v85, 16, v86
	v_mul_f32_e32 v85, 0x3fb8aa3b, v85
	v_fmac_f32_e32 v83, v81, v154
	v_exp_f32_e32 v154, v85
	v_and_b32_e32 v86, 0xffff0000, v86
	v_lshlrev_b32_e32 v85, 16, v87
	v_mul_f32_e32 v86, 0x3fb8aa3b, v86
	v_fmac_f32_e32 v85, v83, v154
	v_exp_f32_e32 v154, v86
	v_and_b32_e32 v86, 0xffff0000, v87
	v_lshlrev_b32_e32 v87, 16, v89
	v_and_b32_e32 v89, 0xffff0000, v89
	v_mul_f32_e32 v89, 0x3fb8aa3b, v89
	v_exp_f32_e32 v89, v89
	v_mul_f32_e32 v87, 0x3fb8aa3b, v87
	v_fmac_f32_e32 v86, v84, v154
	v_exp_f32_e32 v154, v87
	v_lshlrev_b32_e32 v87, 16, v88
	v_and_b32_e32 v88, 0xffff0000, v88
	v_fmac_f32_e32 v88, v86, v89
	v_lshlrev_b32_e32 v89, 16, v91
	v_and_b32_e32 v91, 0xffff0000, v91
	v_mul_f32_e32 v91, 0x3fb8aa3b, v91
	v_exp_f32_e32 v91, v91
	v_mul_f32_e32 v89, 0x3fb8aa3b, v89
	v_fmac_f32_e32 v87, v85, v154
	v_exp_f32_e32 v154, v89
	v_lshlrev_b32_e32 v89, 16, v90
	v_and_b32_e32 v90, 0xffff0000, v90
	v_fmac_f32_e32 v90, v88, v91
	v_lshlrev_b32_e32 v91, 16, v93
	v_and_b32_e32 v93, 0xffff0000, v93
; DEVI float bflo(unsigned u) { return __uint_as_float(u << 16); }
; DEVI float bfhi(unsigned u) { return __uint_as_float(u & 0xffff0000u); }
; DEVI void lru_p3_phase(const Params& p) {
;     ...
; #pragma unroll
;       for (int t = 0; t < 64; ++t) {
;         const unsigned l = *(const unsigned*)(la + (size_t)t * 1024), bv = *(const unsigned*)(bb + (size_t)t * 1024);
;         h0 = __expf(bflo(l)) * h0 + bflo(bv); h1 = __expf(bfhi(l)) * h1 + bfhi(bv); s0[t] = h0; s1[t] = h1;
;       }
	v_mul_f32_e32 v93, 0x3fb8aa3b, v93
	v_exp_f32_e32 v93, v93
	v_mul_f32_e32 v91, 0x3fb8aa3b, v91
	v_fmac_f32_e32 v89, v87, v154
	v_exp_f32_e32 v154, v91
	v_lshlrev_b32_e32 v91, 16, v92
	v_and_b32_e32 v92, 0xffff0000, v92
	v_fmac_f32_e32 v92, v90, v93
	v_lshlrev_b32_e32 v93, 16, v94
	v_mul_f32_e32 v93, 0x3fb8aa3b, v93
	v_fmac_f32_e32 v91, v89, v154
	v_exp_f32_e32 v154, v93
	v_and_b32_e32 v94, 0xffff0000, v94
	v_lshlrev_b32_e32 v93, 16, v95
	v_mul_f32_e32 v94, 0x3fb8aa3b, v94
	v_fmac_f32_e32 v93, v91, v154
	v_exp_f32_e32 v154, v94
	v_and_b32_e32 v94, 0xffff0000, v95
	v_lshlrev_b32_e32 v95, 16, v97
	v_and_b32_e32 v97, 0xffff0000, v97
	v_mul_f32_e32 v97, 0x3fb8aa3b, v97
	v_exp_f32_e32 v97, v97
	v_mul_f32_e32 v95, 0x3fb8aa3b, v95
	v_fmac_f32_e32 v94, v92, v154
	v_exp_f32_e32 v154, v95
	v_lshlrev_b32_e32 v95, 16, v96
	v_and_b32_e32 v96, 0xffff0000, v96
	v_fmac_f32_e32 v96, v94, v97
	v_lshlrev_b32_e32 v97, 16, v99
	v_and_b32_e32 v99, 0xffff0000, v99
	v_mul_f32_e32 v99, 0x3fb8aa3b, v99
	v_exp_f32_e32 v99, v99
	v_mul_f32_e32 v97, 0x3fb8aa3b, v97
	v_fmac_f32_e32 v95, v93, v154
	v_exp_f32_e32 v154, v97
	v_lshlrev_b32_e32 v97, 16, v98
	v_and_b32_e32 v98, 0xffff0000, v98
	v_fmac_f32_e32 v98, v96, v99
	v_lshlrev_b32_e32 v99, 16, v101
	v_and_b32_e32 v101, 0xffff0000, v101
	v_mul_f32_e32 v101, 0x3fb8aa3b, v101
	v_exp_f32_e32 v101, v101
	v_mul_f32_e32 v99, 0x3fb8aa3b, v99
	v_fmac_f32_e32 v97, v95, v154
	v_exp_f32_e32 v154, v99
	v_lshlrev_b32_e32 v99, 16, v100
	v_and_b32_e32 v100, 0xffff0000, v100
	v_fmac_f32_e32 v100, v98, v101
	v_lshlrev_b32_e32 v101, 16, v102
	v_mul_f32_e32 v101, 0x3fb8aa3b, v101
	v_fmac_f32_e32 v99, v97, v154
	v_exp_f32_e32 v154, v101
	v_and_b32_e32 v102, 0xffff0000, v102
	v_lshlrev_b32_e32 v101, 16, v103
	v_mul_f32_e32 v102, 0x3fb8aa3b, v102
	v_fmac_f32_e32 v101, v99, v154
	v_exp_f32_e32 v154, v102
	v_and_b32_e32 v102, 0xffff0000, v103
	v_lshlrev_b32_e32 v103, 16, v105
	v_and_b32_e32 v105, 0xffff0000, v105
	v_mul_f32_e32 v105, 0x3fb8aa3b, v105
	v_exp_f32_e32 v105, v105
	v_mul_f32_e32 v103, 0x3fb8aa3b, v103
	v_fmac_f32_e32 v102, v100, v154
	v_exp_f32_e32 v154, v103
	v_lshlrev_b32_e32 v103, 16, v104
	v_and_b32_e32 v104, 0xffff0000, v104
	v_fmac_f32_e32 v104, v102, v105
	v_lshlrev_b32_e32 v105, 16, v107
	v_and_b32_e32 v107, 0xffff0000, v107
	v_mul_f32_e32 v107, 0x3fb8aa3b, v107
	v_exp_f32_e32 v107, v107
	v_mul_f32_e32 v105, 0x3fb8aa3b, v105
	v_fmac_f32_e32 v103, v101, v154
	v_exp_f32_e32 v154, v105
	v_lshlrev_b32_e32 v105, 16, v106
	v_and_b32_e32 v106, 0xffff0000, v106
	v_fmac_f32_e32 v106, v104, v107
	v_lshlrev_b32_e32 v107, 16, v109
	v_and_b32_e32 v109, 0xffff0000, v109
	v_mul_f32_e32 v109, 0x3fb8aa3b, v109
	v_exp_f32_e32 v109, v109
	v_mul_f32_e32 v107, 0x3fb8aa3b, v107
	v_fmac_f32_e32 v105, v103, v154
	v_exp_f32_e32 v154, v107
	v_lshlrev_b32_e32 v107, 16, v108
	v_and_b32_e32 v108, 0xffff0000, v108
	v_fmac_f32_e32 v108, v106, v109
	v_lshlrev_b32_e32 v109, 16, v111
	v_and_b32_e32 v111, 0xffff0000, v111
	v_mul_f32_e32 v111, 0x3fb8aa3b, v111
	v_exp_f32_e32 v111, v111
	v_mul_f32_e32 v109, 0x3fb8aa3b, v109
	v_fmac_f32_e32 v107, v105, v154
	v_exp_f32_e32 v154, v109
	v_lshlrev_b32_e32 v109, 16, v110
	v_and_b32_e32 v110, 0xffff0000, v110
	v_fmac_f32_e32 v110, v108, v111
	v_lshlrev_b32_e32 v111, 16, v113
	v_and_b32_e32 v113, 0xffff0000, v113
	v_mul_f32_e32 v113, 0x3fb8aa3b, v113
	v_exp_f32_e32 v113, v113
	v_mul_f32_e32 v111, 0x3fb8aa3b, v111
	v_fmac_f32_e32 v109, v107, v154
	v_exp_f32_e32 v154, v111
	v_lshlrev_b32_e32 v111, 16, v112
	v_and_b32_e32 v112, 0xffff0000, v112
	v_fmac_f32_e32 v112, v110, v113
	v_lshlrev_b32_e32 v113, 16, v115
	v_and_b32_e32 v115, 0xffff0000, v115
	v_mul_f32_e32 v115, 0x3fb8aa3b, v115
	v_exp_f32_e32 v115, v115
	v_mul_f32_e32 v113, 0x3fb8aa3b, v113
	v_fmac_f32_e32 v111, v109, v154
	v_exp_f32_e32 v154, v113
	v_lshlrev_b32_e32 v113, 16, v114
	v_and_b32_e32 v114, 0xffff0000, v114
	v_fmac_f32_e32 v114, v112, v115
	v_lshlrev_b32_e32 v115, 16, v117
	v_and_b32_e32 v117, 0xffff0000, v117
	v_mul_f32_e32 v117, 0x3fb8aa3b, v117
	v_exp_f32_e32 v117, v117
	v_mul_f32_e32 v115, 0x3fb8aa3b, v115
	v_fmac_f32_e32 v113, v111, v154
	v_exp_f32_e32 v154, v115
	v_lshlrev_b32_e32 v115, 16, v116
	v_and_b32_e32 v116, 0xffff0000, v116
	v_fmac_f32_e32 v116, v114, v117
	v_lshlrev_b32_e32 v117, 16, v118
	v_mul_f32_e32 v117, 0x3fb8aa3b, v117
	v_fmac_f32_e32 v115, v113, v154
	v_exp_f32_e32 v154, v117
	v_and_b32_e32 v118, 0xffff0000, v118
	v_lshlrev_b32_e32 v117, 16, v119
	v_mul_f32_e32 v118, 0x3fb8aa3b, v118
	v_fmac_f32_e32 v117, v115, v154
	v_exp_f32_e32 v154, v118
	v_and_b32_e32 v118, 0xffff0000, v119
	v_lshlrev_b32_e32 v119, 16, v121
	v_and_b32_e32 v121, 0xffff0000, v121
	v_mul_f32_e32 v121, 0x3fb8aa3b, v121
	v_exp_f32_e32 v121, v121
	v_mul_f32_e32 v119, 0x3fb8aa3b, v119
	v_fmac_f32_e32 v118, v116, v154
	v_exp_f32_e32 v154, v119
	v_lshlrev_b32_e32 v119, 16, v120
	v_and_b32_e32 v120, 0xffff0000, v120
	v_fmac_f32_e32 v120, v118, v121
	v_lshlrev_b32_e32 v121, 16, v123
	v_and_b32_e32 v123, 0xffff0000, v123
	v_mul_f32_e32 v123, 0x3fb8aa3b, v123
	v_exp_f32_e32 v123, v123
	v_mul_f32_e32 v121, 0x3fb8aa3b, v121
	v_fmac_f32_e32 v119, v117, v154
	v_exp_f32_e32 v154, v121
	v_lshlrev_b32_e32 v121, 16, v122
	v_and_b32_e32 v122, 0xffff0000, v122
	v_fmac_f32_e32 v122, v120, v123
	v_lshlrev_b32_e32 v123, 16, v125
	v_and_b32_e32 v125, 0xffff0000, v125
	v_mul_f32_e32 v125, 0x3fb8aa3b, v125
	v_exp_f32_e32 v125, v125
	v_mul_f32_e32 v123, 0x3fb8aa3b, v123
	v_fmac_f32_e32 v121, v119, v154
	v_exp_f32_e32 v154, v123
	v_lshlrev_b32_e32 v123, 16, v124
	v_and_b32_e32 v124, 0xffff0000, v124
	v_fmac_f32_e32 v124, v122, v125
	v_lshlrev_b32_e32 v125, 16, v126
; DEVI unsigned cvtpk(float lo, float hi) { unsigned r; asm("v_cvt_pk_bf16_f32 %0, %1, %2" : "=v"(r) : "v"(lo), "v"(hi)); return r; }
; DEVI float bflo(unsigned u) { return __uint_as_float(u << 16); }
; DEVI float bfhi(unsigned u) { return __uint_as_float(u & 0xffff0000u); }
; DEVI float geluf_(float x) { return 0.5f * x * (1.f + erff(x * 0.70710678118654752f)); }
; DEVI void lru_p3_phase(const Params& p) {
;     ...
; #pragma unroll
;       for (int t = 0; t < 64; ++t) {
;         const unsigned l = *(const unsigned*)(la + (size_t)t * 1024), bv = *(const unsigned*)(bb + (size_t)t * 1024);
;         h0 = __expf(bflo(l)) * h0 + bflo(bv); h1 = __expf(bfhi(l)) * h1 + bfhi(bv); s0[t] = h0; s1[t] = h1;
;       }
;     }
;     {
;       const bf16_t* la = LA + ((size_t)MT + rbase) * 1024 + ch; const bf16_t* bb = BB + ((size_t)MT + rbase) * 1024 + ch;
;       const float2 h2 = *(const float2*)(CAR + ((size_t)(1 * 2 + b) * NCH64B + posb) * 1024 + ch);
;       float h0 = h2.x, h1 = h2.y;
; #pragma unroll
;       for (int t = 63; t >= 0; --t) {
;         const unsigned l = *(const unsigned*)(la + (size_t)t * 1024), bv = *(const unsigned*)(bb + (size_t)t * 1024);
;         h0 = __expf(bflo(l)) * h0 + bflo(bv); h1 = __expf(bfhi(l)) * h1 + bfhi(bv);
;         const unsigned g = *(const unsigned*)(GX + (size_t)(rbase + t) * 2048 + ch);
;         *(unsigned*)(YG + (size_t)(rbase + t) * 1024 + ch) = cvtpk((s0[t] + h0) * geluf_(bflo(g)), (s1[t] + h1) * geluf_(bfhi(g)));
	v_mul_f32_e32 v125, 0x3fb8aa3b, v125
	v_fmac_f32_e32 v123, v121, v154
	v_exp_f32_e32 v154, v125
	v_and_b32_e32 v126, 0xffff0000, v126
	v_lshlrev_b32_e32 v125, 16, v146
	v_mul_f32_e32 v126, 0x3fb8aa3b, v126
	v_fmac_f32_e32 v125, v123, v154
	v_exp_f32_e32 v154, v126
	v_and_b32_e32 v126, 0xffff0000, v146
	v_lshlrev_b32_e32 v146, 16, v152
	v_and_b32_e32 v152, 0xffff0000, v152
	v_mul_f32_e32 v152, 0x3fb8aa3b, v152
	v_exp_f32_e32 v152, v152
	v_mul_f32_e32 v146, 0x3fb8aa3b, v146
	v_fmac_f32_e32 v126, v124, v154
	v_exp_f32_e32 v154, v146
	v_lshlrev_b32_e32 v146, 16, v149
	v_and_b32_e32 v149, 0xffff0000, v149
	v_fmac_f32_e32 v149, v126, v152
	v_lshlrev_b32_e32 v152, 16, v145
	v_and_b32_e32 v145, 0xffff0000, v145
	v_mul_f32_e32 v145, 0x3fb8aa3b, v145
	v_exp_f32_e32 v145, v145
	v_mul_f32_e32 v152, 0x3fb8aa3b, v152
	v_fmac_f32_e32 v146, v125, v154
	v_exp_f32_e32 v154, v152
	v_lshlrev_b32_e32 v152, 16, v142
	v_and_b32_e32 v142, 0xffff0000, v142
	v_fmac_f32_e32 v142, v149, v145
	v_lshlrev_b32_e32 v145, 16, v140
	v_and_b32_e32 v140, 0xffff0000, v140
	v_mul_f32_e32 v140, 0x3fb8aa3b, v140
	v_exp_f32_e32 v140, v140
	v_mul_f32_e32 v145, 0x3fb8aa3b, v145
	v_fmac_f32_e32 v152, v146, v154
	v_exp_f32_e32 v154, v145
	v_lshlrev_b32_e32 v145, 16, v136
	v_and_b32_e32 v136, 0xffff0000, v136
	v_fmac_f32_e32 v136, v142, v140
	v_lshlrev_b32_e32 v140, 16, v144
	v_mul_f32_e32 v140, 0x3fb8aa3b, v140
	v_fmac_f32_e32 v145, v152, v154
	v_exp_f32_e32 v154, v140
	v_and_b32_e32 v144, 0xffff0000, v144
	v_lshlrev_b32_e32 v140, 16, v148
	v_mul_f32_e32 v144, 0x3fb8aa3b, v144
	v_fmac_f32_e32 v140, v145, v154
	v_exp_f32_e32 v154, v144
	v_and_b32_e32 v144, 0xffff0000, v148
	v_lshlrev_b32_e32 v148, 16, v143
	v_and_b32_e32 v143, 0xffff0000, v143
	v_mul_f32_e32 v143, 0x3fb8aa3b, v143
	v_exp_f32_e32 v143, v143
	v_mul_f32_e32 v148, 0x3fb8aa3b, v148
	v_fmac_f32_e32 v144, v136, v154
	v_exp_f32_e32 v154, v148
	v_lshlrev_b32_e32 v148, 16, v141
	v_and_b32_e32 v141, 0xffff0000, v141
	v_fmac_f32_e32 v141, v144, v143
	v_lshlrev_b32_e32 v143, 16, v137
	v_and_b32_e32 v137, 0xffff0000, v137
	v_mul_f32_e32 v137, 0x3fb8aa3b, v137
	v_exp_f32_e32 v137, v137
	v_mul_f32_e32 v143, 0x3fb8aa3b, v143
	v_fmac_f32_e32 v148, v140, v154
	v_exp_f32_e32 v154, v143
	v_lshlrev_b32_e32 v143, 16, v135
	v_and_b32_e32 v135, 0xffff0000, v135
	v_fmac_f32_e32 v135, v141, v137
	v_lshlrev_b32_e32 v137, 16, v134
	v_and_b32_e32 v134, 0xffff0000, v134
	v_mul_f32_e32 v134, 0x3fb8aa3b, v134
	v_exp_f32_e32 v134, v134
	v_mul_f32_e32 v137, 0x3fb8aa3b, v137
	v_fmac_f32_e32 v143, v148, v154
	v_exp_f32_e32 v154, v137
	v_lshlrev_b32_e32 v137, 16, v133
	v_and_b32_e32 v133, 0xffff0000, v133
	v_fmac_f32_e32 v133, v135, v134
	v_lshlrev_b32_e32 v134, 16, v132
	v_and_b32_e32 v132, 0xffff0000, v132
	v_mul_f32_e32 v132, 0x3fb8aa3b, v132
	v_exp_f32_e32 v132, v132
	v_mul_f32_e32 v134, 0x3fb8aa3b, v134
	v_fmac_f32_e32 v137, v143, v154
	v_exp_f32_e32 v154, v134
	v_lshlrev_b32_e32 v134, 16, v131
	v_and_b32_e32 v131, 0xffff0000, v131
	v_fmac_f32_e32 v131, v133, v132
	v_lshlrev_b32_e32 v132, 16, v128
	v_mul_f32_e32 v132, 0x3fb8aa3b, v132
	v_exp_f32_e32 v132, v132
	v_and_b32_e32 v128, 0xffff0000, v128
	v_mul_f32_e32 v128, 0x3fb8aa3b, v128
	v_exp_f32_e32 v128, v128
	v_fmac_f32_e32 v134, v137, v154
	v_lshlrev_b32_e32 v154, 16, v127
	v_fmac_f32_e32 v154, v134, v132
	v_and_b32_e32 v132, 0xffff0000, v127
	v_lshlrev_b32_e32 v127, 16, v130
	v_mul_f32_e32 v127, 0x3fb8aa3b, v127
	v_fmac_f32_e32 v132, v131, v128
	v_exp_f32_e32 v128, v127
	v_lshlrev_b32_e32 v127, 16, v129
	s_add_i32 s2, s14, 62
	s_ashr_i32 s3, s2, 31
	v_fmac_f32_e32 v127, v16, v128
	v_and_b32_e32 v16, 0xffff0000, v130
	v_mul_f32_e32 v16, 0x3fb8aa3b, v16
	v_exp_f32_e32 v128, v16
	v_and_b32_e32 v16, 0xffff0000, v129
	v_bfi_b32 v129, s78, v147, v139
	v_add_f32_e32 v129, 1.0, v129
	v_fmac_f32_e32 v16, v17, v128
	v_mul_f32_e32 v128, 0.5, v138
	v_bfi_b32 v130, s78, v153, v151
	v_add_f32_e32 v17, v154, v127
	v_mul_f32_e32 v128, v128, v129
	v_mul_f32_e32 v129, 0.5, v150
	v_add_f32_e32 v130, 1.0, v130
	v_mul_f32_e32 v17, v17, v128
	v_add_f32_e32 v128, v132, v16
	v_mul_f32_e32 v129, v129, v130
	v_mul_f32_e32 v128, v128, v129
	v_cvt_pk_bf16_f32 v17, v17, v128
	v_lshl_add_u64 v[128:129], v[10:11], 0, s[0:1]
	global_store_dword v[128:129], v17, off
	v_add_co_u32_e32 v128, vcc, s41, v12
	s_lshl_b64 s[0:1], s[2:3], 12
	s_nop 0
	v_addc_co_u32_e32 v129, vcc, 0, v13, vcc
	v_add_co_u32_e32 v138, vcc, 0x1f000, v14
	s_nop 0
	v_addc_co_u32_e32 v139, vcc, 0, v15, vcc
	v_lshl_add_u64 v[138:139], v[8:9], 0, s[0:1]
	s_waitcnt vmcnt(34)
	v_mov_b32_e32 v129, v166
	v_mov_b32_e32 v17, v167
	v_mov_b32_e32 v128, v168
	s_mov_b32 s0, 0x19000
	s_mov_b32 s1, 0
	v_lshl_add_u64 v[198:199], v[12:13], 0, s[0:1]
	v_lshl_add_u64 v[200:201], v[14:15], 0, s[0:1]
	s_add_i32 s0, s14, 50
	s_ashr_i32 s1, s0, 31
	s_lshl_b64 s[0:1], s[0:1], 12
	global_load_dword v166, v[198:199], off
	global_load_dword v167, v[200:201], off
	v_lshl_add_u64 v[202:203], v[8:9], 0, s[0:1]
	global_load_dword v168, v[202:203], off
	v_lshlrev_b32_e32 v130, 16, v128
	v_mul_f32_e32 v132, 0x3f3504f3, v130
	v_cmp_nlt_f32_e64 s[0:1], |v132|, 1.0
	s_and_saveexec_b64 s[16:17], s[0:1]
	s_xor_b64 s[16:17], exec, s[16:17]
	s_cbranch_execz .LBB0_620
	v_fma_f32 v138, |v132|, s29, v223
	v_fma_f32 v138, |v132|, v138, s20
	v_fma_f32 v138, |v132|, v138, s21
	v_fma_f32 v138, |v132|, v138, s28
	v_fma_f32 v138, |v132|, v138, s33
	v_fma_f32 v138, |v132|, v138, s30
	v_fma_f32 v138, |v132|, v138, |v132|
	v_mul_f32_e32 v139, 0xbfb8aa3b, v138
	v_fma_f32 v147, v138, s31, -v139
	v_rndne_f32_e32 v150, v139
	v_fmac_f32_e32 v147, 0xb2a5705f, v138
	v_sub_f32_e32 v139, v139, v150
	v_add_f32_e32 v139, v139, v147
	v_cvt_i32_f32_e32 v147, v150
	v_exp_f32_e32 v139, v139
	v_cmp_nlt_f32_e32 vcc, s96, v138
	v_ldexp_f32 v139, v139, v147
	s_nop 0
	v_cndmask_b32_e32 v139, 0, v139, vcc
	v_cmp_ngt_f32_e32 vcc, s97, v138
	s_nop 1
	v_cndmask_b32_e32 v138, v224, v139, vcc
	v_sub_f32_e32 v138, 1.0, v138

; DEVI unsigned cvtpk(float lo, float hi) { unsigned r; asm("v_cvt_pk_bf16_f32 %0, %1, %2" : "=v"(r) : "v"(lo), "v"(hi)); return r; }
; DEVI float bflo(unsigned u) { return __uint_as_float(u << 16); }
; DEVI float bfhi(unsigned u) { return __uint_as_float(u & 0xffff0000u); }
; DEVI float geluf_(float x) { return 0.5f * x * (1.f + erff(x * 0.70710678118654752f)); }
; DEVI void lru_p3_phase(const Params& p) {
;     ...
;       for (int t = 63; t >= 0; --t) {
;         const unsigned l = *(const unsigned*)(la + (size_t)t * 1024), bv = *(const unsigned*)(bb + (size_t)t * 1024);
;         h0 = __expf(bflo(l)) * h0 + bflo(bv); h1 = __expf(bfhi(l)) * h1 + bfhi(bv);
;         const unsigned g = *(const unsigned*)(GX + (size_t)(rbase + t) * 2048 + ch);
;         *(unsigned*)(YG + (size_t)(rbase + t) * 1024 + ch) = cvtpk((s0[t] + h0) * geluf_(bflo(g)), (s1[t] + h1) * geluf_(bfhi(g)));
.LBB0_624:
	s_andn2_saveexec_b64 s[16:17], s[16:17]
	v_mul_f32_e32 v128, v147, v147
	v_fmamk_f32 v150, v128, 0xba1345e1, v217
	v_fmaak_f32 v150, v128, v150, 0xbcdac9b8
	v_fmaak_f32 v150, v128, v150, 0x3de703be
	v_fmaak_f32 v150, v128, v150, 0xbec09330
	v_fmaak_f32 v128, v128, v150, 0x3e0375d0
	v_fma_f32 v150, |v147|, v128, |v147|
	s_or_b64 exec, exec, s[16:17]
	v_lshlrev_b32_e32 v128, 16, v129
	v_mul_f32_e32 v128, 0x3fb8aa3b, v128
	v_exp_f32_e32 v151, v128
	v_lshlrev_b32_e32 v128, 16, v17
	s_lshl_b64 s[0:1], s[2:3], 11
	s_add_i32 s2, s14, 61
	v_fmac_f32_e32 v128, v127, v151
	v_and_b32_e32 v127, 0xffff0000, v129
	v_mul_f32_e32 v127, 0x3fb8aa3b, v127
	v_exp_f32_e32 v129, v127
	v_and_b32_e32 v127, 0xffff0000, v17
	v_mul_f32_e32 v17, 0.5, v130
	v_bfi_b32 v130, s78, v150, v147
	v_fmac_f32_e32 v127, v16, v129
	v_bfi_b32 v129, s78, v138, v132
	v_add_f32_e32 v129, 1.0, v129
	v_add_f32_e32 v16, v134, v128
	v_mul_f32_e32 v17, v17, v129
	v_mul_f32_e32 v129, 0.5, v139
	v_add_f32_e32 v130, 1.0, v130
	v_mul_f32_e32 v16, v16, v17
	v_add_f32_e32 v17, v131, v127
	v_mul_f32_e32 v129, v129, v130
	v_mul_f32_e32 v17, v17, v129
	v_cvt_pk_bf16_f32 v129, v16, v17
	v_lshl_add_u64 v[16:17], v[10:11], 0, s[0:1]
	global_store_dword v[16:17], v129, off
	v_add_co_u32_e32 v16, vcc, s40, v12
	s_ashr_i32 s3, s2, 31
	s_nop 0
	v_addc_co_u32_e32 v17, vcc, 0, v13, vcc
	v_add_co_u32_e32 v138, vcc, 0x1e000, v14
	s_lshl_b64 s[0:1], s[2:3], 12
	s_nop 0
	v_addc_co_u32_e32 v139, vcc, 0, v15, vcc
	v_lshl_add_u64 v[138:139], v[8:9], 0, s[0:1]
	s_waitcnt vmcnt(35)
	v_mov_b32_e32 v129, v164
	v_mov_b32_e32 v131, v163
	v_mov_b32_e32 v130, v165
	s_mov_b32 s0, 0x18800
	s_mov_b32 s1, 0
	v_lshl_add_u64 v[198:199], v[12:13], 0, s[0:1]
	v_lshl_add_u64 v[200:201], v[14:15], 0, s[0:1]
	s_add_i32 s0, s14, 49
	s_ashr_i32 s1, s0, 31
	s_lshl_b64 s[0:1], s[0:1], 12
	global_load_dword v163, v[198:199], off
	global_load_dword v164, v[200:201], off
	v_lshl_add_u64 v[202:203], v[8:9], 0, s[0:1]
	global_load_dword v165, v[202:203], off
	v_lshlrev_b32_e32 v132, 16, v130
	v_mul_f32_e32 v134, 0x3f3504f3, v132
	v_cmp_nlt_f32_e64 s[0:1], |v134|, 1.0
	s_and_saveexec_b64 s[16:17], s[0:1]
	s_xor_b64 s[16:17], exec, s[16:17]
	s_cbranch_execz .LBB0_628
	v_fma_f32 v138, |v134|, s29, v223
	v_fma_f32 v138, |v134|, v138, s20
	v_fma_f32 v138, |v134|, v138, s21
	v_fma_f32 v138, |v134|, v138, s28
	v_fma_f32 v138, |v134|, v138, s33
	v_fma_f32 v138, |v134|, v138, s30
	v_fma_f32 v138, |v134|, v138, |v134|
	v_mul_f32_e32 v139, 0xbfb8aa3b, v138
	v_fma_f32 v147, v138, s31, -v139
	v_rndne_f32_e32 v150, v139
	v_fmac_f32_e32 v147, 0xb2a5705f, v138
	v_sub_f32_e32 v139, v139, v150
	v_add_f32_e32 v139, v139, v147
	v_cvt_i32_f32_e32 v147, v150
	v_exp_f32_e32 v139, v139
	v_cmp_nlt_f32_e32 vcc, s96, v138
	v_ldexp_f32 v139, v139, v147
	s_nop 0
	v_cndmask_b32_e32 v139, 0, v139, vcc
	v_cmp_ngt_f32_e32 vcc, s97, v138
	s_nop 1
	v_cndmask_b32_e32 v138, v224, v139, vcc
	v_sub_f32_e32 v138, 1.0, v138

; DEVI unsigned cvtpk(float lo, float hi) { unsigned r; asm("v_cvt_pk_bf16_f32 %0, %1, %2" : "=v"(r) : "v"(lo), "v"(hi)); return r; }
; DEVI float bflo(unsigned u) { return __uint_as_float(u << 16); }
; DEVI float bfhi(unsigned u) { return __uint_as_float(u & 0xffff0000u); }
; DEVI float geluf_(float x) { return 0.5f * x * (1.f + erff(x * 0.70710678118654752f)); }
; DEVI void lru_p3_phase(const Params& p) {
;     ...
;       for (int t = 63; t >= 0; --t) {
;         const unsigned l = *(const unsigned*)(la + (size_t)t * 1024), bv = *(const unsigned*)(bb + (size_t)t * 1024);
;         h0 = __expf(bflo(l)) * h0 + bflo(bv); h1 = __expf(bfhi(l)) * h1 + bfhi(bv);
;         const unsigned g = *(const unsigned*)(GX + (size_t)(rbase + t) * 2048 + ch);
;         *(unsigned*)(YG + (size_t)(rbase + t) * 1024 + ch) = cvtpk((s0[t] + h0) * geluf_(bflo(g)), (s1[t] + h1) * geluf_(bfhi(g)));
.LBB0_632:
	s_andn2_saveexec_b64 s[16:17], s[16:17]
	v_mul_f32_e32 v130, v147, v147
	v_fmamk_f32 v150, v130, 0xba1345e1, v217
	v_fmaak_f32 v150, v130, v150, 0xbcdac9b8
	v_fmaak_f32 v150, v130, v150, 0x3de703be
	v_fmaak_f32 v150, v130, v150, 0xbec09330
	v_fmaak_f32 v130, v130, v150, 0x3e0375d0
	v_fma_f32 v150, |v147|, v130, |v147|
	s_or_b64 exec, exec, s[16:17]
	v_lshlrev_b32_e32 v130, 16, v131
	v_mul_f32_e32 v130, 0x3fb8aa3b, v130
	v_exp_f32_e32 v151, v130
	v_lshlrev_b32_e32 v130, 16, v129
	v_and_b32_e32 v129, 0xffff0000, v129
	s_lshl_b64 s[0:1], s[2:3], 11
	v_fmac_f32_e32 v130, v128, v151
	v_and_b32_e32 v128, 0xffff0000, v131
	v_mul_f32_e32 v128, 0x3fb8aa3b, v128
	v_exp_f32_e32 v128, v128
	v_bfi_b32 v131, s78, v138, v134
	v_add_f32_e32 v131, 1.0, v131
	s_add_i32 s2, s14, 60
	v_fmac_f32_e32 v129, v127, v128
	v_mul_f32_e32 v128, 0.5, v132
	v_bfi_b32 v132, s78, v150, v147
	v_add_f32_e32 v127, v137, v130
	v_mul_f32_e32 v128, v128, v131
	v_mul_f32_e32 v131, 0.5, v139
	v_add_f32_e32 v132, 1.0, v132
	v_mul_f32_e32 v127, v127, v128
	v_add_f32_e32 v128, v133, v129
	v_mul_f32_e32 v131, v131, v132
	v_lshl_add_u64 v[132:133], v[10:11], 0, s[0:1]
	v_mul_f32_e32 v128, v128, v131
	v_cvt_pk_bf16_f32 v127, v127, v128
	global_store_dword v[132:133], v127, off
	v_add_co_u32_e32 v132, vcc, 0x1e000, v14
	s_ashr_i32 s3, s2, 31
	s_nop 0
	v_addc_co_u32_e32 v133, vcc, 0, v15, vcc
	s_lshl_b64 s[0:1], s[2:3], 12
	s_nop 0
	v_lshl_add_u64 v[132:133], v[8:9], 0, s[0:1]
	s_waitcnt vmcnt(36)
	v_mov_b32_e32 v17, v160
	v_mov_b32_e32 v16, v161
	v_mov_b32_e32 v127, v162
	s_mov_b32 s0, 0x18000
	s_mov_b32 s1, 0
	v_lshl_add_u64 v[198:199], v[12:13], 0, s[0:1]
	v_lshl_add_u64 v[200:201], v[14:15], 0, s[0:1]
	s_add_i32 s0, s14, 48
	s_ashr_i32 s1, s0, 31
	s_lshl_b64 s[0:1], s[0:1], 12
	global_load_dword v160, v[198:199], off
	global_load_dword v161, v[200:201], off
	v_lshl_add_u64 v[202:203], v[8:9], 0, s[0:1]
	global_load_dword v162, v[202:203], off
	v_lshlrev_b32_e32 v131, 16, v127
	v_mul_f32_e32 v132, 0x3f3504f3, v131
	v_cmp_nlt_f32_e64 s[0:1], |v132|, 1.0
	s_and_saveexec_b64 s[16:17], s[0:1]
	s_xor_b64 s[16:17], exec, s[16:17]
	s_cbranch_execz .LBB0_636
	v_fma_f32 v128, |v132|, s29, v223
	v_fma_f32 v128, |v132|, v128, s20
	v_fma_f32 v128, |v132|, v128, s21
	v_fma_f32 v128, |v132|, v128, s28
	v_fma_f32 v128, |v132|, v128, s33
	v_fma_f32 v128, |v132|, v128, s30
	v_fma_f32 v128, |v132|, v128, |v132|
	v_mul_f32_e32 v133, 0xbfb8aa3b, v128
	v_fma_f32 v134, v128, s31, -v133
	v_rndne_f32_e32 v137, v133
	v_fmac_f32_e32 v134, 0xb2a5705f, v128
	v_sub_f32_e32 v133, v133, v137
	v_add_f32_e32 v133, v133, v134
	v_cvt_i32_f32_e32 v134, v137
	v_exp_f32_e32 v133, v133
	v_cmp_nlt_f32_e32 vcc, s96, v128
	v_ldexp_f32 v133, v133, v134
	s_nop 0
	v_cndmask_b32_e32 v133, 0, v133, vcc
	v_cmp_ngt_f32_e32 vcc, s97, v128
	s_nop 1
	v_cndmask_b32_e32 v128, v224, v133, vcc
	v_sub_f32_e32 v133, 1.0, v128

; DEVI unsigned cvtpk(float lo, float hi) { unsigned r; asm("v_cvt_pk_bf16_f32 %0, %1, %2" : "=v"(r) : "v"(lo), "v"(hi)); return r; }
; DEVI float bflo(unsigned u) { return __uint_as_float(u << 16); }
; DEVI float bfhi(unsigned u) { return __uint_as_float(u & 0xffff0000u); }
; DEVI float geluf_(float x) { return 0.5f * x * (1.f + erff(x * 0.70710678118654752f)); }
; DEVI void lru_p3_phase(const Params& p) {
;     ...
;       for (int t = 63; t >= 0; --t) {
;         const unsigned l = *(const unsigned*)(la + (size_t)t * 1024), bv = *(const unsigned*)(bb + (size_t)t * 1024);
;         h0 = __expf(bflo(l)) * h0 + bflo(bv); h1 = __expf(bfhi(l)) * h1 + bfhi(bv);
;         const unsigned g = *(const unsigned*)(GX + (size_t)(rbase + t) * 2048 + ch);
;         *(unsigned*)(YG + (size_t)(rbase + t) * 1024 + ch) = cvtpk((s0[t] + h0) * geluf_(bflo(g)), (s1[t] + h1) * geluf_(bfhi(g)));
.LBB0_640:
	s_andn2_saveexec_b64 s[16:17], s[16:17]
	v_mul_f32_e32 v127, v137, v137
	v_fmamk_f32 v128, v127, 0xba1345e1, v217
	v_fmaak_f32 v128, v127, v128, 0xbcdac9b8
	v_fmaak_f32 v128, v127, v128, 0x3de703be
	v_fmaak_f32 v128, v127, v128, 0xbec09330
	v_fmaak_f32 v127, v127, v128, 0x3e0375d0
	v_fma_f32 v138, |v137|, v127, |v137|
	s_or_b64 exec, exec, s[16:17]
	v_lshlrev_b32_e32 v127, 16, v17
	v_mul_f32_e32 v127, 0x3fb8aa3b, v127
	v_and_b32_e32 v17, 0xffff0000, v17
	v_exp_f32_e32 v127, v127
	v_mul_f32_e32 v17, 0x3fb8aa3b, v17
	v_exp_f32_e32 v17, v17
	v_lshlrev_b32_e32 v128, 16, v16
	v_fmac_f32_e32 v128, v130, v127
	v_and_b32_e32 v127, 0xffff0000, v16
	v_fmac_f32_e32 v127, v129, v17
	v_bfi_b32 v129, s78, v133, v132
	v_mul_f32_e32 v17, 0.5, v131
	v_add_f32_e32 v129, 1.0, v129
	v_bfi_b32 v130, s78, v138, v137
	v_add_f32_e32 v16, v143, v128
	v_mul_f32_e32 v17, v17, v129
	v_mul_f32_e32 v129, 0.5, v134
	v_add_f32_e32 v130, 1.0, v130
	v_mul_f32_e32 v16, v16, v17
	v_add_f32_e32 v17, v135, v127
	v_mul_f32_e32 v129, v129, v130
	v_mul_f32_e32 v17, v17, v129
	s_lshl_b64 s[0:1], s[2:3], 11
	v_cvt_pk_bf16_f32 v129, v16, v17
	v_lshl_add_u64 v[16:17], v[10:11], 0, s[0:1]
	global_store_dword v[16:17], v129, off
	v_add_co_u32_e32 v16, vcc, s39, v12
	s_add_i32 s2, s14, 59
	s_nop 0
	v_addc_co_u32_e32 v17, vcc, 0, v13, vcc
	v_add_co_u32_e32 v132, vcc, 0x1d000, v14
	s_ashr_i32 s3, s2, 31
	s_nop 0
	v_addc_co_u32_e32 v133, vcc, 0, v15, vcc
	s_lshl_b64 s[0:1], s[2:3], 12
	v_lshl_add_u64 v[132:133], v[8:9], 0, s[0:1]
	s_waitcnt vmcnt(37)
	v_mov_b32_e32 v129, v196
	v_mov_b32_e32 v131, v195
	v_mov_b32_e32 v130, v197
	s_mov_b32 s0, 0x17800
	s_mov_b32 s1, 0
	v_lshl_add_u64 v[198:199], v[12:13], 0, s[0:1]
	v_lshl_add_u64 v[200:201], v[14:15], 0, s[0:1]
	s_add_i32 s0, s14, 47
	s_ashr_i32 s1, s0, 31
	s_lshl_b64 s[0:1], s[0:1], 12
	global_load_dword v195, v[198:199], off
	global_load_dword v196, v[200:201], off
	v_lshl_add_u64 v[202:203], v[8:9], 0, s[0:1]
	global_load_dword v197, v[202:203], off
	v_lshlrev_b32_e32 v132, 16, v130
	v_mul_f32_e32 v133, 0x3f3504f3, v132
	v_cmp_nlt_f32_e64 s[0:1], |v133|, 1.0
	s_and_saveexec_b64 s[16:17], s[0:1]
	s_xor_b64 s[16:17], exec, s[16:17]
	s_cbranch_execz .LBB0_644
	v_fma_f32 v134, |v133|, s29, v223
	v_fma_f32 v134, |v133|, v134, s20
	v_fma_f32 v134, |v133|, v134, s21
	v_fma_f32 v134, |v133|, v134, s28
	v_fma_f32 v134, |v133|, v134, s33
	v_fma_f32 v134, |v133|, v134, s30
	v_fma_f32 v134, |v133|, v134, |v133|
	v_mul_f32_e32 v135, 0xbfb8aa3b, v134
	v_fma_f32 v137, v134, s31, -v135
	v_rndne_f32_e32 v138, v135
	v_fmac_f32_e32 v137, 0xb2a5705f, v134
	v_sub_f32_e32 v135, v135, v138
	v_add_f32_e32 v135, v135, v137
	v_cvt_i32_f32_e32 v137, v138
	v_exp_f32_e32 v135, v135
	v_cmp_nlt_f32_e32 vcc, s96, v134
	v_ldexp_f32 v135, v135, v137
	s_nop 0
	v_cndmask_b32_e32 v135, 0, v135, vcc
	v_cmp_ngt_f32_e32 vcc, s97, v134
	s_nop 1
	v_cndmask_b32_e32 v134, v224, v135, vcc
	v_sub_f32_e32 v134, 1.0, v134

; DEVI unsigned cvtpk(float lo, float hi) { unsigned r; asm("v_cvt_pk_bf16_f32 %0, %1, %2" : "=v"(r) : "v"(lo), "v"(hi)); return r; }
; DEVI float bflo(unsigned u) { return __uint_as_float(u << 16); }
; DEVI float bfhi(unsigned u) { return __uint_as_float(u & 0xffff0000u); }
; DEVI float geluf_(float x) { return 0.5f * x * (1.f + erff(x * 0.70710678118654752f)); }
; DEVI void lru_p3_phase(const Params& p) {
;     ...
;       for (int t = 63; t >= 0; --t) {
;         const unsigned l = *(const unsigned*)(la + (size_t)t * 1024), bv = *(const unsigned*)(bb + (size_t)t * 1024);
;         h0 = __expf(bflo(l)) * h0 + bflo(bv); h1 = __expf(bfhi(l)) * h1 + bfhi(bv);
;         const unsigned g = *(const unsigned*)(GX + (size_t)(rbase + t) * 2048 + ch);
;         *(unsigned*)(YG + (size_t)(rbase + t) * 1024 + ch) = cvtpk((s0[t] + h0) * geluf_(bflo(g)), (s1[t] + h1) * geluf_(bfhi(g)));
.LBB0_648:
	s_andn2_saveexec_b64 s[16:17], s[16:17]
	v_mul_f32_e32 v130, v137, v137
	v_fmamk_f32 v138, v130, 0xba1345e1, v217
	v_fmaak_f32 v138, v130, v138, 0xbcdac9b8
	v_fmaak_f32 v138, v130, v138, 0x3de703be
	v_fmaak_f32 v138, v130, v138, 0xbec09330
	v_fmaak_f32 v130, v130, v138, 0x3e0375d0
	v_fma_f32 v138, |v137|, v130, |v137|
	s_or_b64 exec, exec, s[16:17]
	v_lshlrev_b32_e32 v130, 16, v131
	v_mul_f32_e32 v130, 0x3fb8aa3b, v130
	v_exp_f32_e32 v139, v130
	v_lshlrev_b32_e32 v130, 16, v129
	v_and_b32_e32 v129, 0xffff0000, v129
	s_lshl_b64 s[0:1], s[2:3], 11
	v_fmac_f32_e32 v130, v128, v139
	v_and_b32_e32 v128, 0xffff0000, v131
	v_mul_f32_e32 v128, 0x3fb8aa3b, v128
	v_exp_f32_e32 v128, v128
	v_bfi_b32 v131, s78, v134, v133
	v_add_f32_e32 v131, 1.0, v131
	s_add_i32 s2, s14, 58
	v_fmac_f32_e32 v129, v127, v128
	v_mul_f32_e32 v128, 0.5, v132
	v_bfi_b32 v132, s78, v138, v137
	v_add_f32_e32 v127, v148, v130
	v_mul_f32_e32 v128, v128, v131
	v_mul_f32_e32 v131, 0.5, v135
	v_add_f32_e32 v132, 1.0, v132
	v_mul_f32_e32 v127, v127, v128
	v_add_f32_e32 v128, v141, v129
	v_mul_f32_e32 v131, v131, v132
	v_lshl_add_u64 v[132:133], v[10:11], 0, s[0:1]
	v_mul_f32_e32 v128, v128, v131
	v_cvt_pk_bf16_f32 v127, v127, v128
	global_store_dword v[132:133], v127, off
	v_add_co_u32_e32 v132, vcc, 0x1d000, v14
	s_ashr_i32 s3, s2, 31
	s_nop 0
	v_addc_co_u32_e32 v133, vcc, 0, v15, vcc
	s_lshl_b64 s[0:1], s[2:3], 12
	s_nop 0
	v_lshl_add_u64 v[132:133], v[8:9], 0, s[0:1]
	s_waitcnt vmcnt(38)
	v_mov_b32_e32 v17, v192
	v_mov_b32_e32 v16, v193
	v_mov_b32_e32 v127, v194
	s_mov_b32 s0, 0x17000
	s_mov_b32 s1, 0
	v_lshl_add_u64 v[198:199], v[12:13], 0, s[0:1]
	v_lshl_add_u64 v[200:201], v[14:15], 0, s[0:1]
	s_add_i32 s0, s14, 46
	s_ashr_i32 s1, s0, 31
	s_lshl_b64 s[0:1], s[0:1], 12
	global_load_dword v192, v[198:199], off
	global_load_dword v193, v[200:201], off
	v_lshl_add_u64 v[202:203], v[8:9], 0, s[0:1]
	global_load_dword v194, v[202:203], off
	v_lshlrev_b32_e32 v131, 16, v127
	v_mul_f32_e32 v132, 0x3f3504f3, v131
	v_cmp_nlt_f32_e64 s[0:1], |v132|, 1.0
	s_and_saveexec_b64 s[16:17], s[0:1]
	s_xor_b64 s[16:17], exec, s[16:17]
	s_cbranch_execz .LBB0_652
	v_fma_f32 v128, |v132|, s29, v223
	v_fma_f32 v128, |v132|, v128, s20
	v_fma_f32 v128, |v132|, v128, s21
	v_fma_f32 v128, |v132|, v128, s28
	v_fma_f32 v128, |v132|, v128, s33
	v_fma_f32 v128, |v132|, v128, s30
	v_fma_f32 v128, |v132|, v128, |v132|
	v_mul_f32_e32 v133, 0xbfb8aa3b, v128
	v_fma_f32 v134, v128, s31, -v133
	v_rndne_f32_e32 v135, v133
	v_fmac_f32_e32 v134, 0xb2a5705f, v128
	v_sub_f32_e32 v133, v133, v135
	v_add_f32_e32 v133, v133, v134
	v_cvt_i32_f32_e32 v134, v135
	v_exp_f32_e32 v133, v133
	v_cmp_nlt_f32_e32 vcc, s96, v128
	v_ldexp_f32 v133, v133, v134
	s_nop 0
	v_cndmask_b32_e32 v133, 0, v133, vcc
	v_cmp_ngt_f32_e32 vcc, s97, v128
	s_nop 1
	v_cndmask_b32_e32 v128, v224, v133, vcc
	v_sub_f32_e32 v133, 1.0, v128

; DEVI unsigned cvtpk(float lo, float hi) { unsigned r; asm("v_cvt_pk_bf16_f32 %0, %1, %2" : "=v"(r) : "v"(lo), "v"(hi)); return r; }
; DEVI float bflo(unsigned u) { return __uint_as_float(u << 16); }
; DEVI float bfhi(unsigned u) { return __uint_as_float(u & 0xffff0000u); }
; DEVI float geluf_(float x) { return 0.5f * x * (1.f + erff(x * 0.70710678118654752f)); }
; DEVI void lru_p3_phase(const Params& p) {
;     ...
;       for (int t = 63; t >= 0; --t) {
;         const unsigned l = *(const unsigned*)(la + (size_t)t * 1024), bv = *(const unsigned*)(bb + (size_t)t * 1024);
;         h0 = __expf(bflo(l)) * h0 + bflo(bv); h1 = __expf(bfhi(l)) * h1 + bfhi(bv);
;         const unsigned g = *(const unsigned*)(GX + (size_t)(rbase + t) * 2048 + ch);
;         *(unsigned*)(YG + (size_t)(rbase + t) * 1024 + ch) = cvtpk((s0[t] + h0) * geluf_(bflo(g)), (s1[t] + h1) * geluf_(bfhi(g)));
.LBB0_656:
	s_andn2_saveexec_b64 s[16:17], s[16:17]
	v_mul_f32_e32 v127, v135, v135
	v_fmamk_f32 v128, v127, 0xba1345e1, v217
	v_fmaak_f32 v128, v127, v128, 0xbcdac9b8
	v_fmaak_f32 v128, v127, v128, 0x3de703be
	v_fmaak_f32 v128, v127, v128, 0xbec09330
	v_fmaak_f32 v127, v127, v128, 0x3e0375d0
	v_fma_f32 v137, |v135|, v127, |v135|
	s_or_b64 exec, exec, s[16:17]
	v_lshlrev_b32_e32 v127, 16, v17
	v_mul_f32_e32 v127, 0x3fb8aa3b, v127
	v_and_b32_e32 v17, 0xffff0000, v17
	v_exp_f32_e32 v127, v127
	v_mul_f32_e32 v17, 0x3fb8aa3b, v17
	v_exp_f32_e32 v17, v17
	v_lshlrev_b32_e32 v128, 16, v16
	v_fmac_f32_e32 v128, v130, v127
	v_and_b32_e32 v127, 0xffff0000, v16
	v_fmac_f32_e32 v127, v129, v17
	v_bfi_b32 v129, s78, v133, v132
	v_mul_f32_e32 v17, 0.5, v131
	v_add_f32_e32 v129, 1.0, v129
	v_bfi_b32 v130, s78, v137, v135
	v_add_f32_e32 v16, v140, v128
	v_mul_f32_e32 v17, v17, v129
	v_mul_f32_e32 v129, 0.5, v134
	v_add_f32_e32 v130, 1.0, v130
	v_mul_f32_e32 v16, v16, v17
	v_add_f32_e32 v17, v144, v127
	v_mul_f32_e32 v129, v129, v130
	v_mul_f32_e32 v17, v17, v129
	s_lshl_b64 s[0:1], s[2:3], 11
	v_cvt_pk_bf16_f32 v129, v16, v17
	v_lshl_add_u64 v[16:17], v[10:11], 0, s[0:1]
	s_mov_b32 s0, 0x1c000
	global_store_dword v[16:17], v129, off
	v_add_co_u32_e32 v16, vcc, s0, v12
	s_add_i32 s2, s14, 57
	s_nop 0
	v_addc_co_u32_e32 v17, vcc, 0, v13, vcc
	v_add_co_u32_e32 v132, vcc, 0x1c000, v14
	s_ashr_i32 s3, s2, 31
	s_nop 0
	v_addc_co_u32_e32 v133, vcc, 0, v15, vcc
	s_lshl_b64 s[0:1], s[2:3], 12
	v_lshl_add_u64 v[132:133], v[8:9], 0, s[0:1]
	s_waitcnt vmcnt(39)
	v_mov_b32_e32 v129, v190
	v_mov_b32_e32 v131, v189
	v_mov_b32_e32 v130, v191
	s_mov_b32 s0, 0x16800
	s_mov_b32 s1, 0
	v_lshl_add_u64 v[198:199], v[12:13], 0, s[0:1]
	v_lshl_add_u64 v[200:201], v[14:15], 0, s[0:1]
	s_add_i32 s0, s14, 45
	s_ashr_i32 s1, s0, 31
	s_lshl_b64 s[0:1], s[0:1], 12
	global_load_dword v189, v[198:199], off
	global_load_dword v190, v[200:201], off
	v_lshl_add_u64 v[202:203], v[8:9], 0, s[0:1]
	global_load_dword v191, v[202:203], off
	v_lshlrev_b32_e32 v132, 16, v130
	v_mul_f32_e32 v133, 0x3f3504f3, v132
	v_cmp_nlt_f32_e64 s[0:1], |v133|, 1.0
	s_and_saveexec_b64 s[16:17], s[0:1]
	s_xor_b64 s[16:17], exec, s[16:17]
	s_cbranch_execz .LBB0_660
	v_fma_f32 v134, |v133|, s29, v223
	v_fma_f32 v134, |v133|, v134, s20
	v_fma_f32 v134, |v133|, v134, s21
	v_fma_f32 v134, |v133|, v134, s28
	v_fma_f32 v134, |v133|, v134, s33
	v_fma_f32 v134, |v133|, v134, s30
	v_fma_f32 v134, |v133|, v134, |v133|
	v_mul_f32_e32 v135, 0xbfb8aa3b, v134
	v_fma_f32 v137, v134, s31, -v135
	v_rndne_f32_e32 v138, v135
	v_fmac_f32_e32 v137, 0xb2a5705f, v134
	v_sub_f32_e32 v135, v135, v138
	v_add_f32_e32 v135, v135, v137
	v_cvt_i32_f32_e32 v137, v138
	v_exp_f32_e32 v135, v135
	v_cmp_nlt_f32_e32 vcc, s96, v134
	v_ldexp_f32 v135, v135, v137
	s_nop 0
	v_cndmask_b32_e32 v135, 0, v135, vcc
	v_cmp_ngt_f32_e32 vcc, s97, v134
	s_nop 1
	v_cndmask_b32_e32 v134, v224, v135, vcc
	v_sub_f32_e32 v134, 1.0, v134

; DEVI unsigned cvtpk(float lo, float hi) { unsigned r; asm("v_cvt_pk_bf16_f32 %0, %1, %2" : "=v"(r) : "v"(lo), "v"(hi)); return r; }
; DEVI float bflo(unsigned u) { return __uint_as_float(u << 16); }
; DEVI float bfhi(unsigned u) { return __uint_as_float(u & 0xffff0000u); }
; DEVI float geluf_(float x) { return 0.5f * x * (1.f + erff(x * 0.70710678118654752f)); }
; DEVI void lru_p3_phase(const Params& p) {
;     ...
;       for (int t = 63; t >= 0; --t) {
;         const unsigned l = *(const unsigned*)(la + (size_t)t * 1024), bv = *(const unsigned*)(bb + (size_t)t * 1024);
;         h0 = __expf(bflo(l)) * h0 + bflo(bv); h1 = __expf(bfhi(l)) * h1 + bfhi(bv);
;         const unsigned g = *(const unsigned*)(GX + (size_t)(rbase + t) * 2048 + ch);
;         *(unsigned*)(YG + (size_t)(rbase + t) * 1024 + ch) = cvtpk((s0[t] + h0) * geluf_(bflo(g)), (s1[t] + h1) * geluf_(bfhi(g)));
.LBB0_664:
	s_andn2_saveexec_b64 s[16:17], s[16:17]
	v_mul_f32_e32 v130, v137, v137
	v_fmamk_f32 v138, v130, 0xba1345e1, v217
	v_fmaak_f32 v138, v130, v138, 0xbcdac9b8
	v_fmaak_f32 v138, v130, v138, 0x3de703be
	v_fmaak_f32 v138, v130, v138, 0xbec09330
	v_fmaak_f32 v130, v130, v138, 0x3e0375d0
	v_fma_f32 v138, |v137|, v130, |v137|
	s_or_b64 exec, exec, s[16:17]
	v_lshlrev_b32_e32 v130, 16, v131
	v_mul_f32_e32 v130, 0x3fb8aa3b, v130
	v_exp_f32_e32 v139, v130
	v_lshlrev_b32_e32 v130, 16, v129
	v_and_b32_e32 v129, 0xffff0000, v129
	s_lshl_b64 s[0:1], s[2:3], 11
	v_fmac_f32_e32 v130, v128, v139
	v_and_b32_e32 v128, 0xffff0000, v131
	v_mul_f32_e32 v128, 0x3fb8aa3b, v128
	v_exp_f32_e32 v128, v128
	v_bfi_b32 v131, s78, v134, v133
	v_add_f32_e32 v131, 1.0, v131
	s_add_i32 s2, s14, 56
	v_fmac_f32_e32 v129, v127, v128
	v_mul_f32_e32 v128, 0.5, v132
	v_bfi_b32 v132, s78, v138, v137
	v_add_f32_e32 v127, v145, v130
	v_mul_f32_e32 v128, v128, v131
	v_mul_f32_e32 v131, 0.5, v135
	v_add_f32_e32 v132, 1.0, v132
	v_mul_f32_e32 v127, v127, v128
	v_add_f32_e32 v128, v136, v129
	v_mul_f32_e32 v131, v131, v132
	v_lshl_add_u64 v[132:133], v[10:11], 0, s[0:1]
	v_mul_f32_e32 v128, v128, v131
	v_cvt_pk_bf16_f32 v127, v127, v128
	global_store_dword v[132:133], v127, off
	v_add_co_u32_e32 v132, vcc, 0x1c000, v14
	s_ashr_i32 s3, s2, 31
	s_nop 0
	v_addc_co_u32_e32 v133, vcc, 0, v15, vcc
	s_lshl_b64 s[0:1], s[2:3], 12
	s_nop 0
	v_lshl_add_u64 v[132:133], v[8:9], 0, s[0:1]
	s_waitcnt vmcnt(40)
	v_mov_b32_e32 v17, v186
	v_mov_b32_e32 v16, v187
	v_mov_b32_e32 v127, v188
	s_mov_b32 s0, 0x16000
	s_mov_b32 s1, 0
	v_lshl_add_u64 v[198:199], v[12:13], 0, s[0:1]
	v_lshl_add_u64 v[200:201], v[14:15], 0, s[0:1]
	s_add_i32 s0, s14, 44
	s_ashr_i32 s1, s0, 31
	s_lshl_b64 s[0:1], s[0:1], 12
	global_load_dword v186, v[198:199], off
	global_load_dword v187, v[200:201], off
	v_lshl_add_u64 v[202:203], v[8:9], 0, s[0:1]
	global_load_dword v188, v[202:203], off
	v_lshlrev_b32_e32 v131, 16, v127
	v_mul_f32_e32 v132, 0x3f3504f3, v131
	v_cmp_nlt_f32_e64 s[0:1], |v132|, 1.0
	s_and_saveexec_b64 s[16:17], s[0:1]
	s_xor_b64 s[16:17], exec, s[16:17]
	s_cbranch_execz .LBB0_668
	v_fma_f32 v128, |v132|, s29, v223
	v_fma_f32 v128, |v132|, v128, s20
	v_fma_f32 v128, |v132|, v128, s21
	v_fma_f32 v128, |v132|, v128, s28
	v_fma_f32 v128, |v132|, v128, s33
	v_fma_f32 v128, |v132|, v128, s30
	v_fma_f32 v128, |v132|, v128, |v132|
	v_mul_f32_e32 v133, 0xbfb8aa3b, v128
	v_fma_f32 v134, v128, s31, -v133
	v_rndne_f32_e32 v135, v133
	v_fmac_f32_e32 v134, 0xb2a5705f, v128
	v_sub_f32_e32 v133, v133, v135
	v_add_f32_e32 v133, v133, v134
	v_cvt_i32_f32_e32 v134, v135
	v_exp_f32_e32 v133, v133
	v_cmp_nlt_f32_e32 vcc, s96, v128
	v_ldexp_f32 v133, v133, v134
	s_nop 0
	v_cndmask_b32_e32 v133, 0, v133, vcc
	v_cmp_ngt_f32_e32 vcc, s97, v128
	s_nop 1
	v_cndmask_b32_e32 v128, v224, v133, vcc
	v_sub_f32_e32 v133, 1.0, v128

; DEVI unsigned cvtpk(float lo, float hi) { unsigned r; asm("v_cvt_pk_bf16_f32 %0, %1, %2" : "=v"(r) : "v"(lo), "v"(hi)); return r; }
; DEVI float bflo(unsigned u) { return __uint_as_float(u << 16); }
; DEVI float bfhi(unsigned u) { return __uint_as_float(u & 0xffff0000u); }
; DEVI float geluf_(float x) { return 0.5f * x * (1.f + erff(x * 0.70710678118654752f)); }
; DEVI void lru_p3_phase(const Params& p) {
;     ...
;       for (int t = 63; t >= 0; --t) {
;         const unsigned l = *(const unsigned*)(la + (size_t)t * 1024), bv = *(const unsigned*)(bb + (size_t)t * 1024);
;         h0 = __expf(bflo(l)) * h0 + bflo(bv); h1 = __expf(bfhi(l)) * h1 + bfhi(bv);
;         const unsigned g = *(const unsigned*)(GX + (size_t)(rbase + t) * 2048 + ch);
;         *(unsigned*)(YG + (size_t)(rbase + t) * 1024 + ch) = cvtpk((s0[t] + h0) * geluf_(bflo(g)), (s1[t] + h1) * geluf_(bfhi(g)));
.LBB0_672:
	s_andn2_saveexec_b64 s[16:17], s[16:17]
	v_mul_f32_e32 v127, v135, v135
	v_fmamk_f32 v128, v127, 0xba1345e1, v217
	v_fmaak_f32 v128, v127, v128, 0xbcdac9b8
	v_fmaak_f32 v128, v127, v128, 0x3de703be
	v_fmaak_f32 v128, v127, v128, 0xbec09330
	v_fmaak_f32 v127, v127, v128, 0x3e0375d0
	v_fma_f32 v136, |v135|, v127, |v135|
	s_or_b64 exec, exec, s[16:17]
	v_lshlrev_b32_e32 v127, 16, v17
	v_mul_f32_e32 v127, 0x3fb8aa3b, v127
	v_and_b32_e32 v17, 0xffff0000, v17
	v_exp_f32_e32 v127, v127
	v_mul_f32_e32 v17, 0x3fb8aa3b, v17
	v_exp_f32_e32 v17, v17
	v_lshlrev_b32_e32 v128, 16, v16
	v_fmac_f32_e32 v128, v130, v127
	v_and_b32_e32 v127, 0xffff0000, v16
	v_fmac_f32_e32 v127, v129, v17
	v_bfi_b32 v129, s78, v133, v132
	v_mul_f32_e32 v17, 0.5, v131
	v_add_f32_e32 v129, 1.0, v129
	v_bfi_b32 v130, s78, v136, v135
	v_add_f32_e32 v16, v152, v128
	v_mul_f32_e32 v17, v17, v129
	v_mul_f32_e32 v129, 0.5, v134
	v_add_f32_e32 v130, 1.0, v130
	v_mul_f32_e32 v16, v16, v17
	v_add_f32_e32 v17, v142, v127
	v_mul_f32_e32 v129, v129, v130
	v_mul_f32_e32 v17, v17, v129
	s_lshl_b64 s[0:1], s[2:3], 11
	v_cvt_pk_bf16_f32 v129, v16, v17
	v_lshl_add_u64 v[16:17], v[10:11], 0, s[0:1]
	global_store_dword v[16:17], v129, off
	v_add_co_u32_e32 v16, vcc, s38, v12
	s_add_i32 s2, s14, 55
	s_nop 0
	v_addc_co_u32_e32 v17, vcc, 0, v13, vcc
	v_add_co_u32_e32 v132, vcc, 0x1b000, v14
	s_ashr_i32 s3, s2, 31
	s_nop 0
	v_addc_co_u32_e32 v133, vcc, 0, v15, vcc
	s_lshl_b64 s[0:1], s[2:3], 12
	v_lshl_add_u64 v[132:133], v[8:9], 0, s[0:1]
	s_waitcnt vmcnt(41)
	v_mov_b32_e32 v129, v184
	v_mov_b32_e32 v131, v183
	v_mov_b32_e32 v130, v185
	s_mov_b32 s0, 0x15800
	s_mov_b32 s1, 0
	v_lshl_add_u64 v[198:199], v[12:13], 0, s[0:1]
	v_lshl_add_u64 v[200:201], v[14:15], 0, s[0:1]
	s_add_i32 s0, s14, 43
	s_ashr_i32 s1, s0, 31
	s_lshl_b64 s[0:1], s[0:1], 12
	global_load_dword v183, v[198:199], off
	global_load_dword v184, v[200:201], off
	v_lshl_add_u64 v[202:203], v[8:9], 0, s[0:1]
	global_load_dword v185, v[202:203], off
	v_lshlrev_b32_e32 v132, 16, v130
	v_mul_f32_e32 v133, 0x3f3504f3, v132
	v_cmp_nlt_f32_e64 s[0:1], |v133|, 1.0
	s_and_saveexec_b64 s[16:17], s[0:1]
	s_xor_b64 s[16:17], exec, s[16:17]
	s_cbranch_execz .LBB0_676
	v_fma_f32 v134, |v133|, s29, v223
	v_fma_f32 v134, |v133|, v134, s20
	v_fma_f32 v134, |v133|, v134, s21
	v_fma_f32 v134, |v133|, v134, s28
	v_fma_f32 v134, |v133|, v134, s33
	v_fma_f32 v134, |v133|, v134, s30
	v_fma_f32 v134, |v133|, v134, |v133|
	v_mul_f32_e32 v135, 0xbfb8aa3b, v134
	v_fma_f32 v136, v134, s31, -v135
	v_rndne_f32_e32 v137, v135
	v_fmac_f32_e32 v136, 0xb2a5705f, v134
	v_sub_f32_e32 v135, v135, v137
	v_add_f32_e32 v135, v135, v136
	v_cvt_i32_f32_e32 v136, v137
	v_exp_f32_e32 v135, v135
	v_cmp_nlt_f32_e32 vcc, s96, v134
	v_ldexp_f32 v135, v135, v136
	s_nop 0
	v_cndmask_b32_e32 v135, 0, v135, vcc
	v_cmp_ngt_f32_e32 vcc, s97, v134
	s_nop 1
	v_cndmask_b32_e32 v134, v224, v135, vcc
	v_sub_f32_e32 v134, 1.0, v134

; DEVI unsigned cvtpk(float lo, float hi) { unsigned r; asm("v_cvt_pk_bf16_f32 %0, %1, %2" : "=v"(r) : "v"(lo), "v"(hi)); return r; }
; DEVI float bflo(unsigned u) { return __uint_as_float(u << 16); }
; DEVI float bfhi(unsigned u) { return __uint_as_float(u & 0xffff0000u); }
; DEVI float geluf_(float x) { return 0.5f * x * (1.f + erff(x * 0.70710678118654752f)); }
; DEVI void lru_p3_phase(const Params& p) {
;     ...
;       for (int t = 63; t >= 0; --t) {
;         const unsigned l = *(const unsigned*)(la + (size_t)t * 1024), bv = *(const unsigned*)(bb + (size_t)t * 1024);
;         h0 = __expf(bflo(l)) * h0 + bflo(bv); h1 = __expf(bfhi(l)) * h1 + bfhi(bv);
;         const unsigned g = *(const unsigned*)(GX + (size_t)(rbase + t) * 2048 + ch);
;         *(unsigned*)(YG + (size_t)(rbase + t) * 1024 + ch) = cvtpk((s0[t] + h0) * geluf_(bflo(g)), (s1[t] + h1) * geluf_(bfhi(g)));
.LBB0_680:
	s_andn2_saveexec_b64 s[16:17], s[16:17]
	v_mul_f32_e32 v130, v136, v136
	v_fmamk_f32 v137, v130, 0xba1345e1, v217
	v_fmaak_f32 v137, v130, v137, 0xbcdac9b8
	v_fmaak_f32 v137, v130, v137, 0x3de703be
	v_fmaak_f32 v137, v130, v137, 0xbec09330
	v_fmaak_f32 v130, v130, v137, 0x3e0375d0
	v_fma_f32 v137, |v136|, v130, |v136|
	s_or_b64 exec, exec, s[16:17]
	v_lshlrev_b32_e32 v130, 16, v131
	v_mul_f32_e32 v130, 0x3fb8aa3b, v130
	v_exp_f32_e32 v138, v130
	v_lshlrev_b32_e32 v130, 16, v129
	v_and_b32_e32 v129, 0xffff0000, v129
	s_lshl_b64 s[0:1], s[2:3], 11
	v_fmac_f32_e32 v130, v128, v138
	v_and_b32_e32 v128, 0xffff0000, v131
	v_mul_f32_e32 v128, 0x3fb8aa3b, v128
	v_exp_f32_e32 v128, v128
	v_bfi_b32 v131, s78, v134, v133
	v_add_f32_e32 v131, 1.0, v131
	s_add_i32 s2, s14, 54
	v_fmac_f32_e32 v129, v127, v128
	v_mul_f32_e32 v128, 0.5, v132
	v_bfi_b32 v132, s78, v137, v136
	v_add_f32_e32 v127, v146, v130
	v_mul_f32_e32 v128, v128, v131
	v_mul_f32_e32 v131, 0.5, v135
	v_add_f32_e32 v132, 1.0, v132
	v_mul_f32_e32 v127, v127, v128
	v_add_f32_e32 v128, v149, v129
	v_mul_f32_e32 v131, v131, v132
	v_lshl_add_u64 v[132:133], v[10:11], 0, s[0:1]
	v_mul_f32_e32 v128, v128, v131
	v_cvt_pk_bf16_f32 v127, v127, v128
	global_store_dword v[132:133], v127, off
	v_add_co_u32_e32 v132, vcc, 0x1b000, v14
	s_ashr_i32 s3, s2, 31
	s_nop 0
	v_addc_co_u32_e32 v133, vcc, 0, v15, vcc
	s_lshl_b64 s[0:1], s[2:3], 12
	s_nop 0
	v_lshl_add_u64 v[132:133], v[8:9], 0, s[0:1]
	s_waitcnt vmcnt(42)
	v_mov_b32_e32 v17, v180
	v_mov_b32_e32 v16, v181
	v_mov_b32_e32 v127, v182
	s_mov_b32 s0, 0x15000
	s_mov_b32 s1, 0
	v_lshl_add_u64 v[198:199], v[12:13], 0, s[0:1]
	v_lshl_add_u64 v[200:201], v[14:15], 0, s[0:1]
	s_add_i32 s0, s14, 42
	s_ashr_i32 s1, s0, 31
	s_lshl_b64 s[0:1], s[0:1], 12
	global_load_dword v180, v[198:199], off
	global_load_dword v181, v[200:201], off
	v_lshl_add_u64 v[202:203], v[8:9], 0, s[0:1]
	global_load_dword v182, v[202:203], off
	v_lshlrev_b32_e32 v131, 16, v127
	v_mul_f32_e32 v132, 0x3f3504f3, v131
	v_cmp_nlt_f32_e64 s[0:1], |v132|, 1.0
	s_and_saveexec_b64 s[16:17], s[0:1]
	s_xor_b64 s[16:17], exec, s[16:17]
	s_cbranch_execz .LBB0_684
	v_fma_f32 v128, |v132|, s29, v223
	v_fma_f32 v128, |v132|, v128, s20
	v_fma_f32 v128, |v132|, v128, s21
	v_fma_f32 v128, |v132|, v128, s28
	v_fma_f32 v128, |v132|, v128, s33
	v_fma_f32 v128, |v132|, v128, s30
	v_fma_f32 v128, |v132|, v128, |v132|
	v_mul_f32_e32 v133, 0xbfb8aa3b, v128
	v_fma_f32 v134, v128, s31, -v133
	v_rndne_f32_e32 v135, v133
	v_fmac_f32_e32 v134, 0xb2a5705f, v128
	v_sub_f32_e32 v133, v133, v135
	v_add_f32_e32 v133, v133, v134
	v_cvt_i32_f32_e32 v134, v135
	v_exp_f32_e32 v133, v133
	v_cmp_nlt_f32_e32 vcc, s96, v128
	v_ldexp_f32 v133, v133, v134
	s_nop 0
	v_cndmask_b32_e32 v133, 0, v133, vcc
	v_cmp_ngt_f32_e32 vcc, s97, v128
	s_nop 1
	v_cndmask_b32_e32 v128, v224, v133, vcc
	v_sub_f32_e32 v133, 1.0, v128

; DEVI unsigned cvtpk(float lo, float hi) { unsigned r; asm("v_cvt_pk_bf16_f32 %0, %1, %2" : "=v"(r) : "v"(lo), "v"(hi)); return r; }
; DEVI float bflo(unsigned u) { return __uint_as_float(u << 16); }
; DEVI float bfhi(unsigned u) { return __uint_as_float(u & 0xffff0000u); }
; DEVI float geluf_(float x) { return 0.5f * x * (1.f + erff(x * 0.70710678118654752f)); }
; DEVI void lru_p3_phase(const Params& p) {
;     ...
;       for (int t = 63; t >= 0; --t) {
;         const unsigned l = *(const unsigned*)(la + (size_t)t * 1024), bv = *(const unsigned*)(bb + (size_t)t * 1024);
;         h0 = __expf(bflo(l)) * h0 + bflo(bv); h1 = __expf(bfhi(l)) * h1 + bfhi(bv);
;         const unsigned g = *(const unsigned*)(GX + (size_t)(rbase + t) * 2048 + ch);
;         *(unsigned*)(YG + (size_t)(rbase + t) * 1024 + ch) = cvtpk((s0[t] + h0) * geluf_(bflo(g)), (s1[t] + h1) * geluf_(bfhi(g)));
.LBB0_688:
	s_andn2_saveexec_b64 s[16:17], s[16:17]
	v_mul_f32_e32 v127, v135, v135
	v_fmamk_f32 v128, v127, 0xba1345e1, v217
	v_fmaak_f32 v128, v127, v128, 0xbcdac9b8
	v_fmaak_f32 v128, v127, v128, 0x3de703be
	v_fmaak_f32 v128, v127, v128, 0xbec09330
	v_fmaak_f32 v127, v127, v128, 0x3e0375d0
	v_fma_f32 v136, |v135|, v127, |v135|
	s_or_b64 exec, exec, s[16:17]
	v_lshlrev_b32_e32 v127, 16, v17
	v_mul_f32_e32 v127, 0x3fb8aa3b, v127
	v_exp_f32_e32 v127, v127
	v_and_b32_e32 v17, 0xffff0000, v17
	v_mul_f32_e32 v17, 0x3fb8aa3b, v17
	v_exp_f32_e32 v17, v17
	v_lshlrev_b32_e32 v128, 16, v16
	v_fmac_f32_e32 v128, v130, v127
	v_and_b32_e32 v127, 0xffff0000, v16
	v_add_f32_e32 v16, v125, v128
	v_bfi_b32 v125, s78, v133, v132
	v_fmac_f32_e32 v127, v129, v17
	v_mul_f32_e32 v17, 0.5, v131
	v_add_f32_e32 v125, 1.0, v125
	v_mul_f32_e32 v17, v17, v125
	v_mul_f32_e32 v16, v16, v17
	v_add_f32_e32 v17, v126, v127
	v_bfi_b32 v126, s78, v136, v135
	v_mul_f32_e32 v125, 0.5, v134
	v_add_f32_e32 v126, 1.0, v126
	v_mul_f32_e32 v125, v125, v126
	v_mul_f32_e32 v17, v17, v125
	s_lshl_b64 s[0:1], s[2:3], 11
	v_cvt_pk_bf16_f32 v125, v16, v17
	v_lshl_add_u64 v[16:17], v[10:11], 0, s[0:1]
	global_store_dword v[16:17], v125, off
	v_add_co_u32_e32 v16, vcc, s37, v12
	s_add_i32 s2, s14, 53
	s_nop 0
	v_addc_co_u32_e32 v17, vcc, 0, v13, vcc
	v_add_co_u32_e32 v130, vcc, 0x1a000, v14
	s_ashr_i32 s3, s2, 31
	s_nop 0
	v_addc_co_u32_e32 v131, vcc, 0, v15, vcc
	s_lshl_b64 s[0:1], s[2:3], 12
	v_lshl_add_u64 v[130:131], v[8:9], 0, s[0:1]
	s_waitcnt vmcnt(43)
	v_mov_b32_e32 v125, v176
	v_mov_b32_e32 v129, v175
	v_mov_b32_e32 v126, v177
	s_mov_b32 s0, 0x14800
	s_mov_b32 s1, 0
	v_lshl_add_u64 v[198:199], v[12:13], 0, s[0:1]
	v_lshl_add_u64 v[200:201], v[14:15], 0, s[0:1]
	s_add_i32 s0, s14, 41
	s_ashr_i32 s1, s0, 31
	s_lshl_b64 s[0:1], s[0:1], 12
	global_load_dword v175, v[198:199], off
	global_load_dword v176, v[200:201], off
	v_lshl_add_u64 v[202:203], v[8:9], 0, s[0:1]
	global_load_dword v177, v[202:203], off
	v_lshlrev_b32_e32 v130, 16, v126
	v_mul_f32_e32 v131, 0x3f3504f3, v130
	v_cmp_nlt_f32_e64 s[0:1], |v131|, 1.0
	s_and_saveexec_b64 s[16:17], s[0:1]
	s_xor_b64 s[16:17], exec, s[16:17]
	s_cbranch_execz .LBB0_692
	v_fma_f32 v132, |v131|, s29, v223
	v_fma_f32 v132, |v131|, v132, s20
	v_fma_f32 v132, |v131|, v132, s21
	v_fma_f32 v132, |v131|, v132, s28
	v_fma_f32 v132, |v131|, v132, s33
	v_fma_f32 v132, |v131|, v132, s30
	v_fma_f32 v132, |v131|, v132, |v131|
	v_mul_f32_e32 v133, 0xbfb8aa3b, v132
	v_fma_f32 v134, v132, s31, -v133
	v_rndne_f32_e32 v135, v133
	v_fmac_f32_e32 v134, 0xb2a5705f, v132
	v_sub_f32_e32 v133, v133, v135
	v_add_f32_e32 v133, v133, v134
	v_cvt_i32_f32_e32 v134, v135
	v_exp_f32_e32 v133, v133
	v_cmp_nlt_f32_e32 vcc, s96, v132
	v_ldexp_f32 v133, v133, v134
	s_nop 0
	v_cndmask_b32_e32 v133, 0, v133, vcc
	v_cmp_ngt_f32_e32 vcc, s97, v132
	s_nop 1
	v_cndmask_b32_e32 v132, v224, v133, vcc
	v_sub_f32_e32 v132, 1.0, v132

; DEVI unsigned cvtpk(float lo, float hi) { unsigned r; asm("v_cvt_pk_bf16_f32 %0, %1, %2" : "=v"(r) : "v"(lo), "v"(hi)); return r; }
; DEVI float bflo(unsigned u) { return __uint_as_float(u << 16); }
; DEVI float bfhi(unsigned u) { return __uint_as_float(u & 0xffff0000u); }
; DEVI float geluf_(float x) { return 0.5f * x * (1.f + erff(x * 0.70710678118654752f)); }
; DEVI void lru_p3_phase(const Params& p) {
;     ...
;       for (int t = 63; t >= 0; --t) {
;         const unsigned l = *(const unsigned*)(la + (size_t)t * 1024), bv = *(const unsigned*)(bb + (size_t)t * 1024);
;         h0 = __expf(bflo(l)) * h0 + bflo(bv); h1 = __expf(bfhi(l)) * h1 + bfhi(bv);
;         const unsigned g = *(const unsigned*)(GX + (size_t)(rbase + t) * 2048 + ch);
;         *(unsigned*)(YG + (size_t)(rbase + t) * 1024 + ch) = cvtpk((s0[t] + h0) * geluf_(bflo(g)), (s1[t] + h1) * geluf_(bfhi(g)));
.LBB0_696:
	s_andn2_saveexec_b64 s[16:17], s[16:17]
	v_mul_f32_e32 v126, v134, v134
	v_fmamk_f32 v135, v126, 0xba1345e1, v217
	v_fmaak_f32 v135, v126, v135, 0xbcdac9b8
	v_fmaak_f32 v135, v126, v135, 0x3de703be
	v_fmaak_f32 v135, v126, v135, 0xbec09330
	v_fmaak_f32 v126, v126, v135, 0x3e0375d0
	v_fma_f32 v135, |v134|, v126, |v134|
	s_or_b64 exec, exec, s[16:17]
	v_lshlrev_b32_e32 v126, 16, v129
	v_mul_f32_e32 v126, 0x3fb8aa3b, v126
	v_exp_f32_e32 v136, v126
	v_lshlrev_b32_e32 v126, 16, v125
	v_and_b32_e32 v125, 0xffff0000, v125
	s_lshl_b64 s[0:1], s[2:3], 11
	v_fmac_f32_e32 v126, v128, v136
	v_and_b32_e32 v128, 0xffff0000, v129
	v_mul_f32_e32 v128, 0x3fb8aa3b, v128
	v_exp_f32_e32 v128, v128
	v_add_f32_e32 v123, v123, v126
	s_add_i32 s2, s14, 52
	s_ashr_i32 s3, s2, 31
	v_fmac_f32_e32 v125, v127, v128
	v_bfi_b32 v128, s78, v132, v131
	v_mul_f32_e32 v127, 0.5, v130
	v_add_f32_e32 v128, 1.0, v128
	v_mul_f32_e32 v127, v127, v128
	v_bfi_b32 v128, s78, v135, v134
	v_mul_f32_e32 v123, v123, v127
	v_mul_f32_e32 v127, 0.5, v133
	v_add_f32_e32 v128, 1.0, v128
	v_add_f32_e32 v124, v124, v125
	v_mul_f32_e32 v127, v127, v128
	v_lshl_add_u64 v[128:129], v[10:11], 0, s[0:1]
	v_mul_f32_e32 v124, v124, v127
	v_cvt_pk_bf16_f32 v123, v123, v124
	global_store_dword v[128:129], v123, off
	v_add_co_u32_e32 v128, vcc, 0x1a000, v14
	s_lshl_b64 s[0:1], s[2:3], 12
	s_nop 0
	v_addc_co_u32_e32 v129, vcc, 0, v15, vcc
	s_nop 0
	v_lshl_add_u64 v[128:129], v[8:9], 0, s[0:1]
	s_waitcnt vmcnt(44)
	v_mov_b32_e32 v17, v172
	v_mov_b32_e32 v16, v173
	v_mov_b32_e32 v123, v174
	s_mov_b32 s0, 0x14000
	s_mov_b32 s1, 0
	v_lshl_add_u64 v[198:199], v[12:13], 0, s[0:1]
	v_lshl_add_u64 v[200:201], v[14:15], 0, s[0:1]
	s_add_i32 s0, s14, 40
	s_ashr_i32 s1, s0, 31
	s_lshl_b64 s[0:1], s[0:1], 12
	global_load_dword v172, v[198:199], off
	global_load_dword v173, v[200:201], off
	v_lshl_add_u64 v[202:203], v[8:9], 0, s[0:1]
	global_load_dword v174, v[202:203], off
	v_lshlrev_b32_e32 v127, 16, v123
	v_mul_f32_e32 v128, 0x3f3504f3, v127
	v_cmp_nlt_f32_e64 s[0:1], |v128|, 1.0
	s_and_saveexec_b64 s[16:17], s[0:1]
	s_xor_b64 s[16:17], exec, s[16:17]
	s_cbranch_execz .LBB0_700
	v_fma_f32 v124, |v128|, s29, v223
	v_fma_f32 v124, |v128|, v124, s20
	v_fma_f32 v124, |v128|, v124, s21
	v_fma_f32 v124, |v128|, v124, s28
	v_fma_f32 v124, |v128|, v124, s33
	v_fma_f32 v124, |v128|, v124, s30
	v_fma_f32 v124, |v128|, v124, |v128|
	v_mul_f32_e32 v129, 0xbfb8aa3b, v124
	v_fma_f32 v130, v124, s31, -v129
	v_rndne_f32_e32 v131, v129
	v_fmac_f32_e32 v130, 0xb2a5705f, v124
	v_sub_f32_e32 v129, v129, v131
	v_add_f32_e32 v129, v129, v130
	v_cvt_i32_f32_e32 v130, v131
	v_exp_f32_e32 v129, v129
	v_cmp_nlt_f32_e32 vcc, s96, v124
	v_ldexp_f32 v129, v129, v130
	s_nop 0
	v_cndmask_b32_e32 v129, 0, v129, vcc
	v_cmp_ngt_f32_e32 vcc, s97, v124
	s_nop 1
	v_cndmask_b32_e32 v124, v224, v129, vcc
	v_sub_f32_e32 v129, 1.0, v124

; DEVI unsigned cvtpk(float lo, float hi) { unsigned r; asm("v_cvt_pk_bf16_f32 %0, %1, %2" : "=v"(r) : "v"(lo), "v"(hi)); return r; }
; DEVI float bflo(unsigned u) { return __uint_as_float(u << 16); }
; DEVI float bfhi(unsigned u) { return __uint_as_float(u & 0xffff0000u); }
; DEVI float geluf_(float x) { return 0.5f * x * (1.f + erff(x * 0.70710678118654752f)); }
; DEVI void lru_p3_phase(const Params& p) {
;     ...
;       for (int t = 63; t >= 0; --t) {
;         const unsigned l = *(const unsigned*)(la + (size_t)t * 1024), bv = *(const unsigned*)(bb + (size_t)t * 1024);
;         h0 = __expf(bflo(l)) * h0 + bflo(bv); h1 = __expf(bfhi(l)) * h1 + bfhi(bv);
;         const unsigned g = *(const unsigned*)(GX + (size_t)(rbase + t) * 2048 + ch);
;         *(unsigned*)(YG + (size_t)(rbase + t) * 1024 + ch) = cvtpk((s0[t] + h0) * geluf_(bflo(g)), (s1[t] + h1) * geluf_(bfhi(g)));
.LBB0_704:
	s_andn2_saveexec_b64 s[16:17], s[16:17]
	v_mul_f32_e32 v123, v131, v131
	v_fmamk_f32 v124, v123, 0xba1345e1, v217
	v_fmaak_f32 v124, v123, v124, 0xbcdac9b8
	v_fmaak_f32 v124, v123, v124, 0x3de703be
	v_fmaak_f32 v124, v123, v124, 0xbec09330
	v_fmaak_f32 v123, v123, v124, 0x3e0375d0
	v_fma_f32 v132, |v131|, v123, |v131|
	s_or_b64 exec, exec, s[16:17]
	v_lshlrev_b32_e32 v123, 16, v17
	v_mul_f32_e32 v123, 0x3fb8aa3b, v123
	v_exp_f32_e32 v123, v123
	v_and_b32_e32 v17, 0xffff0000, v17
	v_mul_f32_e32 v17, 0x3fb8aa3b, v17
	v_exp_f32_e32 v17, v17
	v_lshlrev_b32_e32 v124, 16, v16
	v_fmac_f32_e32 v124, v126, v123
	v_and_b32_e32 v123, 0xffff0000, v16
	v_add_f32_e32 v16, v121, v124
	v_bfi_b32 v121, s78, v129, v128
	v_fmac_f32_e32 v123, v125, v17
	v_mul_f32_e32 v17, 0.5, v127
	v_add_f32_e32 v121, 1.0, v121
	v_mul_f32_e32 v17, v17, v121
	v_mul_f32_e32 v16, v16, v17
	v_add_f32_e32 v17, v122, v123
	v_bfi_b32 v122, s78, v132, v131
	v_mul_f32_e32 v121, 0.5, v130
	v_add_f32_e32 v122, 1.0, v122
	v_mul_f32_e32 v121, v121, v122
	v_mul_f32_e32 v17, v17, v121
	s_lshl_b64 s[0:1], s[2:3], 11
	v_cvt_pk_bf16_f32 v121, v16, v17
	v_lshl_add_u64 v[16:17], v[10:11], 0, s[0:1]
	global_store_dword v[16:17], v121, off
	v_add_co_u32_e32 v16, vcc, s36, v12
	s_add_i32 s2, s14, 51
	s_nop 0
	v_addc_co_u32_e32 v17, vcc, 0, v13, vcc
	v_add_co_u32_e32 v126, vcc, 0x19000, v14
	s_ashr_i32 s3, s2, 31
	s_nop 0
	v_addc_co_u32_e32 v127, vcc, 0, v15, vcc
	s_lshl_b64 s[0:1], s[2:3], 12
	v_lshl_add_u64 v[126:127], v[8:9], 0, s[0:1]
	s_waitcnt vmcnt(45)
	v_mov_b32_e32 v121, v170
	v_mov_b32_e32 v125, v169
	v_mov_b32_e32 v122, v171
	s_mov_b32 s0, 0x13800
	s_mov_b32 s1, 0
	v_lshl_add_u64 v[198:199], v[12:13], 0, s[0:1]
	v_lshl_add_u64 v[200:201], v[14:15], 0, s[0:1]
	s_add_i32 s0, s14, 39
	s_ashr_i32 s1, s0, 31
	s_lshl_b64 s[0:1], s[0:1], 12
	global_load_dword v169, v[198:199], off
	global_load_dword v170, v[200:201], off
	v_lshl_add_u64 v[202:203], v[8:9], 0, s[0:1]
	global_load_dword v171, v[202:203], off
	v_lshlrev_b32_e32 v126, 16, v122
	v_mul_f32_e32 v127, 0x3f3504f3, v126
	v_cmp_nlt_f32_e64 s[0:1], |v127|, 1.0
	s_and_saveexec_b64 s[16:17], s[0:1]
	s_xor_b64 s[16:17], exec, s[16:17]
	s_cbranch_execz .LBB0_708
	v_fma_f32 v128, |v127|, s29, v223
	v_fma_f32 v128, |v127|, v128, s20
	v_fma_f32 v128, |v127|, v128, s21
	v_fma_f32 v128, |v127|, v128, s28
	v_fma_f32 v128, |v127|, v128, s33
	v_fma_f32 v128, |v127|, v128, s30
	v_fma_f32 v128, |v127|, v128, |v127|
	v_mul_f32_e32 v129, 0xbfb8aa3b, v128
	v_fma_f32 v130, v128, s31, -v129
	v_rndne_f32_e32 v131, v129
	v_fmac_f32_e32 v130, 0xb2a5705f, v128
	v_sub_f32_e32 v129, v129, v131
	v_add_f32_e32 v129, v129, v130
	v_cvt_i32_f32_e32 v130, v131
	v_exp_f32_e32 v129, v129
	v_cmp_nlt_f32_e32 vcc, s96, v128
	v_ldexp_f32 v129, v129, v130
	s_nop 0
	v_cndmask_b32_e32 v129, 0, v129, vcc
	v_cmp_ngt_f32_e32 vcc, s97, v128
	s_nop 1
	v_cndmask_b32_e32 v128, v224, v129, vcc
	v_sub_f32_e32 v128, 1.0, v128

; DEVI unsigned cvtpk(float lo, float hi) { unsigned r; asm("v_cvt_pk_bf16_f32 %0, %1, %2" : "=v"(r) : "v"(lo), "v"(hi)); return r; }
; DEVI float bflo(unsigned u) { return __uint_as_float(u << 16); }
; DEVI float bfhi(unsigned u) { return __uint_as_float(u & 0xffff0000u); }
; DEVI float geluf_(float x) { return 0.5f * x * (1.f + erff(x * 0.70710678118654752f)); }
; DEVI void lru_p3_phase(const Params& p) {
;     ...
;       for (int t = 63; t >= 0; --t) {
;         const unsigned l = *(const unsigned*)(la + (size_t)t * 1024), bv = *(const unsigned*)(bb + (size_t)t * 1024);
;         h0 = __expf(bflo(l)) * h0 + bflo(bv); h1 = __expf(bfhi(l)) * h1 + bfhi(bv);
;         const unsigned g = *(const unsigned*)(GX + (size_t)(rbase + t) * 2048 + ch);
;         *(unsigned*)(YG + (size_t)(rbase + t) * 1024 + ch) = cvtpk((s0[t] + h0) * geluf_(bflo(g)), (s1[t] + h1) * geluf_(bfhi(g)));
.LBB0_712:
	s_andn2_saveexec_b64 s[16:17], s[16:17]
	v_mul_f32_e32 v122, v130, v130
	v_fmamk_f32 v131, v122, 0xba1345e1, v217
	v_fmaak_f32 v131, v122, v131, 0xbcdac9b8
	v_fmaak_f32 v131, v122, v131, 0x3de703be
	v_fmaak_f32 v131, v122, v131, 0xbec09330
	v_fmaak_f32 v122, v122, v131, 0x3e0375d0
	v_fma_f32 v131, |v130|, v122, |v130|
	s_or_b64 exec, exec, s[16:17]
	v_lshlrev_b32_e32 v122, 16, v125
	v_mul_f32_e32 v122, 0x3fb8aa3b, v122
	v_exp_f32_e32 v132, v122
	v_lshlrev_b32_e32 v122, 16, v121
	v_and_b32_e32 v121, 0xffff0000, v121
	s_lshl_b64 s[0:1], s[2:3], 11
	v_fmac_f32_e32 v122, v124, v132
	v_and_b32_e32 v124, 0xffff0000, v125
	v_mul_f32_e32 v124, 0x3fb8aa3b, v124
	v_exp_f32_e32 v124, v124
	v_add_f32_e32 v119, v119, v122
	s_add_i32 s2, s14, 50
	s_ashr_i32 s3, s2, 31
	v_fmac_f32_e32 v121, v123, v124
	v_bfi_b32 v124, s78, v128, v127
	v_mul_f32_e32 v123, 0.5, v126
	v_add_f32_e32 v124, 1.0, v124
	v_mul_f32_e32 v123, v123, v124
	v_bfi_b32 v124, s78, v131, v130
	v_mul_f32_e32 v119, v119, v123
	v_mul_f32_e32 v123, 0.5, v129
	v_add_f32_e32 v124, 1.0, v124
	v_add_f32_e32 v120, v120, v121
	v_mul_f32_e32 v123, v123, v124
	v_lshl_add_u64 v[124:125], v[10:11], 0, s[0:1]
	v_mul_f32_e32 v120, v120, v123
	v_cvt_pk_bf16_f32 v119, v119, v120
	global_store_dword v[124:125], v119, off
	v_add_co_u32_e32 v124, vcc, 0x19000, v14
	s_lshl_b64 s[0:1], s[2:3], 12
	s_nop 0
	v_addc_co_u32_e32 v125, vcc, 0, v15, vcc
	s_nop 0
	v_lshl_add_u64 v[124:125], v[8:9], 0, s[0:1]
	s_waitcnt vmcnt(45)
	v_mov_b32_e32 v17, v166
	v_mov_b32_e32 v16, v167
	v_mov_b32_e32 v119, v168
	s_mov_b32 s0, 0x13000
	s_mov_b32 s1, 0
	v_lshl_add_u64 v[198:199], v[12:13], 0, s[0:1]
	v_lshl_add_u64 v[200:201], v[14:15], 0, s[0:1]
	s_add_i32 s0, s14, 38
	s_ashr_i32 s1, s0, 31
	s_lshl_b64 s[0:1], s[0:1], 12
	global_load_dword v166, v[198:199], off
	global_load_dword v167, v[200:201], off
	v_lshl_add_u64 v[202:203], v[8:9], 0, s[0:1]
	global_load_dword v168, v[202:203], off
	v_lshlrev_b32_e32 v123, 16, v119
	v_mul_f32_e32 v124, 0x3f3504f3, v123
	v_cmp_nlt_f32_e64 s[0:1], |v124|, 1.0
	s_and_saveexec_b64 s[16:17], s[0:1]
	s_xor_b64 s[16:17], exec, s[16:17]
	s_cbranch_execz .LBB0_716
	v_fma_f32 v120, |v124|, s29, v223
	v_fma_f32 v120, |v124|, v120, s20
	v_fma_f32 v120, |v124|, v120, s21
	v_fma_f32 v120, |v124|, v120, s28
	v_fma_f32 v120, |v124|, v120, s33
	v_fma_f32 v120, |v124|, v120, s30
	v_fma_f32 v120, |v124|, v120, |v124|
	v_mul_f32_e32 v125, 0xbfb8aa3b, v120
	v_fma_f32 v126, v120, s31, -v125
	v_rndne_f32_e32 v127, v125
	v_fmac_f32_e32 v126, 0xb2a5705f, v120
	v_sub_f32_e32 v125, v125, v127
	v_add_f32_e32 v125, v125, v126
	v_cvt_i32_f32_e32 v126, v127
	v_exp_f32_e32 v125, v125
	v_cmp_nlt_f32_e32 vcc, s96, v120
	v_ldexp_f32 v125, v125, v126
	s_nop 0
	v_cndmask_b32_e32 v125, 0, v125, vcc
	v_cmp_ngt_f32_e32 vcc, s97, v120
	s_nop 1
	v_cndmask_b32_e32 v120, v224, v125, vcc
	v_sub_f32_e32 v125, 1.0, v120

; DEVI unsigned cvtpk(float lo, float hi) { unsigned r; asm("v_cvt_pk_bf16_f32 %0, %1, %2" : "=v"(r) : "v"(lo), "v"(hi)); return r; }
; DEVI float bflo(unsigned u) { return __uint_as_float(u << 16); }
; DEVI float bfhi(unsigned u) { return __uint_as_float(u & 0xffff0000u); }
; DEVI float geluf_(float x) { return 0.5f * x * (1.f + erff(x * 0.70710678118654752f)); }
; DEVI void lru_p3_phase(const Params& p) {
;     ...
;       for (int t = 63; t >= 0; --t) {
;         const unsigned l = *(const unsigned*)(la + (size_t)t * 1024), bv = *(const unsigned*)(bb + (size_t)t * 1024);
;         h0 = __expf(bflo(l)) * h0 + bflo(bv); h1 = __expf(bfhi(l)) * h1 + bfhi(bv);
;         const unsigned g = *(const unsigned*)(GX + (size_t)(rbase + t) * 2048 + ch);
;         *(unsigned*)(YG + (size_t)(rbase + t) * 1024 + ch) = cvtpk((s0[t] + h0) * geluf_(bflo(g)), (s1[t] + h1) * geluf_(bfhi(g)));
.LBB0_720:
	s_andn2_saveexec_b64 s[16:17], s[16:17]
	v_mul_f32_e32 v119, v127, v127
	v_fmamk_f32 v120, v119, 0xba1345e1, v217
	v_fmaak_f32 v120, v119, v120, 0xbcdac9b8
	v_fmaak_f32 v120, v119, v120, 0x3de703be
	v_fmaak_f32 v120, v119, v120, 0xbec09330
	v_fmaak_f32 v119, v119, v120, 0x3e0375d0
	v_fma_f32 v128, |v127|, v119, |v127|
	s_or_b64 exec, exec, s[16:17]
	v_lshlrev_b32_e32 v119, 16, v17
	v_mul_f32_e32 v119, 0x3fb8aa3b, v119
	v_exp_f32_e32 v119, v119
	v_and_b32_e32 v17, 0xffff0000, v17
	v_mul_f32_e32 v17, 0x3fb8aa3b, v17
	v_exp_f32_e32 v17, v17
	v_lshlrev_b32_e32 v120, 16, v16
	v_fmac_f32_e32 v120, v122, v119
	v_and_b32_e32 v119, 0xffff0000, v16
	v_add_f32_e32 v16, v117, v120
	v_bfi_b32 v117, s78, v125, v124
	v_fmac_f32_e32 v119, v121, v17
	v_mul_f32_e32 v17, 0.5, v123
	v_add_f32_e32 v117, 1.0, v117
	v_mul_f32_e32 v17, v17, v117
	v_mul_f32_e32 v16, v16, v17
	v_add_f32_e32 v17, v118, v119
	v_bfi_b32 v118, s78, v128, v127
	v_mul_f32_e32 v117, 0.5, v126
	v_add_f32_e32 v118, 1.0, v118
	v_mul_f32_e32 v117, v117, v118
	v_mul_f32_e32 v17, v17, v117
	s_lshl_b64 s[0:1], s[2:3], 11
	v_cvt_pk_bf16_f32 v117, v16, v17
	v_lshl_add_u64 v[16:17], v[10:11], 0, s[0:1]
	global_store_dword v[16:17], v117, off
	v_add_co_u32_e32 v16, vcc, s34, v12
	s_add_i32 s2, s14, 49
	s_nop 0
	v_addc_co_u32_e32 v17, vcc, 0, v13, vcc
	v_add_co_u32_e32 v122, vcc, 0x18000, v14
	s_ashr_i32 s3, s2, 31
	s_nop 0
	v_addc_co_u32_e32 v123, vcc, 0, v15, vcc
	s_lshl_b64 s[0:1], s[2:3], 12
	v_lshl_add_u64 v[122:123], v[8:9], 0, s[0:1]
	s_waitcnt vmcnt(45)
	v_mov_b32_e32 v117, v164
	v_mov_b32_e32 v121, v163
	v_mov_b32_e32 v118, v165
	s_mov_b32 s0, 0x12800
	s_mov_b32 s1, 0
	v_lshl_add_u64 v[198:199], v[12:13], 0, s[0:1]
	v_lshl_add_u64 v[200:201], v[14:15], 0, s[0:1]
	s_add_i32 s0, s14, 37
	s_ashr_i32 s1, s0, 31
	s_lshl_b64 s[0:1], s[0:1], 12
	global_load_dword v163, v[198:199], off
	global_load_dword v164, v[200:201], off
	v_lshl_add_u64 v[202:203], v[8:9], 0, s[0:1]
	global_load_dword v165, v[202:203], off
	v_lshlrev_b32_e32 v122, 16, v118
	v_mul_f32_e32 v123, 0x3f3504f3, v122
	v_cmp_nlt_f32_e64 s[0:1], |v123|, 1.0
	s_and_saveexec_b64 s[16:17], s[0:1]
	s_xor_b64 s[16:17], exec, s[16:17]
	s_cbranch_execz .LBB0_724
	v_fma_f32 v124, |v123|, s29, v223
	v_fma_f32 v124, |v123|, v124, s20
	v_fma_f32 v124, |v123|, v124, s21
	v_fma_f32 v124, |v123|, v124, s28
	v_fma_f32 v124, |v123|, v124, s33
	v_fma_f32 v124, |v123|, v124, s30
	v_fma_f32 v124, |v123|, v124, |v123|
	v_mul_f32_e32 v125, 0xbfb8aa3b, v124
	v_fma_f32 v126, v124, s31, -v125
	v_rndne_f32_e32 v127, v125
	v_fmac_f32_e32 v126, 0xb2a5705f, v124
	v_sub_f32_e32 v125, v125, v127
	v_add_f32_e32 v125, v125, v126
	v_cvt_i32_f32_e32 v126, v127
	v_exp_f32_e32 v125, v125
	v_cmp_nlt_f32_e32 vcc, s96, v124
	v_ldexp_f32 v125, v125, v126
	s_nop 0
	v_cndmask_b32_e32 v125, 0, v125, vcc
	v_cmp_ngt_f32_e32 vcc, s97, v124
	s_nop 1
	v_cndmask_b32_e32 v124, v224, v125, vcc
	v_sub_f32_e32 v124, 1.0, v124

; DEVI unsigned cvtpk(float lo, float hi) { unsigned r; asm("v_cvt_pk_bf16_f32 %0, %1, %2" : "=v"(r) : "v"(lo), "v"(hi)); return r; }
; DEVI float bflo(unsigned u) { return __uint_as_float(u << 16); }
; DEVI float bfhi(unsigned u) { return __uint_as_float(u & 0xffff0000u); }
; DEVI float geluf_(float x) { return 0.5f * x * (1.f + erff(x * 0.70710678118654752f)); }
; DEVI void lru_p3_phase(const Params& p) {
;     ...
;       for (int t = 63; t >= 0; --t) {
;         const unsigned l = *(const unsigned*)(la + (size_t)t * 1024), bv = *(const unsigned*)(bb + (size_t)t * 1024);
;         h0 = __expf(bflo(l)) * h0 + bflo(bv); h1 = __expf(bfhi(l)) * h1 + bfhi(bv);
;         const unsigned g = *(const unsigned*)(GX + (size_t)(rbase + t) * 2048 + ch);
;         *(unsigned*)(YG + (size_t)(rbase + t) * 1024 + ch) = cvtpk((s0[t] + h0) * geluf_(bflo(g)), (s1[t] + h1) * geluf_(bfhi(g)));
.LBB0_728:
	s_andn2_saveexec_b64 s[16:17], s[16:17]
	v_mul_f32_e32 v118, v126, v126
	v_fmamk_f32 v127, v118, 0xba1345e1, v217
	v_fmaak_f32 v127, v118, v127, 0xbcdac9b8
	v_fmaak_f32 v127, v118, v127, 0x3de703be
	v_fmaak_f32 v127, v118, v127, 0xbec09330
	v_fmaak_f32 v118, v118, v127, 0x3e0375d0
	v_fma_f32 v127, |v126|, v118, |v126|
	s_or_b64 exec, exec, s[16:17]
	v_lshlrev_b32_e32 v118, 16, v121
	v_mul_f32_e32 v118, 0x3fb8aa3b, v118
	v_exp_f32_e32 v128, v118
	v_lshlrev_b32_e32 v118, 16, v117
	v_and_b32_e32 v117, 0xffff0000, v117
	s_lshl_b64 s[0:1], s[2:3], 11
	v_fmac_f32_e32 v118, v120, v128
	v_and_b32_e32 v120, 0xffff0000, v121
	v_mul_f32_e32 v120, 0x3fb8aa3b, v120
	v_exp_f32_e32 v120, v120
	v_add_f32_e32 v115, v115, v118
	s_add_i32 s2, s14, 48
	s_ashr_i32 s3, s2, 31
	v_fmac_f32_e32 v117, v119, v120
	v_bfi_b32 v120, s78, v124, v123
	v_mul_f32_e32 v119, 0.5, v122
	v_add_f32_e32 v120, 1.0, v120
	v_mul_f32_e32 v119, v119, v120
	v_bfi_b32 v120, s78, v127, v126
	v_mul_f32_e32 v115, v115, v119
	v_mul_f32_e32 v119, 0.5, v125
	v_add_f32_e32 v120, 1.0, v120
	v_add_f32_e32 v116, v116, v117
	v_mul_f32_e32 v119, v119, v120
	v_lshl_add_u64 v[120:121], v[10:11], 0, s[0:1]
	v_mul_f32_e32 v116, v116, v119
	v_cvt_pk_bf16_f32 v115, v115, v116
	global_store_dword v[120:121], v115, off
	v_add_co_u32_e32 v120, vcc, 0x18000, v14
	s_lshl_b64 s[0:1], s[2:3], 12
	s_nop 0
	v_addc_co_u32_e32 v121, vcc, 0, v15, vcc
	s_nop 0
	v_lshl_add_u64 v[120:121], v[8:9], 0, s[0:1]
	s_waitcnt vmcnt(45)
	v_mov_b32_e32 v17, v160
	v_mov_b32_e32 v16, v161
	v_mov_b32_e32 v115, v162
	s_mov_b32 s0, 0x12000
	s_mov_b32 s1, 0
	v_lshl_add_u64 v[198:199], v[12:13], 0, s[0:1]
	v_lshl_add_u64 v[200:201], v[14:15], 0, s[0:1]
	s_add_i32 s0, s14, 36
	s_ashr_i32 s1, s0, 31
	s_lshl_b64 s[0:1], s[0:1], 12
	global_load_dword v160, v[198:199], off
	global_load_dword v161, v[200:201], off
	v_lshl_add_u64 v[202:203], v[8:9], 0, s[0:1]
	global_load_dword v162, v[202:203], off
	v_lshlrev_b32_e32 v119, 16, v115
	v_mul_f32_e32 v120, 0x3f3504f3, v119
	v_cmp_nlt_f32_e64 s[0:1], |v120|, 1.0
	s_and_saveexec_b64 s[16:17], s[0:1]
	s_xor_b64 s[16:17], exec, s[16:17]
	s_cbranch_execz .LBB0_732
	v_fma_f32 v116, |v120|, s29, v223
	v_fma_f32 v116, |v120|, v116, s20
	v_fma_f32 v116, |v120|, v116, s21
	v_fma_f32 v116, |v120|, v116, s28
	v_fma_f32 v116, |v120|, v116, s33
	v_fma_f32 v116, |v120|, v116, s30
	v_fma_f32 v116, |v120|, v116, |v120|
	v_mul_f32_e32 v121, 0xbfb8aa3b, v116
	v_fma_f32 v122, v116, s31, -v121
	v_rndne_f32_e32 v123, v121
	v_fmac_f32_e32 v122, 0xb2a5705f, v116
	v_sub_f32_e32 v121, v121, v123
	v_add_f32_e32 v121, v121, v122
	v_cvt_i32_f32_e32 v122, v123
	v_exp_f32_e32 v121, v121
	v_cmp_nlt_f32_e32 vcc, s96, v116
	v_ldexp_f32 v121, v121, v122
	s_nop 0
	v_cndmask_b32_e32 v121, 0, v121, vcc
	v_cmp_ngt_f32_e32 vcc, s97, v116
	s_nop 1
	v_cndmask_b32_e32 v116, v224, v121, vcc
	v_sub_f32_e32 v121, 1.0, v116

; DEVI unsigned cvtpk(float lo, float hi) { unsigned r; asm("v_cvt_pk_bf16_f32 %0, %1, %2" : "=v"(r) : "v"(lo), "v"(hi)); return r; }
; DEVI float bflo(unsigned u) { return __uint_as_float(u << 16); }
; DEVI float bfhi(unsigned u) { return __uint_as_float(u & 0xffff0000u); }
; DEVI float geluf_(float x) { return 0.5f * x * (1.f + erff(x * 0.70710678118654752f)); }
; DEVI void lru_p3_phase(const Params& p) {
;     ...
;       for (int t = 63; t >= 0; --t) {
;         const unsigned l = *(const unsigned*)(la + (size_t)t * 1024), bv = *(const unsigned*)(bb + (size_t)t * 1024);
;         h0 = __expf(bflo(l)) * h0 + bflo(bv); h1 = __expf(bfhi(l)) * h1 + bfhi(bv);
;         const unsigned g = *(const unsigned*)(GX + (size_t)(rbase + t) * 2048 + ch);
;         *(unsigned*)(YG + (size_t)(rbase + t) * 1024 + ch) = cvtpk((s0[t] + h0) * geluf_(bflo(g)), (s1[t] + h1) * geluf_(bfhi(g)));
.LBB0_736:
	s_andn2_saveexec_b64 s[16:17], s[16:17]
	v_mul_f32_e32 v115, v123, v123
	v_fmamk_f32 v116, v115, 0xba1345e1, v217
	v_fmaak_f32 v116, v115, v116, 0xbcdac9b8
	v_fmaak_f32 v116, v115, v116, 0x3de703be
	v_fmaak_f32 v116, v115, v116, 0xbec09330
	v_fmaak_f32 v115, v115, v116, 0x3e0375d0
	v_fma_f32 v124, |v123|, v115, |v123|
	s_or_b64 exec, exec, s[16:17]
	v_lshlrev_b32_e32 v115, 16, v17
	v_mul_f32_e32 v115, 0x3fb8aa3b, v115
	v_exp_f32_e32 v115, v115
	v_and_b32_e32 v17, 0xffff0000, v17
	v_mul_f32_e32 v17, 0x3fb8aa3b, v17
	v_exp_f32_e32 v17, v17
	v_lshlrev_b32_e32 v116, 16, v16
	v_fmac_f32_e32 v116, v118, v115
	v_and_b32_e32 v115, 0xffff0000, v16
	v_add_f32_e32 v16, v113, v116
	v_bfi_b32 v113, s78, v121, v120
	v_fmac_f32_e32 v115, v117, v17
	v_mul_f32_e32 v17, 0.5, v119
	v_add_f32_e32 v113, 1.0, v113
	v_mul_f32_e32 v17, v17, v113
	v_mul_f32_e32 v16, v16, v17
	v_add_f32_e32 v17, v114, v115
	v_bfi_b32 v114, s78, v124, v123
	v_mul_f32_e32 v113, 0.5, v122
	v_add_f32_e32 v114, 1.0, v114
	v_mul_f32_e32 v113, v113, v114
	v_mul_f32_e32 v17, v17, v113
	s_lshl_b64 s[0:1], s[2:3], 11
	v_cvt_pk_bf16_f32 v113, v16, v17
	v_lshl_add_u64 v[16:17], v[10:11], 0, s[0:1]
	global_store_dword v[16:17], v113, off
	v_add_co_u32_e32 v16, vcc, s74, v12
	s_add_i32 s2, s14, 47
	s_nop 0
	v_addc_co_u32_e32 v17, vcc, 0, v13, vcc
	v_add_co_u32_e32 v118, vcc, 0x17000, v14
	s_ashr_i32 s3, s2, 31
	s_nop 0
	v_addc_co_u32_e32 v119, vcc, 0, v15, vcc
	s_lshl_b64 s[0:1], s[2:3], 12
	v_lshl_add_u64 v[118:119], v[8:9], 0, s[0:1]
	s_waitcnt vmcnt(45)
	v_mov_b32_e32 v113, v196
	v_mov_b32_e32 v117, v195
	v_mov_b32_e32 v114, v197
	s_mov_b32 s0, 0x11800
	s_mov_b32 s1, 0
	v_lshl_add_u64 v[198:199], v[12:13], 0, s[0:1]
	v_lshl_add_u64 v[200:201], v[14:15], 0, s[0:1]
	s_add_i32 s0, s14, 35
	s_ashr_i32 s1, s0, 31
	s_lshl_b64 s[0:1], s[0:1], 12
	global_load_dword v195, v[198:199], off
	global_load_dword v196, v[200:201], off
	v_lshl_add_u64 v[202:203], v[8:9], 0, s[0:1]
	global_load_dword v197, v[202:203], off
	v_lshlrev_b32_e32 v118, 16, v114
	v_mul_f32_e32 v119, 0x3f3504f3, v118
	v_cmp_nlt_f32_e64 s[0:1], |v119|, 1.0
	s_and_saveexec_b64 s[16:17], s[0:1]
	s_xor_b64 s[16:17], exec, s[16:17]
	s_cbranch_execz .LBB0_740
	v_fma_f32 v120, |v119|, s29, v223
	v_fma_f32 v120, |v119|, v120, s20
	v_fma_f32 v120, |v119|, v120, s21
	v_fma_f32 v120, |v119|, v120, s28
	v_fma_f32 v120, |v119|, v120, s33
	v_fma_f32 v120, |v119|, v120, s30
	v_fma_f32 v120, |v119|, v120, |v119|
	v_mul_f32_e32 v121, 0xbfb8aa3b, v120
	v_fma_f32 v122, v120, s31, -v121
	v_rndne_f32_e32 v123, v121
	v_fmac_f32_e32 v122, 0xb2a5705f, v120
	v_sub_f32_e32 v121, v121, v123
	v_add_f32_e32 v121, v121, v122
	v_cvt_i32_f32_e32 v122, v123
	v_exp_f32_e32 v121, v121
	v_cmp_nlt_f32_e32 vcc, s96, v120
	v_ldexp_f32 v121, v121, v122
	s_nop 0
	v_cndmask_b32_e32 v121, 0, v121, vcc
	v_cmp_ngt_f32_e32 vcc, s97, v120
	s_nop 1
	v_cndmask_b32_e32 v120, v224, v121, vcc
	v_sub_f32_e32 v120, 1.0, v120

; DEVI unsigned cvtpk(float lo, float hi) { unsigned r; asm("v_cvt_pk_bf16_f32 %0, %1, %2" : "=v"(r) : "v"(lo), "v"(hi)); return r; }
; DEVI float bflo(unsigned u) { return __uint_as_float(u << 16); }
; DEVI float bfhi(unsigned u) { return __uint_as_float(u & 0xffff0000u); }
; DEVI float geluf_(float x) { return 0.5f * x * (1.f + erff(x * 0.70710678118654752f)); }
; DEVI void lru_p3_phase(const Params& p) {
;     ...
;       for (int t = 63; t >= 0; --t) {
;         const unsigned l = *(const unsigned*)(la + (size_t)t * 1024), bv = *(const unsigned*)(bb + (size_t)t * 1024);
;         h0 = __expf(bflo(l)) * h0 + bflo(bv); h1 = __expf(bfhi(l)) * h1 + bfhi(bv);
;         const unsigned g = *(const unsigned*)(GX + (size_t)(rbase + t) * 2048 + ch);
;         *(unsigned*)(YG + (size_t)(rbase + t) * 1024 + ch) = cvtpk((s0[t] + h0) * geluf_(bflo(g)), (s1[t] + h1) * geluf_(bfhi(g)));
;       }
.LBB0_744:
	s_andn2_saveexec_b64 s[16:17], s[16:17]
	v_mul_f32_e32 v114, v122, v122
	v_fmamk_f32 v123, v114, 0xba1345e1, v217
	v_fmaak_f32 v123, v114, v123, 0xbcdac9b8
	v_fmaak_f32 v123, v114, v123, 0x3de703be
	v_fmaak_f32 v123, v114, v123, 0xbec09330
	v_fmaak_f32 v114, v114, v123, 0x3e0375d0
	v_fma_f32 v123, |v122|, v114, |v122|
	s_or_b64 exec, exec, s[16:17]
	v_lshlrev_b32_e32 v114, 16, v117
	v_mul_f32_e32 v114, 0x3fb8aa3b, v114
	v_exp_f32_e32 v124, v114
	v_lshlrev_b32_e32 v114, 16, v113
	v_and_b32_e32 v113, 0xffff0000, v113
	s_lshl_b64 s[0:1], s[2:3], 11
	v_fmac_f32_e32 v114, v116, v124
	v_and_b32_e32 v116, 0xffff0000, v117
	v_mul_f32_e32 v116, 0x3fb8aa3b, v116
	v_exp_f32_e32 v116, v116
	v_add_f32_e32 v111, v111, v114
	s_add_i32 s2, s14, 46
	s_ashr_i32 s3, s2, 31
	v_fmac_f32_e32 v113, v115, v116
	v_bfi_b32 v116, s78, v120, v119
	v_mul_f32_e32 v115, 0.5, v118
	v_add_f32_e32 v116, 1.0, v116
	v_mul_f32_e32 v115, v115, v116
	v_bfi_b32 v116, s78, v123, v122
	v_mul_f32_e32 v111, v111, v115
	v_mul_f32_e32 v115, 0.5, v121
	v_add_f32_e32 v116, 1.0, v116
	v_add_f32_e32 v112, v112, v113
	v_mul_f32_e32 v115, v115, v116
	v_lshl_add_u64 v[116:117], v[10:11], 0, s[0:1]
	v_mul_f32_e32 v112, v112, v115
	v_cvt_pk_bf16_f32 v111, v111, v112
	global_store_dword v[116:117], v111, off
	v_add_co_u32_e32 v116, vcc, 0x17000, v14
	s_lshl_b64 s[0:1], s[2:3], 12
	s_nop 0
	v_addc_co_u32_e32 v117, vcc, 0, v15, vcc
	s_nop 0
	v_lshl_add_u64 v[116:117], v[8:9], 0, s[0:1]
	s_waitcnt vmcnt(45)
	v_mov_b32_e32 v17, v192
	v_mov_b32_e32 v16, v193
	v_mov_b32_e32 v111, v194
	s_mov_b32 s0, 0x11000
	s_mov_b32 s1, 0
	v_lshl_add_u64 v[198:199], v[12:13], 0, s[0:1]
	v_lshl_add_u64 v[200:201], v[14:15], 0, s[0:1]
	s_add_i32 s0, s14, 34
	s_ashr_i32 s1, s0, 31
	s_lshl_b64 s[0:1], s[0:1], 12
	global_load_dword v192, v[198:199], off
	global_load_dword v193, v[200:201], off
	v_lshl_add_u64 v[202:203], v[8:9], 0, s[0:1]
	global_load_dword v194, v[202:203], off
	v_lshlrev_b32_e32 v115, 16, v111
	v_mul_f32_e32 v116, 0x3f3504f3, v115
	v_cmp_nlt_f32_e64 s[0:1], |v116|, 1.0
	s_and_saveexec_b64 s[16:17], s[0:1]
	s_xor_b64 s[16:17], exec, s[16:17]
	s_cbranch_execz .LBB0_748
	v_fma_f32 v112, |v116|, s29, v223
	v_fma_f32 v112, |v116|, v112, s20
	v_fma_f32 v112, |v116|, v112, s21
	v_fma_f32 v112, |v116|, v112, s28
	v_fma_f32 v112, |v116|, v112, s33
	v_fma_f32 v112, |v116|, v112, s30
	v_fma_f32 v112, |v116|, v112, |v116|
	v_mul_f32_e32 v117, 0xbfb8aa3b, v112
	v_fma_f32 v118, v112, s31, -v117
	v_rndne_f32_e32 v119, v117
	v_fmac_f32_e32 v118, 0xb2a5705f, v112
	v_sub_f32_e32 v117, v117, v119
	v_add_f32_e32 v117, v117, v118
	v_cvt_i32_f32_e32 v118, v119
	v_exp_f32_e32 v117, v117
	v_cmp_nlt_f32_e32 vcc, s96, v112
	v_ldexp_f32 v117, v117, v118
	s_nop 0
	v_cndmask_b32_e32 v117, 0, v117, vcc
	v_cmp_ngt_f32_e32 vcc, s97, v112
	s_nop 1
	v_cndmask_b32_e32 v112, v224, v117, vcc
	v_sub_f32_e32 v117, 1.0, v112

; DEVI unsigned cvtpk(float lo, float hi) { unsigned r; asm("v_cvt_pk_bf16_f32 %0, %1, %2" : "=v"(r) : "v"(lo), "v"(hi)); return r; }
; DEVI float bflo(unsigned u) { return __uint_as_float(u << 16); }
; DEVI float bfhi(unsigned u) { return __uint_as_float(u & 0xffff0000u); }
; DEVI float geluf_(float x) { return 0.5f * x * (1.f + erff(x * 0.70710678118654752f)); }
; DEVI void lru_p3_phase(const Params& p) {
;     ...
;       for (int t = 63; t >= 0; --t) {
;         const unsigned l = *(const unsigned*)(la + (size_t)t * 1024), bv = *(const unsigned*)(bb + (size_t)t * 1024);
;         h0 = __expf(bflo(l)) * h0 + bflo(bv); h1 = __expf(bfhi(l)) * h1 + bfhi(bv);
;         const unsigned g = *(const unsigned*)(GX + (size_t)(rbase + t) * 2048 + ch);
;         *(unsigned*)(YG + (size_t)(rbase + t) * 1024 + ch) = cvtpk((s0[t] + h0) * geluf_(bflo(g)), (s1[t] + h1) * geluf_(bfhi(g)));
;       }
.LBB0_752:
	s_andn2_saveexec_b64 s[16:17], s[16:17]
	v_mul_f32_e32 v111, v119, v119
	v_fmamk_f32 v112, v111, 0xba1345e1, v217
	v_fmaak_f32 v112, v111, v112, 0xbcdac9b8
	v_fmaak_f32 v112, v111, v112, 0x3de703be
	v_fmaak_f32 v112, v111, v112, 0xbec09330
	v_fmaak_f32 v111, v111, v112, 0x3e0375d0
	v_fma_f32 v120, |v119|, v111, |v119|
	s_or_b64 exec, exec, s[16:17]
	v_lshlrev_b32_e32 v111, 16, v17
	v_mul_f32_e32 v111, 0x3fb8aa3b, v111
	v_exp_f32_e32 v111, v111
	v_and_b32_e32 v17, 0xffff0000, v17
	v_mul_f32_e32 v17, 0x3fb8aa3b, v17
	v_exp_f32_e32 v17, v17
	v_lshlrev_b32_e32 v112, 16, v16
	v_fmac_f32_e32 v112, v114, v111
	v_and_b32_e32 v111, 0xffff0000, v16
	v_add_f32_e32 v16, v109, v112
	v_bfi_b32 v109, s78, v117, v116
	v_fmac_f32_e32 v111, v113, v17
	v_mul_f32_e32 v17, 0.5, v115
	v_add_f32_e32 v109, 1.0, v109
	v_mul_f32_e32 v17, v17, v109
	v_mul_f32_e32 v16, v16, v17
	v_add_f32_e32 v17, v110, v111
	v_bfi_b32 v110, s78, v120, v119
	v_mul_f32_e32 v109, 0.5, v118
	v_add_f32_e32 v110, 1.0, v110
	v_mul_f32_e32 v109, v109, v110
	v_mul_f32_e32 v17, v17, v109
	s_lshl_b64 s[0:1], s[2:3], 11
	v_cvt_pk_bf16_f32 v109, v16, v17
	v_lshl_add_u64 v[16:17], v[10:11], 0, s[0:1]
	global_store_dword v[16:17], v109, off
	v_add_co_u32_e32 v16, vcc, s19, v12
	s_add_i32 s2, s14, 45
	s_nop 0
	v_addc_co_u32_e32 v17, vcc, 0, v13, vcc
	v_add_co_u32_e32 v114, vcc, 0x16000, v14
	s_ashr_i32 s3, s2, 31
	s_nop 0
	v_addc_co_u32_e32 v115, vcc, 0, v15, vcc
	s_lshl_b64 s[0:1], s[2:3], 12
	v_lshl_add_u64 v[114:115], v[8:9], 0, s[0:1]
	s_waitcnt vmcnt(45)
	v_mov_b32_e32 v109, v190
	v_mov_b32_e32 v113, v189
	v_mov_b32_e32 v110, v191
	s_mov_b32 s0, 0x10800
	s_mov_b32 s1, 0
	v_lshl_add_u64 v[198:199], v[12:13], 0, s[0:1]
	v_lshl_add_u64 v[200:201], v[14:15], 0, s[0:1]
	s_add_i32 s0, s14, 33
	s_ashr_i32 s1, s0, 31
	s_lshl_b64 s[0:1], s[0:1], 12
	global_load_dword v189, v[198:199], off
	global_load_dword v190, v[200:201], off
	v_lshl_add_u64 v[202:203], v[8:9], 0, s[0:1]
	global_load_dword v191, v[202:203], off
	v_lshlrev_b32_e32 v114, 16, v110
	v_mul_f32_e32 v115, 0x3f3504f3, v114
	v_cmp_nlt_f32_e64 s[0:1], |v115|, 1.0
	s_and_saveexec_b64 s[16:17], s[0:1]
	s_xor_b64 s[16:17], exec, s[16:17]
	s_cbranch_execz .LBB0_756
	v_fma_f32 v116, |v115|, s29, v223
	v_fma_f32 v116, |v115|, v116, s20
	v_fma_f32 v116, |v115|, v116, s21
	v_fma_f32 v116, |v115|, v116, s28
	v_fma_f32 v116, |v115|, v116, s33
	v_fma_f32 v116, |v115|, v116, s30
	v_fma_f32 v116, |v115|, v116, |v115|
	v_mul_f32_e32 v117, 0xbfb8aa3b, v116
	v_fma_f32 v118, v116, s31, -v117
	v_rndne_f32_e32 v119, v117
	v_fmac_f32_e32 v118, 0xb2a5705f, v116
	v_sub_f32_e32 v117, v117, v119
	v_add_f32_e32 v117, v117, v118
	v_cvt_i32_f32_e32 v118, v119
	v_exp_f32_e32 v117, v117
	v_cmp_nlt_f32_e32 vcc, s96, v116
	v_ldexp_f32 v117, v117, v118
	s_nop 0
	v_cndmask_b32_e32 v117, 0, v117, vcc
	v_cmp_ngt_f32_e32 vcc, s97, v116
	s_nop 1
	v_cndmask_b32_e32 v116, v224, v117, vcc
	v_sub_f32_e32 v116, 1.0, v116

; DEVI unsigned cvtpk(float lo, float hi) { unsigned r; asm("v_cvt_pk_bf16_f32 %0, %1, %2" : "=v"(r) : "v"(lo), "v"(hi)); return r; }
; DEVI float bflo(unsigned u) { return __uint_as_float(u << 16); }
; DEVI float bfhi(unsigned u) { return __uint_as_float(u & 0xffff0000u); }
; DEVI float geluf_(float x) { return 0.5f * x * (1.f + erff(x * 0.70710678118654752f)); }
; DEVI void lru_p3_phase(const Params& p) {
;     ...
;       for (int t = 63; t >= 0; --t) {
;         const unsigned l = *(const unsigned*)(la + (size_t)t * 1024), bv = *(const unsigned*)(bb + (size_t)t * 1024);
;         h0 = __expf(bflo(l)) * h0 + bflo(bv); h1 = __expf(bfhi(l)) * h1 + bfhi(bv);
;         const unsigned g = *(const unsigned*)(GX + (size_t)(rbase + t) * 2048 + ch);
;         *(unsigned*)(YG + (size_t)(rbase + t) * 1024 + ch) = cvtpk((s0[t] + h0) * geluf_(bflo(g)), (s1[t] + h1) * geluf_(bfhi(g)));
;       }
.LBB0_760:
	s_andn2_saveexec_b64 s[16:17], s[16:17]
	v_mul_f32_e32 v110, v118, v118
	v_fmamk_f32 v119, v110, 0xba1345e1, v217
	v_fmaak_f32 v119, v110, v119, 0xbcdac9b8
	v_fmaak_f32 v119, v110, v119, 0x3de703be
	v_fmaak_f32 v119, v110, v119, 0xbec09330
	v_fmaak_f32 v110, v110, v119, 0x3e0375d0
	v_fma_f32 v119, |v118|, v110, |v118|
	s_or_b64 exec, exec, s[16:17]
	v_lshlrev_b32_e32 v110, 16, v113
	v_mul_f32_e32 v110, 0x3fb8aa3b, v110
	v_exp_f32_e32 v120, v110
	v_lshlrev_b32_e32 v110, 16, v109
	v_and_b32_e32 v109, 0xffff0000, v109
	s_lshl_b64 s[0:1], s[2:3], 11
	v_fmac_f32_e32 v110, v112, v120
	v_and_b32_e32 v112, 0xffff0000, v113
	v_mul_f32_e32 v112, 0x3fb8aa3b, v112
	v_exp_f32_e32 v112, v112
	v_add_f32_e32 v107, v107, v110
	s_add_i32 s2, s14, 44
	s_ashr_i32 s3, s2, 31
	v_fmac_f32_e32 v109, v111, v112
	v_bfi_b32 v112, s78, v116, v115
	v_mul_f32_e32 v111, 0.5, v114
	v_add_f32_e32 v112, 1.0, v112
	v_mul_f32_e32 v111, v111, v112
	v_bfi_b32 v112, s78, v119, v118
	v_mul_f32_e32 v107, v107, v111
	v_mul_f32_e32 v111, 0.5, v117
	v_add_f32_e32 v112, 1.0, v112
	v_add_f32_e32 v108, v108, v109
	v_mul_f32_e32 v111, v111, v112
	v_lshl_add_u64 v[112:113], v[10:11], 0, s[0:1]
	v_mul_f32_e32 v108, v108, v111
	v_cvt_pk_bf16_f32 v107, v107, v108
	global_store_dword v[112:113], v107, off
	v_add_co_u32_e32 v112, vcc, 0x16000, v14
	s_lshl_b64 s[0:1], s[2:3], 12
	s_nop 0
	v_addc_co_u32_e32 v113, vcc, 0, v15, vcc
	s_nop 0
	v_lshl_add_u64 v[112:113], v[8:9], 0, s[0:1]
	s_waitcnt vmcnt(45)
	v_mov_b32_e32 v17, v186
	v_mov_b32_e32 v16, v187
	v_mov_b32_e32 v107, v188
	s_mov_b32 s0, 0x10000
	s_mov_b32 s1, 0
	v_lshl_add_u64 v[198:199], v[12:13], 0, s[0:1]
	v_lshl_add_u64 v[200:201], v[14:15], 0, s[0:1]
	s_add_i32 s0, s14, 32
	s_ashr_i32 s1, s0, 31
	s_lshl_b64 s[0:1], s[0:1], 12
	global_load_dword v186, v[198:199], off
	global_load_dword v187, v[200:201], off
	v_lshl_add_u64 v[202:203], v[8:9], 0, s[0:1]
	global_load_dword v188, v[202:203], off
	v_lshlrev_b32_e32 v111, 16, v107
	v_mul_f32_e32 v112, 0x3f3504f3, v111
	v_cmp_nlt_f32_e64 s[0:1], |v112|, 1.0
	s_and_saveexec_b64 s[16:17], s[0:1]
	s_xor_b64 s[16:17], exec, s[16:17]
	s_cbranch_execz .LBB0_764
	v_fma_f32 v108, |v112|, s29, v223
	v_fma_f32 v108, |v112|, v108, s20
	v_fma_f32 v108, |v112|, v108, s21
	v_fma_f32 v108, |v112|, v108, s28
	v_fma_f32 v108, |v112|, v108, s33
	v_fma_f32 v108, |v112|, v108, s30
	v_fma_f32 v108, |v112|, v108, |v112|
	v_mul_f32_e32 v113, 0xbfb8aa3b, v108
	v_fma_f32 v114, v108, s31, -v113
	v_rndne_f32_e32 v115, v113
	v_fmac_f32_e32 v114, 0xb2a5705f, v108
	v_sub_f32_e32 v113, v113, v115
	v_add_f32_e32 v113, v113, v114
	v_cvt_i32_f32_e32 v114, v115
	v_exp_f32_e32 v113, v113
	v_cmp_nlt_f32_e32 vcc, s96, v108
	v_ldexp_f32 v113, v113, v114
	s_nop 0
	v_cndmask_b32_e32 v113, 0, v113, vcc
	v_cmp_ngt_f32_e32 vcc, s97, v108
	s_nop 1
	v_cndmask_b32_e32 v108, v224, v113, vcc
	v_sub_f32_e32 v113, 1.0, v108

; DEVI unsigned cvtpk(float lo, float hi) { unsigned r; asm("v_cvt_pk_bf16_f32 %0, %1, %2" : "=v"(r) : "v"(lo), "v"(hi)); return r; }
; DEVI float bflo(unsigned u) { return __uint_as_float(u << 16); }
; DEVI float bfhi(unsigned u) { return __uint_as_float(u & 0xffff0000u); }
; DEVI float geluf_(float x) { return 0.5f * x * (1.f + erff(x * 0.70710678118654752f)); }
; DEVI void lru_p3_phase(const Params& p) {
;     ...
;       for (int t = 63; t >= 0; --t) {
;         const unsigned l = *(const unsigned*)(la + (size_t)t * 1024), bv = *(const unsigned*)(bb + (size_t)t * 1024);
;         h0 = __expf(bflo(l)) * h0 + bflo(bv); h1 = __expf(bfhi(l)) * h1 + bfhi(bv);
;         const unsigned g = *(const unsigned*)(GX + (size_t)(rbase + t) * 2048 + ch);
;         *(unsigned*)(YG + (size_t)(rbase + t) * 1024 + ch) = cvtpk((s0[t] + h0) * geluf_(bflo(g)), (s1[t] + h1) * geluf_(bfhi(g)));
;       }
.LBB0_768:
	s_andn2_saveexec_b64 s[16:17], s[16:17]
	v_mul_f32_e32 v107, v115, v115
	v_fmamk_f32 v108, v107, 0xba1345e1, v217
	v_fmaak_f32 v108, v107, v108, 0xbcdac9b8
	v_fmaak_f32 v108, v107, v108, 0x3de703be
	v_fmaak_f32 v108, v107, v108, 0xbec09330
	v_fmaak_f32 v107, v107, v108, 0x3e0375d0
	v_fma_f32 v116, |v115|, v107, |v115|
	s_or_b64 exec, exec, s[16:17]
	v_lshlrev_b32_e32 v107, 16, v17
	v_mul_f32_e32 v107, 0x3fb8aa3b, v107
	v_exp_f32_e32 v107, v107
	v_and_b32_e32 v17, 0xffff0000, v17
	v_mul_f32_e32 v17, 0x3fb8aa3b, v17
	v_exp_f32_e32 v17, v17
	v_lshlrev_b32_e32 v108, 16, v16
	v_fmac_f32_e32 v108, v110, v107
	v_and_b32_e32 v107, 0xffff0000, v16
	v_add_f32_e32 v16, v105, v108
	v_bfi_b32 v105, s78, v113, v112
	v_fmac_f32_e32 v107, v109, v17
	v_mul_f32_e32 v17, 0.5, v111
	v_add_f32_e32 v105, 1.0, v105
	v_mul_f32_e32 v17, v17, v105
	v_mul_f32_e32 v16, v16, v17
	v_add_f32_e32 v17, v106, v107
	v_bfi_b32 v106, s78, v116, v115
	v_mul_f32_e32 v105, 0.5, v114
	v_add_f32_e32 v106, 1.0, v106
	v_mul_f32_e32 v105, v105, v106
	v_mul_f32_e32 v17, v17, v105
	s_lshl_b64 s[0:1], s[2:3], 11
	v_cvt_pk_bf16_f32 v105, v16, v17
	v_lshl_add_u64 v[16:17], v[10:11], 0, s[0:1]
	global_store_dword v[16:17], v105, off
	v_add_co_u32_e32 v16, vcc, s18, v12
	s_add_i32 s2, s14, 43
	s_nop 0
	v_addc_co_u32_e32 v17, vcc, 0, v13, vcc
	v_add_co_u32_e32 v110, vcc, 0x15000, v14
	s_ashr_i32 s3, s2, 31
	s_nop 0
	v_addc_co_u32_e32 v111, vcc, 0, v15, vcc
	s_lshl_b64 s[0:1], s[2:3], 12
	v_lshl_add_u64 v[110:111], v[8:9], 0, s[0:1]
	s_waitcnt vmcnt(45)
	v_mov_b32_e32 v105, v184
	v_mov_b32_e32 v109, v183
	v_mov_b32_e32 v106, v185
	s_mov_b32 s0, 0xf800
	s_mov_b32 s1, 0
	v_lshl_add_u64 v[198:199], v[12:13], 0, s[0:1]
	v_lshl_add_u64 v[200:201], v[14:15], 0, s[0:1]
	s_add_i32 s0, s14, 31
	s_ashr_i32 s1, s0, 31
	s_lshl_b64 s[0:1], s[0:1], 12
	global_load_dword v183, v[198:199], off
	global_load_dword v184, v[200:201], off
	v_lshl_add_u64 v[202:203], v[8:9], 0, s[0:1]
	global_load_dword v185, v[202:203], off
	v_lshlrev_b32_e32 v110, 16, v106
	v_mul_f32_e32 v111, 0x3f3504f3, v110
	v_cmp_nlt_f32_e64 s[0:1], |v111|, 1.0
	s_and_saveexec_b64 s[16:17], s[0:1]
	s_xor_b64 s[16:17], exec, s[16:17]
	s_cbranch_execz .LBB0_772
	v_fma_f32 v112, |v111|, s29, v223
	v_fma_f32 v112, |v111|, v112, s20
	v_fma_f32 v112, |v111|, v112, s21
	v_fma_f32 v112, |v111|, v112, s28
	v_fma_f32 v112, |v111|, v112, s33
	v_fma_f32 v112, |v111|, v112, s30
	v_fma_f32 v112, |v111|, v112, |v111|
	v_mul_f32_e32 v113, 0xbfb8aa3b, v112
	v_fma_f32 v114, v112, s31, -v113
	v_rndne_f32_e32 v115, v113
	v_fmac_f32_e32 v114, 0xb2a5705f, v112
	v_sub_f32_e32 v113, v113, v115
	v_add_f32_e32 v113, v113, v114
	v_cvt_i32_f32_e32 v114, v115
	v_exp_f32_e32 v113, v113
	v_cmp_nlt_f32_e32 vcc, s96, v112
	v_ldexp_f32 v113, v113, v114
	s_nop 0
	v_cndmask_b32_e32 v113, 0, v113, vcc
	v_cmp_ngt_f32_e32 vcc, s97, v112
	s_nop 1
	v_cndmask_b32_e32 v112, v224, v113, vcc
	v_sub_f32_e32 v112, 1.0, v112

; DEVI unsigned cvtpk(float lo, float hi) { unsigned r; asm("v_cvt_pk_bf16_f32 %0, %1, %2" : "=v"(r) : "v"(lo), "v"(hi)); return r; }
; DEVI float bflo(unsigned u) { return __uint_as_float(u << 16); }
; DEVI float bfhi(unsigned u) { return __uint_as_float(u & 0xffff0000u); }
; DEVI float geluf_(float x) { return 0.5f * x * (1.f + erff(x * 0.70710678118654752f)); }
; DEVI void lru_p3_phase(const Params& p) {
;     ...
;       for (int t = 63; t >= 0; --t) {
;         const unsigned l = *(const unsigned*)(la + (size_t)t * 1024), bv = *(const unsigned*)(bb + (size_t)t * 1024);
;         h0 = __expf(bflo(l)) * h0 + bflo(bv); h1 = __expf(bfhi(l)) * h1 + bfhi(bv);
;         const unsigned g = *(const unsigned*)(GX + (size_t)(rbase + t) * 2048 + ch);
;         *(unsigned*)(YG + (size_t)(rbase + t) * 1024 + ch) = cvtpk((s0[t] + h0) * geluf_(bflo(g)), (s1[t] + h1) * geluf_(bfhi(g)));
;       }
.LBB0_776:
	s_andn2_saveexec_b64 s[16:17], s[16:17]
	v_mul_f32_e32 v106, v114, v114
	v_fmamk_f32 v115, v106, 0xba1345e1, v217
	v_fmaak_f32 v115, v106, v115, 0xbcdac9b8
	v_fmaak_f32 v115, v106, v115, 0x3de703be
	v_fmaak_f32 v115, v106, v115, 0xbec09330
	v_fmaak_f32 v106, v106, v115, 0x3e0375d0
	v_fma_f32 v115, |v114|, v106, |v114|
	s_or_b64 exec, exec, s[16:17]
	v_lshlrev_b32_e32 v106, 16, v109
	v_mul_f32_e32 v106, 0x3fb8aa3b, v106
	v_exp_f32_e32 v116, v106
	v_lshlrev_b32_e32 v106, 16, v105
	v_and_b32_e32 v105, 0xffff0000, v105
	s_lshl_b64 s[0:1], s[2:3], 11
	v_fmac_f32_e32 v106, v108, v116
	v_and_b32_e32 v108, 0xffff0000, v109
	v_mul_f32_e32 v108, 0x3fb8aa3b, v108
	v_exp_f32_e32 v108, v108
	v_add_f32_e32 v103, v103, v106
	s_add_i32 s2, s14, 42
	s_ashr_i32 s3, s2, 31
	v_fmac_f32_e32 v105, v107, v108
	v_bfi_b32 v108, s78, v112, v111
	v_mul_f32_e32 v107, 0.5, v110
	v_add_f32_e32 v108, 1.0, v108
	v_mul_f32_e32 v107, v107, v108
	v_bfi_b32 v108, s78, v115, v114
	v_mul_f32_e32 v103, v103, v107
	v_mul_f32_e32 v107, 0.5, v113
	v_add_f32_e32 v108, 1.0, v108
	v_add_f32_e32 v104, v104, v105
	v_mul_f32_e32 v107, v107, v108
	v_lshl_add_u64 v[108:109], v[10:11], 0, s[0:1]
	v_mul_f32_e32 v104, v104, v107
	v_cvt_pk_bf16_f32 v103, v103, v104
	global_store_dword v[108:109], v103, off
	v_add_co_u32_e32 v108, vcc, 0x15000, v14
	s_lshl_b64 s[0:1], s[2:3], 12
	s_nop 0
	v_addc_co_u32_e32 v109, vcc, 0, v15, vcc
	s_nop 0
	v_lshl_add_u64 v[108:109], v[8:9], 0, s[0:1]
	s_waitcnt vmcnt(45)
	v_mov_b32_e32 v17, v180
	v_mov_b32_e32 v16, v181
	v_mov_b32_e32 v103, v182
	s_mov_b32 s0, 0xf000
	s_mov_b32 s1, 0
	v_lshl_add_u64 v[198:199], v[12:13], 0, s[0:1]
	v_lshl_add_u64 v[200:201], v[14:15], 0, s[0:1]
	s_add_i32 s0, s14, 30
	s_ashr_i32 s1, s0, 31
	s_lshl_b64 s[0:1], s[0:1], 12
	global_load_dword v180, v[198:199], off
	global_load_dword v181, v[200:201], off
	v_lshl_add_u64 v[202:203], v[8:9], 0, s[0:1]
	global_load_dword v182, v[202:203], off
	v_lshlrev_b32_e32 v107, 16, v103
	v_mul_f32_e32 v108, 0x3f3504f3, v107
	v_cmp_nlt_f32_e64 s[0:1], |v108|, 1.0
	s_and_saveexec_b64 s[16:17], s[0:1]
	s_xor_b64 s[16:17], exec, s[16:17]
	s_cbranch_execz .LBB0_780
	v_fma_f32 v104, |v108|, s29, v223
	v_fma_f32 v104, |v108|, v104, s20
	v_fma_f32 v104, |v108|, v104, s21
	v_fma_f32 v104, |v108|, v104, s28
	v_fma_f32 v104, |v108|, v104, s33
	v_fma_f32 v104, |v108|, v104, s30
	v_fma_f32 v104, |v108|, v104, |v108|
	v_mul_f32_e32 v109, 0xbfb8aa3b, v104
	v_fma_f32 v110, v104, s31, -v109
	v_rndne_f32_e32 v111, v109
	v_fmac_f32_e32 v110, 0xb2a5705f, v104
	v_sub_f32_e32 v109, v109, v111
	v_add_f32_e32 v109, v109, v110
	v_cvt_i32_f32_e32 v110, v111
	v_exp_f32_e32 v109, v109
	v_cmp_nlt_f32_e32 vcc, s96, v104
	v_ldexp_f32 v109, v109, v110
	s_nop 0
	v_cndmask_b32_e32 v109, 0, v109, vcc
	v_cmp_ngt_f32_e32 vcc, s97, v104
	s_nop 1
	v_cndmask_b32_e32 v104, v224, v109, vcc
	v_sub_f32_e32 v109, 1.0, v104

; DEVI unsigned cvtpk(float lo, float hi) { unsigned r; asm("v_cvt_pk_bf16_f32 %0, %1, %2" : "=v"(r) : "v"(lo), "v"(hi)); return r; }
; DEVI float bflo(unsigned u) { return __uint_as_float(u << 16); }
; DEVI float bfhi(unsigned u) { return __uint_as_float(u & 0xffff0000u); }
; DEVI float geluf_(float x) { return 0.5f * x * (1.f + erff(x * 0.70710678118654752f)); }
; DEVI void lru_p3_phase(const Params& p) {
;     ...
;       for (int t = 63; t >= 0; --t) {
;         const unsigned l = *(const unsigned*)(la + (size_t)t * 1024), bv = *(const unsigned*)(bb + (size_t)t * 1024);
;         h0 = __expf(bflo(l)) * h0 + bflo(bv); h1 = __expf(bfhi(l)) * h1 + bfhi(bv);
;         const unsigned g = *(const unsigned*)(GX + (size_t)(rbase + t) * 2048 + ch);
;         *(unsigned*)(YG + (size_t)(rbase + t) * 1024 + ch) = cvtpk((s0[t] + h0) * geluf_(bflo(g)), (s1[t] + h1) * geluf_(bfhi(g)));
;       }
.LBB0_784:
	s_andn2_saveexec_b64 s[16:17], s[16:17]
	v_mul_f32_e32 v103, v111, v111
	v_fmamk_f32 v104, v103, 0xba1345e1, v217
	v_fmaak_f32 v104, v103, v104, 0xbcdac9b8
	v_fmaak_f32 v104, v103, v104, 0x3de703be
	v_fmaak_f32 v104, v103, v104, 0xbec09330
	v_fmaak_f32 v103, v103, v104, 0x3e0375d0
	v_fma_f32 v112, |v111|, v103, |v111|
	s_or_b64 exec, exec, s[16:17]
	v_lshlrev_b32_e32 v103, 16, v17
	v_mul_f32_e32 v103, 0x3fb8aa3b, v103
	v_exp_f32_e32 v103, v103
	v_and_b32_e32 v17, 0xffff0000, v17
	v_mul_f32_e32 v17, 0x3fb8aa3b, v17
	v_exp_f32_e32 v17, v17
	v_lshlrev_b32_e32 v104, 16, v16
	v_fmac_f32_e32 v104, v106, v103
	v_and_b32_e32 v103, 0xffff0000, v16
	v_add_f32_e32 v16, v101, v104
	v_bfi_b32 v101, s78, v109, v108
	v_fmac_f32_e32 v103, v105, v17
	v_mul_f32_e32 v17, 0.5, v107
	v_add_f32_e32 v101, 1.0, v101
	v_mul_f32_e32 v17, v17, v101
	v_mul_f32_e32 v16, v16, v17
	v_add_f32_e32 v17, v102, v103
	v_bfi_b32 v102, s78, v112, v111
	v_mul_f32_e32 v101, 0.5, v110
	v_add_f32_e32 v102, 1.0, v102
	v_mul_f32_e32 v101, v101, v102
	v_mul_f32_e32 v17, v17, v101
	s_lshl_b64 s[0:1], s[2:3], 11
	v_cvt_pk_bf16_f32 v101, v16, v17
	v_lshl_add_u64 v[16:17], v[10:11], 0, s[0:1]
	s_mov_b32 s0, 0x14000
	global_store_dword v[16:17], v101, off
	v_add_co_u32_e32 v16, vcc, s0, v12
	s_add_i32 s2, s14, 41
	s_nop 0
	v_addc_co_u32_e32 v17, vcc, 0, v13, vcc
	v_add_co_u32_e32 v106, vcc, 0x14000, v14
	s_ashr_i32 s3, s2, 31
	s_nop 0
	v_addc_co_u32_e32 v107, vcc, 0, v15, vcc
	s_lshl_b64 s[0:1], s[2:3], 12
	v_lshl_add_u64 v[106:107], v[8:9], 0, s[0:1]
	s_waitcnt vmcnt(45)
	v_mov_b32_e32 v101, v176
	v_mov_b32_e32 v105, v175
	v_mov_b32_e32 v102, v177
	s_mov_b32 s0, 0xe800
	s_mov_b32 s1, 0
	v_lshl_add_u64 v[198:199], v[12:13], 0, s[0:1]
	v_lshl_add_u64 v[200:201], v[14:15], 0, s[0:1]
	s_add_i32 s0, s14, 29
	s_ashr_i32 s1, s0, 31
	s_lshl_b64 s[0:1], s[0:1], 12
	global_load_dword v175, v[198:199], off
	global_load_dword v176, v[200:201], off
	v_lshl_add_u64 v[202:203], v[8:9], 0, s[0:1]
	global_load_dword v177, v[202:203], off
	v_lshlrev_b32_e32 v106, 16, v102
	v_mul_f32_e32 v107, 0x3f3504f3, v106
	v_cmp_nlt_f32_e64 s[0:1], |v107|, 1.0
	s_and_saveexec_b64 s[16:17], s[0:1]
	s_xor_b64 s[16:17], exec, s[16:17]
	s_cbranch_execz .LBB0_788
	v_fma_f32 v108, |v107|, s29, v223
	v_fma_f32 v108, |v107|, v108, s20
	v_fma_f32 v108, |v107|, v108, s21
	v_fma_f32 v108, |v107|, v108, s28
	v_fma_f32 v108, |v107|, v108, s33
	v_fma_f32 v108, |v107|, v108, s30
	v_fma_f32 v108, |v107|, v108, |v107|
	v_mul_f32_e32 v109, 0xbfb8aa3b, v108
	v_fma_f32 v110, v108, s31, -v109
	v_rndne_f32_e32 v111, v109
	v_fmac_f32_e32 v110, 0xb2a5705f, v108
	v_sub_f32_e32 v109, v109, v111
	v_add_f32_e32 v109, v109, v110
	v_cvt_i32_f32_e32 v110, v111
	v_exp_f32_e32 v109, v109
	v_cmp_nlt_f32_e32 vcc, s96, v108
	v_ldexp_f32 v109, v109, v110
	s_nop 0
	v_cndmask_b32_e32 v109, 0, v109, vcc
	v_cmp_ngt_f32_e32 vcc, s97, v108
	s_nop 1
	v_cndmask_b32_e32 v108, v224, v109, vcc
	v_sub_f32_e32 v108, 1.0, v108

; DEVI unsigned cvtpk(float lo, float hi) { unsigned r; asm("v_cvt_pk_bf16_f32 %0, %1, %2" : "=v"(r) : "v"(lo), "v"(hi)); return r; }
; DEVI float bflo(unsigned u) { return __uint_as_float(u << 16); }
; DEVI float bfhi(unsigned u) { return __uint_as_float(u & 0xffff0000u); }
; DEVI float geluf_(float x) { return 0.5f * x * (1.f + erff(x * 0.70710678118654752f)); }
; DEVI void lru_p3_phase(const Params& p) {
;     ...
;       for (int t = 63; t >= 0; --t) {
;         const unsigned l = *(const unsigned*)(la + (size_t)t * 1024), bv = *(const unsigned*)(bb + (size_t)t * 1024);
;         h0 = __expf(bflo(l)) * h0 + bflo(bv); h1 = __expf(bfhi(l)) * h1 + bfhi(bv);
;         const unsigned g = *(const unsigned*)(GX + (size_t)(rbase + t) * 2048 + ch);
;         *(unsigned*)(YG + (size_t)(rbase + t) * 1024 + ch) = cvtpk((s0[t] + h0) * geluf_(bflo(g)), (s1[t] + h1) * geluf_(bfhi(g)));
;       }
.LBB0_792:
	s_andn2_saveexec_b64 s[16:17], s[16:17]
	v_mul_f32_e32 v102, v110, v110
	v_fmamk_f32 v111, v102, 0xba1345e1, v217
	v_fmaak_f32 v111, v102, v111, 0xbcdac9b8
	v_fmaak_f32 v111, v102, v111, 0x3de703be
	v_fmaak_f32 v111, v102, v111, 0xbec09330
	v_fmaak_f32 v102, v102, v111, 0x3e0375d0
	v_fma_f32 v111, |v110|, v102, |v110|
	s_or_b64 exec, exec, s[16:17]
	v_lshlrev_b32_e32 v102, 16, v105
	v_mul_f32_e32 v102, 0x3fb8aa3b, v102
	v_exp_f32_e32 v112, v102
	v_lshlrev_b32_e32 v102, 16, v101
	v_and_b32_e32 v101, 0xffff0000, v101
	s_lshl_b64 s[0:1], s[2:3], 11
	v_fmac_f32_e32 v102, v104, v112
	v_and_b32_e32 v104, 0xffff0000, v105
	v_mul_f32_e32 v104, 0x3fb8aa3b, v104
	v_exp_f32_e32 v104, v104
	v_add_f32_e32 v99, v99, v102
	s_add_i32 s2, s14, 40
	s_ashr_i32 s3, s2, 31
	v_fmac_f32_e32 v101, v103, v104
	v_bfi_b32 v104, s78, v108, v107
	v_mul_f32_e32 v103, 0.5, v106
	v_add_f32_e32 v104, 1.0, v104
	v_mul_f32_e32 v103, v103, v104
	v_bfi_b32 v104, s78, v111, v110
	v_mul_f32_e32 v99, v99, v103
	v_mul_f32_e32 v103, 0.5, v109
	v_add_f32_e32 v104, 1.0, v104
	v_add_f32_e32 v100, v100, v101
	v_mul_f32_e32 v103, v103, v104
	v_lshl_add_u64 v[104:105], v[10:11], 0, s[0:1]
	v_mul_f32_e32 v100, v100, v103
	v_cvt_pk_bf16_f32 v99, v99, v100
	global_store_dword v[104:105], v99, off
	v_add_co_u32_e32 v104, vcc, 0x14000, v14
	s_lshl_b64 s[0:1], s[2:3], 12
	s_nop 0
	v_addc_co_u32_e32 v105, vcc, 0, v15, vcc
	s_nop 0
	v_lshl_add_u64 v[104:105], v[8:9], 0, s[0:1]
	s_waitcnt vmcnt(45)
	v_mov_b32_e32 v17, v172
	v_mov_b32_e32 v16, v173
	v_mov_b32_e32 v99, v174
	s_mov_b32 s0, 0xe000
	s_mov_b32 s1, 0
	v_lshl_add_u64 v[198:199], v[12:13], 0, s[0:1]
	v_lshl_add_u64 v[200:201], v[14:15], 0, s[0:1]
	s_add_i32 s0, s14, 28
	s_ashr_i32 s1, s0, 31
	s_lshl_b64 s[0:1], s[0:1], 12
	global_load_dword v172, v[198:199], off
	global_load_dword v173, v[200:201], off
	v_lshl_add_u64 v[202:203], v[8:9], 0, s[0:1]
	global_load_dword v174, v[202:203], off
	v_lshlrev_b32_e32 v103, 16, v99
	v_mul_f32_e32 v104, 0x3f3504f3, v103
	v_cmp_nlt_f32_e64 s[0:1], |v104|, 1.0
	s_and_saveexec_b64 s[16:17], s[0:1]
	s_xor_b64 s[16:17], exec, s[16:17]
	s_cbranch_execz .LBB0_796
	v_fma_f32 v100, |v104|, s29, v223
	v_fma_f32 v100, |v104|, v100, s20
	v_fma_f32 v100, |v104|, v100, s21
	v_fma_f32 v100, |v104|, v100, s28
	v_fma_f32 v100, |v104|, v100, s33
	v_fma_f32 v100, |v104|, v100, s30
	v_fma_f32 v100, |v104|, v100, |v104|
	v_mul_f32_e32 v105, 0xbfb8aa3b, v100
	v_fma_f32 v106, v100, s31, -v105
	v_rndne_f32_e32 v107, v105
	v_fmac_f32_e32 v106, 0xb2a5705f, v100
	v_sub_f32_e32 v105, v105, v107
	v_add_f32_e32 v105, v105, v106
	v_cvt_i32_f32_e32 v106, v107
	v_exp_f32_e32 v105, v105
	v_cmp_nlt_f32_e32 vcc, s96, v100
	v_ldexp_f32 v105, v105, v106
	s_nop 0
	v_cndmask_b32_e32 v105, 0, v105, vcc
	v_cmp_ngt_f32_e32 vcc, s97, v100
	s_nop 1
	v_cndmask_b32_e32 v100, v224, v105, vcc
	v_sub_f32_e32 v105, 1.0, v100

; DEVI unsigned cvtpk(float lo, float hi) { unsigned r; asm("v_cvt_pk_bf16_f32 %0, %1, %2" : "=v"(r) : "v"(lo), "v"(hi)); return r; }
; DEVI float bflo(unsigned u) { return __uint_as_float(u << 16); }
; DEVI float bfhi(unsigned u) { return __uint_as_float(u & 0xffff0000u); }
; DEVI float geluf_(float x) { return 0.5f * x * (1.f + erff(x * 0.70710678118654752f)); }
; DEVI void lru_p3_phase(const Params& p) {
;     ...
;       for (int t = 63; t >= 0; --t) {
;         const unsigned l = *(const unsigned*)(la + (size_t)t * 1024), bv = *(const unsigned*)(bb + (size_t)t * 1024);
;         h0 = __expf(bflo(l)) * h0 + bflo(bv); h1 = __expf(bfhi(l)) * h1 + bfhi(bv);
;         const unsigned g = *(const unsigned*)(GX + (size_t)(rbase + t) * 2048 + ch);
;         *(unsigned*)(YG + (size_t)(rbase + t) * 1024 + ch) = cvtpk((s0[t] + h0) * geluf_(bflo(g)), (s1[t] + h1) * geluf_(bfhi(g)));
;       }
.LBB0_800:
	s_andn2_saveexec_b64 s[16:17], s[16:17]
	v_mul_f32_e32 v99, v107, v107
	v_fmamk_f32 v100, v99, 0xba1345e1, v217
	v_fmaak_f32 v100, v99, v100, 0xbcdac9b8
	v_fmaak_f32 v100, v99, v100, 0x3de703be
	v_fmaak_f32 v100, v99, v100, 0xbec09330
	v_fmaak_f32 v99, v99, v100, 0x3e0375d0
	v_fma_f32 v108, |v107|, v99, |v107|
	s_or_b64 exec, exec, s[16:17]
	v_lshlrev_b32_e32 v99, 16, v17
	v_mul_f32_e32 v99, 0x3fb8aa3b, v99
	v_exp_f32_e32 v99, v99
	v_and_b32_e32 v17, 0xffff0000, v17
	v_mul_f32_e32 v17, 0x3fb8aa3b, v17
	v_exp_f32_e32 v17, v17
	v_lshlrev_b32_e32 v100, 16, v16
	v_fmac_f32_e32 v100, v102, v99
	v_and_b32_e32 v99, 0xffff0000, v16
	v_add_f32_e32 v16, v97, v100
	v_bfi_b32 v97, s78, v105, v104
	v_fmac_f32_e32 v99, v101, v17
	v_mul_f32_e32 v17, 0.5, v103
	v_add_f32_e32 v97, 1.0, v97
	v_mul_f32_e32 v17, v17, v97
	v_mul_f32_e32 v16, v16, v17
	v_add_f32_e32 v17, v98, v99
	v_bfi_b32 v98, s78, v108, v107
	v_mul_f32_e32 v97, 0.5, v106
	v_add_f32_e32 v98, 1.0, v98
	v_mul_f32_e32 v97, v97, v98
	v_mul_f32_e32 v17, v17, v97
	s_lshl_b64 s[0:1], s[2:3], 11
	v_cvt_pk_bf16_f32 v97, v16, v17
	v_lshl_add_u64 v[16:17], v[10:11], 0, s[0:1]
	global_store_dword v[16:17], v97, off
	v_add_co_u32_e32 v16, vcc, s55, v12
	s_add_i32 s2, s14, 39
	s_nop 0
	v_addc_co_u32_e32 v17, vcc, 0, v13, vcc
	v_add_co_u32_e32 v102, vcc, 0x13000, v14
	s_ashr_i32 s3, s2, 31
	s_nop 0
	v_addc_co_u32_e32 v103, vcc, 0, v15, vcc
	s_lshl_b64 s[0:1], s[2:3], 12
	v_lshl_add_u64 v[102:103], v[8:9], 0, s[0:1]
	s_waitcnt vmcnt(45)
	v_mov_b32_e32 v97, v170
	v_mov_b32_e32 v101, v169
	v_mov_b32_e32 v98, v171
	s_mov_b32 s0, 0xd800
	s_mov_b32 s1, 0
	v_lshl_add_u64 v[198:199], v[12:13], 0, s[0:1]
	v_lshl_add_u64 v[200:201], v[14:15], 0, s[0:1]
	s_add_i32 s0, s14, 27
	s_ashr_i32 s1, s0, 31
	s_lshl_b64 s[0:1], s[0:1], 12
	global_load_dword v169, v[198:199], off
	global_load_dword v170, v[200:201], off
	v_lshl_add_u64 v[202:203], v[8:9], 0, s[0:1]
	global_load_dword v171, v[202:203], off
	v_lshlrev_b32_e32 v102, 16, v98
	v_mul_f32_e32 v103, 0x3f3504f3, v102
	v_cmp_nlt_f32_e64 s[0:1], |v103|, 1.0
	s_and_saveexec_b64 s[16:17], s[0:1]
	s_xor_b64 s[16:17], exec, s[16:17]
	s_cbranch_execz .LBB0_804
	v_fma_f32 v104, |v103|, s29, v223
	v_fma_f32 v104, |v103|, v104, s20
	v_fma_f32 v104, |v103|, v104, s21
	v_fma_f32 v104, |v103|, v104, s28
	v_fma_f32 v104, |v103|, v104, s33
	v_fma_f32 v104, |v103|, v104, s30
	v_fma_f32 v104, |v103|, v104, |v103|
	v_mul_f32_e32 v105, 0xbfb8aa3b, v104
	v_fma_f32 v106, v104, s31, -v105
	v_rndne_f32_e32 v107, v105
	v_fmac_f32_e32 v106, 0xb2a5705f, v104
	v_sub_f32_e32 v105, v105, v107
	v_add_f32_e32 v105, v105, v106
	v_cvt_i32_f32_e32 v106, v107
	v_exp_f32_e32 v105, v105
	v_cmp_nlt_f32_e32 vcc, s96, v104
	v_ldexp_f32 v105, v105, v106
	s_nop 0
	v_cndmask_b32_e32 v105, 0, v105, vcc
	v_cmp_ngt_f32_e32 vcc, s97, v104
	s_nop 1
	v_cndmask_b32_e32 v104, v224, v105, vcc
	v_sub_f32_e32 v104, 1.0, v104

; DEVI unsigned cvtpk(float lo, float hi) { unsigned r; asm("v_cvt_pk_bf16_f32 %0, %1, %2" : "=v"(r) : "v"(lo), "v"(hi)); return r; }
; DEVI float bflo(unsigned u) { return __uint_as_float(u << 16); }
; DEVI float bfhi(unsigned u) { return __uint_as_float(u & 0xffff0000u); }
; DEVI float geluf_(float x) { return 0.5f * x * (1.f + erff(x * 0.70710678118654752f)); }
; DEVI void lru_p3_phase(const Params& p) {
;     ...
;       for (int t = 63; t >= 0; --t) {
;         const unsigned l = *(const unsigned*)(la + (size_t)t * 1024), bv = *(const unsigned*)(bb + (size_t)t * 1024);
;         h0 = __expf(bflo(l)) * h0 + bflo(bv); h1 = __expf(bfhi(l)) * h1 + bfhi(bv);
;         const unsigned g = *(const unsigned*)(GX + (size_t)(rbase + t) * 2048 + ch);
;         *(unsigned*)(YG + (size_t)(rbase + t) * 1024 + ch) = cvtpk((s0[t] + h0) * geluf_(bflo(g)), (s1[t] + h1) * geluf_(bfhi(g)));
;       }
.LBB0_808:
	s_andn2_saveexec_b64 s[16:17], s[16:17]
	v_mul_f32_e32 v98, v106, v106
	v_fmamk_f32 v107, v98, 0xba1345e1, v217
	v_fmaak_f32 v107, v98, v107, 0xbcdac9b8
	v_fmaak_f32 v107, v98, v107, 0x3de703be
	v_fmaak_f32 v107, v98, v107, 0xbec09330
	v_fmaak_f32 v98, v98, v107, 0x3e0375d0
	v_fma_f32 v107, |v106|, v98, |v106|
	s_or_b64 exec, exec, s[16:17]
	v_lshlrev_b32_e32 v98, 16, v101
	v_mul_f32_e32 v98, 0x3fb8aa3b, v98
	v_exp_f32_e32 v108, v98
	v_lshlrev_b32_e32 v98, 16, v97
	v_and_b32_e32 v97, 0xffff0000, v97
	s_lshl_b64 s[0:1], s[2:3], 11
	v_fmac_f32_e32 v98, v100, v108
	v_and_b32_e32 v100, 0xffff0000, v101
	v_mul_f32_e32 v100, 0x3fb8aa3b, v100
	v_exp_f32_e32 v100, v100
	v_add_f32_e32 v95, v95, v98
	s_add_i32 s2, s14, 38
	s_ashr_i32 s3, s2, 31
	v_fmac_f32_e32 v97, v99, v100
	v_bfi_b32 v100, s78, v104, v103
	v_mul_f32_e32 v99, 0.5, v102
	v_add_f32_e32 v100, 1.0, v100
	v_mul_f32_e32 v99, v99, v100
	v_bfi_b32 v100, s78, v107, v106
	v_mul_f32_e32 v95, v95, v99
	v_mul_f32_e32 v99, 0.5, v105
	v_add_f32_e32 v100, 1.0, v100
	v_add_f32_e32 v96, v96, v97
	v_mul_f32_e32 v99, v99, v100
	v_lshl_add_u64 v[100:101], v[10:11], 0, s[0:1]
	v_mul_f32_e32 v96, v96, v99
	v_cvt_pk_bf16_f32 v95, v95, v96
	global_store_dword v[100:101], v95, off
	v_add_co_u32_e32 v100, vcc, 0x13000, v14
	s_lshl_b64 s[0:1], s[2:3], 12
	s_nop 0
	v_addc_co_u32_e32 v101, vcc, 0, v15, vcc
	s_nop 0
	v_lshl_add_u64 v[100:101], v[8:9], 0, s[0:1]
	s_waitcnt vmcnt(45)
	v_mov_b32_e32 v17, v166
	v_mov_b32_e32 v16, v167
	v_mov_b32_e32 v95, v168
	s_mov_b32 s0, 0xd000
	s_mov_b32 s1, 0
	v_lshl_add_u64 v[198:199], v[12:13], 0, s[0:1]
	v_lshl_add_u64 v[200:201], v[14:15], 0, s[0:1]
	s_add_i32 s0, s14, 26
	s_ashr_i32 s1, s0, 31
	s_lshl_b64 s[0:1], s[0:1], 12
	global_load_dword v166, v[198:199], off
	global_load_dword v167, v[200:201], off
	v_lshl_add_u64 v[202:203], v[8:9], 0, s[0:1]
	global_load_dword v168, v[202:203], off
	v_lshlrev_b32_e32 v99, 16, v95
	v_mul_f32_e32 v100, 0x3f3504f3, v99
	v_cmp_nlt_f32_e64 s[0:1], |v100|, 1.0
	s_and_saveexec_b64 s[16:17], s[0:1]
	s_xor_b64 s[16:17], exec, s[16:17]
	s_cbranch_execz .LBB0_812
	v_fma_f32 v96, |v100|, s29, v223
	v_fma_f32 v96, |v100|, v96, s20
	v_fma_f32 v96, |v100|, v96, s21
	v_fma_f32 v96, |v100|, v96, s28
	v_fma_f32 v96, |v100|, v96, s33
	v_fma_f32 v96, |v100|, v96, s30
	v_fma_f32 v96, |v100|, v96, |v100|
	v_mul_f32_e32 v101, 0xbfb8aa3b, v96
	v_fma_f32 v102, v96, s31, -v101
	v_rndne_f32_e32 v103, v101
	v_fmac_f32_e32 v102, 0xb2a5705f, v96
	v_sub_f32_e32 v101, v101, v103
	v_add_f32_e32 v101, v101, v102
	v_cvt_i32_f32_e32 v102, v103
	v_exp_f32_e32 v101, v101
	v_cmp_nlt_f32_e32 vcc, s96, v96
	v_ldexp_f32 v101, v101, v102
	s_nop 0
	v_cndmask_b32_e32 v101, 0, v101, vcc
	v_cmp_ngt_f32_e32 vcc, s97, v96
	s_nop 1
	v_cndmask_b32_e32 v96, v224, v101, vcc
	v_sub_f32_e32 v101, 1.0, v96

; DEVI unsigned cvtpk(float lo, float hi) { unsigned r; asm("v_cvt_pk_bf16_f32 %0, %1, %2" : "=v"(r) : "v"(lo), "v"(hi)); return r; }
; DEVI float bflo(unsigned u) { return __uint_as_float(u << 16); }
; DEVI float bfhi(unsigned u) { return __uint_as_float(u & 0xffff0000u); }
; DEVI float geluf_(float x) { return 0.5f * x * (1.f + erff(x * 0.70710678118654752f)); }
; DEVI void lru_p3_phase(const Params& p) {
;     ...
;       for (int t = 63; t >= 0; --t) {
;         const unsigned l = *(const unsigned*)(la + (size_t)t * 1024), bv = *(const unsigned*)(bb + (size_t)t * 1024);
;         h0 = __expf(bflo(l)) * h0 + bflo(bv); h1 = __expf(bfhi(l)) * h1 + bfhi(bv);
;         const unsigned g = *(const unsigned*)(GX + (size_t)(rbase + t) * 2048 + ch);
;         *(unsigned*)(YG + (size_t)(rbase + t) * 1024 + ch) = cvtpk((s0[t] + h0) * geluf_(bflo(g)), (s1[t] + h1) * geluf_(bfhi(g)));
;       }
.LBB0_816:
	s_andn2_saveexec_b64 s[16:17], s[16:17]
	v_mul_f32_e32 v95, v103, v103
	v_fmamk_f32 v96, v95, 0xba1345e1, v217
	v_fmaak_f32 v96, v95, v96, 0xbcdac9b8
	v_fmaak_f32 v96, v95, v96, 0x3de703be
	v_fmaak_f32 v96, v95, v96, 0xbec09330
	v_fmaak_f32 v95, v95, v96, 0x3e0375d0
	v_fma_f32 v104, |v103|, v95, |v103|
	s_or_b64 exec, exec, s[16:17]
	v_lshlrev_b32_e32 v95, 16, v17
	v_mul_f32_e32 v95, 0x3fb8aa3b, v95
	v_exp_f32_e32 v95, v95
	v_and_b32_e32 v17, 0xffff0000, v17
	v_mul_f32_e32 v17, 0x3fb8aa3b, v17
	v_exp_f32_e32 v17, v17
	v_lshlrev_b32_e32 v96, 16, v16
	v_fmac_f32_e32 v96, v98, v95
	v_and_b32_e32 v95, 0xffff0000, v16
	v_add_f32_e32 v16, v93, v96
	v_bfi_b32 v93, s78, v101, v100
	v_fmac_f32_e32 v95, v97, v17
	v_mul_f32_e32 v17, 0.5, v99
	v_add_f32_e32 v93, 1.0, v93
	v_mul_f32_e32 v17, v17, v93
	v_mul_f32_e32 v16, v16, v17
	v_add_f32_e32 v17, v94, v95
	v_bfi_b32 v94, s78, v104, v103
	v_mul_f32_e32 v93, 0.5, v102
	v_add_f32_e32 v94, 1.0, v94
	v_mul_f32_e32 v93, v93, v94
	v_mul_f32_e32 v17, v17, v93
	s_lshl_b64 s[0:1], s[2:3], 11
	v_cvt_pk_bf16_f32 v93, v16, v17
	v_lshl_add_u64 v[16:17], v[10:11], 0, s[0:1]
	global_store_dword v[16:17], v93, off
	v_add_co_u32_e32 v16, vcc, s25, v12
	s_add_i32 s2, s14, 37
	s_nop 0
	v_addc_co_u32_e32 v17, vcc, 0, v13, vcc
	v_add_co_u32_e32 v98, vcc, 0x12000, v14
	s_ashr_i32 s3, s2, 31
	s_nop 0
	v_addc_co_u32_e32 v99, vcc, 0, v15, vcc
	s_lshl_b64 s[0:1], s[2:3], 12
	v_lshl_add_u64 v[98:99], v[8:9], 0, s[0:1]
	s_waitcnt vmcnt(45)
	v_mov_b32_e32 v93, v164
	v_mov_b32_e32 v97, v163
	v_mov_b32_e32 v94, v165
	s_mov_b32 s0, 0xc800
	s_mov_b32 s1, 0
	v_lshl_add_u64 v[198:199], v[12:13], 0, s[0:1]
	v_lshl_add_u64 v[200:201], v[14:15], 0, s[0:1]
	s_add_i32 s0, s14, 25
	s_ashr_i32 s1, s0, 31
	s_lshl_b64 s[0:1], s[0:1], 12
	global_load_dword v163, v[198:199], off
	global_load_dword v164, v[200:201], off
	v_lshl_add_u64 v[202:203], v[8:9], 0, s[0:1]
	global_load_dword v165, v[202:203], off
	v_lshlrev_b32_e32 v98, 16, v94
	v_mul_f32_e32 v99, 0x3f3504f3, v98
	v_cmp_nlt_f32_e64 s[0:1], |v99|, 1.0
	s_and_saveexec_b64 s[16:17], s[0:1]
	s_xor_b64 s[16:17], exec, s[16:17]
	s_cbranch_execz .LBB0_820
	v_fma_f32 v100, |v99|, s29, v223
	v_fma_f32 v100, |v99|, v100, s20
	v_fma_f32 v100, |v99|, v100, s21
	v_fma_f32 v100, |v99|, v100, s28
	v_fma_f32 v100, |v99|, v100, s33
	v_fma_f32 v100, |v99|, v100, s30
	v_fma_f32 v100, |v99|, v100, |v99|
	v_mul_f32_e32 v101, 0xbfb8aa3b, v100
	v_fma_f32 v102, v100, s31, -v101
	v_rndne_f32_e32 v103, v101
	v_fmac_f32_e32 v102, 0xb2a5705f, v100
	v_sub_f32_e32 v101, v101, v103
	v_add_f32_e32 v101, v101, v102
	v_cvt_i32_f32_e32 v102, v103
	v_exp_f32_e32 v101, v101
	v_cmp_nlt_f32_e32 vcc, s96, v100
	v_ldexp_f32 v101, v101, v102
	s_nop 0
	v_cndmask_b32_e32 v101, 0, v101, vcc
	v_cmp_ngt_f32_e32 vcc, s97, v100
	s_nop 1
	v_cndmask_b32_e32 v100, v224, v101, vcc
	v_sub_f32_e32 v100, 1.0, v100

; DEVI unsigned cvtpk(float lo, float hi) { unsigned r; asm("v_cvt_pk_bf16_f32 %0, %1, %2" : "=v"(r) : "v"(lo), "v"(hi)); return r; }
; DEVI float bflo(unsigned u) { return __uint_as_float(u << 16); }
; DEVI float bfhi(unsigned u) { return __uint_as_float(u & 0xffff0000u); }
; DEVI float geluf_(float x) { return 0.5f * x * (1.f + erff(x * 0.70710678118654752f)); }
; DEVI void lru_p3_phase(const Params& p) {
;     ...
;       for (int t = 63; t >= 0; --t) {
;         const unsigned l = *(const unsigned*)(la + (size_t)t * 1024), bv = *(const unsigned*)(bb + (size_t)t * 1024);
;         h0 = __expf(bflo(l)) * h0 + bflo(bv); h1 = __expf(bfhi(l)) * h1 + bfhi(bv);
;         const unsigned g = *(const unsigned*)(GX + (size_t)(rbase + t) * 2048 + ch);
;         *(unsigned*)(YG + (size_t)(rbase + t) * 1024 + ch) = cvtpk((s0[t] + h0) * geluf_(bflo(g)), (s1[t] + h1) * geluf_(bfhi(g)));
;       }
.LBB0_824:
	s_andn2_saveexec_b64 s[16:17], s[16:17]
	v_mul_f32_e32 v94, v102, v102
	v_fmamk_f32 v103, v94, 0xba1345e1, v217
	v_fmaak_f32 v103, v94, v103, 0xbcdac9b8
	v_fmaak_f32 v103, v94, v103, 0x3de703be
	v_fmaak_f32 v103, v94, v103, 0xbec09330
	v_fmaak_f32 v94, v94, v103, 0x3e0375d0
	v_fma_f32 v103, |v102|, v94, |v102|
	s_or_b64 exec, exec, s[16:17]
	v_lshlrev_b32_e32 v94, 16, v97
	v_mul_f32_e32 v94, 0x3fb8aa3b, v94
	v_exp_f32_e32 v104, v94
	v_lshlrev_b32_e32 v94, 16, v93
	v_and_b32_e32 v93, 0xffff0000, v93
	s_lshl_b64 s[0:1], s[2:3], 11
	v_fmac_f32_e32 v94, v96, v104
	v_and_b32_e32 v96, 0xffff0000, v97
	v_mul_f32_e32 v96, 0x3fb8aa3b, v96
	v_exp_f32_e32 v96, v96
	v_add_f32_e32 v91, v91, v94
	s_add_i32 s2, s14, 36
	s_ashr_i32 s3, s2, 31
	v_fmac_f32_e32 v93, v95, v96
	v_bfi_b32 v96, s78, v100, v99
	v_mul_f32_e32 v95, 0.5, v98
	v_add_f32_e32 v96, 1.0, v96
	v_mul_f32_e32 v95, v95, v96
	v_bfi_b32 v96, s78, v103, v102
	v_mul_f32_e32 v91, v91, v95
	v_mul_f32_e32 v95, 0.5, v101
	v_add_f32_e32 v96, 1.0, v96
	v_add_f32_e32 v92, v92, v93
	v_mul_f32_e32 v95, v95, v96
	v_lshl_add_u64 v[96:97], v[10:11], 0, s[0:1]
	v_mul_f32_e32 v92, v92, v95
	v_cvt_pk_bf16_f32 v91, v91, v92
	global_store_dword v[96:97], v91, off
	v_add_co_u32_e32 v96, vcc, 0x12000, v14
	s_lshl_b64 s[0:1], s[2:3], 12
	s_nop 0
	v_addc_co_u32_e32 v97, vcc, 0, v15, vcc
	s_nop 0
	v_lshl_add_u64 v[96:97], v[8:9], 0, s[0:1]
	s_waitcnt vmcnt(45)
	v_mov_b32_e32 v17, v160
	v_mov_b32_e32 v16, v161
	v_mov_b32_e32 v91, v162
	s_mov_b32 s0, 0xc000
	s_mov_b32 s1, 0
	v_lshl_add_u64 v[198:199], v[12:13], 0, s[0:1]
	v_lshl_add_u64 v[200:201], v[14:15], 0, s[0:1]
	s_add_i32 s0, s14, 24
	s_ashr_i32 s1, s0, 31
	s_lshl_b64 s[0:1], s[0:1], 12
	global_load_dword v160, v[198:199], off
	global_load_dword v161, v[200:201], off
	v_lshl_add_u64 v[202:203], v[8:9], 0, s[0:1]
	global_load_dword v162, v[202:203], off
	v_lshlrev_b32_e32 v95, 16, v91
	v_mul_f32_e32 v96, 0x3f3504f3, v95
	v_cmp_nlt_f32_e64 s[0:1], |v96|, 1.0
	s_and_saveexec_b64 s[16:17], s[0:1]
	s_xor_b64 s[16:17], exec, s[16:17]
	s_cbranch_execz .LBB0_828
	v_fma_f32 v92, |v96|, s29, v223
	v_fma_f32 v92, |v96|, v92, s20
	v_fma_f32 v92, |v96|, v92, s21
	v_fma_f32 v92, |v96|, v92, s28
	v_fma_f32 v92, |v96|, v92, s33
	v_fma_f32 v92, |v96|, v92, s30
	v_fma_f32 v92, |v96|, v92, |v96|
	v_mul_f32_e32 v97, 0xbfb8aa3b, v92
	v_fma_f32 v98, v92, s31, -v97
	v_rndne_f32_e32 v99, v97
	v_fmac_f32_e32 v98, 0xb2a5705f, v92
	v_sub_f32_e32 v97, v97, v99
	v_add_f32_e32 v97, v97, v98
	v_cvt_i32_f32_e32 v98, v99
	v_exp_f32_e32 v97, v97
	v_cmp_nlt_f32_e32 vcc, s96, v92
	v_ldexp_f32 v97, v97, v98
	s_nop 0
	v_cndmask_b32_e32 v97, 0, v97, vcc
	v_cmp_ngt_f32_e32 vcc, s97, v92
	s_nop 1
	v_cndmask_b32_e32 v92, v224, v97, vcc
	v_sub_f32_e32 v97, 1.0, v92

; DEVI unsigned cvtpk(float lo, float hi) { unsigned r; asm("v_cvt_pk_bf16_f32 %0, %1, %2" : "=v"(r) : "v"(lo), "v"(hi)); return r; }
; DEVI float bflo(unsigned u) { return __uint_as_float(u << 16); }
; DEVI float bfhi(unsigned u) { return __uint_as_float(u & 0xffff0000u); }
; DEVI float geluf_(float x) { return 0.5f * x * (1.f + erff(x * 0.70710678118654752f)); }
; DEVI void lru_p3_phase(const Params& p) {
;     ...
;       for (int t = 63; t >= 0; --t) {
;         const unsigned l = *(const unsigned*)(la + (size_t)t * 1024), bv = *(const unsigned*)(bb + (size_t)t * 1024);
;         h0 = __expf(bflo(l)) * h0 + bflo(bv); h1 = __expf(bfhi(l)) * h1 + bfhi(bv);
;         const unsigned g = *(const unsigned*)(GX + (size_t)(rbase + t) * 2048 + ch);
;         *(unsigned*)(YG + (size_t)(rbase + t) * 1024 + ch) = cvtpk((s0[t] + h0) * geluf_(bflo(g)), (s1[t] + h1) * geluf_(bfhi(g)));
;       }
.LBB0_832:
	s_andn2_saveexec_b64 s[16:17], s[16:17]
	v_mul_f32_e32 v91, v99, v99
	v_fmamk_f32 v92, v91, 0xba1345e1, v217
	v_fmaak_f32 v92, v91, v92, 0xbcdac9b8
	v_fmaak_f32 v92, v91, v92, 0x3de703be
	v_fmaak_f32 v92, v91, v92, 0xbec09330
	v_fmaak_f32 v91, v91, v92, 0x3e0375d0
	v_fma_f32 v100, |v99|, v91, |v99|
	s_or_b64 exec, exec, s[16:17]
	v_lshlrev_b32_e32 v91, 16, v17
	v_mul_f32_e32 v91, 0x3fb8aa3b, v91
	v_exp_f32_e32 v91, v91
	v_and_b32_e32 v17, 0xffff0000, v17
	v_mul_f32_e32 v17, 0x3fb8aa3b, v17
	v_exp_f32_e32 v17, v17
	v_lshlrev_b32_e32 v92, 16, v16
	v_fmac_f32_e32 v92, v94, v91
	v_and_b32_e32 v91, 0xffff0000, v16
	v_add_f32_e32 v16, v89, v92
	v_bfi_b32 v89, s78, v97, v96
	v_fmac_f32_e32 v91, v93, v17
	v_mul_f32_e32 v17, 0.5, v95
	v_add_f32_e32 v89, 1.0, v89
	v_mul_f32_e32 v17, v17, v89
	v_mul_f32_e32 v16, v16, v17
	v_add_f32_e32 v17, v90, v91
	v_bfi_b32 v90, s78, v100, v99
	v_mul_f32_e32 v89, 0.5, v98
	v_add_f32_e32 v90, 1.0, v90
	v_mul_f32_e32 v89, v89, v90
	v_mul_f32_e32 v17, v17, v89
	s_lshl_b64 s[0:1], s[2:3], 11
	v_cvt_pk_bf16_f32 v89, v16, v17
	v_lshl_add_u64 v[16:17], v[10:11], 0, s[0:1]
	global_store_dword v[16:17], v89, off
	v_add_co_u32_e32 v16, vcc, s43, v12
	s_add_i32 s2, s14, 35
	s_nop 0
	v_addc_co_u32_e32 v17, vcc, 0, v13, vcc
	v_add_co_u32_e32 v94, vcc, 0x11000, v14
	s_ashr_i32 s3, s2, 31
	s_nop 0
	v_addc_co_u32_e32 v95, vcc, 0, v15, vcc
	s_lshl_b64 s[0:1], s[2:3], 12
	v_lshl_add_u64 v[94:95], v[8:9], 0, s[0:1]
	s_waitcnt vmcnt(45)
	v_mov_b32_e32 v89, v196
	v_mov_b32_e32 v93, v195
	v_mov_b32_e32 v90, v197
	s_mov_b32 s0, 0xb800
	s_mov_b32 s1, 0
	v_lshl_add_u64 v[198:199], v[12:13], 0, s[0:1]
	v_lshl_add_u64 v[200:201], v[14:15], 0, s[0:1]
	s_add_i32 s0, s14, 23
	s_ashr_i32 s1, s0, 31
	s_lshl_b64 s[0:1], s[0:1], 12
	global_load_dword v195, v[198:199], off
	global_load_dword v196, v[200:201], off
	v_lshl_add_u64 v[202:203], v[8:9], 0, s[0:1]
	global_load_dword v197, v[202:203], off
	v_lshlrev_b32_e32 v94, 16, v90
	v_mul_f32_e32 v95, 0x3f3504f3, v94
	v_cmp_nlt_f32_e64 s[0:1], |v95|, 1.0
	s_and_saveexec_b64 s[16:17], s[0:1]
	s_xor_b64 s[16:17], exec, s[16:17]
	s_cbranch_execz .LBB0_836
	v_fma_f32 v96, |v95|, s29, v223
	v_fma_f32 v96, |v95|, v96, s20
	v_fma_f32 v96, |v95|, v96, s21
	v_fma_f32 v96, |v95|, v96, s28
	v_fma_f32 v96, |v95|, v96, s33
	v_fma_f32 v96, |v95|, v96, s30
	v_fma_f32 v96, |v95|, v96, |v95|
	v_mul_f32_e32 v97, 0xbfb8aa3b, v96
	v_fma_f32 v98, v96, s31, -v97
	v_rndne_f32_e32 v99, v97
	v_fmac_f32_e32 v98, 0xb2a5705f, v96
	v_sub_f32_e32 v97, v97, v99
	v_add_f32_e32 v97, v97, v98
	v_cvt_i32_f32_e32 v98, v99
	v_exp_f32_e32 v97, v97
	v_cmp_nlt_f32_e32 vcc, s96, v96
	v_ldexp_f32 v97, v97, v98
	s_nop 0
	v_cndmask_b32_e32 v97, 0, v97, vcc
	v_cmp_ngt_f32_e32 vcc, s97, v96
	s_nop 1
	v_cndmask_b32_e32 v96, v224, v97, vcc
	v_sub_f32_e32 v96, 1.0, v96

; DEVI unsigned cvtpk(float lo, float hi) { unsigned r; asm("v_cvt_pk_bf16_f32 %0, %1, %2" : "=v"(r) : "v"(lo), "v"(hi)); return r; }
; DEVI float bflo(unsigned u) { return __uint_as_float(u << 16); }
; DEVI float bfhi(unsigned u) { return __uint_as_float(u & 0xffff0000u); }
; DEVI float geluf_(float x) { return 0.5f * x * (1.f + erff(x * 0.70710678118654752f)); }
; DEVI void lru_p3_phase(const Params& p) {
;     ...
;       for (int t = 63; t >= 0; --t) {
;         const unsigned l = *(const unsigned*)(la + (size_t)t * 1024), bv = *(const unsigned*)(bb + (size_t)t * 1024);
;         h0 = __expf(bflo(l)) * h0 + bflo(bv); h1 = __expf(bfhi(l)) * h1 + bfhi(bv);
;         const unsigned g = *(const unsigned*)(GX + (size_t)(rbase + t) * 2048 + ch);
;         *(unsigned*)(YG + (size_t)(rbase + t) * 1024 + ch) = cvtpk((s0[t] + h0) * geluf_(bflo(g)), (s1[t] + h1) * geluf_(bfhi(g)));
;       }
.LBB0_840:
	s_andn2_saveexec_b64 s[16:17], s[16:17]
	v_mul_f32_e32 v90, v98, v98
	v_fmamk_f32 v99, v90, 0xba1345e1, v217
	v_fmaak_f32 v99, v90, v99, 0xbcdac9b8
	v_fmaak_f32 v99, v90, v99, 0x3de703be
	v_fmaak_f32 v99, v90, v99, 0xbec09330
	v_fmaak_f32 v90, v90, v99, 0x3e0375d0
	v_fma_f32 v99, |v98|, v90, |v98|
	s_or_b64 exec, exec, s[16:17]
	v_lshlrev_b32_e32 v90, 16, v93
	v_mul_f32_e32 v90, 0x3fb8aa3b, v90
	v_exp_f32_e32 v100, v90
	v_lshlrev_b32_e32 v90, 16, v89
	v_and_b32_e32 v89, 0xffff0000, v89
	s_lshl_b64 s[0:1], s[2:3], 11
	v_fmac_f32_e32 v90, v92, v100
	v_and_b32_e32 v92, 0xffff0000, v93
	v_mul_f32_e32 v92, 0x3fb8aa3b, v92
	v_exp_f32_e32 v92, v92
	v_add_f32_e32 v87, v87, v90
	s_add_i32 s2, s14, 34
	s_ashr_i32 s3, s2, 31
	v_fmac_f32_e32 v89, v91, v92
	v_bfi_b32 v92, s78, v96, v95
	v_mul_f32_e32 v91, 0.5, v94
	v_add_f32_e32 v92, 1.0, v92
	v_mul_f32_e32 v91, v91, v92
	v_bfi_b32 v92, s78, v99, v98
	v_mul_f32_e32 v87, v87, v91
	v_mul_f32_e32 v91, 0.5, v97
	v_add_f32_e32 v92, 1.0, v92
	v_add_f32_e32 v88, v88, v89
	v_mul_f32_e32 v91, v91, v92
	v_lshl_add_u64 v[92:93], v[10:11], 0, s[0:1]
	v_mul_f32_e32 v88, v88, v91
	v_cvt_pk_bf16_f32 v87, v87, v88
	global_store_dword v[92:93], v87, off
	v_add_co_u32_e32 v92, vcc, 0x11000, v14
	s_lshl_b64 s[0:1], s[2:3], 12
	s_nop 0
	v_addc_co_u32_e32 v93, vcc, 0, v15, vcc
	s_nop 0
	v_lshl_add_u64 v[92:93], v[8:9], 0, s[0:1]
	s_waitcnt vmcnt(45)
	v_mov_b32_e32 v17, v192
	v_mov_b32_e32 v16, v193
	v_mov_b32_e32 v87, v194
	s_mov_b32 s0, 0xb000
	s_mov_b32 s1, 0
	v_lshl_add_u64 v[198:199], v[12:13], 0, s[0:1]
	v_lshl_add_u64 v[200:201], v[14:15], 0, s[0:1]
	s_add_i32 s0, s14, 22
	s_ashr_i32 s1, s0, 31
	s_lshl_b64 s[0:1], s[0:1], 12
	global_load_dword v192, v[198:199], off
	global_load_dword v193, v[200:201], off
	v_lshl_add_u64 v[202:203], v[8:9], 0, s[0:1]
	global_load_dword v194, v[202:203], off
	v_lshlrev_b32_e32 v91, 16, v87
	v_mul_f32_e32 v92, 0x3f3504f3, v91
	v_cmp_nlt_f32_e64 s[0:1], |v92|, 1.0
	s_and_saveexec_b64 s[16:17], s[0:1]
	s_xor_b64 s[16:17], exec, s[16:17]
	s_cbranch_execz .LBB0_844
	v_fma_f32 v88, |v92|, s29, v223
	v_fma_f32 v88, |v92|, v88, s20
	v_fma_f32 v88, |v92|, v88, s21
	v_fma_f32 v88, |v92|, v88, s28
	v_fma_f32 v88, |v92|, v88, s33
	v_fma_f32 v88, |v92|, v88, s30
	v_fma_f32 v88, |v92|, v88, |v92|
	v_mul_f32_e32 v93, 0xbfb8aa3b, v88
	v_fma_f32 v94, v88, s31, -v93
	v_rndne_f32_e32 v95, v93
	v_fmac_f32_e32 v94, 0xb2a5705f, v88
	v_sub_f32_e32 v93, v93, v95
	v_add_f32_e32 v93, v93, v94
	v_cvt_i32_f32_e32 v94, v95
	v_exp_f32_e32 v93, v93
	v_cmp_nlt_f32_e32 vcc, s96, v88
	v_ldexp_f32 v93, v93, v94
	s_nop 0
	v_cndmask_b32_e32 v93, 0, v93, vcc
	v_cmp_ngt_f32_e32 vcc, s97, v88
	s_nop 1
	v_cndmask_b32_e32 v88, v224, v93, vcc
	v_sub_f32_e32 v93, 1.0, v88

; DEVI unsigned cvtpk(float lo, float hi) { unsigned r; asm("v_cvt_pk_bf16_f32 %0, %1, %2" : "=v"(r) : "v"(lo), "v"(hi)); return r; }
; DEVI float bflo(unsigned u) { return __uint_as_float(u << 16); }
; DEVI float bfhi(unsigned u) { return __uint_as_float(u & 0xffff0000u); }
; DEVI float geluf_(float x) { return 0.5f * x * (1.f + erff(x * 0.70710678118654752f)); }
; DEVI void lru_p3_phase(const Params& p) {
;     ...
;       for (int t = 63; t >= 0; --t) {
;         const unsigned l = *(const unsigned*)(la + (size_t)t * 1024), bv = *(const unsigned*)(bb + (size_t)t * 1024);
;         h0 = __expf(bflo(l)) * h0 + bflo(bv); h1 = __expf(bfhi(l)) * h1 + bfhi(bv);
;         const unsigned g = *(const unsigned*)(GX + (size_t)(rbase + t) * 2048 + ch);
;         *(unsigned*)(YG + (size_t)(rbase + t) * 1024 + ch) = cvtpk((s0[t] + h0) * geluf_(bflo(g)), (s1[t] + h1) * geluf_(bfhi(g)));
;       }
.LBB0_848:
	s_andn2_saveexec_b64 s[16:17], s[16:17]
	v_mul_f32_e32 v87, v95, v95
	v_fmamk_f32 v88, v87, 0xba1345e1, v217
	v_fmaak_f32 v88, v87, v88, 0xbcdac9b8
	v_fmaak_f32 v88, v87, v88, 0x3de703be
	v_fmaak_f32 v88, v87, v88, 0xbec09330
	v_fmaak_f32 v87, v87, v88, 0x3e0375d0
	v_fma_f32 v96, |v95|, v87, |v95|
	s_or_b64 exec, exec, s[16:17]
	v_lshlrev_b32_e32 v87, 16, v17
	v_mul_f32_e32 v87, 0x3fb8aa3b, v87
	v_exp_f32_e32 v87, v87
	v_and_b32_e32 v17, 0xffff0000, v17
	v_mul_f32_e32 v17, 0x3fb8aa3b, v17
	v_exp_f32_e32 v17, v17
	v_lshlrev_b32_e32 v88, 16, v16
	v_fmac_f32_e32 v88, v90, v87
	v_and_b32_e32 v87, 0xffff0000, v16
	v_add_f32_e32 v16, v85, v88
	v_bfi_b32 v85, s78, v93, v92
	v_fmac_f32_e32 v87, v89, v17
	v_mul_f32_e32 v17, 0.5, v91
	v_add_f32_e32 v85, 1.0, v85
	v_mul_f32_e32 v17, v17, v85
	v_mul_f32_e32 v16, v16, v17
	v_add_f32_e32 v17, v86, v87
	v_bfi_b32 v86, s78, v96, v95
	v_mul_f32_e32 v85, 0.5, v94
	v_add_f32_e32 v86, 1.0, v86
	v_mul_f32_e32 v85, v85, v86
	v_mul_f32_e32 v17, v17, v85
	s_lshl_b64 s[0:1], s[2:3], 11
	v_cvt_pk_bf16_f32 v85, v16, v17
	v_lshl_add_u64 v[16:17], v[10:11], 0, s[0:1]
	s_mov_b32 s0, 0x10000
	global_store_dword v[16:17], v85, off
	v_add_co_u32_e32 v16, vcc, s0, v12
	s_add_i32 s2, s14, 33
	s_nop 0
	v_addc_co_u32_e32 v17, vcc, 0, v13, vcc
	v_add_co_u32_e32 v90, vcc, 0x10000, v14
	s_ashr_i32 s3, s2, 31
	s_nop 0
	v_addc_co_u32_e32 v91, vcc, 0, v15, vcc
	s_lshl_b64 s[0:1], s[2:3], 12
	v_lshl_add_u64 v[90:91], v[8:9], 0, s[0:1]
	s_waitcnt vmcnt(45)
	v_mov_b32_e32 v85, v190
	v_mov_b32_e32 v89, v189
	v_mov_b32_e32 v86, v191
	s_mov_b32 s0, 0xa800
	s_mov_b32 s1, 0
	v_lshl_add_u64 v[198:199], v[12:13], 0, s[0:1]
	v_lshl_add_u64 v[200:201], v[14:15], 0, s[0:1]
	s_add_i32 s0, s14, 21
	s_ashr_i32 s1, s0, 31
	s_lshl_b64 s[0:1], s[0:1], 12
	global_load_dword v189, v[198:199], off
	global_load_dword v190, v[200:201], off
	v_lshl_add_u64 v[202:203], v[8:9], 0, s[0:1]
	global_load_dword v191, v[202:203], off
	v_lshlrev_b32_e32 v90, 16, v86
	v_mul_f32_e32 v91, 0x3f3504f3, v90
	v_cmp_nlt_f32_e64 s[0:1], |v91|, 1.0
	s_and_saveexec_b64 s[16:17], s[0:1]
	s_xor_b64 s[16:17], exec, s[16:17]
	s_cbranch_execz .LBB0_852
	v_fma_f32 v92, |v91|, s29, v223
	v_fma_f32 v92, |v91|, v92, s20
	v_fma_f32 v92, |v91|, v92, s21
	v_fma_f32 v92, |v91|, v92, s28
	v_fma_f32 v92, |v91|, v92, s33
	v_fma_f32 v92, |v91|, v92, s30
	v_fma_f32 v92, |v91|, v92, |v91|
	v_mul_f32_e32 v93, 0xbfb8aa3b, v92
	v_fma_f32 v94, v92, s31, -v93
	v_rndne_f32_e32 v95, v93
	v_fmac_f32_e32 v94, 0xb2a5705f, v92
	v_sub_f32_e32 v93, v93, v95
	v_add_f32_e32 v93, v93, v94
	v_cvt_i32_f32_e32 v94, v95
	v_exp_f32_e32 v93, v93
	v_cmp_nlt_f32_e32 vcc, s96, v92
	v_ldexp_f32 v93, v93, v94
	s_nop 0
	v_cndmask_b32_e32 v93, 0, v93, vcc
	v_cmp_ngt_f32_e32 vcc, s97, v92
	s_nop 1
	v_cndmask_b32_e32 v92, v224, v93, vcc
	v_sub_f32_e32 v92, 1.0, v92

; DEVI unsigned cvtpk(float lo, float hi) { unsigned r; asm("v_cvt_pk_bf16_f32 %0, %1, %2" : "=v"(r) : "v"(lo), "v"(hi)); return r; }
; DEVI float bflo(unsigned u) { return __uint_as_float(u << 16); }
; DEVI float bfhi(unsigned u) { return __uint_as_float(u & 0xffff0000u); }
; DEVI float geluf_(float x) { return 0.5f * x * (1.f + erff(x * 0.70710678118654752f)); }
; DEVI void lru_p3_phase(const Params& p) {
;     ...
;       for (int t = 63; t >= 0; --t) {
;         const unsigned l = *(const unsigned*)(la + (size_t)t * 1024), bv = *(const unsigned*)(bb + (size_t)t * 1024);
;         h0 = __expf(bflo(l)) * h0 + bflo(bv); h1 = __expf(bfhi(l)) * h1 + bfhi(bv);
;         const unsigned g = *(const unsigned*)(GX + (size_t)(rbase + t) * 2048 + ch);
;         *(unsigned*)(YG + (size_t)(rbase + t) * 1024 + ch) = cvtpk((s0[t] + h0) * geluf_(bflo(g)), (s1[t] + h1) * geluf_(bfhi(g)));
;       }
.LBB0_856:
	s_andn2_saveexec_b64 s[16:17], s[16:17]
	v_mul_f32_e32 v86, v94, v94
	v_fmamk_f32 v95, v86, 0xba1345e1, v217
	v_fmaak_f32 v95, v86, v95, 0xbcdac9b8
	v_fmaak_f32 v95, v86, v95, 0x3de703be
	v_fmaak_f32 v95, v86, v95, 0xbec09330
	v_fmaak_f32 v86, v86, v95, 0x3e0375d0
	v_fma_f32 v95, |v94|, v86, |v94|
	s_or_b64 exec, exec, s[16:17]
	v_lshlrev_b32_e32 v86, 16, v89
	v_mul_f32_e32 v86, 0x3fb8aa3b, v86
	v_exp_f32_e32 v96, v86
	v_lshlrev_b32_e32 v86, 16, v85
	v_and_b32_e32 v85, 0xffff0000, v85
	s_lshl_b64 s[0:1], s[2:3], 11
	v_fmac_f32_e32 v86, v88, v96
	v_and_b32_e32 v88, 0xffff0000, v89
	v_mul_f32_e32 v88, 0x3fb8aa3b, v88
	v_exp_f32_e32 v88, v88
	v_add_f32_e32 v83, v83, v86
	s_add_i32 s2, s14, 32
	s_ashr_i32 s3, s2, 31
	v_fmac_f32_e32 v85, v87, v88
	v_bfi_b32 v88, s78, v92, v91
	v_mul_f32_e32 v87, 0.5, v90
	v_add_f32_e32 v88, 1.0, v88
	v_mul_f32_e32 v87, v87, v88
	v_bfi_b32 v88, s78, v95, v94
	v_mul_f32_e32 v83, v83, v87
	v_mul_f32_e32 v87, 0.5, v93
	v_add_f32_e32 v88, 1.0, v88
	v_add_f32_e32 v84, v84, v85
	v_mul_f32_e32 v87, v87, v88
	v_lshl_add_u64 v[88:89], v[10:11], 0, s[0:1]
	v_mul_f32_e32 v84, v84, v87
	v_cvt_pk_bf16_f32 v83, v83, v84
	global_store_dword v[88:89], v83, off
	v_add_co_u32_e32 v88, vcc, 0x10000, v14
	s_lshl_b64 s[0:1], s[2:3], 12
	s_nop 0
	v_addc_co_u32_e32 v89, vcc, 0, v15, vcc
	s_nop 0
	v_lshl_add_u64 v[88:89], v[8:9], 0, s[0:1]
	s_waitcnt vmcnt(45)
	v_mov_b32_e32 v17, v186
	v_mov_b32_e32 v16, v187
	v_mov_b32_e32 v83, v188
	s_mov_b32 s0, 0xa000
	s_mov_b32 s1, 0
	v_lshl_add_u64 v[198:199], v[12:13], 0, s[0:1]
	v_lshl_add_u64 v[200:201], v[14:15], 0, s[0:1]
	s_add_i32 s0, s14, 20
	s_ashr_i32 s1, s0, 31
	s_lshl_b64 s[0:1], s[0:1], 12
	global_load_dword v186, v[198:199], off
	global_load_dword v187, v[200:201], off
	v_lshl_add_u64 v[202:203], v[8:9], 0, s[0:1]
	global_load_dword v188, v[202:203], off
	v_lshlrev_b32_e32 v87, 16, v83
	v_mul_f32_e32 v88, 0x3f3504f3, v87
	v_cmp_nlt_f32_e64 s[0:1], |v88|, 1.0
	s_and_saveexec_b64 s[16:17], s[0:1]
	s_xor_b64 s[16:17], exec, s[16:17]
	s_cbranch_execz .LBB0_860
	v_fma_f32 v84, |v88|, s29, v223
	v_fma_f32 v84, |v88|, v84, s20
	v_fma_f32 v84, |v88|, v84, s21
	v_fma_f32 v84, |v88|, v84, s28
	v_fma_f32 v84, |v88|, v84, s33
	v_fma_f32 v84, |v88|, v84, s30
	v_fma_f32 v84, |v88|, v84, |v88|
	v_mul_f32_e32 v89, 0xbfb8aa3b, v84
	v_fma_f32 v90, v84, s31, -v89
	v_rndne_f32_e32 v91, v89
	v_fmac_f32_e32 v90, 0xb2a5705f, v84
	v_sub_f32_e32 v89, v89, v91
	v_add_f32_e32 v89, v89, v90
	v_cvt_i32_f32_e32 v90, v91
	v_exp_f32_e32 v89, v89
	v_cmp_nlt_f32_e32 vcc, s96, v84
	v_ldexp_f32 v89, v89, v90
	s_nop 0
	v_cndmask_b32_e32 v89, 0, v89, vcc
	v_cmp_ngt_f32_e32 vcc, s97, v84
	s_nop 1
	v_cndmask_b32_e32 v84, v224, v89, vcc
	v_sub_f32_e32 v89, 1.0, v84

; DEVI unsigned cvtpk(float lo, float hi) { unsigned r; asm("v_cvt_pk_bf16_f32 %0, %1, %2" : "=v"(r) : "v"(lo), "v"(hi)); return r; }
; DEVI float bflo(unsigned u) { return __uint_as_float(u << 16); }
; DEVI float bfhi(unsigned u) { return __uint_as_float(u & 0xffff0000u); }
; DEVI float geluf_(float x) { return 0.5f * x * (1.f + erff(x * 0.70710678118654752f)); }
; DEVI void lru_p3_phase(const Params& p) {
;     ...
;       for (int t = 63; t >= 0; --t) {
;         const unsigned l = *(const unsigned*)(la + (size_t)t * 1024), bv = *(const unsigned*)(bb + (size_t)t * 1024);
;         h0 = __expf(bflo(l)) * h0 + bflo(bv); h1 = __expf(bfhi(l)) * h1 + bfhi(bv);
;         const unsigned g = *(const unsigned*)(GX + (size_t)(rbase + t) * 2048 + ch);
;         *(unsigned*)(YG + (size_t)(rbase + t) * 1024 + ch) = cvtpk((s0[t] + h0) * geluf_(bflo(g)), (s1[t] + h1) * geluf_(bfhi(g)));
;       }
.LBB0_864:
	s_andn2_saveexec_b64 s[16:17], s[16:17]
	v_mul_f32_e32 v83, v91, v91
	v_fmamk_f32 v84, v83, 0xba1345e1, v217
	v_fmaak_f32 v84, v83, v84, 0xbcdac9b8
	v_fmaak_f32 v84, v83, v84, 0x3de703be
	v_fmaak_f32 v84, v83, v84, 0xbec09330
	v_fmaak_f32 v83, v83, v84, 0x3e0375d0
	v_fma_f32 v92, |v91|, v83, |v91|
	s_or_b64 exec, exec, s[16:17]
	v_lshlrev_b32_e32 v83, 16, v17
	v_mul_f32_e32 v83, 0x3fb8aa3b, v83
	v_exp_f32_e32 v83, v83
	v_and_b32_e32 v17, 0xffff0000, v17
	v_mul_f32_e32 v17, 0x3fb8aa3b, v17
	v_exp_f32_e32 v17, v17
	v_lshlrev_b32_e32 v84, 16, v16
	v_fmac_f32_e32 v84, v86, v83
	v_and_b32_e32 v83, 0xffff0000, v16
	v_add_f32_e32 v16, v81, v84
	v_bfi_b32 v81, s78, v89, v88
	v_fmac_f32_e32 v83, v85, v17
	v_mul_f32_e32 v17, 0.5, v87
	v_add_f32_e32 v81, 1.0, v81
	v_mul_f32_e32 v17, v17, v81
	v_mul_f32_e32 v16, v16, v17
	v_add_f32_e32 v17, v82, v83
	v_bfi_b32 v82, s78, v92, v91
	v_mul_f32_e32 v81, 0.5, v90
	v_add_f32_e32 v82, 1.0, v82
	v_mul_f32_e32 v81, v81, v82
	v_mul_f32_e32 v17, v17, v81
	s_lshl_b64 s[0:1], s[2:3], 11
	v_cvt_pk_bf16_f32 v81, v16, v17
	v_lshl_add_u64 v[16:17], v[10:11], 0, s[0:1]
	global_store_dword v[16:17], v81, off
	v_add_co_u32_e32 v16, vcc, s54, v12
	s_add_i32 s2, s14, 31
	s_nop 0
	v_addc_co_u32_e32 v17, vcc, 0, v13, vcc
	v_add_co_u32_e32 v86, vcc, 0xf000, v14
	s_ashr_i32 s3, s2, 31
	s_nop 0
	v_addc_co_u32_e32 v87, vcc, 0, v15, vcc
	s_lshl_b64 s[0:1], s[2:3], 12
	v_lshl_add_u64 v[86:87], v[8:9], 0, s[0:1]
	s_waitcnt vmcnt(45)
	v_mov_b32_e32 v81, v184
	v_mov_b32_e32 v85, v183
	v_mov_b32_e32 v82, v185
	s_mov_b32 s0, 0x9800
	s_mov_b32 s1, 0
	v_lshl_add_u64 v[198:199], v[12:13], 0, s[0:1]
	v_lshl_add_u64 v[200:201], v[14:15], 0, s[0:1]
	s_add_i32 s0, s14, 19
	s_ashr_i32 s1, s0, 31
	s_lshl_b64 s[0:1], s[0:1], 12
	global_load_dword v183, v[198:199], off
	global_load_dword v184, v[200:201], off
	v_lshl_add_u64 v[202:203], v[8:9], 0, s[0:1]
	global_load_dword v185, v[202:203], off
	v_lshlrev_b32_e32 v86, 16, v82
	v_mul_f32_e32 v87, 0x3f3504f3, v86
	v_cmp_nlt_f32_e64 s[0:1], |v87|, 1.0
	s_and_saveexec_b64 s[16:17], s[0:1]
	s_xor_b64 s[16:17], exec, s[16:17]
	s_cbranch_execz .LBB0_868
	v_fma_f32 v88, |v87|, s29, v223
	v_fma_f32 v88, |v87|, v88, s20
	v_fma_f32 v88, |v87|, v88, s21
	v_fma_f32 v88, |v87|, v88, s28
	v_fma_f32 v88, |v87|, v88, s33
	v_fma_f32 v88, |v87|, v88, s30
	v_fma_f32 v88, |v87|, v88, |v87|
	v_mul_f32_e32 v89, 0xbfb8aa3b, v88
	v_fma_f32 v90, v88, s31, -v89
	v_rndne_f32_e32 v91, v89
	v_fmac_f32_e32 v90, 0xb2a5705f, v88
	v_sub_f32_e32 v89, v89, v91
	v_add_f32_e32 v89, v89, v90
	v_cvt_i32_f32_e32 v90, v91
	v_exp_f32_e32 v89, v89
	v_cmp_nlt_f32_e32 vcc, s96, v88
	v_ldexp_f32 v89, v89, v90
	s_nop 0
	v_cndmask_b32_e32 v89, 0, v89, vcc
	v_cmp_ngt_f32_e32 vcc, s97, v88
	s_nop 1
	v_cndmask_b32_e32 v88, v224, v89, vcc
	v_sub_f32_e32 v88, 1.0, v88

; DEVI unsigned cvtpk(float lo, float hi) { unsigned r; asm("v_cvt_pk_bf16_f32 %0, %1, %2" : "=v"(r) : "v"(lo), "v"(hi)); return r; }
; DEVI float bflo(unsigned u) { return __uint_as_float(u << 16); }
; DEVI float bfhi(unsigned u) { return __uint_as_float(u & 0xffff0000u); }
; DEVI float geluf_(float x) { return 0.5f * x * (1.f + erff(x * 0.70710678118654752f)); }
; DEVI void lru_p3_phase(const Params& p) {
;     ...
;       for (int t = 63; t >= 0; --t) {
;         const unsigned l = *(const unsigned*)(la + (size_t)t * 1024), bv = *(const unsigned*)(bb + (size_t)t * 1024);
;         h0 = __expf(bflo(l)) * h0 + bflo(bv); h1 = __expf(bfhi(l)) * h1 + bfhi(bv);
;         const unsigned g = *(const unsigned*)(GX + (size_t)(rbase + t) * 2048 + ch);
;         *(unsigned*)(YG + (size_t)(rbase + t) * 1024 + ch) = cvtpk((s0[t] + h0) * geluf_(bflo(g)), (s1[t] + h1) * geluf_(bfhi(g)));
;       }
.LBB0_872:
	s_andn2_saveexec_b64 s[16:17], s[16:17]
	v_mul_f32_e32 v82, v90, v90
	v_fmamk_f32 v91, v82, 0xba1345e1, v217
	v_fmaak_f32 v91, v82, v91, 0xbcdac9b8
	v_fmaak_f32 v91, v82, v91, 0x3de703be
	v_fmaak_f32 v91, v82, v91, 0xbec09330
	v_fmaak_f32 v82, v82, v91, 0x3e0375d0
	v_fma_f32 v91, |v90|, v82, |v90|
	s_or_b64 exec, exec, s[16:17]
	v_lshlrev_b32_e32 v82, 16, v85
	v_mul_f32_e32 v82, 0x3fb8aa3b, v82
	v_exp_f32_e32 v92, v82
	v_lshlrev_b32_e32 v82, 16, v81
	v_and_b32_e32 v81, 0xffff0000, v81
	s_lshl_b64 s[0:1], s[2:3], 11
	v_fmac_f32_e32 v82, v84, v92
	v_and_b32_e32 v84, 0xffff0000, v85
	v_mul_f32_e32 v84, 0x3fb8aa3b, v84
	v_exp_f32_e32 v84, v84
	v_add_f32_e32 v79, v79, v82
	s_add_i32 s2, s14, 30
	s_ashr_i32 s3, s2, 31
	v_fmac_f32_e32 v81, v83, v84
	v_bfi_b32 v84, s78, v88, v87
	v_mul_f32_e32 v83, 0.5, v86
	v_add_f32_e32 v84, 1.0, v84
	v_mul_f32_e32 v83, v83, v84
	v_bfi_b32 v84, s78, v91, v90
	v_mul_f32_e32 v79, v79, v83
	v_mul_f32_e32 v83, 0.5, v89
	v_add_f32_e32 v84, 1.0, v84
	v_add_f32_e32 v80, v80, v81
	v_mul_f32_e32 v83, v83, v84
	v_lshl_add_u64 v[84:85], v[10:11], 0, s[0:1]
	v_mul_f32_e32 v80, v80, v83
	v_cvt_pk_bf16_f32 v79, v79, v80
	global_store_dword v[84:85], v79, off
	v_add_co_u32_e32 v84, vcc, 0xf000, v14
	s_lshl_b64 s[0:1], s[2:3], 12
	s_nop 0
	v_addc_co_u32_e32 v85, vcc, 0, v15, vcc
	s_nop 0
	v_lshl_add_u64 v[84:85], v[8:9], 0, s[0:1]
	s_waitcnt vmcnt(45)
	v_mov_b32_e32 v17, v180
	v_mov_b32_e32 v16, v181
	v_mov_b32_e32 v79, v182
	s_mov_b32 s0, 0x9000
	s_mov_b32 s1, 0
	v_lshl_add_u64 v[198:199], v[12:13], 0, s[0:1]
	v_lshl_add_u64 v[200:201], v[14:15], 0, s[0:1]
	s_add_i32 s0, s14, 18
	s_ashr_i32 s1, s0, 31
	s_lshl_b64 s[0:1], s[0:1], 12
	global_load_dword v180, v[198:199], off
	global_load_dword v181, v[200:201], off
	v_lshl_add_u64 v[202:203], v[8:9], 0, s[0:1]
	global_load_dword v182, v[202:203], off
	v_lshlrev_b32_e32 v83, 16, v79
	v_mul_f32_e32 v84, 0x3f3504f3, v83
	v_cmp_nlt_f32_e64 s[0:1], |v84|, 1.0
	s_and_saveexec_b64 s[16:17], s[0:1]
	s_xor_b64 s[16:17], exec, s[16:17]
	s_cbranch_execz .LBB0_876
	v_fma_f32 v80, |v84|, s29, v223
	v_fma_f32 v80, |v84|, v80, s20
	v_fma_f32 v80, |v84|, v80, s21
	v_fma_f32 v80, |v84|, v80, s28
	v_fma_f32 v80, |v84|, v80, s33
	v_fma_f32 v80, |v84|, v80, s30
	v_fma_f32 v80, |v84|, v80, |v84|
	v_mul_f32_e32 v85, 0xbfb8aa3b, v80
	v_fma_f32 v86, v80, s31, -v85
	v_rndne_f32_e32 v87, v85
	v_fmac_f32_e32 v86, 0xb2a5705f, v80
	v_sub_f32_e32 v85, v85, v87
	v_add_f32_e32 v85, v85, v86
	v_cvt_i32_f32_e32 v86, v87
	v_exp_f32_e32 v85, v85
	v_cmp_nlt_f32_e32 vcc, s96, v80
	v_ldexp_f32 v85, v85, v86
	s_nop 0
	v_cndmask_b32_e32 v85, 0, v85, vcc
	v_cmp_ngt_f32_e32 vcc, s97, v80
	s_nop 1
	v_cndmask_b32_e32 v80, v224, v85, vcc
	v_sub_f32_e32 v85, 1.0, v80

; DEVI unsigned cvtpk(float lo, float hi) { unsigned r; asm("v_cvt_pk_bf16_f32 %0, %1, %2" : "=v"(r) : "v"(lo), "v"(hi)); return r; }
; DEVI float bflo(unsigned u) { return __uint_as_float(u << 16); }
; DEVI float bfhi(unsigned u) { return __uint_as_float(u & 0xffff0000u); }
; DEVI float geluf_(float x) { return 0.5f * x * (1.f + erff(x * 0.70710678118654752f)); }
; DEVI void lru_p3_phase(const Params& p) {
;     ...
;       for (int t = 63; t >= 0; --t) {
;         const unsigned l = *(const unsigned*)(la + (size_t)t * 1024), bv = *(const unsigned*)(bb + (size_t)t * 1024);
;         h0 = __expf(bflo(l)) * h0 + bflo(bv); h1 = __expf(bfhi(l)) * h1 + bfhi(bv);
;         const unsigned g = *(const unsigned*)(GX + (size_t)(rbase + t) * 2048 + ch);
;         *(unsigned*)(YG + (size_t)(rbase + t) * 1024 + ch) = cvtpk((s0[t] + h0) * geluf_(bflo(g)), (s1[t] + h1) * geluf_(bfhi(g)));
;       }
.LBB0_880:
	s_andn2_saveexec_b64 s[16:17], s[16:17]
	v_mul_f32_e32 v79, v87, v87
	v_fmamk_f32 v80, v79, 0xba1345e1, v217
	v_fmaak_f32 v80, v79, v80, 0xbcdac9b8
	v_fmaak_f32 v80, v79, v80, 0x3de703be
	v_fmaak_f32 v80, v79, v80, 0xbec09330
	v_fmaak_f32 v79, v79, v80, 0x3e0375d0
	v_fma_f32 v88, |v87|, v79, |v87|
	s_or_b64 exec, exec, s[16:17]
	v_lshlrev_b32_e32 v79, 16, v17
	v_mul_f32_e32 v79, 0x3fb8aa3b, v79
	v_exp_f32_e32 v79, v79
	v_and_b32_e32 v17, 0xffff0000, v17
	v_mul_f32_e32 v17, 0x3fb8aa3b, v17
	v_exp_f32_e32 v17, v17
	v_lshlrev_b32_e32 v80, 16, v16
	v_fmac_f32_e32 v80, v82, v79
	v_and_b32_e32 v79, 0xffff0000, v16
	v_add_f32_e32 v16, v77, v80
	v_bfi_b32 v77, s78, v85, v84
	v_fmac_f32_e32 v79, v81, v17
	v_mul_f32_e32 v17, 0.5, v83
	v_add_f32_e32 v77, 1.0, v77
	v_mul_f32_e32 v17, v17, v77
	v_mul_f32_e32 v16, v16, v17
	v_add_f32_e32 v17, v78, v79
	v_bfi_b32 v78, s78, v88, v87
	v_mul_f32_e32 v77, 0.5, v86
	v_add_f32_e32 v78, 1.0, v78
	v_mul_f32_e32 v77, v77, v78
	v_mul_f32_e32 v17, v17, v77
	s_lshl_b64 s[0:1], s[2:3], 11
	v_cvt_pk_bf16_f32 v77, v16, v17
	v_lshl_add_u64 v[16:17], v[10:11], 0, s[0:1]
	global_store_dword v[16:17], v77, off
	v_add_co_u32_e32 v16, vcc, s49, v12
	s_add_i32 s2, s14, 29
	s_nop 0
	v_addc_co_u32_e32 v17, vcc, 0, v13, vcc
	v_add_co_u32_e32 v82, vcc, 0xe000, v14
	s_ashr_i32 s3, s2, 31
	s_nop 0
	v_addc_co_u32_e32 v83, vcc, 0, v15, vcc
	s_lshl_b64 s[0:1], s[2:3], 12
	v_lshl_add_u64 v[82:83], v[8:9], 0, s[0:1]
	s_waitcnt vmcnt(45)
	v_mov_b32_e32 v77, v176
	v_mov_b32_e32 v81, v175
	v_mov_b32_e32 v78, v177
	s_mov_b32 s0, 0x8800
	s_mov_b32 s1, 0
	v_lshl_add_u64 v[198:199], v[12:13], 0, s[0:1]
	v_lshl_add_u64 v[200:201], v[14:15], 0, s[0:1]
	s_add_i32 s0, s14, 17
	s_ashr_i32 s1, s0, 31
	s_lshl_b64 s[0:1], s[0:1], 12
	global_load_dword v175, v[198:199], off
	global_load_dword v176, v[200:201], off
	v_lshl_add_u64 v[202:203], v[8:9], 0, s[0:1]
	global_load_dword v177, v[202:203], off
	v_lshlrev_b32_e32 v82, 16, v78
	v_mul_f32_e32 v83, 0x3f3504f3, v82
	v_cmp_nlt_f32_e64 s[0:1], |v83|, 1.0
	s_and_saveexec_b64 s[16:17], s[0:1]
	s_xor_b64 s[16:17], exec, s[16:17]
	s_cbranch_execz .LBB0_884
	v_fma_f32 v84, |v83|, s29, v223
	v_fma_f32 v84, |v83|, v84, s20
	v_fma_f32 v84, |v83|, v84, s21
	v_fma_f32 v84, |v83|, v84, s28
	v_fma_f32 v84, |v83|, v84, s33
	v_fma_f32 v84, |v83|, v84, s30
	v_fma_f32 v84, |v83|, v84, |v83|
	v_mul_f32_e32 v85, 0xbfb8aa3b, v84
	v_fma_f32 v86, v84, s31, -v85
	v_rndne_f32_e32 v87, v85
	v_fmac_f32_e32 v86, 0xb2a5705f, v84
	v_sub_f32_e32 v85, v85, v87
	v_add_f32_e32 v85, v85, v86
	v_cvt_i32_f32_e32 v86, v87
	v_exp_f32_e32 v85, v85
	v_cmp_nlt_f32_e32 vcc, s96, v84
	v_ldexp_f32 v85, v85, v86
	s_nop 0
	v_cndmask_b32_e32 v85, 0, v85, vcc
	v_cmp_ngt_f32_e32 vcc, s97, v84
	s_nop 1
	v_cndmask_b32_e32 v84, v224, v85, vcc
	v_sub_f32_e32 v84, 1.0, v84

; DEVI unsigned cvtpk(float lo, float hi) { unsigned r; asm("v_cvt_pk_bf16_f32 %0, %1, %2" : "=v"(r) : "v"(lo), "v"(hi)); return r; }
; DEVI float bflo(unsigned u) { return __uint_as_float(u << 16); }
; DEVI float bfhi(unsigned u) { return __uint_as_float(u & 0xffff0000u); }
; DEVI float geluf_(float x) { return 0.5f * x * (1.f + erff(x * 0.70710678118654752f)); }
; DEVI void lru_p3_phase(const Params& p) {
;     ...
;       for (int t = 63; t >= 0; --t) {
;         const unsigned l = *(const unsigned*)(la + (size_t)t * 1024), bv = *(const unsigned*)(bb + (size_t)t * 1024);
;         h0 = __expf(bflo(l)) * h0 + bflo(bv); h1 = __expf(bfhi(l)) * h1 + bfhi(bv);
;         const unsigned g = *(const unsigned*)(GX + (size_t)(rbase + t) * 2048 + ch);
;         *(unsigned*)(YG + (size_t)(rbase + t) * 1024 + ch) = cvtpk((s0[t] + h0) * geluf_(bflo(g)), (s1[t] + h1) * geluf_(bfhi(g)));
;       }
.LBB0_888:
	s_andn2_saveexec_b64 s[16:17], s[16:17]
	v_mul_f32_e32 v78, v86, v86
	v_fmamk_f32 v87, v78, 0xba1345e1, v217
	v_fmaak_f32 v87, v78, v87, 0xbcdac9b8
	v_fmaak_f32 v87, v78, v87, 0x3de703be
	v_fmaak_f32 v87, v78, v87, 0xbec09330
	v_fmaak_f32 v78, v78, v87, 0x3e0375d0
	v_fma_f32 v87, |v86|, v78, |v86|
	s_or_b64 exec, exec, s[16:17]
	v_lshlrev_b32_e32 v78, 16, v81
	v_mul_f32_e32 v78, 0x3fb8aa3b, v78
	v_exp_f32_e32 v88, v78
	v_lshlrev_b32_e32 v78, 16, v77
	v_and_b32_e32 v77, 0xffff0000, v77
	s_lshl_b64 s[0:1], s[2:3], 11
	v_fmac_f32_e32 v78, v80, v88
	v_and_b32_e32 v80, 0xffff0000, v81
	v_mul_f32_e32 v80, 0x3fb8aa3b, v80
	v_exp_f32_e32 v80, v80
	v_add_f32_e32 v75, v75, v78
	s_add_i32 s2, s14, 28
	s_ashr_i32 s3, s2, 31
	v_fmac_f32_e32 v77, v79, v80
	v_bfi_b32 v80, s78, v84, v83
	v_mul_f32_e32 v79, 0.5, v82
	v_add_f32_e32 v80, 1.0, v80
	v_mul_f32_e32 v79, v79, v80
	v_bfi_b32 v80, s78, v87, v86
	v_mul_f32_e32 v75, v75, v79
	v_mul_f32_e32 v79, 0.5, v85
	v_add_f32_e32 v80, 1.0, v80
	v_add_f32_e32 v76, v76, v77
	v_mul_f32_e32 v79, v79, v80
	v_lshl_add_u64 v[80:81], v[10:11], 0, s[0:1]
	v_mul_f32_e32 v76, v76, v79
	v_cvt_pk_bf16_f32 v75, v75, v76
	global_store_dword v[80:81], v75, off
	v_add_co_u32_e32 v80, vcc, 0xe000, v14
	s_lshl_b64 s[0:1], s[2:3], 12
	s_nop 0
	v_addc_co_u32_e32 v81, vcc, 0, v15, vcc
	s_nop 0
	v_lshl_add_u64 v[80:81], v[8:9], 0, s[0:1]
	s_waitcnt vmcnt(45)
	v_mov_b32_e32 v17, v172
	v_mov_b32_e32 v16, v173
	v_mov_b32_e32 v75, v174
	s_mov_b32 s0, 0x8000
	s_mov_b32 s1, 0
	v_lshl_add_u64 v[198:199], v[12:13], 0, s[0:1]
	v_lshl_add_u64 v[200:201], v[14:15], 0, s[0:1]
	s_add_i32 s0, s14, 16
	s_ashr_i32 s1, s0, 31
	s_lshl_b64 s[0:1], s[0:1], 12
	global_load_dword v172, v[198:199], off
	global_load_dword v173, v[200:201], off
	v_lshl_add_u64 v[202:203], v[8:9], 0, s[0:1]
	global_load_dword v174, v[202:203], off
	v_lshlrev_b32_e32 v79, 16, v75
	v_mul_f32_e32 v80, 0x3f3504f3, v79
	v_cmp_nlt_f32_e64 s[0:1], |v80|, 1.0
	s_and_saveexec_b64 s[16:17], s[0:1]
	s_xor_b64 s[16:17], exec, s[16:17]
	s_cbranch_execz .LBB0_892
	v_fma_f32 v76, |v80|, s29, v223
	v_fma_f32 v76, |v80|, v76, s20
	v_fma_f32 v76, |v80|, v76, s21
	v_fma_f32 v76, |v80|, v76, s28
	v_fma_f32 v76, |v80|, v76, s33
	v_fma_f32 v76, |v80|, v76, s30
	v_fma_f32 v76, |v80|, v76, |v80|
	v_mul_f32_e32 v81, 0xbfb8aa3b, v76
	v_fma_f32 v82, v76, s31, -v81
	v_rndne_f32_e32 v83, v81
	v_fmac_f32_e32 v82, 0xb2a5705f, v76
	v_sub_f32_e32 v81, v81, v83
	v_add_f32_e32 v81, v81, v82
	v_cvt_i32_f32_e32 v82, v83
	v_exp_f32_e32 v81, v81
	v_cmp_nlt_f32_e32 vcc, s96, v76
	v_ldexp_f32 v81, v81, v82
	s_nop 0
	v_cndmask_b32_e32 v81, 0, v81, vcc
	v_cmp_ngt_f32_e32 vcc, s97, v76
	s_nop 1
	v_cndmask_b32_e32 v76, v224, v81, vcc
	v_sub_f32_e32 v81, 1.0, v76

; DEVI unsigned cvtpk(float lo, float hi) { unsigned r; asm("v_cvt_pk_bf16_f32 %0, %1, %2" : "=v"(r) : "v"(lo), "v"(hi)); return r; }
; DEVI float bflo(unsigned u) { return __uint_as_float(u << 16); }
; DEVI float bfhi(unsigned u) { return __uint_as_float(u & 0xffff0000u); }
; DEVI float geluf_(float x) { return 0.5f * x * (1.f + erff(x * 0.70710678118654752f)); }
; DEVI void lru_p3_phase(const Params& p) {
;     ...
;       for (int t = 63; t >= 0; --t) {
;         const unsigned l = *(const unsigned*)(la + (size_t)t * 1024), bv = *(const unsigned*)(bb + (size_t)t * 1024);
;         h0 = __expf(bflo(l)) * h0 + bflo(bv); h1 = __expf(bfhi(l)) * h1 + bfhi(bv);
;         const unsigned g = *(const unsigned*)(GX + (size_t)(rbase + t) * 2048 + ch);
;         *(unsigned*)(YG + (size_t)(rbase + t) * 1024 + ch) = cvtpk((s0[t] + h0) * geluf_(bflo(g)), (s1[t] + h1) * geluf_(bfhi(g)));
;       }
.LBB0_896:
	s_andn2_saveexec_b64 s[16:17], s[16:17]
	v_mul_f32_e32 v75, v83, v83
	v_fmamk_f32 v76, v75, 0xba1345e1, v217
	v_fmaak_f32 v76, v75, v76, 0xbcdac9b8
	v_fmaak_f32 v76, v75, v76, 0x3de703be
	v_fmaak_f32 v76, v75, v76, 0xbec09330
	v_fmaak_f32 v75, v75, v76, 0x3e0375d0
	v_fma_f32 v84, |v83|, v75, |v83|
	s_or_b64 exec, exec, s[16:17]
	v_lshlrev_b32_e32 v75, 16, v17
	v_mul_f32_e32 v75, 0x3fb8aa3b, v75
	v_exp_f32_e32 v75, v75
	v_and_b32_e32 v17, 0xffff0000, v17
	v_mul_f32_e32 v17, 0x3fb8aa3b, v17
	v_exp_f32_e32 v17, v17
	v_lshlrev_b32_e32 v76, 16, v16
	v_fmac_f32_e32 v76, v78, v75
	v_and_b32_e32 v75, 0xffff0000, v16
	v_add_f32_e32 v16, v73, v76
	v_bfi_b32 v73, s78, v81, v80
	v_fmac_f32_e32 v75, v77, v17
	v_mul_f32_e32 v17, 0.5, v79
	v_add_f32_e32 v73, 1.0, v73
	v_mul_f32_e32 v17, v17, v73
	v_mul_f32_e32 v16, v16, v17
	v_add_f32_e32 v17, v74, v75
	v_bfi_b32 v74, s78, v84, v83
	v_mul_f32_e32 v73, 0.5, v82
	v_add_f32_e32 v74, 1.0, v74
	v_mul_f32_e32 v73, v73, v74
	v_mul_f32_e32 v17, v17, v73
	s_lshl_b64 s[0:1], s[2:3], 11
	v_cvt_pk_bf16_f32 v73, v16, v17
	v_lshl_add_u64 v[16:17], v[10:11], 0, s[0:1]
	global_store_dword v[16:17], v73, off
	v_add_co_u32_e32 v16, vcc, s48, v12
	s_add_i32 s2, s14, 27
	s_nop 0
	v_addc_co_u32_e32 v17, vcc, 0, v13, vcc
	v_add_co_u32_e32 v78, vcc, 0xd000, v14
	s_ashr_i32 s3, s2, 31
	s_nop 0
	v_addc_co_u32_e32 v79, vcc, 0, v15, vcc
	s_lshl_b64 s[0:1], s[2:3], 12
	v_lshl_add_u64 v[78:79], v[8:9], 0, s[0:1]
	s_waitcnt vmcnt(45)
	v_mov_b32_e32 v73, v170
	v_mov_b32_e32 v77, v169
	v_mov_b32_e32 v74, v171
	s_mov_b32 s0, 0x7800
	s_mov_b32 s1, 0
	v_lshl_add_u64 v[198:199], v[12:13], 0, s[0:1]
	v_lshl_add_u64 v[200:201], v[14:15], 0, s[0:1]
	s_add_i32 s0, s14, 15
	s_ashr_i32 s1, s0, 31
	s_lshl_b64 s[0:1], s[0:1], 12
	global_load_dword v169, v[198:199], off
	global_load_dword v170, v[200:201], off
	v_lshl_add_u64 v[202:203], v[8:9], 0, s[0:1]
	global_load_dword v171, v[202:203], off
	v_lshlrev_b32_e32 v78, 16, v74
	v_mul_f32_e32 v79, 0x3f3504f3, v78
	v_cmp_nlt_f32_e64 s[0:1], |v79|, 1.0
	s_and_saveexec_b64 s[16:17], s[0:1]
	s_xor_b64 s[16:17], exec, s[16:17]
	s_cbranch_execz .LBB0_900
	v_fma_f32 v80, |v79|, s29, v223
	v_fma_f32 v80, |v79|, v80, s20
	v_fma_f32 v80, |v79|, v80, s21
	v_fma_f32 v80, |v79|, v80, s28
	v_fma_f32 v80, |v79|, v80, s33
	v_fma_f32 v80, |v79|, v80, s30
	v_fma_f32 v80, |v79|, v80, |v79|
	v_mul_f32_e32 v81, 0xbfb8aa3b, v80
	v_fma_f32 v82, v80, s31, -v81
	v_rndne_f32_e32 v83, v81
	v_fmac_f32_e32 v82, 0xb2a5705f, v80
	v_sub_f32_e32 v81, v81, v83
	v_add_f32_e32 v81, v81, v82
	v_cvt_i32_f32_e32 v82, v83
	v_exp_f32_e32 v81, v81
	v_cmp_nlt_f32_e32 vcc, s96, v80
	v_ldexp_f32 v81, v81, v82
	s_nop 0
	v_cndmask_b32_e32 v81, 0, v81, vcc
	v_cmp_ngt_f32_e32 vcc, s97, v80
	s_nop 1
	v_cndmask_b32_e32 v80, v224, v81, vcc
	v_sub_f32_e32 v80, 1.0, v80

; DEVI unsigned cvtpk(float lo, float hi) { unsigned r; asm("v_cvt_pk_bf16_f32 %0, %1, %2" : "=v"(r) : "v"(lo), "v"(hi)); return r; }
; DEVI float bflo(unsigned u) { return __uint_as_float(u << 16); }
; DEVI float bfhi(unsigned u) { return __uint_as_float(u & 0xffff0000u); }
; DEVI float geluf_(float x) { return 0.5f * x * (1.f + erff(x * 0.70710678118654752f)); }
; DEVI void lru_p3_phase(const Params& p) {
;     ...
;       for (int t = 63; t >= 0; --t) {
;         const unsigned l = *(const unsigned*)(la + (size_t)t * 1024), bv = *(const unsigned*)(bb + (size_t)t * 1024);
;         h0 = __expf(bflo(l)) * h0 + bflo(bv); h1 = __expf(bfhi(l)) * h1 + bfhi(bv);
;         const unsigned g = *(const unsigned*)(GX + (size_t)(rbase + t) * 2048 + ch);
;         *(unsigned*)(YG + (size_t)(rbase + t) * 1024 + ch) = cvtpk((s0[t] + h0) * geluf_(bflo(g)), (s1[t] + h1) * geluf_(bfhi(g)));
;       }
.LBB0_904:
	s_andn2_saveexec_b64 s[16:17], s[16:17]
	v_mul_f32_e32 v74, v82, v82
	v_fmamk_f32 v83, v74, 0xba1345e1, v217
	v_fmaak_f32 v83, v74, v83, 0xbcdac9b8
	v_fmaak_f32 v83, v74, v83, 0x3de703be
	v_fmaak_f32 v83, v74, v83, 0xbec09330
	v_fmaak_f32 v74, v74, v83, 0x3e0375d0
	v_fma_f32 v83, |v82|, v74, |v82|
	s_or_b64 exec, exec, s[16:17]
	v_lshlrev_b32_e32 v74, 16, v77
	v_mul_f32_e32 v74, 0x3fb8aa3b, v74
	v_exp_f32_e32 v84, v74
	v_lshlrev_b32_e32 v74, 16, v73
	v_and_b32_e32 v73, 0xffff0000, v73
	s_lshl_b64 s[0:1], s[2:3], 11
	v_fmac_f32_e32 v74, v76, v84
	v_and_b32_e32 v76, 0xffff0000, v77
	v_mul_f32_e32 v76, 0x3fb8aa3b, v76
	v_exp_f32_e32 v76, v76
	v_add_f32_e32 v71, v71, v74
	s_add_i32 s2, s14, 26
	s_ashr_i32 s3, s2, 31
	v_fmac_f32_e32 v73, v75, v76
	v_bfi_b32 v76, s78, v80, v79
	v_mul_f32_e32 v75, 0.5, v78
	v_add_f32_e32 v76, 1.0, v76
	v_mul_f32_e32 v75, v75, v76
	v_bfi_b32 v76, s78, v83, v82
	v_mul_f32_e32 v71, v71, v75
	v_mul_f32_e32 v75, 0.5, v81
	v_add_f32_e32 v76, 1.0, v76
	v_add_f32_e32 v72, v72, v73
	v_mul_f32_e32 v75, v75, v76
	v_lshl_add_u64 v[76:77], v[10:11], 0, s[0:1]
	v_mul_f32_e32 v72, v72, v75
	v_cvt_pk_bf16_f32 v71, v71, v72
	global_store_dword v[76:77], v71, off
	v_add_co_u32_e32 v76, vcc, 0xd000, v14
	s_lshl_b64 s[0:1], s[2:3], 12
	s_nop 0
	v_addc_co_u32_e32 v77, vcc, 0, v15, vcc
	s_nop 0
	v_lshl_add_u64 v[76:77], v[8:9], 0, s[0:1]
	s_waitcnt vmcnt(45)
	v_mov_b32_e32 v17, v166
	v_mov_b32_e32 v16, v167
	v_mov_b32_e32 v71, v168
	s_mov_b32 s0, 0x7000
	s_mov_b32 s1, 0
	v_lshl_add_u64 v[198:199], v[12:13], 0, s[0:1]
	v_lshl_add_u64 v[200:201], v[14:15], 0, s[0:1]
	s_add_i32 s0, s14, 14
	s_ashr_i32 s1, s0, 31
	s_lshl_b64 s[0:1], s[0:1], 12
	global_load_dword v166, v[198:199], off
	global_load_dword v167, v[200:201], off
	v_lshl_add_u64 v[202:203], v[8:9], 0, s[0:1]
	global_load_dword v168, v[202:203], off
	v_lshlrev_b32_e32 v75, 16, v71
	v_mul_f32_e32 v76, 0x3f3504f3, v75
	v_cmp_nlt_f32_e64 s[0:1], |v76|, 1.0
	s_and_saveexec_b64 s[16:17], s[0:1]
	s_xor_b64 s[16:17], exec, s[16:17]
	s_cbranch_execz .LBB0_908
	v_fma_f32 v72, |v76|, s29, v223
	v_fma_f32 v72, |v76|, v72, s20
	v_fma_f32 v72, |v76|, v72, s21
	v_fma_f32 v72, |v76|, v72, s28
	v_fma_f32 v72, |v76|, v72, s33
	v_fma_f32 v72, |v76|, v72, s30
	v_fma_f32 v72, |v76|, v72, |v76|
	v_mul_f32_e32 v77, 0xbfb8aa3b, v72
	v_fma_f32 v78, v72, s31, -v77
	v_rndne_f32_e32 v79, v77
	v_fmac_f32_e32 v78, 0xb2a5705f, v72
	v_sub_f32_e32 v77, v77, v79
	v_add_f32_e32 v77, v77, v78
	v_cvt_i32_f32_e32 v78, v79
	v_exp_f32_e32 v77, v77
	v_cmp_nlt_f32_e32 vcc, s96, v72
	v_ldexp_f32 v77, v77, v78
	s_nop 0
	v_cndmask_b32_e32 v77, 0, v77, vcc
	v_cmp_ngt_f32_e32 vcc, s97, v72
	s_nop 1
	v_cndmask_b32_e32 v72, v224, v77, vcc
	v_sub_f32_e32 v77, 1.0, v72

; DEVI unsigned cvtpk(float lo, float hi) { unsigned r; asm("v_cvt_pk_bf16_f32 %0, %1, %2" : "=v"(r) : "v"(lo), "v"(hi)); return r; }
; DEVI float bflo(unsigned u) { return __uint_as_float(u << 16); }
; DEVI float bfhi(unsigned u) { return __uint_as_float(u & 0xffff0000u); }
; DEVI float geluf_(float x) { return 0.5f * x * (1.f + erff(x * 0.70710678118654752f)); }
; DEVI void lru_p3_phase(const Params& p) {
;     ...
;       for (int t = 63; t >= 0; --t) {
;         const unsigned l = *(const unsigned*)(la + (size_t)t * 1024), bv = *(const unsigned*)(bb + (size_t)t * 1024);
;         h0 = __expf(bflo(l)) * h0 + bflo(bv); h1 = __expf(bfhi(l)) * h1 + bfhi(bv);
;         const unsigned g = *(const unsigned*)(GX + (size_t)(rbase + t) * 2048 + ch);
;         *(unsigned*)(YG + (size_t)(rbase + t) * 1024 + ch) = cvtpk((s0[t] + h0) * geluf_(bflo(g)), (s1[t] + h1) * geluf_(bfhi(g)));
;       }
.LBB0_912:
	s_andn2_saveexec_b64 s[16:17], s[16:17]
	v_mul_f32_e32 v71, v79, v79
	v_fmamk_f32 v72, v71, 0xba1345e1, v217
	v_fmaak_f32 v72, v71, v72, 0xbcdac9b8
	v_fmaak_f32 v72, v71, v72, 0x3de703be
	v_fmaak_f32 v72, v71, v72, 0xbec09330
	v_fmaak_f32 v71, v71, v72, 0x3e0375d0
	v_fma_f32 v80, |v79|, v71, |v79|
	s_or_b64 exec, exec, s[16:17]
	v_lshlrev_b32_e32 v71, 16, v17
	v_mul_f32_e32 v71, 0x3fb8aa3b, v71
	v_exp_f32_e32 v71, v71
	v_and_b32_e32 v17, 0xffff0000, v17
	v_mul_f32_e32 v17, 0x3fb8aa3b, v17
	v_exp_f32_e32 v17, v17
	v_lshlrev_b32_e32 v72, 16, v16
	v_fmac_f32_e32 v72, v74, v71
	v_and_b32_e32 v71, 0xffff0000, v16
	v_add_f32_e32 v16, v69, v72
	v_bfi_b32 v69, s78, v77, v76
	v_fmac_f32_e32 v71, v73, v17
	v_mul_f32_e32 v17, 0.5, v75
	v_add_f32_e32 v69, 1.0, v69
	v_mul_f32_e32 v17, v17, v69
	v_mul_f32_e32 v16, v16, v17
	v_add_f32_e32 v17, v70, v71
	v_bfi_b32 v70, s78, v80, v79
	v_mul_f32_e32 v69, 0.5, v78
	v_add_f32_e32 v70, 1.0, v70
	v_mul_f32_e32 v69, v69, v70
	v_mul_f32_e32 v17, v17, v69
	s_lshl_b64 s[0:1], s[2:3], 11
	v_cvt_pk_bf16_f32 v69, v16, v17
	v_lshl_add_u64 v[16:17], v[10:11], 0, s[0:1]
	global_store_dword v[16:17], v69, off
	v_add_co_u32_e32 v16, vcc, s23, v12
	s_add_i32 s2, s14, 25
	s_nop 0
	v_addc_co_u32_e32 v17, vcc, 0, v13, vcc
	v_add_co_u32_e32 v74, vcc, 0xc000, v14
	s_ashr_i32 s3, s2, 31
	s_nop 0
	v_addc_co_u32_e32 v75, vcc, 0, v15, vcc
	s_lshl_b64 s[0:1], s[2:3], 12
	v_lshl_add_u64 v[74:75], v[8:9], 0, s[0:1]
	s_waitcnt vmcnt(45)
	v_mov_b32_e32 v69, v164
	v_mov_b32_e32 v73, v163
	v_mov_b32_e32 v70, v165
	s_mov_b32 s0, 0x6800
	s_mov_b32 s1, 0
	v_lshl_add_u64 v[198:199], v[12:13], 0, s[0:1]
	v_lshl_add_u64 v[200:201], v[14:15], 0, s[0:1]
	s_add_i32 s0, s14, 13
	s_ashr_i32 s1, s0, 31
	s_lshl_b64 s[0:1], s[0:1], 12
	global_load_dword v163, v[198:199], off
	global_load_dword v164, v[200:201], off
	v_lshl_add_u64 v[202:203], v[8:9], 0, s[0:1]
	global_load_dword v165, v[202:203], off
	v_lshlrev_b32_e32 v74, 16, v70
	v_mul_f32_e32 v75, 0x3f3504f3, v74
	v_cmp_nlt_f32_e64 s[0:1], |v75|, 1.0
	s_and_saveexec_b64 s[16:17], s[0:1]
	s_xor_b64 s[16:17], exec, s[16:17]
	s_cbranch_execz .LBB0_916
	v_fma_f32 v76, |v75|, s29, v223
	v_fma_f32 v76, |v75|, v76, s20
	v_fma_f32 v76, |v75|, v76, s21
	v_fma_f32 v76, |v75|, v76, s28
	v_fma_f32 v76, |v75|, v76, s33
	v_fma_f32 v76, |v75|, v76, s30
	v_fma_f32 v76, |v75|, v76, |v75|
	v_mul_f32_e32 v77, 0xbfb8aa3b, v76
	v_fma_f32 v78, v76, s31, -v77
	v_rndne_f32_e32 v79, v77
	v_fmac_f32_e32 v78, 0xb2a5705f, v76
	v_sub_f32_e32 v77, v77, v79
	v_add_f32_e32 v77, v77, v78
	v_cvt_i32_f32_e32 v78, v79
	v_exp_f32_e32 v77, v77
	v_cmp_nlt_f32_e32 vcc, s96, v76
	v_ldexp_f32 v77, v77, v78
	s_nop 0
	v_cndmask_b32_e32 v77, 0, v77, vcc
	v_cmp_ngt_f32_e32 vcc, s97, v76
	s_nop 1
	v_cndmask_b32_e32 v76, v224, v77, vcc
	v_sub_f32_e32 v76, 1.0, v76

; DEVI unsigned cvtpk(float lo, float hi) { unsigned r; asm("v_cvt_pk_bf16_f32 %0, %1, %2" : "=v"(r) : "v"(lo), "v"(hi)); return r; }
; DEVI float bflo(unsigned u) { return __uint_as_float(u << 16); }
; DEVI float bfhi(unsigned u) { return __uint_as_float(u & 0xffff0000u); }
; DEVI float geluf_(float x) { return 0.5f * x * (1.f + erff(x * 0.70710678118654752f)); }
; DEVI void lru_p3_phase(const Params& p) {
;     ...
;       for (int t = 63; t >= 0; --t) {
;         const unsigned l = *(const unsigned*)(la + (size_t)t * 1024), bv = *(const unsigned*)(bb + (size_t)t * 1024);
;         h0 = __expf(bflo(l)) * h0 + bflo(bv); h1 = __expf(bfhi(l)) * h1 + bfhi(bv);
;         const unsigned g = *(const unsigned*)(GX + (size_t)(rbase + t) * 2048 + ch);
;         *(unsigned*)(YG + (size_t)(rbase + t) * 1024 + ch) = cvtpk((s0[t] + h0) * geluf_(bflo(g)), (s1[t] + h1) * geluf_(bfhi(g)));
;       }
.LBB0_920:
	s_andn2_saveexec_b64 s[16:17], s[16:17]
	v_mul_f32_e32 v70, v78, v78
	v_fmamk_f32 v79, v70, 0xba1345e1, v217
	v_fmaak_f32 v79, v70, v79, 0xbcdac9b8
	v_fmaak_f32 v79, v70, v79, 0x3de703be
	v_fmaak_f32 v79, v70, v79, 0xbec09330
	v_fmaak_f32 v70, v70, v79, 0x3e0375d0
	v_fma_f32 v79, |v78|, v70, |v78|
	s_or_b64 exec, exec, s[16:17]
	v_lshlrev_b32_e32 v70, 16, v73
	v_mul_f32_e32 v70, 0x3fb8aa3b, v70
	v_exp_f32_e32 v80, v70
	v_lshlrev_b32_e32 v70, 16, v69
	v_and_b32_e32 v69, 0xffff0000, v69
	s_lshl_b64 s[0:1], s[2:3], 11
	v_fmac_f32_e32 v70, v72, v80
	v_and_b32_e32 v72, 0xffff0000, v73
	v_mul_f32_e32 v72, 0x3fb8aa3b, v72
	v_exp_f32_e32 v72, v72
	v_add_f32_e32 v67, v67, v70
	s_add_i32 s2, s14, 24
	s_ashr_i32 s3, s2, 31
	v_fmac_f32_e32 v69, v71, v72
	v_bfi_b32 v72, s78, v76, v75
	v_mul_f32_e32 v71, 0.5, v74
	v_add_f32_e32 v72, 1.0, v72
	v_mul_f32_e32 v71, v71, v72
	v_bfi_b32 v72, s78, v79, v78
	v_mul_f32_e32 v67, v67, v71
	v_mul_f32_e32 v71, 0.5, v77
	v_add_f32_e32 v72, 1.0, v72
	v_add_f32_e32 v68, v68, v69
	v_mul_f32_e32 v71, v71, v72
	v_lshl_add_u64 v[72:73], v[10:11], 0, s[0:1]
	v_mul_f32_e32 v68, v68, v71
	v_cvt_pk_bf16_f32 v67, v67, v68
	global_store_dword v[72:73], v67, off
	v_add_co_u32_e32 v72, vcc, 0xc000, v14
	s_lshl_b64 s[0:1], s[2:3], 12
	s_nop 0
	v_addc_co_u32_e32 v73, vcc, 0, v15, vcc
	s_nop 0
	v_lshl_add_u64 v[72:73], v[8:9], 0, s[0:1]
	s_waitcnt vmcnt(45)
	v_mov_b32_e32 v17, v160
	v_mov_b32_e32 v16, v161
	v_mov_b32_e32 v67, v162
	s_mov_b32 s0, 0x6000
	s_mov_b32 s1, 0
	v_lshl_add_u64 v[198:199], v[12:13], 0, s[0:1]
	v_lshl_add_u64 v[200:201], v[14:15], 0, s[0:1]
	s_add_i32 s0, s14, 12
	s_ashr_i32 s1, s0, 31
	s_lshl_b64 s[0:1], s[0:1], 12
	global_load_dword v160, v[198:199], off
	global_load_dword v161, v[200:201], off
	v_lshl_add_u64 v[202:203], v[8:9], 0, s[0:1]
	global_load_dword v162, v[202:203], off
	v_lshlrev_b32_e32 v71, 16, v67
	v_mul_f32_e32 v72, 0x3f3504f3, v71
	v_cmp_nlt_f32_e64 s[0:1], |v72|, 1.0
	s_and_saveexec_b64 s[16:17], s[0:1]
	s_xor_b64 s[16:17], exec, s[16:17]
	s_cbranch_execz .LBB0_924
	v_fma_f32 v68, |v72|, s29, v223
	v_fma_f32 v68, |v72|, v68, s20
	v_fma_f32 v68, |v72|, v68, s21
	v_fma_f32 v68, |v72|, v68, s28
	v_fma_f32 v68, |v72|, v68, s33
	v_fma_f32 v68, |v72|, v68, s30
	v_fma_f32 v68, |v72|, v68, |v72|
	v_mul_f32_e32 v73, 0xbfb8aa3b, v68
	v_fma_f32 v74, v68, s31, -v73
	v_rndne_f32_e32 v75, v73
	v_fmac_f32_e32 v74, 0xb2a5705f, v68
	v_sub_f32_e32 v73, v73, v75
	v_add_f32_e32 v73, v73, v74
	v_cvt_i32_f32_e32 v74, v75
	v_exp_f32_e32 v73, v73
	v_cmp_nlt_f32_e32 vcc, s96, v68
	v_ldexp_f32 v73, v73, v74
	s_nop 0
	v_cndmask_b32_e32 v73, 0, v73, vcc
	v_cmp_ngt_f32_e32 vcc, s97, v68
	s_nop 1
	v_cndmask_b32_e32 v68, v224, v73, vcc
	v_sub_f32_e32 v73, 1.0, v68

; DEVI unsigned cvtpk(float lo, float hi) { unsigned r; asm("v_cvt_pk_bf16_f32 %0, %1, %2" : "=v"(r) : "v"(lo), "v"(hi)); return r; }
; DEVI float bflo(unsigned u) { return __uint_as_float(u << 16); }
; DEVI float bfhi(unsigned u) { return __uint_as_float(u & 0xffff0000u); }
; DEVI float geluf_(float x) { return 0.5f * x * (1.f + erff(x * 0.70710678118654752f)); }
; DEVI void lru_p3_phase(const Params& p) {
;     ...
;       for (int t = 63; t >= 0; --t) {
;         const unsigned l = *(const unsigned*)(la + (size_t)t * 1024), bv = *(const unsigned*)(bb + (size_t)t * 1024);
;         h0 = __expf(bflo(l)) * h0 + bflo(bv); h1 = __expf(bfhi(l)) * h1 + bfhi(bv);
;         const unsigned g = *(const unsigned*)(GX + (size_t)(rbase + t) * 2048 + ch);
;         *(unsigned*)(YG + (size_t)(rbase + t) * 1024 + ch) = cvtpk((s0[t] + h0) * geluf_(bflo(g)), (s1[t] + h1) * geluf_(bfhi(g)));
;       }
.LBB0_928:
	s_andn2_saveexec_b64 s[16:17], s[16:17]
	v_mul_f32_e32 v67, v75, v75
	v_fmamk_f32 v68, v67, 0xba1345e1, v217
	v_fmaak_f32 v68, v67, v68, 0xbcdac9b8
	v_fmaak_f32 v68, v67, v68, 0x3de703be
	v_fmaak_f32 v68, v67, v68, 0xbec09330
	v_fmaak_f32 v67, v67, v68, 0x3e0375d0
	v_fma_f32 v76, |v75|, v67, |v75|
	s_or_b64 exec, exec, s[16:17]
	v_lshlrev_b32_e32 v67, 16, v17
	v_mul_f32_e32 v67, 0x3fb8aa3b, v67
	v_exp_f32_e32 v67, v67
	v_and_b32_e32 v17, 0xffff0000, v17
	v_mul_f32_e32 v17, 0x3fb8aa3b, v17
	v_exp_f32_e32 v17, v17
	v_lshlrev_b32_e32 v68, 16, v16
	v_fmac_f32_e32 v68, v70, v67
	v_and_b32_e32 v67, 0xffff0000, v16
	v_add_f32_e32 v16, v65, v68
	v_bfi_b32 v65, s78, v73, v72
	v_fmac_f32_e32 v67, v69, v17
	v_mul_f32_e32 v17, 0.5, v71
	v_add_f32_e32 v65, 1.0, v65
	v_mul_f32_e32 v17, v17, v65
	v_mul_f32_e32 v16, v16, v17
	v_add_f32_e32 v17, v66, v67
	v_bfi_b32 v66, s78, v76, v75
	v_mul_f32_e32 v65, 0.5, v74
	v_add_f32_e32 v66, 1.0, v66
	v_mul_f32_e32 v65, v65, v66
	v_mul_f32_e32 v17, v17, v65
	s_lshl_b64 s[0:1], s[2:3], 11
	v_cvt_pk_bf16_f32 v65, v16, v17
	v_lshl_add_u64 v[16:17], v[10:11], 0, s[0:1]
	global_store_dword v[16:17], v65, off
	v_add_co_u32_e32 v16, vcc, s47, v12
	s_add_i32 s2, s14, 23
	s_nop 0
	v_addc_co_u32_e32 v17, vcc, 0, v13, vcc
	v_add_co_u32_e32 v70, vcc, 0xb000, v14
	s_ashr_i32 s3, s2, 31
	s_nop 0
	v_addc_co_u32_e32 v71, vcc, 0, v15, vcc
	s_lshl_b64 s[0:1], s[2:3], 12
	v_lshl_add_u64 v[70:71], v[8:9], 0, s[0:1]
	s_waitcnt vmcnt(45)
	v_mov_b32_e32 v65, v196
	v_mov_b32_e32 v69, v195
	v_mov_b32_e32 v66, v197
	s_mov_b32 s0, 0x5800
	s_mov_b32 s1, 0
	v_lshl_add_u64 v[198:199], v[12:13], 0, s[0:1]
	v_lshl_add_u64 v[200:201], v[14:15], 0, s[0:1]
	s_add_i32 s0, s14, 11
	s_ashr_i32 s1, s0, 31
	s_lshl_b64 s[0:1], s[0:1], 12
	global_load_dword v195, v[198:199], off
	global_load_dword v196, v[200:201], off
	v_lshl_add_u64 v[202:203], v[8:9], 0, s[0:1]
	global_load_dword v197, v[202:203], off
	v_lshlrev_b32_e32 v70, 16, v66
	v_mul_f32_e32 v71, 0x3f3504f3, v70
	v_cmp_nlt_f32_e64 s[0:1], |v71|, 1.0
	s_and_saveexec_b64 s[16:17], s[0:1]
	s_xor_b64 s[16:17], exec, s[16:17]
	s_cbranch_execz .LBB0_932
	v_fma_f32 v72, |v71|, s29, v223
	v_fma_f32 v72, |v71|, v72, s20
	v_fma_f32 v72, |v71|, v72, s21
	v_fma_f32 v72, |v71|, v72, s28
	v_fma_f32 v72, |v71|, v72, s33
	v_fma_f32 v72, |v71|, v72, s30
	v_fma_f32 v72, |v71|, v72, |v71|
	v_mul_f32_e32 v73, 0xbfb8aa3b, v72
	v_fma_f32 v74, v72, s31, -v73
	v_rndne_f32_e32 v75, v73
	v_fmac_f32_e32 v74, 0xb2a5705f, v72
	v_sub_f32_e32 v73, v73, v75
	v_add_f32_e32 v73, v73, v74
	v_cvt_i32_f32_e32 v74, v75
	v_exp_f32_e32 v73, v73
	v_cmp_nlt_f32_e32 vcc, s96, v72
	v_ldexp_f32 v73, v73, v74
	s_nop 0
	v_cndmask_b32_e32 v73, 0, v73, vcc
	v_cmp_ngt_f32_e32 vcc, s97, v72
	s_nop 1
	v_cndmask_b32_e32 v72, v224, v73, vcc
	v_sub_f32_e32 v72, 1.0, v72

; DEVI unsigned cvtpk(float lo, float hi) { unsigned r; asm("v_cvt_pk_bf16_f32 %0, %1, %2" : "=v"(r) : "v"(lo), "v"(hi)); return r; }
; DEVI float bflo(unsigned u) { return __uint_as_float(u << 16); }
; DEVI float bfhi(unsigned u) { return __uint_as_float(u & 0xffff0000u); }
; DEVI float geluf_(float x) { return 0.5f * x * (1.f + erff(x * 0.70710678118654752f)); }
; DEVI void lru_p3_phase(const Params& p) {
;     ...
;       for (int t = 63; t >= 0; --t) {
;         const unsigned l = *(const unsigned*)(la + (size_t)t * 1024), bv = *(const unsigned*)(bb + (size_t)t * 1024);
;         h0 = __expf(bflo(l)) * h0 + bflo(bv); h1 = __expf(bfhi(l)) * h1 + bfhi(bv);
;         const unsigned g = *(const unsigned*)(GX + (size_t)(rbase + t) * 2048 + ch);
;         *(unsigned*)(YG + (size_t)(rbase + t) * 1024 + ch) = cvtpk((s0[t] + h0) * geluf_(bflo(g)), (s1[t] + h1) * geluf_(bfhi(g)));
;       }
.LBB0_936:
	s_andn2_saveexec_b64 s[16:17], s[16:17]
	v_mul_f32_e32 v66, v74, v74
	v_fmamk_f32 v75, v66, 0xba1345e1, v217
	v_fmaak_f32 v75, v66, v75, 0xbcdac9b8
	v_fmaak_f32 v75, v66, v75, 0x3de703be
	v_fmaak_f32 v75, v66, v75, 0xbec09330
	v_fmaak_f32 v66, v66, v75, 0x3e0375d0
	v_fma_f32 v75, |v74|, v66, |v74|
	s_or_b64 exec, exec, s[16:17]
	v_lshlrev_b32_e32 v66, 16, v69
	v_mul_f32_e32 v66, 0x3fb8aa3b, v66
	v_exp_f32_e32 v76, v66
	v_lshlrev_b32_e32 v66, 16, v65
	v_and_b32_e32 v65, 0xffff0000, v65
	s_lshl_b64 s[0:1], s[2:3], 11
	v_fmac_f32_e32 v66, v68, v76
	v_and_b32_e32 v68, 0xffff0000, v69
	v_mul_f32_e32 v68, 0x3fb8aa3b, v68
	v_exp_f32_e32 v68, v68
	v_add_f32_e32 v63, v63, v66
	s_add_i32 s2, s14, 22
	s_ashr_i32 s3, s2, 31
	v_fmac_f32_e32 v65, v67, v68
	v_bfi_b32 v68, s78, v72, v71
	v_mul_f32_e32 v67, 0.5, v70
	v_add_f32_e32 v68, 1.0, v68
	v_mul_f32_e32 v67, v67, v68
	v_bfi_b32 v68, s78, v75, v74
	v_mul_f32_e32 v63, v63, v67
	v_mul_f32_e32 v67, 0.5, v73
	v_add_f32_e32 v68, 1.0, v68
	v_add_f32_e32 v64, v64, v65
	v_mul_f32_e32 v67, v67, v68
	v_lshl_add_u64 v[68:69], v[10:11], 0, s[0:1]
	v_mul_f32_e32 v64, v64, v67
	v_cvt_pk_bf16_f32 v63, v63, v64
	global_store_dword v[68:69], v63, off
	v_add_co_u32_e32 v68, vcc, 0xb000, v14
	s_lshl_b64 s[0:1], s[2:3], 12
	s_nop 0
	v_addc_co_u32_e32 v69, vcc, 0, v15, vcc
	s_nop 0
	v_lshl_add_u64 v[68:69], v[8:9], 0, s[0:1]
	s_waitcnt vmcnt(45)
	v_mov_b32_e32 v17, v192
	v_mov_b32_e32 v16, v193
	v_mov_b32_e32 v63, v194
	s_mov_b32 s0, 0x5000
	s_mov_b32 s1, 0
	v_lshl_add_u64 v[198:199], v[12:13], 0, s[0:1]
	v_lshl_add_u64 v[200:201], v[14:15], 0, s[0:1]
	s_add_i32 s0, s14, 10
	s_ashr_i32 s1, s0, 31
	s_lshl_b64 s[0:1], s[0:1], 12
	global_load_dword v192, v[198:199], off
	global_load_dword v193, v[200:201], off
	v_lshl_add_u64 v[202:203], v[8:9], 0, s[0:1]
	global_load_dword v194, v[202:203], off
	v_lshlrev_b32_e32 v67, 16, v63
	v_mul_f32_e32 v68, 0x3f3504f3, v67
	v_cmp_nlt_f32_e64 s[0:1], |v68|, 1.0
	s_and_saveexec_b64 s[16:17], s[0:1]
	s_xor_b64 s[16:17], exec, s[16:17]
	s_cbranch_execz .LBB0_940
	v_fma_f32 v64, |v68|, s29, v223
	v_fma_f32 v64, |v68|, v64, s20
	v_fma_f32 v64, |v68|, v64, s21
	v_fma_f32 v64, |v68|, v64, s28
	v_fma_f32 v64, |v68|, v64, s33
	v_fma_f32 v64, |v68|, v64, s30
	v_fma_f32 v64, |v68|, v64, |v68|
	v_mul_f32_e32 v69, 0xbfb8aa3b, v64
	v_fma_f32 v70, v64, s31, -v69
	v_rndne_f32_e32 v71, v69
	v_fmac_f32_e32 v70, 0xb2a5705f, v64
	v_sub_f32_e32 v69, v69, v71
	v_add_f32_e32 v69, v69, v70
	v_cvt_i32_f32_e32 v70, v71
	v_exp_f32_e32 v69, v69
	v_cmp_nlt_f32_e32 vcc, s96, v64
	v_ldexp_f32 v69, v69, v70
	s_nop 0
	v_cndmask_b32_e32 v69, 0, v69, vcc
	v_cmp_ngt_f32_e32 vcc, s97, v64
	s_nop 1
	v_cndmask_b32_e32 v64, v224, v69, vcc
	v_sub_f32_e32 v69, 1.0, v64

; DEVI unsigned cvtpk(float lo, float hi) { unsigned r; asm("v_cvt_pk_bf16_f32 %0, %1, %2" : "=v"(r) : "v"(lo), "v"(hi)); return r; }
; DEVI float bflo(unsigned u) { return __uint_as_float(u << 16); }
; DEVI float bfhi(unsigned u) { return __uint_as_float(u & 0xffff0000u); }
; DEVI float geluf_(float x) { return 0.5f * x * (1.f + erff(x * 0.70710678118654752f)); }
; DEVI void lru_p3_phase(const Params& p) {
;     ...
;       for (int t = 63; t >= 0; --t) {
;         const unsigned l = *(const unsigned*)(la + (size_t)t * 1024), bv = *(const unsigned*)(bb + (size_t)t * 1024);
;         h0 = __expf(bflo(l)) * h0 + bflo(bv); h1 = __expf(bfhi(l)) * h1 + bfhi(bv);
;         const unsigned g = *(const unsigned*)(GX + (size_t)(rbase + t) * 2048 + ch);
;         *(unsigned*)(YG + (size_t)(rbase + t) * 1024 + ch) = cvtpk((s0[t] + h0) * geluf_(bflo(g)), (s1[t] + h1) * geluf_(bfhi(g)));
;       }
.LBB0_944:
	s_andn2_saveexec_b64 s[16:17], s[16:17]
	v_mul_f32_e32 v63, v71, v71
	v_fmamk_f32 v64, v63, 0xba1345e1, v217
	v_fmaak_f32 v64, v63, v64, 0xbcdac9b8
	v_fmaak_f32 v64, v63, v64, 0x3de703be
	v_fmaak_f32 v64, v63, v64, 0xbec09330
	v_fmaak_f32 v63, v63, v64, 0x3e0375d0
	v_fma_f32 v72, |v71|, v63, |v71|
	s_or_b64 exec, exec, s[16:17]
	v_lshlrev_b32_e32 v63, 16, v17
	v_mul_f32_e32 v63, 0x3fb8aa3b, v63
	v_exp_f32_e32 v63, v63
	v_and_b32_e32 v17, 0xffff0000, v17
	v_mul_f32_e32 v17, 0x3fb8aa3b, v17
	v_exp_f32_e32 v17, v17
	v_lshlrev_b32_e32 v64, 16, v16
	v_fmac_f32_e32 v64, v66, v63
	v_and_b32_e32 v63, 0xffff0000, v16
	v_add_f32_e32 v16, v61, v64
	v_bfi_b32 v61, s78, v69, v68
	v_fmac_f32_e32 v63, v65, v17
	v_mul_f32_e32 v17, 0.5, v67
	v_add_f32_e32 v61, 1.0, v61
	v_mul_f32_e32 v17, v17, v61
	v_mul_f32_e32 v16, v16, v17
	v_add_f32_e32 v17, v62, v63
	v_bfi_b32 v62, s78, v72, v71
	v_mul_f32_e32 v61, 0.5, v70
	v_add_f32_e32 v62, 1.0, v62
	v_mul_f32_e32 v61, v61, v62
	v_mul_f32_e32 v17, v17, v61
	s_lshl_b64 s[0:1], s[2:3], 11
	v_cvt_pk_bf16_f32 v61, v16, v17
	v_lshl_add_u64 v[16:17], v[10:11], 0, s[0:1]
	global_store_dword v[16:17], v61, off
	v_add_co_u32_e32 v16, vcc, s46, v12
	s_add_i32 s2, s14, 21
	s_nop 0
	v_addc_co_u32_e32 v17, vcc, 0, v13, vcc
	v_add_co_u32_e32 v66, vcc, 0xa000, v14
	s_ashr_i32 s3, s2, 31
	s_nop 0
	v_addc_co_u32_e32 v67, vcc, 0, v15, vcc
	s_lshl_b64 s[0:1], s[2:3], 12
	v_lshl_add_u64 v[66:67], v[8:9], 0, s[0:1]
	s_waitcnt vmcnt(45)
	v_mov_b32_e32 v61, v190
	v_mov_b32_e32 v65, v189
	v_mov_b32_e32 v62, v191
	s_mov_b32 s0, 0x4800
	s_mov_b32 s1, 0
	v_lshl_add_u64 v[198:199], v[12:13], 0, s[0:1]
	v_lshl_add_u64 v[200:201], v[14:15], 0, s[0:1]
	s_add_i32 s0, s14, 9
	s_ashr_i32 s1, s0, 31
	s_lshl_b64 s[0:1], s[0:1], 12
	global_load_dword v189, v[198:199], off
	global_load_dword v190, v[200:201], off
	v_lshl_add_u64 v[202:203], v[8:9], 0, s[0:1]
	global_load_dword v191, v[202:203], off
	v_lshlrev_b32_e32 v66, 16, v62
	v_mul_f32_e32 v67, 0x3f3504f3, v66
	v_cmp_nlt_f32_e64 s[0:1], |v67|, 1.0
	s_and_saveexec_b64 s[16:17], s[0:1]
	s_xor_b64 s[16:17], exec, s[16:17]
	s_cbranch_execz .LBB0_948
	v_fma_f32 v68, |v67|, s29, v223
	v_fma_f32 v68, |v67|, v68, s20
	v_fma_f32 v68, |v67|, v68, s21
	v_fma_f32 v68, |v67|, v68, s28
	v_fma_f32 v68, |v67|, v68, s33
	v_fma_f32 v68, |v67|, v68, s30
	v_fma_f32 v68, |v67|, v68, |v67|
	v_mul_f32_e32 v69, 0xbfb8aa3b, v68
	v_fma_f32 v70, v68, s31, -v69
	v_rndne_f32_e32 v71, v69
	v_fmac_f32_e32 v70, 0xb2a5705f, v68
	v_sub_f32_e32 v69, v69, v71
	v_add_f32_e32 v69, v69, v70
	v_cvt_i32_f32_e32 v70, v71
	v_exp_f32_e32 v69, v69
	v_cmp_nlt_f32_e32 vcc, s96, v68
	v_ldexp_f32 v69, v69, v70
	s_nop 0
	v_cndmask_b32_e32 v69, 0, v69, vcc
	v_cmp_ngt_f32_e32 vcc, s97, v68
	s_nop 1
	v_cndmask_b32_e32 v68, v224, v69, vcc
	v_sub_f32_e32 v68, 1.0, v68

; DEVI unsigned cvtpk(float lo, float hi) { unsigned r; asm("v_cvt_pk_bf16_f32 %0, %1, %2" : "=v"(r) : "v"(lo), "v"(hi)); return r; }
; DEVI float bflo(unsigned u) { return __uint_as_float(u << 16); }
; DEVI float bfhi(unsigned u) { return __uint_as_float(u & 0xffff0000u); }
; DEVI float geluf_(float x) { return 0.5f * x * (1.f + erff(x * 0.70710678118654752f)); }
; DEVI void lru_p3_phase(const Params& p) {
;     ...
;       for (int t = 63; t >= 0; --t) {
;         const unsigned l = *(const unsigned*)(la + (size_t)t * 1024), bv = *(const unsigned*)(bb + (size_t)t * 1024);
;         h0 = __expf(bflo(l)) * h0 + bflo(bv); h1 = __expf(bfhi(l)) * h1 + bfhi(bv);
;         const unsigned g = *(const unsigned*)(GX + (size_t)(rbase + t) * 2048 + ch);
;         *(unsigned*)(YG + (size_t)(rbase + t) * 1024 + ch) = cvtpk((s0[t] + h0) * geluf_(bflo(g)), (s1[t] + h1) * geluf_(bfhi(g)));
;       }
.LBB0_952:
	s_andn2_saveexec_b64 s[16:17], s[16:17]
	v_mul_f32_e32 v62, v70, v70
	v_fmamk_f32 v71, v62, 0xba1345e1, v217
	v_fmaak_f32 v71, v62, v71, 0xbcdac9b8
	v_fmaak_f32 v71, v62, v71, 0x3de703be
	v_fmaak_f32 v71, v62, v71, 0xbec09330
	v_fmaak_f32 v62, v62, v71, 0x3e0375d0
	v_fma_f32 v71, |v70|, v62, |v70|
	s_or_b64 exec, exec, s[16:17]
	v_lshlrev_b32_e32 v62, 16, v65
	v_mul_f32_e32 v62, 0x3fb8aa3b, v62
	v_exp_f32_e32 v72, v62
	v_lshlrev_b32_e32 v62, 16, v61
	v_and_b32_e32 v61, 0xffff0000, v61
	s_lshl_b64 s[0:1], s[2:3], 11
	v_fmac_f32_e32 v62, v64, v72
	v_and_b32_e32 v64, 0xffff0000, v65
	v_mul_f32_e32 v64, 0x3fb8aa3b, v64
	v_exp_f32_e32 v64, v64
	v_add_f32_e32 v59, v59, v62
	s_add_i32 s2, s14, 20
	s_ashr_i32 s3, s2, 31
	v_fmac_f32_e32 v61, v63, v64
	v_bfi_b32 v64, s78, v68, v67
	v_mul_f32_e32 v63, 0.5, v66
	v_add_f32_e32 v64, 1.0, v64
	v_mul_f32_e32 v63, v63, v64
	v_bfi_b32 v64, s78, v71, v70
	v_mul_f32_e32 v59, v59, v63
	v_mul_f32_e32 v63, 0.5, v69
	v_add_f32_e32 v64, 1.0, v64
	v_add_f32_e32 v60, v60, v61
	v_mul_f32_e32 v63, v63, v64
	v_lshl_add_u64 v[64:65], v[10:11], 0, s[0:1]
	v_mul_f32_e32 v60, v60, v63
	v_cvt_pk_bf16_f32 v59, v59, v60
	global_store_dword v[64:65], v59, off
	v_add_co_u32_e32 v64, vcc, 0xa000, v14
	s_lshl_b64 s[0:1], s[2:3], 12
	s_nop 0
	v_addc_co_u32_e32 v65, vcc, 0, v15, vcc
	s_nop 0
	v_lshl_add_u64 v[64:65], v[8:9], 0, s[0:1]
	s_waitcnt vmcnt(45)
	v_mov_b32_e32 v17, v186
	v_mov_b32_e32 v16, v187
	v_mov_b32_e32 v59, v188
	s_mov_b32 s0, 0x4000
	s_mov_b32 s1, 0
	v_lshl_add_u64 v[198:199], v[12:13], 0, s[0:1]
	v_lshl_add_u64 v[200:201], v[14:15], 0, s[0:1]
	s_add_i32 s0, s14, 8
	s_ashr_i32 s1, s0, 31
	s_lshl_b64 s[0:1], s[0:1], 12
	global_load_dword v186, v[198:199], off
	global_load_dword v187, v[200:201], off
	v_lshl_add_u64 v[202:203], v[8:9], 0, s[0:1]
	global_load_dword v188, v[202:203], off
	v_lshlrev_b32_e32 v63, 16, v59
	v_mul_f32_e32 v64, 0x3f3504f3, v63
	v_cmp_nlt_f32_e64 s[0:1], |v64|, 1.0
	s_and_saveexec_b64 s[16:17], s[0:1]
	s_xor_b64 s[16:17], exec, s[16:17]
	s_cbranch_execz .LBB0_956
	v_fma_f32 v60, |v64|, s29, v223
	v_fma_f32 v60, |v64|, v60, s20
	v_fma_f32 v60, |v64|, v60, s21
	v_fma_f32 v60, |v64|, v60, s28
	v_fma_f32 v60, |v64|, v60, s33
	v_fma_f32 v60, |v64|, v60, s30
	v_fma_f32 v60, |v64|, v60, |v64|
	v_mul_f32_e32 v65, 0xbfb8aa3b, v60
	v_fma_f32 v66, v60, s31, -v65
	v_rndne_f32_e32 v67, v65
	v_fmac_f32_e32 v66, 0xb2a5705f, v60
	v_sub_f32_e32 v65, v65, v67
	v_add_f32_e32 v65, v65, v66
	v_cvt_i32_f32_e32 v66, v67
	v_exp_f32_e32 v65, v65
	v_cmp_nlt_f32_e32 vcc, s96, v60
	v_ldexp_f32 v65, v65, v66
	s_nop 0
	v_cndmask_b32_e32 v65, 0, v65, vcc
	v_cmp_ngt_f32_e32 vcc, s97, v60
	s_nop 1
	v_cndmask_b32_e32 v60, v224, v65, vcc
	v_sub_f32_e32 v65, 1.0, v60

; DEVI unsigned cvtpk(float lo, float hi) { unsigned r; asm("v_cvt_pk_bf16_f32 %0, %1, %2" : "=v"(r) : "v"(lo), "v"(hi)); return r; }
; DEVI float bflo(unsigned u) { return __uint_as_float(u << 16); }
; DEVI float bfhi(unsigned u) { return __uint_as_float(u & 0xffff0000u); }
; DEVI float geluf_(float x) { return 0.5f * x * (1.f + erff(x * 0.70710678118654752f)); }
; DEVI void lru_p3_phase(const Params& p) {
;     ...
;       for (int t = 63; t >= 0; --t) {
;         const unsigned l = *(const unsigned*)(la + (size_t)t * 1024), bv = *(const unsigned*)(bb + (size_t)t * 1024);
;         h0 = __expf(bflo(l)) * h0 + bflo(bv); h1 = __expf(bfhi(l)) * h1 + bfhi(bv);
;         const unsigned g = *(const unsigned*)(GX + (size_t)(rbase + t) * 2048 + ch);
;         *(unsigned*)(YG + (size_t)(rbase + t) * 1024 + ch) = cvtpk((s0[t] + h0) * geluf_(bflo(g)), (s1[t] + h1) * geluf_(bfhi(g)));
;       }
.LBB0_960:
	s_andn2_saveexec_b64 s[16:17], s[16:17]
	v_mul_f32_e32 v59, v67, v67
	v_fmamk_f32 v60, v59, 0xba1345e1, v217
	v_fmaak_f32 v60, v59, v60, 0xbcdac9b8
	v_fmaak_f32 v60, v59, v60, 0x3de703be
	v_fmaak_f32 v60, v59, v60, 0xbec09330
	v_fmaak_f32 v59, v59, v60, 0x3e0375d0
	v_fma_f32 v68, |v67|, v59, |v67|
	s_or_b64 exec, exec, s[16:17]
	v_lshlrev_b32_e32 v59, 16, v17
	v_mul_f32_e32 v59, 0x3fb8aa3b, v59
	v_exp_f32_e32 v59, v59
	v_and_b32_e32 v17, 0xffff0000, v17
	v_mul_f32_e32 v17, 0x3fb8aa3b, v17
	v_exp_f32_e32 v17, v17
	v_lshlrev_b32_e32 v60, 16, v16
	v_fmac_f32_e32 v60, v62, v59
	v_and_b32_e32 v59, 0xffff0000, v16
	v_add_f32_e32 v16, v57, v60
	v_bfi_b32 v57, s78, v65, v64
	v_fmac_f32_e32 v59, v61, v17
	v_mul_f32_e32 v17, 0.5, v63
	v_add_f32_e32 v57, 1.0, v57
	v_mul_f32_e32 v17, v17, v57
	v_mul_f32_e32 v16, v16, v17
	v_add_f32_e32 v17, v58, v59
	v_bfi_b32 v58, s78, v68, v67
	v_mul_f32_e32 v57, 0.5, v66
	v_add_f32_e32 v58, 1.0, v58
	v_mul_f32_e32 v57, v57, v58
	v_mul_f32_e32 v17, v17, v57
	s_lshl_b64 s[0:1], s[2:3], 11
	v_cvt_pk_bf16_f32 v57, v16, v17
	v_lshl_add_u64 v[16:17], v[10:11], 0, s[0:1]
	global_store_dword v[16:17], v57, off
	v_add_co_u32_e32 v16, vcc, s45, v12
	s_add_i32 s2, s14, 19
	s_nop 0
	v_addc_co_u32_e32 v17, vcc, 0, v13, vcc
	v_add_co_u32_e32 v62, vcc, 0x9000, v14
	s_ashr_i32 s3, s2, 31
	s_nop 0
	v_addc_co_u32_e32 v63, vcc, 0, v15, vcc
	s_lshl_b64 s[0:1], s[2:3], 12
	v_lshl_add_u64 v[62:63], v[8:9], 0, s[0:1]
	s_waitcnt vmcnt(45)
	v_mov_b32_e32 v57, v184
	v_mov_b32_e32 v61, v183
	v_mov_b32_e32 v58, v185
	s_mov_b32 s0, 0x3800
	s_mov_b32 s1, 0
	v_lshl_add_u64 v[198:199], v[12:13], 0, s[0:1]
	v_lshl_add_u64 v[200:201], v[14:15], 0, s[0:1]
	s_add_i32 s0, s14, 7
	s_ashr_i32 s1, s0, 31
	s_lshl_b64 s[0:1], s[0:1], 12
	global_load_dword v183, v[198:199], off
	global_load_dword v184, v[200:201], off
	v_lshl_add_u64 v[202:203], v[8:9], 0, s[0:1]
	global_load_dword v185, v[202:203], off
	v_lshlrev_b32_e32 v62, 16, v58
	v_mul_f32_e32 v63, 0x3f3504f3, v62
	v_cmp_nlt_f32_e64 s[0:1], |v63|, 1.0
	s_and_saveexec_b64 s[16:17], s[0:1]
	s_xor_b64 s[16:17], exec, s[16:17]
	s_cbranch_execz .LBB0_964
	v_fma_f32 v64, |v63|, s29, v223
	v_fma_f32 v64, |v63|, v64, s20
	v_fma_f32 v64, |v63|, v64, s21
	v_fma_f32 v64, |v63|, v64, s28
	v_fma_f32 v64, |v63|, v64, s33
	v_fma_f32 v64, |v63|, v64, s30
	v_fma_f32 v64, |v63|, v64, |v63|
	v_mul_f32_e32 v65, 0xbfb8aa3b, v64
	v_fma_f32 v66, v64, s31, -v65
	v_rndne_f32_e32 v67, v65
	v_fmac_f32_e32 v66, 0xb2a5705f, v64
	v_sub_f32_e32 v65, v65, v67
	v_add_f32_e32 v65, v65, v66
	v_cvt_i32_f32_e32 v66, v67
	v_exp_f32_e32 v65, v65
	v_cmp_nlt_f32_e32 vcc, s96, v64
	v_ldexp_f32 v65, v65, v66
	s_nop 0
	v_cndmask_b32_e32 v65, 0, v65, vcc
	v_cmp_ngt_f32_e32 vcc, s97, v64
	s_nop 1
	v_cndmask_b32_e32 v64, v224, v65, vcc
	v_sub_f32_e32 v64, 1.0, v64

; DEVI unsigned cvtpk(float lo, float hi) { unsigned r; asm("v_cvt_pk_bf16_f32 %0, %1, %2" : "=v"(r) : "v"(lo), "v"(hi)); return r; }
; DEVI float bflo(unsigned u) { return __uint_as_float(u << 16); }
; DEVI float bfhi(unsigned u) { return __uint_as_float(u & 0xffff0000u); }
; DEVI float geluf_(float x) { return 0.5f * x * (1.f + erff(x * 0.70710678118654752f)); }
; DEVI void lru_p3_phase(const Params& p) {
;     ...
;       for (int t = 63; t >= 0; --t) {
;         const unsigned l = *(const unsigned*)(la + (size_t)t * 1024), bv = *(const unsigned*)(bb + (size_t)t * 1024);
;         h0 = __expf(bflo(l)) * h0 + bflo(bv); h1 = __expf(bfhi(l)) * h1 + bfhi(bv);
;         const unsigned g = *(const unsigned*)(GX + (size_t)(rbase + t) * 2048 + ch);
;         *(unsigned*)(YG + (size_t)(rbase + t) * 1024 + ch) = cvtpk((s0[t] + h0) * geluf_(bflo(g)), (s1[t] + h1) * geluf_(bfhi(g)));
;       }
.LBB0_968:
	s_andn2_saveexec_b64 s[16:17], s[16:17]
	v_mul_f32_e32 v58, v66, v66
	v_fmamk_f32 v67, v58, 0xba1345e1, v217
	v_fmaak_f32 v67, v58, v67, 0xbcdac9b8
	v_fmaak_f32 v67, v58, v67, 0x3de703be
	v_fmaak_f32 v67, v58, v67, 0xbec09330
	v_fmaak_f32 v58, v58, v67, 0x3e0375d0
	v_fma_f32 v67, |v66|, v58, |v66|
	s_or_b64 exec, exec, s[16:17]
	v_lshlrev_b32_e32 v58, 16, v61
	v_mul_f32_e32 v58, 0x3fb8aa3b, v58
	v_exp_f32_e32 v68, v58
	v_lshlrev_b32_e32 v58, 16, v57
	v_and_b32_e32 v57, 0xffff0000, v57
	s_lshl_b64 s[0:1], s[2:3], 11
	v_fmac_f32_e32 v58, v60, v68
	v_and_b32_e32 v60, 0xffff0000, v61
	v_mul_f32_e32 v60, 0x3fb8aa3b, v60
	v_exp_f32_e32 v60, v60
	v_add_f32_e32 v55, v55, v58
	s_add_i32 s2, s14, 18
	s_ashr_i32 s3, s2, 31
	v_fmac_f32_e32 v57, v59, v60
	v_bfi_b32 v60, s78, v64, v63
	v_mul_f32_e32 v59, 0.5, v62
	v_add_f32_e32 v60, 1.0, v60
	v_mul_f32_e32 v59, v59, v60
	v_bfi_b32 v60, s78, v67, v66
	v_mul_f32_e32 v55, v55, v59
	v_mul_f32_e32 v59, 0.5, v65
	v_add_f32_e32 v60, 1.0, v60
	v_add_f32_e32 v56, v56, v57
	v_mul_f32_e32 v59, v59, v60
	v_lshl_add_u64 v[60:61], v[10:11], 0, s[0:1]
	v_mul_f32_e32 v56, v56, v59
	v_cvt_pk_bf16_f32 v55, v55, v56
	global_store_dword v[60:61], v55, off
	v_add_co_u32_e32 v60, vcc, 0x9000, v14
	s_lshl_b64 s[0:1], s[2:3], 12
	s_nop 0
	v_addc_co_u32_e32 v61, vcc, 0, v15, vcc
	s_nop 0
	v_lshl_add_u64 v[60:61], v[8:9], 0, s[0:1]
	s_waitcnt vmcnt(45)
	v_mov_b32_e32 v17, v180
	v_mov_b32_e32 v16, v181
	v_mov_b32_e32 v55, v182
	s_mov_b32 s0, 0x3000
	s_mov_b32 s1, 0
	v_lshl_add_u64 v[198:199], v[12:13], 0, s[0:1]
	v_lshl_add_u64 v[200:201], v[14:15], 0, s[0:1]
	s_add_i32 s0, s14, 6
	s_ashr_i32 s1, s0, 31
	s_lshl_b64 s[0:1], s[0:1], 12
	global_load_dword v180, v[198:199], off
	global_load_dword v181, v[200:201], off
	v_lshl_add_u64 v[202:203], v[8:9], 0, s[0:1]
	global_load_dword v182, v[202:203], off
	v_lshlrev_b32_e32 v59, 16, v55
	v_mul_f32_e32 v60, 0x3f3504f3, v59
	v_cmp_nlt_f32_e64 s[0:1], |v60|, 1.0
	s_and_saveexec_b64 s[16:17], s[0:1]
	s_xor_b64 s[16:17], exec, s[16:17]
	s_cbranch_execz .LBB0_972
	v_fma_f32 v56, |v60|, s29, v223
	v_fma_f32 v56, |v60|, v56, s20
	v_fma_f32 v56, |v60|, v56, s21
	v_fma_f32 v56, |v60|, v56, s28
	v_fma_f32 v56, |v60|, v56, s33
	v_fma_f32 v56, |v60|, v56, s30
	v_fma_f32 v56, |v60|, v56, |v60|
	v_mul_f32_e32 v61, 0xbfb8aa3b, v56
	v_fma_f32 v62, v56, s31, -v61
	v_rndne_f32_e32 v63, v61
	v_fmac_f32_e32 v62, 0xb2a5705f, v56
	v_sub_f32_e32 v61, v61, v63
	v_add_f32_e32 v61, v61, v62
	v_cvt_i32_f32_e32 v62, v63
	v_exp_f32_e32 v61, v61
	v_cmp_nlt_f32_e32 vcc, s96, v56
	v_ldexp_f32 v61, v61, v62
	s_nop 0
	v_cndmask_b32_e32 v61, 0, v61, vcc
	v_cmp_ngt_f32_e32 vcc, s97, v56
	s_nop 1
	v_cndmask_b32_e32 v56, v224, v61, vcc
	v_sub_f32_e32 v61, 1.0, v56

; DEVI unsigned cvtpk(float lo, float hi) { unsigned r; asm("v_cvt_pk_bf16_f32 %0, %1, %2" : "=v"(r) : "v"(lo), "v"(hi)); return r; }
; DEVI float bflo(unsigned u) { return __uint_as_float(u << 16); }
; DEVI float bfhi(unsigned u) { return __uint_as_float(u & 0xffff0000u); }
; DEVI float geluf_(float x) { return 0.5f * x * (1.f + erff(x * 0.70710678118654752f)); }
; DEVI void lru_p3_phase(const Params& p) {
;     ...
;       for (int t = 63; t >= 0; --t) {
;         const unsigned l = *(const unsigned*)(la + (size_t)t * 1024), bv = *(const unsigned*)(bb + (size_t)t * 1024);
;         h0 = __expf(bflo(l)) * h0 + bflo(bv); h1 = __expf(bfhi(l)) * h1 + bfhi(bv);
;         const unsigned g = *(const unsigned*)(GX + (size_t)(rbase + t) * 2048 + ch);
;         *(unsigned*)(YG + (size_t)(rbase + t) * 1024 + ch) = cvtpk((s0[t] + h0) * geluf_(bflo(g)), (s1[t] + h1) * geluf_(bfhi(g)));
;       }
.LBB0_976:
	s_andn2_saveexec_b64 s[16:17], s[16:17]
	v_mul_f32_e32 v55, v63, v63
	v_fmamk_f32 v56, v55, 0xba1345e1, v217
	v_fmaak_f32 v56, v55, v56, 0xbcdac9b8
	v_fmaak_f32 v56, v55, v56, 0x3de703be
	v_fmaak_f32 v56, v55, v56, 0xbec09330
	v_fmaak_f32 v55, v55, v56, 0x3e0375d0
	v_fma_f32 v64, |v63|, v55, |v63|
	s_or_b64 exec, exec, s[16:17]
	v_lshlrev_b32_e32 v55, 16, v17
	v_mul_f32_e32 v55, 0x3fb8aa3b, v55
	v_exp_f32_e32 v55, v55
	v_and_b32_e32 v17, 0xffff0000, v17
	v_mul_f32_e32 v17, 0x3fb8aa3b, v17
	v_exp_f32_e32 v17, v17
	v_lshlrev_b32_e32 v56, 16, v16
	v_fmac_f32_e32 v56, v58, v55
	v_and_b32_e32 v55, 0xffff0000, v16
	v_add_f32_e32 v16, v53, v56
	v_bfi_b32 v53, s78, v61, v60
	v_fmac_f32_e32 v55, v57, v17
	v_mul_f32_e32 v17, 0.5, v59
	v_add_f32_e32 v53, 1.0, v53
	v_mul_f32_e32 v17, v17, v53
	v_mul_f32_e32 v16, v16, v17
	v_add_f32_e32 v17, v54, v55
	v_bfi_b32 v54, s78, v64, v63
	v_mul_f32_e32 v53, 0.5, v62
	v_add_f32_e32 v54, 1.0, v54
	v_mul_f32_e32 v53, v53, v54
	v_mul_f32_e32 v17, v17, v53
	s_lshl_b64 s[0:1], s[2:3], 11
	v_cvt_pk_bf16_f32 v53, v16, v17
	v_lshl_add_u64 v[16:17], v[10:11], 0, s[0:1]
	global_store_dword v[16:17], v53, off
	v_add_co_u32_e32 v16, vcc, s79, v12
	s_add_i32 s2, s14, 17
	s_nop 0
	v_addc_co_u32_e32 v17, vcc, 0, v13, vcc
	v_add_co_u32_e32 v58, vcc, 0x8000, v14
	s_ashr_i32 s3, s2, 31
	s_nop 0
	v_addc_co_u32_e32 v59, vcc, 0, v15, vcc
	s_lshl_b64 s[0:1], s[2:3], 12
	v_lshl_add_u64 v[58:59], v[8:9], 0, s[0:1]
	s_waitcnt vmcnt(45)
	v_mov_b32_e32 v53, v176
	v_mov_b32_e32 v57, v175
	v_mov_b32_e32 v54, v177
	s_mov_b32 s0, 0x2800
	s_mov_b32 s1, 0
	v_lshl_add_u64 v[198:199], v[12:13], 0, s[0:1]
	v_lshl_add_u64 v[200:201], v[14:15], 0, s[0:1]
	s_add_i32 s0, s14, 5
	s_ashr_i32 s1, s0, 31
	s_lshl_b64 s[0:1], s[0:1], 12
	global_load_dword v175, v[198:199], off
	global_load_dword v176, v[200:201], off
	v_lshl_add_u64 v[202:203], v[8:9], 0, s[0:1]
	global_load_dword v177, v[202:203], off
	v_lshlrev_b32_e32 v58, 16, v54
	v_mul_f32_e32 v59, 0x3f3504f3, v58
	v_cmp_nlt_f32_e64 s[0:1], |v59|, 1.0
	s_and_saveexec_b64 s[16:17], s[0:1]
	s_xor_b64 s[16:17], exec, s[16:17]
	s_cbranch_execz .LBB0_980
	v_fma_f32 v60, |v59|, s29, v223
	v_fma_f32 v60, |v59|, v60, s20
	v_fma_f32 v60, |v59|, v60, s21
	v_fma_f32 v60, |v59|, v60, s28
	v_fma_f32 v60, |v59|, v60, s33
	v_fma_f32 v60, |v59|, v60, s30
	v_fma_f32 v60, |v59|, v60, |v59|
	v_mul_f32_e32 v61, 0xbfb8aa3b, v60
	v_fma_f32 v62, v60, s31, -v61
	v_rndne_f32_e32 v63, v61
	v_fmac_f32_e32 v62, 0xb2a5705f, v60
	v_sub_f32_e32 v61, v61, v63
	v_add_f32_e32 v61, v61, v62
	v_cvt_i32_f32_e32 v62, v63
	v_exp_f32_e32 v61, v61
	v_cmp_nlt_f32_e32 vcc, s96, v60
	v_ldexp_f32 v61, v61, v62
	s_nop 0
	v_cndmask_b32_e32 v61, 0, v61, vcc
	v_cmp_ngt_f32_e32 vcc, s97, v60
	s_nop 1
	v_cndmask_b32_e32 v60, v224, v61, vcc
	v_sub_f32_e32 v60, 1.0, v60

; DEVI unsigned cvtpk(float lo, float hi) { unsigned r; asm("v_cvt_pk_bf16_f32 %0, %1, %2" : "=v"(r) : "v"(lo), "v"(hi)); return r; }
; DEVI float bflo(unsigned u) { return __uint_as_float(u << 16); }
; DEVI float bfhi(unsigned u) { return __uint_as_float(u & 0xffff0000u); }
; DEVI float geluf_(float x) { return 0.5f * x * (1.f + erff(x * 0.70710678118654752f)); }
; DEVI void lru_p3_phase(const Params& p) {
;     ...
;       for (int t = 63; t >= 0; --t) {
;         const unsigned l = *(const unsigned*)(la + (size_t)t * 1024), bv = *(const unsigned*)(bb + (size_t)t * 1024);
;         h0 = __expf(bflo(l)) * h0 + bflo(bv); h1 = __expf(bfhi(l)) * h1 + bfhi(bv);
;         const unsigned g = *(const unsigned*)(GX + (size_t)(rbase + t) * 2048 + ch);
;         *(unsigned*)(YG + (size_t)(rbase + t) * 1024 + ch) = cvtpk((s0[t] + h0) * geluf_(bflo(g)), (s1[t] + h1) * geluf_(bfhi(g)));
;       }
.LBB0_984:
	s_andn2_saveexec_b64 s[16:17], s[16:17]
	v_mul_f32_e32 v54, v62, v62
	v_fmamk_f32 v63, v54, 0xba1345e1, v217
	v_fmaak_f32 v63, v54, v63, 0xbcdac9b8
	v_fmaak_f32 v63, v54, v63, 0x3de703be
	v_fmaak_f32 v63, v54, v63, 0xbec09330
	v_fmaak_f32 v54, v54, v63, 0x3e0375d0
	v_fma_f32 v63, |v62|, v54, |v62|
	s_or_b64 exec, exec, s[16:17]
	v_lshlrev_b32_e32 v54, 16, v57
	v_mul_f32_e32 v54, 0x3fb8aa3b, v54
	v_exp_f32_e32 v64, v54
	v_lshlrev_b32_e32 v54, 16, v53
	v_and_b32_e32 v53, 0xffff0000, v53
	s_lshl_b64 s[0:1], s[2:3], 11
	v_fmac_f32_e32 v54, v56, v64
	v_and_b32_e32 v56, 0xffff0000, v57
	v_mul_f32_e32 v56, 0x3fb8aa3b, v56
	v_exp_f32_e32 v56, v56
	v_add_f32_e32 v51, v51, v54
	s_add_i32 s2, s14, 16
	s_ashr_i32 s3, s2, 31
	v_fmac_f32_e32 v53, v55, v56
	v_bfi_b32 v56, s78, v60, v59
	v_mul_f32_e32 v55, 0.5, v58
	v_add_f32_e32 v56, 1.0, v56
	v_mul_f32_e32 v55, v55, v56
	v_bfi_b32 v56, s78, v63, v62
	v_mul_f32_e32 v51, v51, v55
	v_mul_f32_e32 v55, 0.5, v61
	v_add_f32_e32 v56, 1.0, v56
	v_add_f32_e32 v52, v52, v53
	v_mul_f32_e32 v55, v55, v56
	v_lshl_add_u64 v[56:57], v[10:11], 0, s[0:1]
	v_mul_f32_e32 v52, v52, v55
	v_cvt_pk_bf16_f32 v51, v51, v52
	global_store_dword v[56:57], v51, off
	v_add_co_u32_e32 v56, vcc, 0x8000, v14
	s_lshl_b64 s[0:1], s[2:3], 12
	s_nop 0
	v_addc_co_u32_e32 v57, vcc, 0, v15, vcc
	s_nop 0
	v_lshl_add_u64 v[56:57], v[8:9], 0, s[0:1]
	s_waitcnt vmcnt(45)
	v_mov_b32_e32 v17, v172
	v_mov_b32_e32 v16, v173
	v_mov_b32_e32 v51, v174
	s_mov_b32 s0, 0x2000
	s_mov_b32 s1, 0
	v_lshl_add_u64 v[198:199], v[12:13], 0, s[0:1]
	v_lshl_add_u64 v[200:201], v[14:15], 0, s[0:1]
	s_add_i32 s0, s14, 4
	s_ashr_i32 s1, s0, 31
	s_lshl_b64 s[0:1], s[0:1], 12
	global_load_dword v172, v[198:199], off
	global_load_dword v173, v[200:201], off
	v_lshl_add_u64 v[202:203], v[8:9], 0, s[0:1]
	global_load_dword v174, v[202:203], off
	v_lshlrev_b32_e32 v55, 16, v51
	v_mul_f32_e32 v56, 0x3f3504f3, v55
	v_cmp_nlt_f32_e64 s[0:1], |v56|, 1.0
	s_and_saveexec_b64 s[16:17], s[0:1]
	s_xor_b64 s[16:17], exec, s[16:17]
	s_cbranch_execz .LBB0_988
	v_fma_f32 v52, |v56|, s29, v223
	v_fma_f32 v52, |v56|, v52, s20
	v_fma_f32 v52, |v56|, v52, s21
	v_fma_f32 v52, |v56|, v52, s28
	v_fma_f32 v52, |v56|, v52, s33
	v_fma_f32 v52, |v56|, v52, s30
	v_fma_f32 v52, |v56|, v52, |v56|
	v_mul_f32_e32 v57, 0xbfb8aa3b, v52
	v_fma_f32 v58, v52, s31, -v57
	v_rndne_f32_e32 v59, v57
	v_fmac_f32_e32 v58, 0xb2a5705f, v52
	v_sub_f32_e32 v57, v57, v59
	v_add_f32_e32 v57, v57, v58
	v_cvt_i32_f32_e32 v58, v59
	v_exp_f32_e32 v57, v57
	v_cmp_nlt_f32_e32 vcc, s96, v52
	v_ldexp_f32 v57, v57, v58
	s_nop 0
	v_cndmask_b32_e32 v57, 0, v57, vcc
	v_cmp_ngt_f32_e32 vcc, s97, v52
	s_nop 1
	v_cndmask_b32_e32 v52, v224, v57, vcc
	v_sub_f32_e32 v57, 1.0, v52

; DEVI unsigned cvtpk(float lo, float hi) { unsigned r; asm("v_cvt_pk_bf16_f32 %0, %1, %2" : "=v"(r) : "v"(lo), "v"(hi)); return r; }
; DEVI float bflo(unsigned u) { return __uint_as_float(u << 16); }
; DEVI float bfhi(unsigned u) { return __uint_as_float(u & 0xffff0000u); }
; DEVI float geluf_(float x) { return 0.5f * x * (1.f + erff(x * 0.70710678118654752f)); }
; DEVI void lru_p3_phase(const Params& p) {
;     ...
;       for (int t = 63; t >= 0; --t) {
;         const unsigned l = *(const unsigned*)(la + (size_t)t * 1024), bv = *(const unsigned*)(bb + (size_t)t * 1024);
;         h0 = __expf(bflo(l)) * h0 + bflo(bv); h1 = __expf(bfhi(l)) * h1 + bfhi(bv);
;         const unsigned g = *(const unsigned*)(GX + (size_t)(rbase + t) * 2048 + ch);
;         *(unsigned*)(YG + (size_t)(rbase + t) * 1024 + ch) = cvtpk((s0[t] + h0) * geluf_(bflo(g)), (s1[t] + h1) * geluf_(bfhi(g)));
;       }
.LBB0_992:
	s_andn2_saveexec_b64 s[16:17], s[16:17]
	v_mul_f32_e32 v51, v59, v59
	v_fmamk_f32 v52, v51, 0xba1345e1, v217
	v_fmaak_f32 v52, v51, v52, 0xbcdac9b8
	v_fmaak_f32 v52, v51, v52, 0x3de703be
	v_fmaak_f32 v52, v51, v52, 0xbec09330
	v_fmaak_f32 v51, v51, v52, 0x3e0375d0
	v_fma_f32 v60, |v59|, v51, |v59|
	s_or_b64 exec, exec, s[16:17]
	v_lshlrev_b32_e32 v51, 16, v17
	v_mul_f32_e32 v51, 0x3fb8aa3b, v51
	v_exp_f32_e32 v51, v51
	v_and_b32_e32 v17, 0xffff0000, v17
	v_mul_f32_e32 v17, 0x3fb8aa3b, v17
	v_exp_f32_e32 v17, v17
	v_lshlrev_b32_e32 v52, 16, v16
	v_fmac_f32_e32 v52, v54, v51
	v_and_b32_e32 v51, 0xffff0000, v16
	v_add_f32_e32 v16, v49, v52
	v_bfi_b32 v49, s78, v57, v56
	v_fmac_f32_e32 v51, v53, v17
	v_mul_f32_e32 v17, 0.5, v55
	v_add_f32_e32 v49, 1.0, v49
	v_mul_f32_e32 v17, v17, v49
	v_mul_f32_e32 v16, v16, v17
	v_add_f32_e32 v17, v50, v51
	v_bfi_b32 v50, s78, v60, v59
	v_mul_f32_e32 v49, 0.5, v58
	v_add_f32_e32 v50, 1.0, v50
	v_mul_f32_e32 v49, v49, v50
	v_mul_f32_e32 v17, v17, v49
	s_lshl_b64 s[0:1], s[2:3], 11
	v_cvt_pk_bf16_f32 v49, v16, v17
	v_lshl_add_u64 v[16:17], v[10:11], 0, s[0:1]
	global_store_dword v[16:17], v49, off
	v_add_co_u32_e32 v16, vcc, s44, v12
	s_add_i32 s2, s14, 15
	s_nop 0
	v_addc_co_u32_e32 v17, vcc, 0, v13, vcc
	v_add_co_u32_e32 v54, vcc, 0x7000, v14
	s_ashr_i32 s3, s2, 31
	s_nop 0
	v_addc_co_u32_e32 v55, vcc, 0, v15, vcc
	s_lshl_b64 s[0:1], s[2:3], 12
	v_lshl_add_u64 v[54:55], v[8:9], 0, s[0:1]
	s_waitcnt vmcnt(45)
	v_mov_b32_e32 v49, v170
	v_mov_b32_e32 v53, v169
	v_mov_b32_e32 v50, v171
	s_mov_b32 s0, 0x1800
	s_mov_b32 s1, 0
	v_lshl_add_u64 v[198:199], v[12:13], 0, s[0:1]
	v_lshl_add_u64 v[200:201], v[14:15], 0, s[0:1]
	s_add_i32 s0, s14, 3
	s_ashr_i32 s1, s0, 31
	s_lshl_b64 s[0:1], s[0:1], 12
	global_load_dword v169, v[198:199], off
	global_load_dword v170, v[200:201], off
	v_lshl_add_u64 v[202:203], v[8:9], 0, s[0:1]
	global_load_dword v171, v[202:203], off
	v_lshlrev_b32_e32 v54, 16, v50
	v_mul_f32_e32 v55, 0x3f3504f3, v54
	v_cmp_nlt_f32_e64 s[0:1], |v55|, 1.0
	s_and_saveexec_b64 s[16:17], s[0:1]
	s_xor_b64 s[16:17], exec, s[16:17]
	s_cbranch_execz .LBB0_996
	v_fma_f32 v56, |v55|, s29, v223
	v_fma_f32 v56, |v55|, v56, s20
	v_fma_f32 v56, |v55|, v56, s21
	v_fma_f32 v56, |v55|, v56, s28
	v_fma_f32 v56, |v55|, v56, s33
	v_fma_f32 v56, |v55|, v56, s30
	v_fma_f32 v56, |v55|, v56, |v55|
	v_mul_f32_e32 v57, 0xbfb8aa3b, v56
	v_fma_f32 v58, v56, s31, -v57
	v_rndne_f32_e32 v59, v57
	v_fmac_f32_e32 v58, 0xb2a5705f, v56
	v_sub_f32_e32 v57, v57, v59
	v_add_f32_e32 v57, v57, v58
	v_cvt_i32_f32_e32 v58, v59
	v_exp_f32_e32 v57, v57
	v_cmp_nlt_f32_e32 vcc, s96, v56
	v_ldexp_f32 v57, v57, v58
	s_nop 0
	v_cndmask_b32_e32 v57, 0, v57, vcc
	v_cmp_ngt_f32_e32 vcc, s97, v56
	s_nop 1
	v_cndmask_b32_e32 v56, v224, v57, vcc
	v_sub_f32_e32 v56, 1.0, v56

; DEVI unsigned cvtpk(float lo, float hi) { unsigned r; asm("v_cvt_pk_bf16_f32 %0, %1, %2" : "=v"(r) : "v"(lo), "v"(hi)); return r; }
; DEVI float bflo(unsigned u) { return __uint_as_float(u << 16); }
; DEVI float bfhi(unsigned u) { return __uint_as_float(u & 0xffff0000u); }
; DEVI float geluf_(float x) { return 0.5f * x * (1.f + erff(x * 0.70710678118654752f)); }
; DEVI void lru_p3_phase(const Params& p) {
;     ...
;       for (int t = 63; t >= 0; --t) {
;         const unsigned l = *(const unsigned*)(la + (size_t)t * 1024), bv = *(const unsigned*)(bb + (size_t)t * 1024);
;         h0 = __expf(bflo(l)) * h0 + bflo(bv); h1 = __expf(bfhi(l)) * h1 + bfhi(bv);
;         const unsigned g = *(const unsigned*)(GX + (size_t)(rbase + t) * 2048 + ch);
;         *(unsigned*)(YG + (size_t)(rbase + t) * 1024 + ch) = cvtpk((s0[t] + h0) * geluf_(bflo(g)), (s1[t] + h1) * geluf_(bfhi(g)));
;       }
.LBB0_1000:
	s_andn2_saveexec_b64 s[16:17], s[16:17]
	v_mul_f32_e32 v50, v58, v58
	v_fmamk_f32 v59, v50, 0xba1345e1, v217
	v_fmaak_f32 v59, v50, v59, 0xbcdac9b8
	v_fmaak_f32 v59, v50, v59, 0x3de703be
	v_fmaak_f32 v59, v50, v59, 0xbec09330
	v_fmaak_f32 v50, v50, v59, 0x3e0375d0
	v_fma_f32 v59, |v58|, v50, |v58|
	s_or_b64 exec, exec, s[16:17]
	v_lshlrev_b32_e32 v50, 16, v53
	v_mul_f32_e32 v50, 0x3fb8aa3b, v50
	v_exp_f32_e32 v60, v50
	v_lshlrev_b32_e32 v50, 16, v49
	v_and_b32_e32 v49, 0xffff0000, v49
	s_lshl_b64 s[0:1], s[2:3], 11
	v_fmac_f32_e32 v50, v52, v60
	v_and_b32_e32 v52, 0xffff0000, v53
	v_mul_f32_e32 v52, 0x3fb8aa3b, v52
	v_exp_f32_e32 v52, v52
	v_add_f32_e32 v47, v47, v50
	s_add_i32 s2, s14, 14
	s_ashr_i32 s3, s2, 31
	v_fmac_f32_e32 v49, v51, v52
	v_bfi_b32 v52, s78, v56, v55
	v_mul_f32_e32 v51, 0.5, v54
	v_add_f32_e32 v52, 1.0, v52
	v_mul_f32_e32 v51, v51, v52
	v_bfi_b32 v52, s78, v59, v58
	v_mul_f32_e32 v47, v47, v51
	v_mul_f32_e32 v51, 0.5, v57
	v_add_f32_e32 v52, 1.0, v52
	v_add_f32_e32 v48, v48, v49
	v_mul_f32_e32 v51, v51, v52
	v_lshl_add_u64 v[52:53], v[10:11], 0, s[0:1]
	v_mul_f32_e32 v48, v48, v51
	v_cvt_pk_bf16_f32 v47, v47, v48
	global_store_dword v[52:53], v47, off
	v_add_co_u32_e32 v52, vcc, 0x7000, v14
	s_lshl_b64 s[0:1], s[2:3], 12
	s_nop 0
	v_addc_co_u32_e32 v53, vcc, 0, v15, vcc
	s_nop 0
	v_lshl_add_u64 v[52:53], v[8:9], 0, s[0:1]
	s_waitcnt vmcnt(45)
	v_mov_b32_e32 v17, v166
	v_mov_b32_e32 v16, v167
	v_mov_b32_e32 v47, v168
	s_mov_b32 s0, 0x1000
	s_mov_b32 s1, 0
	v_lshl_add_u64 v[198:199], v[12:13], 0, s[0:1]
	v_lshl_add_u64 v[200:201], v[14:15], 0, s[0:1]
	s_add_i32 s0, s14, 2
	s_ashr_i32 s1, s0, 31
	s_lshl_b64 s[0:1], s[0:1], 12
	global_load_dword v166, v[198:199], off
	global_load_dword v167, v[200:201], off
	v_lshl_add_u64 v[202:203], v[8:9], 0, s[0:1]
	global_load_dword v168, v[202:203], off
	v_lshlrev_b32_e32 v51, 16, v47
	v_mul_f32_e32 v52, 0x3f3504f3, v51
	v_cmp_nlt_f32_e64 s[0:1], |v52|, 1.0
	s_and_saveexec_b64 s[16:17], s[0:1]
	s_xor_b64 s[16:17], exec, s[16:17]
	s_cbranch_execz .LBB0_1004
	v_fma_f32 v48, |v52|, s29, v223
	v_fma_f32 v48, |v52|, v48, s20
	v_fma_f32 v48, |v52|, v48, s21
	v_fma_f32 v48, |v52|, v48, s28
	v_fma_f32 v48, |v52|, v48, s33
	v_fma_f32 v48, |v52|, v48, s30
	v_fma_f32 v48, |v52|, v48, |v52|
	v_mul_f32_e32 v53, 0xbfb8aa3b, v48
	v_fma_f32 v54, v48, s31, -v53
	v_rndne_f32_e32 v55, v53
	v_fmac_f32_e32 v54, 0xb2a5705f, v48
	v_sub_f32_e32 v53, v53, v55
	v_add_f32_e32 v53, v53, v54
	v_cvt_i32_f32_e32 v54, v55
	v_exp_f32_e32 v53, v53
	v_cmp_nlt_f32_e32 vcc, s96, v48
	v_ldexp_f32 v53, v53, v54
	s_nop 0
	v_cndmask_b32_e32 v53, 0, v53, vcc
	v_cmp_ngt_f32_e32 vcc, s97, v48
	s_nop 1
	v_cndmask_b32_e32 v48, v224, v53, vcc
	v_sub_f32_e32 v53, 1.0, v48

; DEVI unsigned cvtpk(float lo, float hi) { unsigned r; asm("v_cvt_pk_bf16_f32 %0, %1, %2" : "=v"(r) : "v"(lo), "v"(hi)); return r; }
; DEVI float bflo(unsigned u) { return __uint_as_float(u << 16); }
; DEVI float bfhi(unsigned u) { return __uint_as_float(u & 0xffff0000u); }
; DEVI float geluf_(float x) { return 0.5f * x * (1.f + erff(x * 0.70710678118654752f)); }
; DEVI void lru_p3_phase(const Params& p) {
;     ...
;       for (int t = 63; t >= 0; --t) {
;         const unsigned l = *(const unsigned*)(la + (size_t)t * 1024), bv = *(const unsigned*)(bb + (size_t)t * 1024);
;         h0 = __expf(bflo(l)) * h0 + bflo(bv); h1 = __expf(bfhi(l)) * h1 + bfhi(bv);
;         const unsigned g = *(const unsigned*)(GX + (size_t)(rbase + t) * 2048 + ch);
;         *(unsigned*)(YG + (size_t)(rbase + t) * 1024 + ch) = cvtpk((s0[t] + h0) * geluf_(bflo(g)), (s1[t] + h1) * geluf_(bfhi(g)));
;       }
.LBB0_1008:
	s_andn2_saveexec_b64 s[16:17], s[16:17]
	v_mul_f32_e32 v47, v55, v55
	v_fmamk_f32 v48, v47, 0xba1345e1, v217
	v_fmaak_f32 v48, v47, v48, 0xbcdac9b8
	v_fmaak_f32 v48, v47, v48, 0x3de703be
	v_fmaak_f32 v48, v47, v48, 0xbec09330
	v_fmaak_f32 v47, v47, v48, 0x3e0375d0
	v_fma_f32 v56, |v55|, v47, |v55|
	s_or_b64 exec, exec, s[16:17]
	v_lshlrev_b32_e32 v47, 16, v17
	v_mul_f32_e32 v47, 0x3fb8aa3b, v47
	v_exp_f32_e32 v47, v47
	v_and_b32_e32 v17, 0xffff0000, v17
	v_mul_f32_e32 v17, 0x3fb8aa3b, v17
	v_exp_f32_e32 v17, v17
	v_lshlrev_b32_e32 v48, 16, v16
	v_fmac_f32_e32 v48, v50, v47
	v_and_b32_e32 v47, 0xffff0000, v16
	v_add_f32_e32 v16, v45, v48
	v_bfi_b32 v45, s78, v53, v52
	v_fmac_f32_e32 v47, v49, v17
	v_mul_f32_e32 v17, 0.5, v51
	v_add_f32_e32 v45, 1.0, v45
	v_mul_f32_e32 v17, v17, v45
	v_mul_f32_e32 v16, v16, v17
	v_add_f32_e32 v17, v46, v47
	v_bfi_b32 v46, s78, v56, v55
	v_mul_f32_e32 v45, 0.5, v54
	v_add_f32_e32 v46, 1.0, v46
	v_mul_f32_e32 v45, v45, v46
	v_mul_f32_e32 v17, v17, v45
	s_lshl_b64 s[0:1], s[2:3], 11
	v_cvt_pk_bf16_f32 v45, v16, v17
	v_lshl_add_u64 v[16:17], v[10:11], 0, s[0:1]
	global_store_dword v[16:17], v45, off
	v_add_co_u32_e32 v16, vcc, s24, v12
	s_add_i32 s2, s14, 13
	s_nop 0
	v_addc_co_u32_e32 v17, vcc, 0, v13, vcc
	v_add_co_u32_e32 v50, vcc, 0x6000, v14
	s_ashr_i32 s3, s2, 31
	s_nop 0
	v_addc_co_u32_e32 v51, vcc, 0, v15, vcc
	s_lshl_b64 s[0:1], s[2:3], 12
	v_lshl_add_u64 v[50:51], v[8:9], 0, s[0:1]
	s_waitcnt vmcnt(45)
	v_mov_b32_e32 v45, v164
	v_mov_b32_e32 v49, v163
	v_mov_b32_e32 v46, v165
	v_lshlrev_b32_e32 v50, 16, v46
	v_mul_f32_e32 v51, 0x3f3504f3, v50
	v_cmp_nlt_f32_e64 s[0:1], |v51|, 1.0
	s_and_saveexec_b64 s[16:17], s[0:1]
	s_xor_b64 s[16:17], exec, s[16:17]
	s_cbranch_execz .LBB0_1012
	v_fma_f32 v52, |v51|, s29, v223
	v_fma_f32 v52, |v51|, v52, s20
	v_fma_f32 v52, |v51|, v52, s21
	v_fma_f32 v52, |v51|, v52, s28
	v_fma_f32 v52, |v51|, v52, s33
	v_fma_f32 v52, |v51|, v52, s30
	v_fma_f32 v52, |v51|, v52, |v51|
	v_mul_f32_e32 v53, 0xbfb8aa3b, v52
	v_fma_f32 v54, v52, s31, -v53
	v_rndne_f32_e32 v55, v53
	v_fmac_f32_e32 v54, 0xb2a5705f, v52
	v_sub_f32_e32 v53, v53, v55
	v_add_f32_e32 v53, v53, v54
	v_cvt_i32_f32_e32 v54, v55
	v_exp_f32_e32 v53, v53
	v_cmp_nlt_f32_e32 vcc, s96, v52
	v_ldexp_f32 v53, v53, v54
	s_nop 0
	v_cndmask_b32_e32 v53, 0, v53, vcc
	v_cmp_ngt_f32_e32 vcc, s97, v52
	s_nop 1
	v_cndmask_b32_e32 v52, v224, v53, vcc
	v_sub_f32_e32 v52, 1.0, v52

; DEVI unsigned cvtpk(float lo, float hi) { unsigned r; asm("v_cvt_pk_bf16_f32 %0, %1, %2" : "=v"(r) : "v"(lo), "v"(hi)); return r; }
; DEVI float bflo(unsigned u) { return __uint_as_float(u << 16); }
; DEVI float bfhi(unsigned u) { return __uint_as_float(u & 0xffff0000u); }
; DEVI float geluf_(float x) { return 0.5f * x * (1.f + erff(x * 0.70710678118654752f)); }
; DEVI void lru_p3_phase(const Params& p) {
;     ...
;       for (int t = 63; t >= 0; --t) {
;         const unsigned l = *(const unsigned*)(la + (size_t)t * 1024), bv = *(const unsigned*)(bb + (size_t)t * 1024);
;         h0 = __expf(bflo(l)) * h0 + bflo(bv); h1 = __expf(bfhi(l)) * h1 + bfhi(bv);
;         const unsigned g = *(const unsigned*)(GX + (size_t)(rbase + t) * 2048 + ch);
;         *(unsigned*)(YG + (size_t)(rbase + t) * 1024 + ch) = cvtpk((s0[t] + h0) * geluf_(bflo(g)), (s1[t] + h1) * geluf_(bfhi(g)));
;       }
.LBB0_1016:
	s_andn2_saveexec_b64 s[16:17], s[16:17]
	v_mul_f32_e32 v46, v54, v54
	v_fmamk_f32 v55, v46, 0xba1345e1, v217
	v_fmaak_f32 v55, v46, v55, 0xbcdac9b8
	v_fmaak_f32 v55, v46, v55, 0x3de703be
	v_fmaak_f32 v55, v46, v55, 0xbec09330
	v_fmaak_f32 v46, v46, v55, 0x3e0375d0
	v_fma_f32 v55, |v54|, v46, |v54|
	s_or_b64 exec, exec, s[16:17]
	v_lshlrev_b32_e32 v46, 16, v49
	v_mul_f32_e32 v46, 0x3fb8aa3b, v46
	v_exp_f32_e32 v56, v46
	v_lshlrev_b32_e32 v46, 16, v45
	v_and_b32_e32 v45, 0xffff0000, v45
	s_lshl_b64 s[0:1], s[2:3], 11
	v_fmac_f32_e32 v46, v48, v56
	v_and_b32_e32 v48, 0xffff0000, v49
	v_mul_f32_e32 v48, 0x3fb8aa3b, v48
	v_exp_f32_e32 v48, v48
	v_add_f32_e32 v43, v43, v46
	s_add_i32 s2, s14, 12
	s_ashr_i32 s3, s2, 31
	v_fmac_f32_e32 v45, v47, v48
	v_bfi_b32 v48, s78, v52, v51
	v_mul_f32_e32 v47, 0.5, v50
	v_add_f32_e32 v48, 1.0, v48
	v_mul_f32_e32 v47, v47, v48
	v_bfi_b32 v48, s78, v55, v54
	v_mul_f32_e32 v43, v43, v47
	v_mul_f32_e32 v47, 0.5, v53
	v_add_f32_e32 v48, 1.0, v48
	v_add_f32_e32 v44, v44, v45
	v_mul_f32_e32 v47, v47, v48
	v_lshl_add_u64 v[48:49], v[10:11], 0, s[0:1]
	v_mul_f32_e32 v44, v44, v47
	v_cvt_pk_bf16_f32 v43, v43, v44
	global_store_dword v[48:49], v43, off
	v_add_co_u32_e32 v48, vcc, 0x6000, v14
	s_lshl_b64 s[0:1], s[2:3], 12
	s_nop 0
	v_addc_co_u32_e32 v49, vcc, 0, v15, vcc
	s_nop 0
	v_lshl_add_u64 v[48:49], v[8:9], 0, s[0:1]
	s_waitcnt vmcnt(42)
	v_mov_b32_e32 v17, v160
	v_mov_b32_e32 v16, v161
	v_mov_b32_e32 v43, v162
	v_lshlrev_b32_e32 v47, 16, v43
	v_mul_f32_e32 v48, 0x3f3504f3, v47
	v_cmp_nlt_f32_e64 s[0:1], |v48|, 1.0
	s_and_saveexec_b64 s[16:17], s[0:1]
	s_xor_b64 s[16:17], exec, s[16:17]
	s_cbranch_execz .LBB0_1020
	v_fma_f32 v44, |v48|, s29, v223
	v_fma_f32 v44, |v48|, v44, s20
	v_fma_f32 v44, |v48|, v44, s21
	v_fma_f32 v44, |v48|, v44, s28
	v_fma_f32 v44, |v48|, v44, s33
	v_fma_f32 v44, |v48|, v44, s30
	v_fma_f32 v44, |v48|, v44, |v48|
	v_mul_f32_e32 v49, 0xbfb8aa3b, v44
	v_fma_f32 v50, v44, s31, -v49
	v_rndne_f32_e32 v51, v49
	v_fmac_f32_e32 v50, 0xb2a5705f, v44
	v_sub_f32_e32 v49, v49, v51
	v_add_f32_e32 v49, v49, v50
	v_cvt_i32_f32_e32 v50, v51
	v_exp_f32_e32 v49, v49
	v_cmp_nlt_f32_e32 vcc, s96, v44
	v_ldexp_f32 v49, v49, v50
	s_nop 0
	v_cndmask_b32_e32 v49, 0, v49, vcc
	v_cmp_ngt_f32_e32 vcc, s97, v44
	s_nop 1
	v_cndmask_b32_e32 v44, v224, v49, vcc
	v_sub_f32_e32 v49, 1.0, v44

; DEVI unsigned cvtpk(float lo, float hi) { unsigned r; asm("v_cvt_pk_bf16_f32 %0, %1, %2" : "=v"(r) : "v"(lo), "v"(hi)); return r; }
; DEVI float bflo(unsigned u) { return __uint_as_float(u << 16); }
; DEVI float bfhi(unsigned u) { return __uint_as_float(u & 0xffff0000u); }
; DEVI float geluf_(float x) { return 0.5f * x * (1.f + erff(x * 0.70710678118654752f)); }
; DEVI void lru_p3_phase(const Params& p) {
;     ...
;       for (int t = 63; t >= 0; --t) {
;         const unsigned l = *(const unsigned*)(la + (size_t)t * 1024), bv = *(const unsigned*)(bb + (size_t)t * 1024);
;         h0 = __expf(bflo(l)) * h0 + bflo(bv); h1 = __expf(bfhi(l)) * h1 + bfhi(bv);
;         const unsigned g = *(const unsigned*)(GX + (size_t)(rbase + t) * 2048 + ch);
;         *(unsigned*)(YG + (size_t)(rbase + t) * 1024 + ch) = cvtpk((s0[t] + h0) * geluf_(bflo(g)), (s1[t] + h1) * geluf_(bfhi(g)));
;       }
.LBB0_1024:
	s_andn2_saveexec_b64 s[16:17], s[16:17]
	v_mul_f32_e32 v43, v51, v51
	v_fmamk_f32 v44, v43, 0xba1345e1, v217
	v_fmaak_f32 v44, v43, v44, 0xbcdac9b8
	v_fmaak_f32 v44, v43, v44, 0x3de703be
	v_fmaak_f32 v44, v43, v44, 0xbec09330
	v_fmaak_f32 v43, v43, v44, 0x3e0375d0
	v_fma_f32 v52, |v51|, v43, |v51|
	s_or_b64 exec, exec, s[16:17]
	v_lshlrev_b32_e32 v43, 16, v17
	v_mul_f32_e32 v43, 0x3fb8aa3b, v43
	v_exp_f32_e32 v43, v43
	v_and_b32_e32 v17, 0xffff0000, v17
	v_mul_f32_e32 v17, 0x3fb8aa3b, v17
	v_exp_f32_e32 v17, v17
	v_lshlrev_b32_e32 v44, 16, v16
	v_fmac_f32_e32 v44, v46, v43
	v_and_b32_e32 v43, 0xffff0000, v16
	v_add_f32_e32 v16, v41, v44
	v_bfi_b32 v41, s78, v49, v48
	v_fmac_f32_e32 v43, v45, v17
	v_mul_f32_e32 v17, 0.5, v47
	v_add_f32_e32 v41, 1.0, v41
	v_mul_f32_e32 v17, v17, v41
	v_mul_f32_e32 v16, v16, v17
	v_add_f32_e32 v17, v42, v43
	v_bfi_b32 v42, s78, v52, v51
	v_mul_f32_e32 v41, 0.5, v50
	v_add_f32_e32 v42, 1.0, v42
	v_mul_f32_e32 v41, v41, v42
	v_mul_f32_e32 v17, v17, v41
	s_lshl_b64 s[0:1], s[2:3], 11
	v_cvt_pk_bf16_f32 v41, v16, v17
	v_lshl_add_u64 v[16:17], v[10:11], 0, s[0:1]
	global_store_dword v[16:17], v41, off
	v_add_co_u32_e32 v16, vcc, s42, v12
	s_add_i32 s2, s14, 11
	s_nop 0
	v_addc_co_u32_e32 v17, vcc, 0, v13, vcc
	v_add_co_u32_e32 v46, vcc, 0x5000, v14
	s_ashr_i32 s3, s2, 31
	s_nop 0
	v_addc_co_u32_e32 v47, vcc, 0, v15, vcc
	s_lshl_b64 s[0:1], s[2:3], 12
	v_lshl_add_u64 v[46:47], v[8:9], 0, s[0:1]
	s_waitcnt vmcnt(39)
	v_mov_b32_e32 v41, v196
	v_mov_b32_e32 v45, v195
	v_mov_b32_e32 v42, v197
	v_lshlrev_b32_e32 v46, 16, v42
	v_mul_f32_e32 v47, 0x3f3504f3, v46
	v_cmp_nlt_f32_e64 s[0:1], |v47|, 1.0
	s_and_saveexec_b64 s[16:17], s[0:1]
	s_xor_b64 s[16:17], exec, s[16:17]
	s_cbranch_execz .LBB0_1028
	v_fma_f32 v48, |v47|, s29, v223
	v_fma_f32 v48, |v47|, v48, s20
	v_fma_f32 v48, |v47|, v48, s21
	v_fma_f32 v48, |v47|, v48, s28
	v_fma_f32 v48, |v47|, v48, s33
	v_fma_f32 v48, |v47|, v48, s30
	v_fma_f32 v48, |v47|, v48, |v47|
	v_mul_f32_e32 v49, 0xbfb8aa3b, v48
	v_fma_f32 v50, v48, s31, -v49
	v_rndne_f32_e32 v51, v49
	v_fmac_f32_e32 v50, 0xb2a5705f, v48
	v_sub_f32_e32 v49, v49, v51
	v_add_f32_e32 v49, v49, v50
	v_cvt_i32_f32_e32 v50, v51
	v_exp_f32_e32 v49, v49
	v_cmp_nlt_f32_e32 vcc, s96, v48
	v_ldexp_f32 v49, v49, v50
	s_nop 0
	v_cndmask_b32_e32 v49, 0, v49, vcc
	v_cmp_ngt_f32_e32 vcc, s97, v48
	s_nop 1
	v_cndmask_b32_e32 v48, v224, v49, vcc
	v_sub_f32_e32 v48, 1.0, v48

; DEVI unsigned cvtpk(float lo, float hi) { unsigned r; asm("v_cvt_pk_bf16_f32 %0, %1, %2" : "=v"(r) : "v"(lo), "v"(hi)); return r; }
; DEVI float bflo(unsigned u) { return __uint_as_float(u << 16); }
; DEVI float bfhi(unsigned u) { return __uint_as_float(u & 0xffff0000u); }
; DEVI float geluf_(float x) { return 0.5f * x * (1.f + erff(x * 0.70710678118654752f)); }
; DEVI void lru_p3_phase(const Params& p) {
;     ...
;       for (int t = 63; t >= 0; --t) {
;         const unsigned l = *(const unsigned*)(la + (size_t)t * 1024), bv = *(const unsigned*)(bb + (size_t)t * 1024);
;         h0 = __expf(bflo(l)) * h0 + bflo(bv); h1 = __expf(bfhi(l)) * h1 + bfhi(bv);
;         const unsigned g = *(const unsigned*)(GX + (size_t)(rbase + t) * 2048 + ch);
;         *(unsigned*)(YG + (size_t)(rbase + t) * 1024 + ch) = cvtpk((s0[t] + h0) * geluf_(bflo(g)), (s1[t] + h1) * geluf_(bfhi(g)));
;       }
.LBB0_1032:
	s_andn2_saveexec_b64 s[16:17], s[16:17]
	v_mul_f32_e32 v42, v50, v50
	v_fmamk_f32 v51, v42, 0xba1345e1, v217
	v_fmaak_f32 v51, v42, v51, 0xbcdac9b8
	v_fmaak_f32 v51, v42, v51, 0x3de703be
	v_fmaak_f32 v51, v42, v51, 0xbec09330
	v_fmaak_f32 v42, v42, v51, 0x3e0375d0
	v_fma_f32 v51, |v50|, v42, |v50|
	s_or_b64 exec, exec, s[16:17]
	v_lshlrev_b32_e32 v42, 16, v45
	v_mul_f32_e32 v42, 0x3fb8aa3b, v42
	v_exp_f32_e32 v52, v42
	v_lshlrev_b32_e32 v42, 16, v41
	v_and_b32_e32 v41, 0xffff0000, v41
	s_lshl_b64 s[0:1], s[2:3], 11
	v_fmac_f32_e32 v42, v44, v52
	v_and_b32_e32 v44, 0xffff0000, v45
	v_mul_f32_e32 v44, 0x3fb8aa3b, v44
	v_exp_f32_e32 v44, v44
	v_add_f32_e32 v39, v39, v42
	s_add_i32 s2, s14, 10
	s_ashr_i32 s3, s2, 31
	v_fmac_f32_e32 v41, v43, v44
	v_bfi_b32 v44, s78, v48, v47
	v_mul_f32_e32 v43, 0.5, v46
	v_add_f32_e32 v44, 1.0, v44
	v_mul_f32_e32 v43, v43, v44
	v_bfi_b32 v44, s78, v51, v50
	v_mul_f32_e32 v39, v39, v43
	v_mul_f32_e32 v43, 0.5, v49
	v_add_f32_e32 v44, 1.0, v44
	v_add_f32_e32 v40, v40, v41
	v_mul_f32_e32 v43, v43, v44
	v_lshl_add_u64 v[44:45], v[10:11], 0, s[0:1]
	v_mul_f32_e32 v40, v40, v43
	v_cvt_pk_bf16_f32 v39, v39, v40
	global_store_dword v[44:45], v39, off
	v_add_co_u32_e32 v44, vcc, 0x5000, v14
	s_lshl_b64 s[0:1], s[2:3], 12
	s_nop 0
	v_addc_co_u32_e32 v45, vcc, 0, v15, vcc
	s_nop 0
	v_lshl_add_u64 v[44:45], v[8:9], 0, s[0:1]
	s_waitcnt vmcnt(36)
	v_mov_b32_e32 v17, v192
	v_mov_b32_e32 v16, v193
	v_mov_b32_e32 v39, v194
	v_lshlrev_b32_e32 v43, 16, v39
	v_mul_f32_e32 v44, 0x3f3504f3, v43
	v_cmp_nlt_f32_e64 s[0:1], |v44|, 1.0
	s_and_saveexec_b64 s[16:17], s[0:1]
	s_xor_b64 s[16:17], exec, s[16:17]
	s_cbranch_execz .LBB0_1036
	v_fma_f32 v40, |v44|, s29, v223
	v_fma_f32 v40, |v44|, v40, s20
	v_fma_f32 v40, |v44|, v40, s21
	v_fma_f32 v40, |v44|, v40, s28
	v_fma_f32 v40, |v44|, v40, s33
	v_fma_f32 v40, |v44|, v40, s30
	v_fma_f32 v40, |v44|, v40, |v44|
	v_mul_f32_e32 v45, 0xbfb8aa3b, v40
	v_fma_f32 v46, v40, s31, -v45
	v_rndne_f32_e32 v47, v45
	v_fmac_f32_e32 v46, 0xb2a5705f, v40
	v_sub_f32_e32 v45, v45, v47
	v_add_f32_e32 v45, v45, v46
	v_cvt_i32_f32_e32 v46, v47
	v_exp_f32_e32 v45, v45
	v_cmp_nlt_f32_e32 vcc, s96, v40
	v_ldexp_f32 v45, v45, v46
	s_nop 0
	v_cndmask_b32_e32 v45, 0, v45, vcc
	v_cmp_ngt_f32_e32 vcc, s97, v40
	s_nop 1
	v_cndmask_b32_e32 v40, v224, v45, vcc
	v_sub_f32_e32 v45, 1.0, v40

; DEVI unsigned cvtpk(float lo, float hi) { unsigned r; asm("v_cvt_pk_bf16_f32 %0, %1, %2" : "=v"(r) : "v"(lo), "v"(hi)); return r; }
; DEVI float bflo(unsigned u) { return __uint_as_float(u << 16); }
; DEVI float bfhi(unsigned u) { return __uint_as_float(u & 0xffff0000u); }
; DEVI float geluf_(float x) { return 0.5f * x * (1.f + erff(x * 0.70710678118654752f)); }
; DEVI void lru_p3_phase(const Params& p) {
;     ...
;       for (int t = 63; t >= 0; --t) {
;         const unsigned l = *(const unsigned*)(la + (size_t)t * 1024), bv = *(const unsigned*)(bb + (size_t)t * 1024);
;         h0 = __expf(bflo(l)) * h0 + bflo(bv); h1 = __expf(bfhi(l)) * h1 + bfhi(bv);
;         const unsigned g = *(const unsigned*)(GX + (size_t)(rbase + t) * 2048 + ch);
;         *(unsigned*)(YG + (size_t)(rbase + t) * 1024 + ch) = cvtpk((s0[t] + h0) * geluf_(bflo(g)), (s1[t] + h1) * geluf_(bfhi(g)));
;       }
.LBB0_1040:
	s_andn2_saveexec_b64 s[16:17], s[16:17]
	v_mul_f32_e32 v39, v47, v47
	v_fmamk_f32 v40, v39, 0xba1345e1, v217
	v_fmaak_f32 v40, v39, v40, 0xbcdac9b8
	v_fmaak_f32 v40, v39, v40, 0x3de703be
	v_fmaak_f32 v40, v39, v40, 0xbec09330
	v_fmaak_f32 v39, v39, v40, 0x3e0375d0
	v_fma_f32 v48, |v47|, v39, |v47|
	s_or_b64 exec, exec, s[16:17]
	v_lshlrev_b32_e32 v39, 16, v17
	v_mul_f32_e32 v39, 0x3fb8aa3b, v39
	v_exp_f32_e32 v39, v39
	v_and_b32_e32 v17, 0xffff0000, v17
	v_mul_f32_e32 v17, 0x3fb8aa3b, v17
	v_exp_f32_e32 v17, v17
	v_lshlrev_b32_e32 v40, 16, v16
	v_fmac_f32_e32 v40, v42, v39
	v_and_b32_e32 v39, 0xffff0000, v16
	v_add_f32_e32 v16, v37, v40
	v_bfi_b32 v37, s78, v45, v44
	v_fmac_f32_e32 v39, v41, v17
	v_mul_f32_e32 v17, 0.5, v43
	v_add_f32_e32 v37, 1.0, v37
	v_mul_f32_e32 v17, v17, v37
	v_mul_f32_e32 v16, v16, v17
	v_add_f32_e32 v17, v38, v39
	v_bfi_b32 v38, s78, v48, v47
	v_mul_f32_e32 v37, 0.5, v46
	v_add_f32_e32 v38, 1.0, v38
	v_mul_f32_e32 v37, v37, v38
	v_mul_f32_e32 v17, v17, v37
	s_lshl_b64 s[0:1], s[2:3], 11
	v_cvt_pk_bf16_f32 v37, v16, v17
	v_lshl_add_u64 v[16:17], v[10:11], 0, s[0:1]
	s_movk_i32 s0, 0x4000
	global_store_dword v[16:17], v37, off
	v_add_co_u32_e32 v16, vcc, s0, v12
	s_add_i32 s2, s14, 9
	s_nop 0
	v_addc_co_u32_e32 v17, vcc, 0, v13, vcc
	v_add_co_u32_e32 v42, vcc, 0x4000, v14
	s_ashr_i32 s3, s2, 31
	s_nop 0
	v_addc_co_u32_e32 v43, vcc, 0, v15, vcc
	s_lshl_b64 s[0:1], s[2:3], 12
	v_lshl_add_u64 v[42:43], v[8:9], 0, s[0:1]
	s_waitcnt vmcnt(33)
	v_mov_b32_e32 v37, v190
	v_mov_b32_e32 v41, v189
	v_mov_b32_e32 v38, v191
	v_lshlrev_b32_e32 v42, 16, v38
	v_mul_f32_e32 v43, 0x3f3504f3, v42
	v_cmp_nlt_f32_e64 s[0:1], |v43|, 1.0
	s_and_saveexec_b64 s[16:17], s[0:1]
	s_xor_b64 s[16:17], exec, s[16:17]
	s_cbranch_execz .LBB0_1044
	v_fma_f32 v44, |v43|, s29, v223
	v_fma_f32 v44, |v43|, v44, s20
	v_fma_f32 v44, |v43|, v44, s21
	v_fma_f32 v44, |v43|, v44, s28
	v_fma_f32 v44, |v43|, v44, s33
	v_fma_f32 v44, |v43|, v44, s30
	v_fma_f32 v44, |v43|, v44, |v43|
	v_mul_f32_e32 v45, 0xbfb8aa3b, v44
	v_fma_f32 v46, v44, s31, -v45
	v_rndne_f32_e32 v47, v45
	v_fmac_f32_e32 v46, 0xb2a5705f, v44
	v_sub_f32_e32 v45, v45, v47
	v_add_f32_e32 v45, v45, v46
	v_cvt_i32_f32_e32 v46, v47
	v_exp_f32_e32 v45, v45
	v_cmp_nlt_f32_e32 vcc, s96, v44
	v_ldexp_f32 v45, v45, v46
	s_nop 0
	v_cndmask_b32_e32 v45, 0, v45, vcc
	v_cmp_ngt_f32_e32 vcc, s97, v44
	s_nop 1
	v_cndmask_b32_e32 v44, v224, v45, vcc
	v_sub_f32_e32 v44, 1.0, v44

; DEVI unsigned cvtpk(float lo, float hi) { unsigned r; asm("v_cvt_pk_bf16_f32 %0, %1, %2" : "=v"(r) : "v"(lo), "v"(hi)); return r; }
; DEVI float bflo(unsigned u) { return __uint_as_float(u << 16); }
; DEVI float bfhi(unsigned u) { return __uint_as_float(u & 0xffff0000u); }
; DEVI float geluf_(float x) { return 0.5f * x * (1.f + erff(x * 0.70710678118654752f)); }
; DEVI void lru_p3_phase(const Params& p) {
;     ...
;       for (int t = 63; t >= 0; --t) {
;         const unsigned l = *(const unsigned*)(la + (size_t)t * 1024), bv = *(const unsigned*)(bb + (size_t)t * 1024);
;         h0 = __expf(bflo(l)) * h0 + bflo(bv); h1 = __expf(bfhi(l)) * h1 + bfhi(bv);
;         const unsigned g = *(const unsigned*)(GX + (size_t)(rbase + t) * 2048 + ch);
;         *(unsigned*)(YG + (size_t)(rbase + t) * 1024 + ch) = cvtpk((s0[t] + h0) * geluf_(bflo(g)), (s1[t] + h1) * geluf_(bfhi(g)));
;       }
.LBB0_1048:
	s_andn2_saveexec_b64 s[16:17], s[16:17]
	v_mul_f32_e32 v38, v46, v46
	v_fmamk_f32 v47, v38, 0xba1345e1, v217
	v_fmaak_f32 v47, v38, v47, 0xbcdac9b8
	v_fmaak_f32 v47, v38, v47, 0x3de703be
	v_fmaak_f32 v47, v38, v47, 0xbec09330
	v_fmaak_f32 v38, v38, v47, 0x3e0375d0
	v_fma_f32 v47, |v46|, v38, |v46|
	s_or_b64 exec, exec, s[16:17]
	v_lshlrev_b32_e32 v38, 16, v41
	v_mul_f32_e32 v38, 0x3fb8aa3b, v38
	v_exp_f32_e32 v48, v38
	v_lshlrev_b32_e32 v38, 16, v37
	v_and_b32_e32 v37, 0xffff0000, v37
	s_lshl_b64 s[0:1], s[2:3], 11
	v_fmac_f32_e32 v38, v40, v48
	v_and_b32_e32 v40, 0xffff0000, v41
	v_mul_f32_e32 v40, 0x3fb8aa3b, v40
	v_exp_f32_e32 v40, v40
	v_add_f32_e32 v35, v35, v38
	s_add_i32 s2, s14, 8
	s_ashr_i32 s3, s2, 31
	v_fmac_f32_e32 v37, v39, v40
	v_bfi_b32 v40, s78, v44, v43
	v_mul_f32_e32 v39, 0.5, v42
	v_add_f32_e32 v40, 1.0, v40
	v_mul_f32_e32 v39, v39, v40
	v_bfi_b32 v40, s78, v47, v46
	v_mul_f32_e32 v35, v35, v39
	v_mul_f32_e32 v39, 0.5, v45
	v_add_f32_e32 v40, 1.0, v40
	v_add_f32_e32 v36, v36, v37
	v_mul_f32_e32 v39, v39, v40
	v_lshl_add_u64 v[40:41], v[10:11], 0, s[0:1]
	v_mul_f32_e32 v36, v36, v39
	v_cvt_pk_bf16_f32 v35, v35, v36
	global_store_dword v[40:41], v35, off
	v_add_co_u32_e32 v40, vcc, 0x4000, v14
	s_lshl_b64 s[0:1], s[2:3], 12
	s_nop 0
	v_addc_co_u32_e32 v41, vcc, 0, v15, vcc
	s_nop 0
	v_lshl_add_u64 v[40:41], v[8:9], 0, s[0:1]
	s_waitcnt vmcnt(30)
	v_mov_b32_e32 v17, v186
	v_mov_b32_e32 v16, v187
	v_mov_b32_e32 v35, v188
	v_lshlrev_b32_e32 v39, 16, v35
	v_mul_f32_e32 v40, 0x3f3504f3, v39
	v_cmp_nlt_f32_e64 s[0:1], |v40|, 1.0
	s_and_saveexec_b64 s[16:17], s[0:1]
	s_xor_b64 s[16:17], exec, s[16:17]
	s_cbranch_execz .LBB0_1052
	v_fma_f32 v36, |v40|, s29, v223
	v_fma_f32 v36, |v40|, v36, s20
	v_fma_f32 v36, |v40|, v36, s21
	v_fma_f32 v36, |v40|, v36, s28
	v_fma_f32 v36, |v40|, v36, s33
	v_fma_f32 v36, |v40|, v36, s30
	v_fma_f32 v36, |v40|, v36, |v40|
	v_mul_f32_e32 v41, 0xbfb8aa3b, v36
	v_fma_f32 v42, v36, s31, -v41
	v_rndne_f32_e32 v43, v41
	v_fmac_f32_e32 v42, 0xb2a5705f, v36
	v_sub_f32_e32 v41, v41, v43
	v_add_f32_e32 v41, v41, v42
	v_cvt_i32_f32_e32 v42, v43
	v_exp_f32_e32 v41, v41
	v_cmp_nlt_f32_e32 vcc, s96, v36
	v_ldexp_f32 v41, v41, v42
	s_nop 0
	v_cndmask_b32_e32 v41, 0, v41, vcc
	v_cmp_ngt_f32_e32 vcc, s97, v36
	s_nop 1
	v_cndmask_b32_e32 v36, v224, v41, vcc
	v_sub_f32_e32 v41, 1.0, v36

; DEVI unsigned cvtpk(float lo, float hi) { unsigned r; asm("v_cvt_pk_bf16_f32 %0, %1, %2" : "=v"(r) : "v"(lo), "v"(hi)); return r; }
; DEVI float bflo(unsigned u) { return __uint_as_float(u << 16); }
; DEVI float bfhi(unsigned u) { return __uint_as_float(u & 0xffff0000u); }
; DEVI float geluf_(float x) { return 0.5f * x * (1.f + erff(x * 0.70710678118654752f)); }
; DEVI void lru_p3_phase(const Params& p) {
;     ...
;       for (int t = 63; t >= 0; --t) {
;         const unsigned l = *(const unsigned*)(la + (size_t)t * 1024), bv = *(const unsigned*)(bb + (size_t)t * 1024);
;         h0 = __expf(bflo(l)) * h0 + bflo(bv); h1 = __expf(bfhi(l)) * h1 + bfhi(bv);
;         const unsigned g = *(const unsigned*)(GX + (size_t)(rbase + t) * 2048 + ch);
;         *(unsigned*)(YG + (size_t)(rbase + t) * 1024 + ch) = cvtpk((s0[t] + h0) * geluf_(bflo(g)), (s1[t] + h1) * geluf_(bfhi(g)));
;       }
.LBB0_1056:
	s_andn2_saveexec_b64 s[16:17], s[16:17]
	v_mul_f32_e32 v35, v43, v43
	v_fmamk_f32 v36, v35, 0xba1345e1, v217
	v_fmaak_f32 v36, v35, v36, 0xbcdac9b8
	v_fmaak_f32 v36, v35, v36, 0x3de703be
	v_fmaak_f32 v36, v35, v36, 0xbec09330
	v_fmaak_f32 v35, v35, v36, 0x3e0375d0
	v_fma_f32 v44, |v43|, v35, |v43|
	s_or_b64 exec, exec, s[16:17]
	v_lshlrev_b32_e32 v35, 16, v17
	v_mul_f32_e32 v35, 0x3fb8aa3b, v35
	v_exp_f32_e32 v35, v35
	v_and_b32_e32 v17, 0xffff0000, v17
	v_mul_f32_e32 v17, 0x3fb8aa3b, v17
	v_exp_f32_e32 v17, v17
	v_lshlrev_b32_e32 v36, 16, v16
	v_fmac_f32_e32 v36, v38, v35
	v_and_b32_e32 v35, 0xffff0000, v16
	v_add_f32_e32 v16, v33, v36
	v_bfi_b32 v33, s78, v41, v40
	v_fmac_f32_e32 v35, v37, v17
	v_mul_f32_e32 v17, 0.5, v39
	v_add_f32_e32 v33, 1.0, v33
	v_mul_f32_e32 v17, v17, v33
	v_mul_f32_e32 v16, v16, v17
	v_add_f32_e32 v17, v34, v35
	v_bfi_b32 v34, s78, v44, v43
	v_mul_f32_e32 v33, 0.5, v42
	v_add_f32_e32 v34, 1.0, v34
	v_mul_f32_e32 v33, v33, v34
	v_mul_f32_e32 v17, v17, v33
	s_lshl_b64 s[0:1], s[2:3], 11
	v_cvt_pk_bf16_f32 v33, v16, v17
	v_lshl_add_u64 v[16:17], v[10:11], 0, s[0:1]
	global_store_dword v[16:17], v33, off
	v_add_co_u32_e32 v16, vcc, s35, v12
	s_add_i32 s2, s14, 7
	s_nop 0
	v_addc_co_u32_e32 v17, vcc, 0, v13, vcc
	v_add_co_u32_e32 v38, vcc, 0x3000, v14
	s_ashr_i32 s3, s2, 31
	s_nop 0
	v_addc_co_u32_e32 v39, vcc, 0, v15, vcc
	s_lshl_b64 s[0:1], s[2:3], 12
	v_lshl_add_u64 v[38:39], v[8:9], 0, s[0:1]
	s_waitcnt vmcnt(27)
	v_mov_b32_e32 v33, v184
	v_mov_b32_e32 v37, v183
	v_mov_b32_e32 v34, v185
	v_lshlrev_b32_e32 v38, 16, v34
	v_mul_f32_e32 v39, 0x3f3504f3, v38
	v_cmp_nlt_f32_e64 s[0:1], |v39|, 1.0
	s_and_saveexec_b64 s[16:17], s[0:1]
	s_xor_b64 s[16:17], exec, s[16:17]
	s_cbranch_execz .LBB0_1060
	v_fma_f32 v40, |v39|, s29, v223
	v_fma_f32 v40, |v39|, v40, s20
	v_fma_f32 v40, |v39|, v40, s21
	v_fma_f32 v40, |v39|, v40, s28
	v_fma_f32 v40, |v39|, v40, s33
	v_fma_f32 v40, |v39|, v40, s30
	v_fma_f32 v40, |v39|, v40, |v39|
	v_mul_f32_e32 v41, 0xbfb8aa3b, v40
	v_fma_f32 v42, v40, s31, -v41
	v_rndne_f32_e32 v43, v41
	v_fmac_f32_e32 v42, 0xb2a5705f, v40
	v_sub_f32_e32 v41, v41, v43
	v_add_f32_e32 v41, v41, v42
	v_cvt_i32_f32_e32 v42, v43
	v_exp_f32_e32 v41, v41
	v_cmp_nlt_f32_e32 vcc, s96, v40
	v_ldexp_f32 v41, v41, v42
	s_nop 0
	v_cndmask_b32_e32 v41, 0, v41, vcc
	v_cmp_ngt_f32_e32 vcc, s97, v40
	s_nop 1
	v_cndmask_b32_e32 v40, v224, v41, vcc
	v_sub_f32_e32 v40, 1.0, v40

; DEVI unsigned cvtpk(float lo, float hi) { unsigned r; asm("v_cvt_pk_bf16_f32 %0, %1, %2" : "=v"(r) : "v"(lo), "v"(hi)); return r; }
; DEVI float bflo(unsigned u) { return __uint_as_float(u << 16); }
; DEVI float bfhi(unsigned u) { return __uint_as_float(u & 0xffff0000u); }
; DEVI float geluf_(float x) { return 0.5f * x * (1.f + erff(x * 0.70710678118654752f)); }
; DEVI void lru_p3_phase(const Params& p) {
;     ...
;       for (int t = 63; t >= 0; --t) {
;         const unsigned l = *(const unsigned*)(la + (size_t)t * 1024), bv = *(const unsigned*)(bb + (size_t)t * 1024);
;         h0 = __expf(bflo(l)) * h0 + bflo(bv); h1 = __expf(bfhi(l)) * h1 + bfhi(bv);
;         const unsigned g = *(const unsigned*)(GX + (size_t)(rbase + t) * 2048 + ch);
;         *(unsigned*)(YG + (size_t)(rbase + t) * 1024 + ch) = cvtpk((s0[t] + h0) * geluf_(bflo(g)), (s1[t] + h1) * geluf_(bfhi(g)));
;       }
.LBB0_1064:
	s_andn2_saveexec_b64 s[16:17], s[16:17]
	v_mul_f32_e32 v34, v42, v42
	v_fmamk_f32 v43, v34, 0xba1345e1, v217
	v_fmaak_f32 v43, v34, v43, 0xbcdac9b8
	v_fmaak_f32 v43, v34, v43, 0x3de703be
	v_fmaak_f32 v43, v34, v43, 0xbec09330
	v_fmaak_f32 v34, v34, v43, 0x3e0375d0
	v_fma_f32 v43, |v42|, v34, |v42|
	s_or_b64 exec, exec, s[16:17]
	v_lshlrev_b32_e32 v34, 16, v37
	v_mul_f32_e32 v34, 0x3fb8aa3b, v34
	v_exp_f32_e32 v44, v34
	v_lshlrev_b32_e32 v34, 16, v33
	v_and_b32_e32 v33, 0xffff0000, v33
	s_lshl_b64 s[0:1], s[2:3], 11
	v_fmac_f32_e32 v34, v36, v44
	v_and_b32_e32 v36, 0xffff0000, v37
	v_mul_f32_e32 v36, 0x3fb8aa3b, v36
	v_exp_f32_e32 v36, v36
	v_add_f32_e32 v31, v31, v34
	s_add_i32 s2, s14, 6
	s_ashr_i32 s3, s2, 31
	v_fmac_f32_e32 v33, v35, v36
	v_bfi_b32 v36, s78, v40, v39
	v_mul_f32_e32 v35, 0.5, v38
	v_add_f32_e32 v36, 1.0, v36
	v_mul_f32_e32 v35, v35, v36
	v_bfi_b32 v36, s78, v43, v42
	v_mul_f32_e32 v31, v31, v35
	v_mul_f32_e32 v35, 0.5, v41
	v_add_f32_e32 v36, 1.0, v36
	v_add_f32_e32 v32, v32, v33
	v_mul_f32_e32 v35, v35, v36
	v_lshl_add_u64 v[36:37], v[10:11], 0, s[0:1]
	v_mul_f32_e32 v32, v32, v35
	v_cvt_pk_bf16_f32 v31, v31, v32
	global_store_dword v[36:37], v31, off
	v_add_co_u32_e32 v36, vcc, 0x3000, v14
	s_lshl_b64 s[0:1], s[2:3], 12
	s_nop 0
	v_addc_co_u32_e32 v37, vcc, 0, v15, vcc
	s_nop 0
	v_lshl_add_u64 v[36:37], v[8:9], 0, s[0:1]
	s_waitcnt vmcnt(24)
	v_mov_b32_e32 v17, v180
	v_mov_b32_e32 v16, v181
	v_mov_b32_e32 v31, v182
	v_lshlrev_b32_e32 v35, 16, v31
	v_mul_f32_e32 v36, 0x3f3504f3, v35
	v_cmp_nlt_f32_e64 s[0:1], |v36|, 1.0
	s_and_saveexec_b64 s[16:17], s[0:1]
	s_xor_b64 s[16:17], exec, s[16:17]
	s_cbranch_execz .LBB0_1068
	v_fma_f32 v32, |v36|, s29, v223
	v_fma_f32 v32, |v36|, v32, s20
	v_fma_f32 v32, |v36|, v32, s21
	v_fma_f32 v32, |v36|, v32, s28
	v_fma_f32 v32, |v36|, v32, s33
	v_fma_f32 v32, |v36|, v32, s30
	v_fma_f32 v32, |v36|, v32, |v36|
	v_mul_f32_e32 v37, 0xbfb8aa3b, v32
	v_fma_f32 v38, v32, s31, -v37
	v_rndne_f32_e32 v39, v37
	v_fmac_f32_e32 v38, 0xb2a5705f, v32
	v_sub_f32_e32 v37, v37, v39
	v_add_f32_e32 v37, v37, v38
	v_cvt_i32_f32_e32 v38, v39
	v_exp_f32_e32 v37, v37
	v_cmp_nlt_f32_e32 vcc, s96, v32
	v_ldexp_f32 v37, v37, v38
	s_nop 0
	v_cndmask_b32_e32 v37, 0, v37, vcc
	v_cmp_ngt_f32_e32 vcc, s97, v32
	s_nop 1
	v_cndmask_b32_e32 v32, v224, v37, vcc
	v_sub_f32_e32 v37, 1.0, v32

; DEVI unsigned cvtpk(float lo, float hi) { unsigned r; asm("v_cvt_pk_bf16_f32 %0, %1, %2" : "=v"(r) : "v"(lo), "v"(hi)); return r; }
; DEVI float bflo(unsigned u) { return __uint_as_float(u << 16); }
; DEVI float bfhi(unsigned u) { return __uint_as_float(u & 0xffff0000u); }
; DEVI float geluf_(float x) { return 0.5f * x * (1.f + erff(x * 0.70710678118654752f)); }
; DEVI void lru_p3_phase(const Params& p) {
;     ...
;       for (int t = 63; t >= 0; --t) {
;         const unsigned l = *(const unsigned*)(la + (size_t)t * 1024), bv = *(const unsigned*)(bb + (size_t)t * 1024);
;         h0 = __expf(bflo(l)) * h0 + bflo(bv); h1 = __expf(bfhi(l)) * h1 + bfhi(bv);
;         const unsigned g = *(const unsigned*)(GX + (size_t)(rbase + t) * 2048 + ch);
;         *(unsigned*)(YG + (size_t)(rbase + t) * 1024 + ch) = cvtpk((s0[t] + h0) * geluf_(bflo(g)), (s1[t] + h1) * geluf_(bfhi(g)));
;       }
.LBB0_1072:
	s_andn2_saveexec_b64 s[16:17], s[16:17]
	v_mul_f32_e32 v31, v39, v39
	v_fmamk_f32 v32, v31, 0xba1345e1, v217
	v_fmaak_f32 v32, v31, v32, 0xbcdac9b8
	v_fmaak_f32 v32, v31, v32, 0x3de703be
	v_fmaak_f32 v32, v31, v32, 0xbec09330
	v_fmaak_f32 v31, v31, v32, 0x3e0375d0
	v_fma_f32 v40, |v39|, v31, |v39|
	s_or_b64 exec, exec, s[16:17]
	v_lshlrev_b32_e32 v31, 16, v17
	v_mul_f32_e32 v31, 0x3fb8aa3b, v31
	v_exp_f32_e32 v31, v31
	v_and_b32_e32 v17, 0xffff0000, v17
	v_mul_f32_e32 v17, 0x3fb8aa3b, v17
	v_exp_f32_e32 v17, v17
	v_lshlrev_b32_e32 v32, 16, v16
	v_fmac_f32_e32 v32, v34, v31
	v_and_b32_e32 v31, 0xffff0000, v16
	v_add_f32_e32 v16, v29, v32
	v_bfi_b32 v29, s78, v37, v36
	v_fmac_f32_e32 v31, v33, v17
	v_mul_f32_e32 v17, 0.5, v35
	v_add_f32_e32 v29, 1.0, v29
	v_mul_f32_e32 v17, v17, v29
	v_mul_f32_e32 v16, v16, v17
	v_add_f32_e32 v17, v30, v31
	v_bfi_b32 v30, s78, v40, v39
	v_mul_f32_e32 v29, 0.5, v38
	v_add_f32_e32 v30, 1.0, v30
	v_mul_f32_e32 v29, v29, v30
	v_mul_f32_e32 v17, v17, v29
	s_lshl_b64 s[0:1], s[2:3], 11
	v_cvt_pk_bf16_f32 v29, v16, v17
	v_lshl_add_u64 v[16:17], v[10:11], 0, s[0:1]
	global_store_dword v[16:17], v29, off
	v_add_co_u32_e32 v16, vcc, s52, v12
	s_add_i32 s2, s14, 5
	s_nop 0
	v_addc_co_u32_e32 v17, vcc, 0, v13, vcc
	v_add_co_u32_e32 v34, vcc, 0x2000, v14
	s_ashr_i32 s3, s2, 31
	s_nop 0
	v_addc_co_u32_e32 v35, vcc, 0, v15, vcc
	s_lshl_b64 s[0:1], s[2:3], 12
	v_lshl_add_u64 v[34:35], v[8:9], 0, s[0:1]
	s_waitcnt vmcnt(21)
	v_mov_b32_e32 v29, v176
	v_mov_b32_e32 v33, v175
	v_mov_b32_e32 v30, v177
	v_lshlrev_b32_e32 v34, 16, v30
	v_mul_f32_e32 v35, 0x3f3504f3, v34
	v_cmp_nlt_f32_e64 s[0:1], |v35|, 1.0
	s_and_saveexec_b64 s[16:17], s[0:1]
	s_xor_b64 s[16:17], exec, s[16:17]
	s_cbranch_execz .LBB0_1076
	v_fma_f32 v36, |v35|, s29, v223
	v_fma_f32 v36, |v35|, v36, s20
	v_fma_f32 v36, |v35|, v36, s21
	v_fma_f32 v36, |v35|, v36, s28
	v_fma_f32 v36, |v35|, v36, s33
	v_fma_f32 v36, |v35|, v36, s30
	v_fma_f32 v36, |v35|, v36, |v35|
	v_mul_f32_e32 v37, 0xbfb8aa3b, v36
	v_fma_f32 v38, v36, s31, -v37
	v_rndne_f32_e32 v39, v37
	v_fmac_f32_e32 v38, 0xb2a5705f, v36
	v_sub_f32_e32 v37, v37, v39
	v_add_f32_e32 v37, v37, v38
	v_cvt_i32_f32_e32 v38, v39
	v_exp_f32_e32 v37, v37
	v_cmp_nlt_f32_e32 vcc, s96, v36
	v_ldexp_f32 v37, v37, v38
	s_nop 0
	v_cndmask_b32_e32 v37, 0, v37, vcc
	v_cmp_ngt_f32_e32 vcc, s97, v36
	s_nop 1
	v_cndmask_b32_e32 v36, v224, v37, vcc
	v_sub_f32_e32 v36, 1.0, v36

; DEVI unsigned cvtpk(float lo, float hi) { unsigned r; asm("v_cvt_pk_bf16_f32 %0, %1, %2" : "=v"(r) : "v"(lo), "v"(hi)); return r; }
; DEVI float bflo(unsigned u) { return __uint_as_float(u << 16); }
; DEVI float bfhi(unsigned u) { return __uint_as_float(u & 0xffff0000u); }
; DEVI float geluf_(float x) { return 0.5f * x * (1.f + erff(x * 0.70710678118654752f)); }
; DEVI void lru_p3_phase(const Params& p) {
;     ...
;       for (int t = 63; t >= 0; --t) {
;         const unsigned l = *(const unsigned*)(la + (size_t)t * 1024), bv = *(const unsigned*)(bb + (size_t)t * 1024);
;         h0 = __expf(bflo(l)) * h0 + bflo(bv); h1 = __expf(bfhi(l)) * h1 + bfhi(bv);
;         const unsigned g = *(const unsigned*)(GX + (size_t)(rbase + t) * 2048 + ch);
;         *(unsigned*)(YG + (size_t)(rbase + t) * 1024 + ch) = cvtpk((s0[t] + h0) * geluf_(bflo(g)), (s1[t] + h1) * geluf_(bfhi(g)));
;       }
.LBB0_1080:
	s_andn2_saveexec_b64 s[16:17], s[16:17]
	v_mul_f32_e32 v30, v38, v38
	v_fmamk_f32 v39, v30, 0xba1345e1, v217
	v_fmaak_f32 v39, v30, v39, 0xbcdac9b8
	v_fmaak_f32 v39, v30, v39, 0x3de703be
	v_fmaak_f32 v39, v30, v39, 0xbec09330
	v_fmaak_f32 v30, v30, v39, 0x3e0375d0
	v_fma_f32 v39, |v38|, v30, |v38|
	s_or_b64 exec, exec, s[16:17]
	v_lshlrev_b32_e32 v30, 16, v33
	v_mul_f32_e32 v30, 0x3fb8aa3b, v30
	v_exp_f32_e32 v40, v30
	v_lshlrev_b32_e32 v30, 16, v29
	v_and_b32_e32 v29, 0xffff0000, v29
	s_lshl_b64 s[0:1], s[2:3], 11
	v_fmac_f32_e32 v30, v32, v40
	v_and_b32_e32 v32, 0xffff0000, v33
	v_mul_f32_e32 v32, 0x3fb8aa3b, v32
	v_exp_f32_e32 v32, v32
	v_add_f32_e32 v27, v27, v30
	s_add_i32 s2, s14, 4
	s_ashr_i32 s3, s2, 31
	v_fmac_f32_e32 v29, v31, v32
	v_bfi_b32 v32, s78, v36, v35
	v_mul_f32_e32 v31, 0.5, v34
	v_add_f32_e32 v32, 1.0, v32
	v_mul_f32_e32 v31, v31, v32
	v_bfi_b32 v32, s78, v39, v38
	v_mul_f32_e32 v27, v27, v31
	v_mul_f32_e32 v31, 0.5, v37
	v_add_f32_e32 v32, 1.0, v32
	v_add_f32_e32 v28, v28, v29
	v_mul_f32_e32 v31, v31, v32
	v_lshl_add_u64 v[32:33], v[10:11], 0, s[0:1]
	v_mul_f32_e32 v28, v28, v31
	v_cvt_pk_bf16_f32 v27, v27, v28
	global_store_dword v[32:33], v27, off
	v_add_co_u32_e32 v32, vcc, 0x2000, v14
	s_lshl_b64 s[0:1], s[2:3], 12
	s_nop 0
	v_addc_co_u32_e32 v33, vcc, 0, v15, vcc
	s_nop 0
	v_lshl_add_u64 v[32:33], v[8:9], 0, s[0:1]
	s_waitcnt vmcnt(18)
	v_mov_b32_e32 v17, v172
	v_mov_b32_e32 v16, v173
	v_mov_b32_e32 v27, v174
	v_lshlrev_b32_e32 v31, 16, v27
	v_mul_f32_e32 v32, 0x3f3504f3, v31
	v_cmp_nlt_f32_e64 s[0:1], |v32|, 1.0
	s_and_saveexec_b64 s[16:17], s[0:1]
	s_xor_b64 s[16:17], exec, s[16:17]
	s_cbranch_execz .LBB0_1084
	v_fma_f32 v28, |v32|, s29, v223
	v_fma_f32 v28, |v32|, v28, s20
	v_fma_f32 v28, |v32|, v28, s21
	v_fma_f32 v28, |v32|, v28, s28
	v_fma_f32 v28, |v32|, v28, s33
	v_fma_f32 v28, |v32|, v28, s30
	v_fma_f32 v28, |v32|, v28, |v32|
	v_mul_f32_e32 v33, 0xbfb8aa3b, v28
	v_fma_f32 v34, v28, s31, -v33
	v_rndne_f32_e32 v35, v33
	v_fmac_f32_e32 v34, 0xb2a5705f, v28
	v_sub_f32_e32 v33, v33, v35
	v_add_f32_e32 v33, v33, v34
	v_cvt_i32_f32_e32 v34, v35
	v_exp_f32_e32 v33, v33
	v_cmp_nlt_f32_e32 vcc, s96, v28
	v_ldexp_f32 v33, v33, v34
	s_nop 0
	v_cndmask_b32_e32 v33, 0, v33, vcc
	v_cmp_ngt_f32_e32 vcc, s97, v28
	s_nop 1
	v_cndmask_b32_e32 v28, v224, v33, vcc
	v_sub_f32_e32 v33, 1.0, v28

; DEVI unsigned cvtpk(float lo, float hi) { unsigned r; asm("v_cvt_pk_bf16_f32 %0, %1, %2" : "=v"(r) : "v"(lo), "v"(hi)); return r; }
; DEVI float bflo(unsigned u) { return __uint_as_float(u << 16); }
; DEVI float bfhi(unsigned u) { return __uint_as_float(u & 0xffff0000u); }
; DEVI float geluf_(float x) { return 0.5f * x * (1.f + erff(x * 0.70710678118654752f)); }
; DEVI void lru_p3_phase(const Params& p) {
;     ...
;       for (int t = 63; t >= 0; --t) {
;         const unsigned l = *(const unsigned*)(la + (size_t)t * 1024), bv = *(const unsigned*)(bb + (size_t)t * 1024);
;         h0 = __expf(bflo(l)) * h0 + bflo(bv); h1 = __expf(bfhi(l)) * h1 + bfhi(bv);
;         const unsigned g = *(const unsigned*)(GX + (size_t)(rbase + t) * 2048 + ch);
;         *(unsigned*)(YG + (size_t)(rbase + t) * 1024 + ch) = cvtpk((s0[t] + h0) * geluf_(bflo(g)), (s1[t] + h1) * geluf_(bfhi(g)));
;       }
.LBB0_1088:
	s_andn2_saveexec_b64 s[16:17], s[16:17]
	v_mul_f32_e32 v27, v35, v35
	v_fmamk_f32 v28, v27, 0xba1345e1, v217
	v_fmaak_f32 v28, v27, v28, 0xbcdac9b8
	v_fmaak_f32 v28, v27, v28, 0x3de703be
	v_fmaak_f32 v28, v27, v28, 0xbec09330
	v_fmaak_f32 v27, v27, v28, 0x3e0375d0
	v_fma_f32 v36, |v35|, v27, |v35|
	s_or_b64 exec, exec, s[16:17]
	v_lshlrev_b32_e32 v27, 16, v17
	v_mul_f32_e32 v27, 0x3fb8aa3b, v27
	v_exp_f32_e32 v27, v27
	v_and_b32_e32 v17, 0xffff0000, v17
	v_mul_f32_e32 v17, 0x3fb8aa3b, v17
	v_exp_f32_e32 v17, v17
	v_lshlrev_b32_e32 v28, 16, v16
	v_fmac_f32_e32 v28, v30, v27
	v_and_b32_e32 v27, 0xffff0000, v16
	v_add_f32_e32 v16, v25, v28
	v_bfi_b32 v25, s78, v33, v32
	v_fmac_f32_e32 v27, v29, v17
	v_mul_f32_e32 v17, 0.5, v31
	v_add_f32_e32 v25, 1.0, v25
	v_mul_f32_e32 v17, v17, v25
	v_mul_f32_e32 v16, v16, v17
	v_add_f32_e32 v17, v26, v27
	v_bfi_b32 v26, s78, v36, v35
	v_mul_f32_e32 v25, 0.5, v34
	v_add_f32_e32 v26, 1.0, v26
	v_mul_f32_e32 v25, v25, v26
	v_mul_f32_e32 v17, v17, v25
	s_lshl_b64 s[0:1], s[2:3], 11
	v_cvt_pk_bf16_f32 v25, v16, v17
	v_lshl_add_u64 v[16:17], v[10:11], 0, s[0:1]
	global_store_dword v[16:17], v25, off
	v_add_co_u32_e32 v16, vcc, s51, v12
	s_add_i32 s2, s14, 3
	s_nop 0
	v_addc_co_u32_e32 v17, vcc, 0, v13, vcc
	v_add_co_u32_e32 v30, vcc, 0x1000, v14
	s_ashr_i32 s3, s2, 31
	s_nop 0
	v_addc_co_u32_e32 v31, vcc, 0, v15, vcc
	s_lshl_b64 s[0:1], s[2:3], 12
	v_lshl_add_u64 v[30:31], v[8:9], 0, s[0:1]
	s_waitcnt vmcnt(15)
	v_mov_b32_e32 v26, v170
	v_mov_b32_e32 v29, v169
	v_mov_b32_e32 v25, v171
	v_lshlrev_b32_e32 v30, 16, v25
	v_mul_f32_e32 v31, 0x3f3504f3, v30
	v_cmp_nlt_f32_e64 s[0:1], |v31|, 1.0
	s_and_saveexec_b64 s[16:17], s[0:1]
	s_xor_b64 s[16:17], exec, s[16:17]
	s_cbranch_execz .LBB0_1092
	v_fma_f32 v32, |v31|, s29, v223
	v_fma_f32 v32, |v31|, v32, s20
	v_fma_f32 v32, |v31|, v32, s21
	v_fma_f32 v32, |v31|, v32, s28
	v_fma_f32 v32, |v31|, v32, s33
	v_fma_f32 v32, |v31|, v32, s30
	v_fma_f32 v32, |v31|, v32, |v31|
	v_mul_f32_e32 v33, 0xbfb8aa3b, v32
	v_fma_f32 v34, v32, s31, -v33
	v_rndne_f32_e32 v35, v33
	v_fmac_f32_e32 v34, 0xb2a5705f, v32
	v_sub_f32_e32 v33, v33, v35
	v_add_f32_e32 v33, v33, v34
	v_cvt_i32_f32_e32 v34, v35
	v_exp_f32_e32 v33, v33
	v_cmp_nlt_f32_e32 vcc, s96, v32
	v_ldexp_f32 v33, v33, v34
	s_nop 0
	v_cndmask_b32_e32 v33, 0, v33, vcc
	v_cmp_ngt_f32_e32 vcc, s97, v32
	s_nop 1
	v_cndmask_b32_e32 v32, v224, v33, vcc
	v_sub_f32_e32 v32, 1.0, v32

; DEVI unsigned cvtpk(float lo, float hi) { unsigned r; asm("v_cvt_pk_bf16_f32 %0, %1, %2" : "=v"(r) : "v"(lo), "v"(hi)); return r; }
; DEVI float bflo(unsigned u) { return __uint_as_float(u << 16); }
; DEVI float bfhi(unsigned u) { return __uint_as_float(u & 0xffff0000u); }
; DEVI float geluf_(float x) { return 0.5f * x * (1.f + erff(x * 0.70710678118654752f)); }
; DEVI void lru_p3_phase(const Params& p) {
;     ...
;       for (int t = 63; t >= 0; --t) {
;         const unsigned l = *(const unsigned*)(la + (size_t)t * 1024), bv = *(const unsigned*)(bb + (size_t)t * 1024);
;         h0 = __expf(bflo(l)) * h0 + bflo(bv); h1 = __expf(bfhi(l)) * h1 + bfhi(bv);
;         const unsigned g = *(const unsigned*)(GX + (size_t)(rbase + t) * 2048 + ch);
;         *(unsigned*)(YG + (size_t)(rbase + t) * 1024 + ch) = cvtpk((s0[t] + h0) * geluf_(bflo(g)), (s1[t] + h1) * geluf_(bfhi(g)));
;       }
.LBB0_1096:
	s_andn2_saveexec_b64 s[16:17], s[16:17]
	v_mul_f32_e32 v25, v34, v34
	v_fmamk_f32 v35, v25, 0xba1345e1, v217
	v_fmaak_f32 v35, v25, v35, 0xbcdac9b8
	v_fmaak_f32 v35, v25, v35, 0x3de703be
	v_fmaak_f32 v35, v25, v35, 0xbec09330
	v_fmaak_f32 v25, v25, v35, 0x3e0375d0
	v_fma_f32 v35, |v34|, v25, |v34|
	s_or_b64 exec, exec, s[16:17]
	v_lshlrev_b32_e32 v25, 16, v29
	v_mul_f32_e32 v25, 0x3fb8aa3b, v25
	v_exp_f32_e32 v36, v25
	v_lshlrev_b32_e32 v25, 16, v26
	v_and_b32_e32 v26, 0xffff0000, v26
	s_lshl_b64 s[0:1], s[2:3], 11
	v_fmac_f32_e32 v25, v28, v36
	v_and_b32_e32 v28, 0xffff0000, v29
	v_mul_f32_e32 v28, 0x3fb8aa3b, v28
	v_exp_f32_e32 v28, v28
	v_add_f32_e32 v23, v23, v25
	s_add_i32 s2, s14, 2
	s_ashr_i32 s3, s2, 31
	v_fmac_f32_e32 v26, v27, v28
	v_bfi_b32 v28, s78, v32, v31
	v_mul_f32_e32 v27, 0.5, v30
	v_add_f32_e32 v28, 1.0, v28
	v_mul_f32_e32 v27, v27, v28
	v_bfi_b32 v28, s78, v35, v34
	v_mul_f32_e32 v23, v23, v27
	v_mul_f32_e32 v27, 0.5, v33
	v_add_f32_e32 v28, 1.0, v28
	v_add_f32_e32 v24, v24, v26
	v_mul_f32_e32 v27, v27, v28
	v_lshl_add_u64 v[28:29], v[10:11], 0, s[0:1]
	v_mul_f32_e32 v24, v24, v27
	v_cvt_pk_bf16_f32 v23, v23, v24
	global_store_dword v[28:29], v23, off
	v_add_co_u32_e32 v28, vcc, 0x1000, v14
	s_lshl_b64 s[0:1], s[2:3], 12
	s_nop 0
	v_addc_co_u32_e32 v29, vcc, 0, v15, vcc
	s_nop 0
	v_lshl_add_u64 v[28:29], v[8:9], 0, s[0:1]
	s_waitcnt vmcnt(12)
	v_mov_b32_e32 v16, v166
	v_mov_b32_e32 v17, v167
	v_mov_b32_e32 v23, v168
	v_lshlrev_b32_e32 v24, 16, v23
	v_mul_f32_e32 v27, 0x3f3504f3, v24
	v_cmp_nlt_f32_e64 s[0:1], |v27|, 1.0
	s_and_saveexec_b64 s[16:17], s[0:1]
	s_xor_b64 s[16:17], exec, s[16:17]
	s_cbranch_execz .LBB0_1100
	v_fma_f32 v28, |v27|, s29, v223
	v_fma_f32 v28, |v27|, v28, s20
	v_fma_f32 v28, |v27|, v28, s21
	v_fma_f32 v28, |v27|, v28, s28
	v_fma_f32 v28, |v27|, v28, s33
	v_fma_f32 v28, |v27|, v28, s30
	v_fma_f32 v28, |v27|, v28, |v27|
	v_mul_f32_e32 v29, 0xbfb8aa3b, v28
	v_fma_f32 v30, v28, s31, -v29
	v_rndne_f32_e32 v31, v29
	v_fmac_f32_e32 v30, 0xb2a5705f, v28
	v_sub_f32_e32 v29, v29, v31
	v_add_f32_e32 v29, v29, v30
	v_cvt_i32_f32_e32 v30, v31
	v_exp_f32_e32 v29, v29
	v_cmp_nlt_f32_e32 vcc, s96, v28
	v_ldexp_f32 v29, v29, v30
	s_nop 0
	v_cndmask_b32_e32 v29, 0, v29, vcc
	v_cmp_ngt_f32_e32 vcc, s97, v28
	s_nop 1
	v_cndmask_b32_e32 v28, v224, v29, vcc
	v_sub_f32_e32 v28, 1.0, v28
